# v28 + MLA score MFMAs seeded from persistent -m block, wave_sum via DPP, ts table hoisted in phase 12
# speedup vs baseline: 1.0213x; 1.0051x over previous
; #define LAS __attribute__((address_space(3)))
; __device__ __forceinline__ void xprep_row(const f32x4 (&v)[8], const int m, LAS float* wf, bf16_t* XB, float* LOGF, const float* bfg, const int lane) {
;         unsigned* o4 = (unsigned*)((unsigned char*)XB + (size_t)m * DM) + lane;
; #pragma unroll
;         for (int j = 0; j < 8; ++j) o4[64 * j] = pg8::pack4i8(v[j] * ASC_XI8);
;         float f[8];
; #pragma unroll
;         for (int e = 0; e < 8; ++e) { float s = 0.f;
; #pragma unroll
;             for (int j = 0; j < 8; ++j) { const f32x4 w = *(const LAS f32x4*)(wf + e * 2048 + 256 * j + 4 * lane); s = fmaf(v[j][0], w[0], s); s = fmaf(v[j][1], w[1], s); s = fmaf(v[j][2], w[2], s); s = fmaf(v[j][3], w[3], s); }
;             f[e] = wave_sum(s); }
.LBB0_989:
	s_or_b64 exec, exec, s[28:29]
	ds_read_b128 v[98:101], v65
	ds_read_b128 v[102:105], v65 offset:1024
	s_waitcnt vmcnt(7) lgkmcnt(4)
	v_pk_mul_f32 v[88:89], v[2:3], s[26:27] op_sel_hi:[1,0]
	s_waitcnt lgkmcnt(3)
	v_pk_mul_f32 v[90:91], v[0:1], s[26:27] op_sel_hi:[1,0]
	v_med3_f32 v88, v88, s35, v85
	v_med3_f32 v75, v90, s35, v85
	v_med3_f32 v90, v91, s35, v85
	v_med3_f32 v89, v89, s35, v85
	v_ashrrev_i32_e32 v79, 31, v78
	v_add_f32_e32 v75, 0x4b400000, v75
	v_add_f32_e32 v90, 0x4b400000, v90
	v_add_f32_e32 v88, 0x4b400000, v88
	v_add_f32_e32 v89, 0x4b400000, v89
	v_lshlrev_b64 v[80:81], 11, v[78:79]
	v_perm_b32 v75, v90, v75, s36
	v_perm_b32 v88, v89, v88, s37
	v_lshl_add_u64 v[80:81], v[68:69], 0, v[80:81]
	v_or_b32_e32 v75, v75, v88
	s_waitcnt vmcnt(6)
	v_pk_mul_f32 v[88:89], v[6:7], s[26:27] op_sel_hi:[1,0]
	v_pk_mul_f32 v[90:91], v[4:5], s[26:27] op_sel_hi:[1,0]
	s_waitcnt lgkmcnt(1)
	v_fma_f32 v97, v0, v98, 0
	global_store_dword v[80:81], v75, off
	v_med3_f32 v75, v90, s35, v85
	v_med3_f32 v90, v91, s35, v85
	v_med3_f32 v88, v88, s35, v85
	v_med3_f32 v89, v89, s35, v85
	v_fmac_f32_e32 v97, v1, v99
	v_add_f32_e32 v75, 0x4b400000, v75
	v_add_f32_e32 v90, 0x4b400000, v90
	v_add_f32_e32 v88, 0x4b400000, v88
	v_add_f32_e32 v89, 0x4b400000, v89
	v_fmac_f32_e32 v97, v2, v100
	v_perm_b32 v75, v90, v75, s36
	v_perm_b32 v88, v89, v88, s37
	v_fmac_f32_e32 v97, v3, v101
	ds_read_b128 v[98:101], v65 offset:2048
	v_or_b32_e32 v75, v75, v88
	s_waitcnt vmcnt(6)
	v_pk_mul_f32 v[88:89], v[10:11], s[26:27] op_sel_hi:[1,0]
	v_pk_mul_f32 v[90:91], v[8:9], s[26:27] op_sel_hi:[1,0]
	s_waitcnt lgkmcnt(1)
	v_fmac_f32_e32 v97, v4, v102
	global_store_dword v[80:81], v75, off offset:256
	v_med3_f32 v75, v90, s35, v85
	v_med3_f32 v90, v91, s35, v85
	v_med3_f32 v88, v88, s35, v85
	v_med3_f32 v89, v89, s35, v85
	v_fmac_f32_e32 v97, v5, v103
	v_add_f32_e32 v75, 0x4b400000, v75
	v_add_f32_e32 v90, 0x4b400000, v90
	v_add_f32_e32 v88, 0x4b400000, v88
	v_add_f32_e32 v89, 0x4b400000, v89
	v_fmac_f32_e32 v97, v6, v104
	v_perm_b32 v75, v90, v75, s36
	v_perm_b32 v88, v89, v88, s37
	v_fmac_f32_e32 v97, v7, v105
	ds_read_b128 v[102:105], v65 offset:3072
	v_or_b32_e32 v75, v75, v88
	s_waitcnt vmcnt(6)
	v_pk_mul_f32 v[88:89], v[14:15], s[26:27] op_sel_hi:[1,0]
	v_pk_mul_f32 v[90:91], v[12:13], s[26:27] op_sel_hi:[1,0]
	s_waitcnt lgkmcnt(1)
	v_fmac_f32_e32 v97, v8, v98
	global_store_dword v[80:81], v75, off offset:512
	v_med3_f32 v75, v90, s35, v85
	v_med3_f32 v90, v91, s35, v85
	v_med3_f32 v88, v88, s35, v85
	v_med3_f32 v89, v89, s35, v85
	v_fmac_f32_e32 v97, v9, v99
	v_add_f32_e32 v75, 0x4b400000, v75
	v_add_f32_e32 v90, 0x4b400000, v90
	v_add_f32_e32 v88, 0x4b400000, v88
	v_add_f32_e32 v89, 0x4b400000, v89
	v_fmac_f32_e32 v97, v10, v100
	v_perm_b32 v75, v90, v75, s36
	v_perm_b32 v88, v89, v88, s37
	v_fmac_f32_e32 v97, v11, v101
	ds_read_b128 v[98:101], v65 offset:4096
	v_or_b32_e32 v75, v75, v88
	s_waitcnt vmcnt(6)
	v_pk_mul_f32 v[88:89], v[18:19], s[26:27] op_sel_hi:[1,0]
	v_pk_mul_f32 v[90:91], v[16:17], s[26:27] op_sel_hi:[1,0]
	s_waitcnt lgkmcnt(1)
	v_fmac_f32_e32 v97, v12, v102
	global_store_dword v[80:81], v75, off offset:768
	v_med3_f32 v75, v90, s35, v85
	v_med3_f32 v90, v91, s35, v85
	v_med3_f32 v88, v88, s35, v85
	v_med3_f32 v89, v89, s35, v85
	v_fmac_f32_e32 v97, v13, v103
	v_add_f32_e32 v75, 0x4b400000, v75
	v_add_f32_e32 v90, 0x4b400000, v90
	v_add_f32_e32 v88, 0x4b400000, v88
	v_add_f32_e32 v89, 0x4b400000, v89
	v_fmac_f32_e32 v97, v14, v104
	v_perm_b32 v75, v90, v75, s36
	v_perm_b32 v88, v89, v88, s37
	v_fmac_f32_e32 v97, v15, v105
	ds_read_b128 v[102:105], v65 offset:5120
	v_or_b32_e32 v75, v75, v88
	s_waitcnt vmcnt(6)
	v_pk_mul_f32 v[88:89], v[22:23], s[26:27] op_sel_hi:[1,0]
	v_pk_mul_f32 v[90:91], v[20:21], s[26:27] op_sel_hi:[1,0]
	s_waitcnt lgkmcnt(1)
	v_fmac_f32_e32 v97, v16, v98
	global_store_dword v[80:81], v75, off offset:1024
	v_med3_f32 v75, v90, s35, v85
	v_med3_f32 v90, v91, s35, v85
	v_med3_f32 v88, v88, s35, v85
	v_med3_f32 v89, v89, s35, v85
	v_fmac_f32_e32 v97, v17, v99
	v_add_f32_e32 v75, 0x4b400000, v75
	v_add_f32_e32 v90, 0x4b400000, v90
	v_add_f32_e32 v88, 0x4b400000, v88
	v_add_f32_e32 v89, 0x4b400000, v89
	v_fmac_f32_e32 v97, v18, v100
	v_perm_b32 v75, v90, v75, s36
	v_perm_b32 v88, v89, v88, s37
	v_fmac_f32_e32 v97, v19, v101
	ds_read_b128 v[98:101], v65 offset:6144
	v_or_b32_e32 v75, v75, v88
	s_waitcnt vmcnt(6)
	v_pk_mul_f32 v[88:89], v[26:27], s[26:27] op_sel_hi:[1,0]
	v_pk_mul_f32 v[90:91], v[24:25], s[26:27] op_sel_hi:[1,0]
	s_waitcnt lgkmcnt(1)
	v_fmac_f32_e32 v97, v20, v102
	global_store_dword v[80:81], v75, off offset:1280
	v_med3_f32 v75, v90, s35, v85
	v_med3_f32 v90, v91, s35, v85
	v_med3_f32 v88, v88, s35, v85
	v_med3_f32 v89, v89, s35, v85
	v_fmac_f32_e32 v97, v21, v103
	v_add_f32_e32 v75, 0x4b400000, v75
	v_add_f32_e32 v90, 0x4b400000, v90
	v_add_f32_e32 v88, 0x4b400000, v88
	v_add_f32_e32 v89, 0x4b400000, v89
	v_fmac_f32_e32 v97, v22, v104
	v_perm_b32 v75, v90, v75, s36
	v_perm_b32 v88, v89, v88, s37
	v_fmac_f32_e32 v97, v23, v105
	ds_read_b128 v[102:105], v65 offset:7168
	v_or_b32_e32 v75, v75, v88
	s_waitcnt vmcnt(6)
	v_pk_mul_f32 v[88:89], v[30:31], s[26:27] op_sel_hi:[1,0]
	s_waitcnt lgkmcnt(1)
	v_fmac_f32_e32 v97, v24, v98
	v_med3_f32 v88, v88, s35, v85
	v_fmac_f32_e32 v97, v25, v99
	v_add_f32_e32 v95, 0x4b400000, v88
	v_med3_f32 v88, v89, s35, v85
	v_fmac_f32_e32 v97, v26, v100
	v_add_f32_e32 v96, 0x4b400000, v88
	v_and_b32_e32 v88, 64, v86
	v_fmac_f32_e32 v97, v27, v101
	v_add_u32_e32 v93, 64, v88
	v_xor_b32_e32 v88, 1, v86
	s_waitcnt lgkmcnt(0)
; #define LAS __attribute__((address_space(3)))
; __device__ __forceinline__ float wave_sum(float v) {
; #pragma unroll
;     for (int o = 1; o < 64; o <<= 1) v += __shfl_xor(v, o);
;     return v;
; }
; __device__ __forceinline__ void xprep_row(const f32x4 (&v)[8], const int m, LAS float* wf, bf16_t* XB, float* LOGF, const float* bfg, const int lane) {
;     ...
;         for (int e = 0; e < 8; ++e) { float s = 0.f;
; #pragma unroll
;             for (int j = 0; j < 8; ++j) { const f32x4 w = *(const LAS f32x4*)(wf + e * 2048 + 256 * j + 4 * lane); s = fmaf(v[j][0], w[0], s); s = fmaf(v[j][1], w[1], s); s = fmaf(v[j][2], w[2], s); s = fmaf(v[j][3], w[3], s); }
;             f[e] = wave_sum(s); }
	v_fmac_f32_e32 v97, v28, v102
	v_pk_mul_f32 v[90:91], v[28:29], s[26:27] op_sel_hi:[1,0]
	v_cmp_lt_i32_e32 vcc, v88, v93
	v_fmac_f32_e32 v97, v29, v103
	global_store_dword v[80:81], v75, off offset:1536
	v_med3_f32 v75, v90, s35, v85
	v_med3_f32 v90, v91, s35, v85
	v_cndmask_b32_e32 v88, v86, v88, vcc
	v_fmac_f32_e32 v97, v30, v104
	v_add_f32_e32 v94, 0x4b400000, v90
	v_lshlrev_b32_e32 v90, 2, v88
	v_fmac_f32_e32 v97, v31, v105
	s_nop 1
	v_mov_b32_dpp v102, v97 quad_perm:[1,0,3,2] row_mask:0xf bank_mask:0xf
	ds_read_b128 v[98:101], v65 offset:8192
	v_xor_b32_e32 v88, 2, v86
	v_cmp_lt_i32_e32 vcc, v88, v93
	v_xor_b32_e32 v91, 8, v86
	s_waitcnt lgkmcnt(0)
	v_add_f32_e32 v97, v97, v102
	ds_read_b128 v[102:105], v65 offset:9216
	s_waitcnt lgkmcnt(1)
	v_fma_f32 v108, v0, v98, 0
	v_fmac_f32_e32 v108, v1, v99
	v_fmac_f32_e32 v108, v2, v100
	v_fmac_f32_e32 v108, v3, v101
	ds_read_b128 v[98:101], v65 offset:10240
	s_waitcnt lgkmcnt(1)
	v_fmac_f32_e32 v108, v4, v102
	v_fmac_f32_e32 v108, v5, v103
	v_fmac_f32_e32 v108, v6, v104
	v_fmac_f32_e32 v108, v7, v105
	ds_read_b128 v[102:105], v65 offset:11264
	s_waitcnt lgkmcnt(1)
	v_fmac_f32_e32 v108, v8, v98
	v_fmac_f32_e32 v108, v9, v99
	v_fmac_f32_e32 v108, v10, v100
	v_fmac_f32_e32 v108, v11, v101
	ds_read_b128 v[98:101], v65 offset:12288
	s_waitcnt lgkmcnt(1)
	v_fmac_f32_e32 v108, v12, v102
	v_fmac_f32_e32 v108, v13, v103
	v_fmac_f32_e32 v108, v14, v104
	v_fmac_f32_e32 v108, v15, v105
	ds_read_b128 v[102:105], v65 offset:13312
	s_waitcnt lgkmcnt(1)
	v_fmac_f32_e32 v108, v16, v98
	v_fmac_f32_e32 v108, v17, v99
	v_fmac_f32_e32 v108, v18, v100
	v_fmac_f32_e32 v108, v19, v101
	ds_read_b128 v[98:101], v65 offset:14336
	s_waitcnt lgkmcnt(1)
	v_fmac_f32_e32 v108, v20, v102
	v_fmac_f32_e32 v108, v21, v103
	v_fmac_f32_e32 v108, v22, v104
	v_fmac_f32_e32 v108, v23, v105
	ds_read_b128 v[102:105], v65 offset:15360
	s_waitcnt lgkmcnt(1)
	v_fmac_f32_e32 v108, v24, v98
	v_fmac_f32_e32 v108, v25, v99
	v_cndmask_b32_e32 v88, v86, v88, vcc
	v_fmac_f32_e32 v108, v26, v100
	v_lshlrev_b32_e32 v89, 2, v88
	v_fmac_f32_e32 v108, v27, v101
	s_nop 1
	v_mov_b32_dpp v107, v97 quad_perm:[2,3,0,1] row_mask:0xf bank_mask:0xf
	s_waitcnt lgkmcnt(0)
	v_fmac_f32_e32 v108, v28, v102
	v_fmac_f32_e32 v108, v29, v103
	v_xor_b32_e32 v88, 4, v86
	v_fmac_f32_e32 v108, v30, v104
	v_cmp_lt_i32_e32 vcc, v88, v93
	v_fmac_f32_e32 v108, v31, v105
	s_nop 1
	v_mov_b32_dpp v98, v108 quad_perm:[1,0,3,2] row_mask:0xf bank_mask:0xf
	v_cndmask_b32_e32 v88, v86, v88, vcc
	v_lshlrev_b32_e32 v88, 2, v88
	s_waitcnt lgkmcnt(0)
	v_add_f32_e32 v97, v97, v107
	s_nop 1
	v_mov_b32_dpp v99, v97 row_half_mirror row_mask:0xf bank_mask:0xf
	s_waitcnt lgkmcnt(0)
	v_add_f32_e32 v102, v108, v98
	s_nop 1
	v_mov_b32_dpp v103, v102 quad_perm:[2,3,0,1] row_mask:0xf bank_mask:0xf
	v_cmp_lt_i32_e32 vcc, v91, v93
	v_xor_b32_e32 v92, 16, v86
	s_waitcnt lgkmcnt(0)
	v_add_f32_e32 v97, v97, v99
	ds_read_b128 v[98:101], v65 offset:16384
	s_waitcnt lgkmcnt(1)
	v_add_f32_e32 v107, v102, v103
	ds_read_b128 v[102:105], v65 offset:17408
	v_cndmask_b32_e32 v91, v86, v91, vcc
	v_cmp_lt_i32_e32 vcc, v92, v93
	s_waitcnt lgkmcnt(1)
	v_fma_f32 v109, v0, v98, 0
	v_fmac_f32_e32 v109, v1, v99
	v_fmac_f32_e32 v109, v2, v100
	v_fmac_f32_e32 v109, v3, v101
	ds_read_b128 v[98:101], v65 offset:18432
	s_waitcnt lgkmcnt(1)
	v_fmac_f32_e32 v109, v4, v102
	v_fmac_f32_e32 v109, v5, v103
	v_fmac_f32_e32 v109, v6, v104
	v_fmac_f32_e32 v109, v7, v105
	ds_read_b128 v[102:105], v65 offset:19456
	s_waitcnt lgkmcnt(1)
	v_fmac_f32_e32 v109, v8, v98
	v_fmac_f32_e32 v109, v9, v99
	v_fmac_f32_e32 v109, v10, v100
	v_fmac_f32_e32 v109, v11, v101
	ds_read_b128 v[98:101], v65 offset:20480
	s_waitcnt lgkmcnt(1)
	v_fmac_f32_e32 v109, v12, v102
	v_fmac_f32_e32 v109, v13, v103
	v_fmac_f32_e32 v109, v14, v104
	v_fmac_f32_e32 v109, v15, v105
	ds_read_b128 v[102:105], v65 offset:21504
	s_waitcnt lgkmcnt(1)
	v_fmac_f32_e32 v109, v16, v98
	v_fmac_f32_e32 v109, v17, v99
	v_fmac_f32_e32 v109, v18, v100
	v_fmac_f32_e32 v109, v19, v101
	ds_read_b128 v[98:101], v65 offset:22528
	s_waitcnt lgkmcnt(1)
	v_fmac_f32_e32 v109, v20, v102
	v_fmac_f32_e32 v109, v21, v103
	v_fmac_f32_e32 v109, v22, v104
	v_fmac_f32_e32 v109, v23, v105
	ds_read_b128 v[102:105], v65 offset:23552
	s_waitcnt lgkmcnt(1)
	v_fmac_f32_e32 v109, v24, v98
	v_fmac_f32_e32 v109, v25, v99
	v_fmac_f32_e32 v109, v26, v100
	v_fmac_f32_e32 v109, v27, v101
	s_waitcnt lgkmcnt(0)
	v_fmac_f32_e32 v109, v28, v102
	v_fmac_f32_e32 v109, v29, v103
	v_xor_b32_e32 v106, 32, v86
	v_fmac_f32_e32 v109, v30, v104
	v_lshlrev_b32_e32 v91, 2, v91
	v_cndmask_b32_e32 v92, v86, v92, vcc
	v_cmp_lt_i32_e32 vcc, v106, v93
	v_fmac_f32_e32 v109, v31, v105
	s_nop 1
	v_mov_b32_dpp v108, v107 row_half_mirror row_mask:0xf bank_mask:0xf
	v_cndmask_b32_e32 v93, v86, v106, vcc
	s_nop 1
	v_mov_b32_dpp v106, v97 row_mirror row_mask:0xf bank_mask:0xf
	s_nop 1
	v_mov_b32_dpp v98, v109 quad_perm:[1,0,3,2] row_mask:0xf bank_mask:0xf
	v_lshlrev_b32_e32 v92, 2, v92
	s_waitcnt lgkmcnt(0)
	v_add_f32_e32 v104, v107, v108
	s_nop 1
	v_mov_b32_dpp v105, v104 row_mirror row_mask:0xf bank_mask:0xf
	s_waitcnt lgkmcnt(1)
	v_add_f32_e32 v97, v97, v106
	s_waitcnt lgkmcnt(0)
	v_add_f32_e32 v106, v109, v98
	ds_bpermute_b32 v99, v92, v97
	s_nop 1
	v_mov_b32_dpp v107, v106 quad_perm:[2,3,0,1] row_mask:0xf bank_mask:0xf
	ds_read_b128 v[100:103], v65 offset:24576
	v_lshlrev_b32_e32 v93, 2, v93
	v_add_f32_e32 v75, 0x4b400000, v75
	s_waitcnt lgkmcnt(1)
	v_add_f32_e32 v97, v97, v99
	v_add_f32_e32 v99, v104, v105
	s_waitcnt lgkmcnt(0)
	v_add_f32_e32 v108, v106, v107
	ds_read_b128 v[104:107], v65 offset:25600
	s_waitcnt lgkmcnt(1)
; #define LAS __attribute__((address_space(3)))
; __device__ __forceinline__ float wave_sum(float v) {
; #pragma unroll
;     for (int o = 1; o < 64; o <<= 1) v += __shfl_xor(v, o);
;     return v;
; }
; __device__ __forceinline__ void xprep_row(const f32x4 (&v)[8], const int m, LAS float* wf, bf16_t* XB, float* LOGF, const float* bfg, const int lane) {
;     ...
;         for (int e = 0; e < 8; ++e) { float s = 0.f;
; #pragma unroll
;             for (int j = 0; j < 8; ++j) { const f32x4 w = *(const LAS f32x4*)(wf + e * 2048 + 256 * j + 4 * lane); s = fmaf(v[j][0], w[0], s); s = fmaf(v[j][1], w[1], s); s = fmaf(v[j][2], w[2], s); s = fmaf(v[j][3], w[3], s); }
;             f[e] = wave_sum(s); }
	v_fma_f32 v110, v0, v100, 0
	v_fmac_f32_e32 v110, v1, v101
	v_fmac_f32_e32 v110, v2, v102
	v_fmac_f32_e32 v110, v3, v103
	ds_read_b128 v[100:103], v65 offset:26624
	s_waitcnt lgkmcnt(1)
	v_fmac_f32_e32 v110, v4, v104
	v_fmac_f32_e32 v110, v5, v105
	v_fmac_f32_e32 v110, v6, v106
	v_fmac_f32_e32 v110, v7, v107
	ds_read_b128 v[104:107], v65 offset:27648
	s_waitcnt lgkmcnt(1)
	v_fmac_f32_e32 v110, v8, v100
	v_fmac_f32_e32 v110, v9, v101
	v_fmac_f32_e32 v110, v10, v102
	v_fmac_f32_e32 v110, v11, v103
	ds_read_b128 v[100:103], v65 offset:28672
	s_waitcnt lgkmcnt(1)
	v_fmac_f32_e32 v110, v12, v104
	v_fmac_f32_e32 v110, v13, v105
	v_fmac_f32_e32 v110, v14, v106
	v_fmac_f32_e32 v110, v15, v107
	ds_read_b128 v[104:107], v65 offset:29696
	s_waitcnt lgkmcnt(1)
	v_fmac_f32_e32 v110, v16, v100
	v_fmac_f32_e32 v110, v17, v101
	v_fmac_f32_e32 v110, v18, v102
	v_fmac_f32_e32 v110, v19, v103
	ds_read_b128 v[100:103], v65 offset:30720
	s_waitcnt lgkmcnt(1)
	v_fmac_f32_e32 v110, v20, v104
	v_fmac_f32_e32 v110, v21, v105
	v_fmac_f32_e32 v110, v22, v106
	v_fmac_f32_e32 v110, v23, v107
	ds_read_b128 v[104:107], v65 offset:31744
	s_waitcnt lgkmcnt(1)
	v_fmac_f32_e32 v110, v24, v100
	v_fmac_f32_e32 v110, v25, v101
	v_fmac_f32_e32 v110, v26, v102
	v_fmac_f32_e32 v110, v27, v103
	ds_read_b128 v[100:103], v65 offset:32768
	s_waitcnt lgkmcnt(1)
	v_fmac_f32_e32 v110, v28, v104
	v_fmac_f32_e32 v110, v29, v105
	v_fmac_f32_e32 v110, v30, v106
	v_fmac_f32_e32 v110, v31, v107
	ds_read_b128 v[104:107], v65 offset:33792
	s_waitcnt lgkmcnt(1)
	v_fma_f32 v112, v0, v100, 0
	v_fmac_f32_e32 v112, v1, v101
	v_fmac_f32_e32 v112, v2, v102
	v_fmac_f32_e32 v112, v3, v103
	ds_read_b128 v[100:103], v65 offset:34816
	s_waitcnt lgkmcnt(1)
	v_fmac_f32_e32 v112, v4, v104
	v_fmac_f32_e32 v112, v5, v105
	v_fmac_f32_e32 v112, v6, v106
	v_fmac_f32_e32 v112, v7, v107
	ds_read_b128 v[104:107], v65 offset:35840
	s_waitcnt lgkmcnt(1)
	v_fmac_f32_e32 v112, v8, v100
	v_fmac_f32_e32 v112, v9, v101
	v_fmac_f32_e32 v112, v10, v102
	v_fmac_f32_e32 v112, v11, v103
	ds_read_b128 v[100:103], v65 offset:36864
	s_waitcnt lgkmcnt(1)
	v_fmac_f32_e32 v112, v12, v104
	v_fmac_f32_e32 v112, v13, v105
	v_fmac_f32_e32 v112, v14, v106
	v_fmac_f32_e32 v112, v15, v107
	ds_read_b128 v[104:107], v65 offset:37888
	s_waitcnt lgkmcnt(1)
	v_fmac_f32_e32 v112, v16, v100
	v_fmac_f32_e32 v112, v17, v101
	v_fmac_f32_e32 v112, v18, v102
	v_fmac_f32_e32 v112, v19, v103
	ds_read_b128 v[100:103], v65 offset:38912
	s_waitcnt lgkmcnt(1)
	v_fmac_f32_e32 v112, v20, v104
	s_nop 1
	v_mov_b32_dpp v111, v110 quad_perm:[1,0,3,2] row_mask:0xf bank_mask:0xf
	v_fmac_f32_e32 v112, v21, v105
	v_fmac_f32_e32 v112, v22, v106
	v_fmac_f32_e32 v112, v23, v107
	ds_read_b128 v[104:107], v65 offset:39936
	s_waitcnt lgkmcnt(1)
	v_fmac_f32_e32 v112, v24, v100
	v_fmac_f32_e32 v112, v25, v101
	v_fmac_f32_e32 v112, v26, v102
	s_waitcnt lgkmcnt(0)
	v_add_f32_e32 v102, v110, v111
	v_fmac_f32_e32 v112, v27, v103
	s_nop 1
	v_mov_b32_dpp v103, v102 quad_perm:[2,3,0,1] row_mask:0xf bank_mask:0xf
	s_waitcnt lgkmcnt(0)
	v_fmac_f32_e32 v112, v28, v104
	v_fmac_f32_e32 v112, v29, v105
	v_fmac_f32_e32 v112, v30, v106
	v_fmac_f32_e32 v112, v31, v107
	s_nop 1
	v_mov_b32_dpp v100, v112 quad_perm:[1,0,3,2] row_mask:0xf bank_mask:0xf
	s_waitcnt lgkmcnt(0)
	v_add_f32_e32 v102, v102, v103
	s_nop 1
	v_mov_b32_dpp v103, v102 row_half_mirror row_mask:0xf bank_mask:0xf
	s_nop 1
	v_mov_b32_dpp v109, v108 row_half_mirror row_mask:0xf bank_mask:0xf
	ds_bpermute_b32 v101, v92, v99
	s_waitcnt lgkmcnt(1)
	v_add_f32_e32 v100, v112, v100
	s_nop 1
	v_mov_b32_dpp v105, v100 quad_perm:[2,3,0,1] row_mask:0xf bank_mask:0xf
	s_waitcnt lgkmcnt(0)
	v_add_f32_e32 v102, v102, v103
	s_nop 1
	v_mov_b32_dpp v103, v102 row_mirror row_mask:0xf bank_mask:0xf
	s_waitcnt lgkmcnt(2)
	v_add_f32_e32 v104, v108, v109
	s_nop 1
	v_mov_b32_dpp v106, v104 row_mirror row_mask:0xf bank_mask:0xf
	s_waitcnt lgkmcnt(0)
	v_add_f32_e32 v100, v100, v105
	v_add_f32_e32 v99, v99, v101
	s_nop 1
	v_mov_b32_dpp v101, v100 row_half_mirror row_mask:0xf bank_mask:0xf
	s_waitcnt lgkmcnt(1)
	v_add_f32_e32 v103, v102, v103
	ds_bpermute_b32 v108, v92, v103
	s_waitcnt lgkmcnt(1)
	v_add_f32_e32 v104, v104, v106
	ds_bpermute_b32 v105, v92, v104
	s_waitcnt lgkmcnt(1)
	v_add_f32_e32 v106, v100, v101
	s_nop 1
	v_mov_b32_dpp v107, v106 row_mirror row_mask:0xf bank_mask:0xf
	s_waitcnt lgkmcnt(0)
	v_add_f32_e32 v103, v103, v108
	ds_read_b128 v[108:111], v65 offset:40960
	ds_read_b128 v[112:115], v65 offset:41984
	s_waitcnt lgkmcnt(3)
	v_add_f32_e32 v101, v104, v105
	s_waitcnt lgkmcnt(2)
	v_add_f32_e32 v105, v106, v107
	ds_bpermute_b32 v106, v92, v105
	s_waitcnt lgkmcnt(2)
	v_fma_f32 v107, v0, v108, 0
	v_fmac_f32_e32 v107, v1, v109
	v_fmac_f32_e32 v107, v2, v110
	v_fmac_f32_e32 v107, v3, v111
	ds_read_b128 v[108:111], v65 offset:43008
	s_waitcnt lgkmcnt(2)
	v_fmac_f32_e32 v107, v4, v112
	v_fmac_f32_e32 v107, v5, v113
	v_fmac_f32_e32 v107, v6, v114
	v_fmac_f32_e32 v107, v7, v115
	ds_read_b128 v[112:115], v65 offset:44032
	s_waitcnt lgkmcnt(1)
	v_fmac_f32_e32 v107, v8, v108
	v_fmac_f32_e32 v107, v9, v109
	v_fmac_f32_e32 v107, v10, v110
	v_fmac_f32_e32 v107, v11, v111
	ds_read_b128 v[108:111], v65 offset:45056
	s_waitcnt lgkmcnt(1)
	v_fmac_f32_e32 v107, v12, v112
	v_fmac_f32_e32 v107, v13, v113
	v_fmac_f32_e32 v107, v14, v114
	v_fmac_f32_e32 v107, v15, v115
	ds_read_b128 v[112:115], v65 offset:46080
	s_waitcnt lgkmcnt(1)
	v_fmac_f32_e32 v107, v16, v108
	v_fmac_f32_e32 v107, v17, v109
	v_fmac_f32_e32 v107, v18, v110
	v_fmac_f32_e32 v107, v19, v111
	ds_read_b128 v[108:111], v65 offset:47104
	s_waitcnt lgkmcnt(1)
; #define LAS __attribute__((address_space(3)))
; __device__ __forceinline__ float wave_sum(float v) {
; #pragma unroll
;     for (int o = 1; o < 64; o <<= 1) v += __shfl_xor(v, o);
;     return v;
; }
; __device__ __forceinline__ void xprep_row(const f32x4 (&v)[8], const int m, LAS float* wf, bf16_t* XB, float* LOGF, const float* bfg, const int lane) {
;     ...
;         for (int e = 0; e < 8; ++e) { float s = 0.f;
; #pragma unroll
;             for (int j = 0; j < 8; ++j) { const f32x4 w = *(const LAS f32x4*)(wf + e * 2048 + 256 * j + 4 * lane); s = fmaf(v[j][0], w[0], s); s = fmaf(v[j][1], w[1], s); s = fmaf(v[j][2], w[2], s); s = fmaf(v[j][3], w[3], s); }
;             f[e] = wave_sum(s); }
	v_fmac_f32_e32 v107, v20, v112
	v_fmac_f32_e32 v107, v21, v113
	v_fmac_f32_e32 v107, v22, v114
	v_fmac_f32_e32 v107, v23, v115
	ds_read_b128 v[112:115], v65 offset:48128
	s_waitcnt lgkmcnt(1)
	v_fmac_f32_e32 v107, v24, v108
	v_fmac_f32_e32 v107, v25, v109
	v_fmac_f32_e32 v107, v26, v110
	v_fmac_f32_e32 v107, v27, v111
	ds_read_b128 v[108:111], v65 offset:49152
	s_waitcnt lgkmcnt(1)
	v_fmac_f32_e32 v107, v28, v112
	v_fmac_f32_e32 v107, v29, v113
	v_fmac_f32_e32 v107, v30, v114
	v_fmac_f32_e32 v107, v31, v115
	ds_read_b128 v[112:115], v65 offset:50176
	s_waitcnt lgkmcnt(1)
	v_fma_f32 v117, v0, v108, 0
	v_fmac_f32_e32 v117, v1, v109
	v_fmac_f32_e32 v117, v2, v110
	v_fmac_f32_e32 v117, v3, v111
	ds_read_b128 v[108:111], v65 offset:51200
	s_waitcnt lgkmcnt(1)
	v_fmac_f32_e32 v117, v4, v112
	v_fmac_f32_e32 v117, v5, v113
	v_fmac_f32_e32 v117, v6, v114
	v_fmac_f32_e32 v117, v7, v115
	ds_read_b128 v[112:115], v65 offset:52224
	s_waitcnt lgkmcnt(1)
	v_fmac_f32_e32 v117, v8, v108
	v_fmac_f32_e32 v117, v9, v109
	v_fmac_f32_e32 v117, v10, v110
	v_fmac_f32_e32 v117, v11, v111
	ds_read_b128 v[108:111], v65 offset:53248
	s_waitcnt lgkmcnt(1)
	v_fmac_f32_e32 v117, v12, v112
	v_fmac_f32_e32 v117, v13, v113
	v_fmac_f32_e32 v117, v14, v114
	v_fmac_f32_e32 v117, v15, v115
	ds_read_b128 v[112:115], v65 offset:54272
	s_waitcnt lgkmcnt(1)
	v_fmac_f32_e32 v117, v16, v108
	v_fmac_f32_e32 v117, v17, v109
	v_fmac_f32_e32 v117, v18, v110
	v_fmac_f32_e32 v117, v19, v111
	ds_read_b128 v[108:111], v65 offset:55296
	s_waitcnt lgkmcnt(1)
	v_fmac_f32_e32 v117, v20, v112
	v_fmac_f32_e32 v117, v21, v113
	v_fmac_f32_e32 v117, v22, v114
	v_fmac_f32_e32 v117, v23, v115
	ds_read_b128 v[112:115], v65 offset:56320
	s_waitcnt lgkmcnt(1)
	v_fmac_f32_e32 v117, v24, v108
	v_fmac_f32_e32 v117, v25, v109
	v_fmac_f32_e32 v117, v26, v110
	v_fmac_f32_e32 v117, v27, v111
	ds_read_b128 v[108:111], v65 offset:57344
	s_waitcnt lgkmcnt(1)
	v_fmac_f32_e32 v117, v28, v112
	v_fmac_f32_e32 v117, v29, v113
	v_fmac_f32_e32 v117, v30, v114
	v_fmac_f32_e32 v117, v31, v115
	ds_read_b128 v[112:115], v65 offset:58368
	s_waitcnt lgkmcnt(1)
	v_fma_f32 v119, v0, v108, 0
	v_fmac_f32_e32 v119, v1, v109
	v_fmac_f32_e32 v119, v2, v110
	v_fmac_f32_e32 v119, v3, v111
	ds_read_b128 v[108:111], v65 offset:59392
	s_waitcnt lgkmcnt(1)
	v_fmac_f32_e32 v119, v4, v112
	v_fmac_f32_e32 v119, v5, v113
	v_fmac_f32_e32 v119, v6, v114
	v_fmac_f32_e32 v119, v7, v115
	ds_read_b128 v[112:115], v65 offset:60416
	s_waitcnt lgkmcnt(1)
	v_fmac_f32_e32 v119, v8, v108
	v_fmac_f32_e32 v119, v9, v109
	v_fmac_f32_e32 v119, v10, v110
	v_fmac_f32_e32 v119, v11, v111
	ds_read_b128 v[108:111], v65 offset:61440
	s_waitcnt lgkmcnt(1)
	v_fmac_f32_e32 v119, v12, v112
	v_fmac_f32_e32 v119, v13, v113
	v_fmac_f32_e32 v119, v14, v114
	v_fmac_f32_e32 v119, v15, v115
	ds_read_b128 v[112:115], v65 offset:62464
	s_waitcnt lgkmcnt(1)
	v_fmac_f32_e32 v119, v16, v108
	v_fmac_f32_e32 v119, v17, v109
	v_fmac_f32_e32 v119, v18, v110
	v_fmac_f32_e32 v119, v19, v111
	ds_read_b128 v[108:111], v65 offset:63488
	s_waitcnt lgkmcnt(1)
	v_fmac_f32_e32 v119, v20, v112
	v_fmac_f32_e32 v119, v21, v113
	v_fmac_f32_e32 v119, v22, v114
	v_fmac_f32_e32 v119, v23, v115
	ds_read_b128 v[112:115], v65 offset:64512
	s_waitcnt lgkmcnt(1)
	v_fmac_f32_e32 v119, v24, v108
	v_fmac_f32_e32 v119, v25, v109
	v_fmac_f32_e32 v119, v26, v110
	v_fmac_f32_e32 v119, v27, v111
	s_waitcnt lgkmcnt(0)
	v_fmac_f32_e32 v119, v28, v112
	v_fmac_f32_e32 v119, v29, v113
	v_fmac_f32_e32 v119, v30, v114
	v_fmac_f32_e32 v119, v31, v115
	s_nop 1
	v_mov_b32_dpp v116, v107 quad_perm:[1,0,3,2] row_mask:0xf bank_mask:0xf
	s_nop 1
	v_mov_b32_dpp v118, v117 quad_perm:[1,0,3,2] row_mask:0xf bank_mask:0xf
	s_nop 1
	v_mov_b32_dpp v108, v119 quad_perm:[1,0,3,2] row_mask:0xf bank_mask:0xf
	v_add_f32_e32 v105, v105, v106
	ds_bpermute_b32 v98, v93, v97
	s_waitcnt lgkmcnt(0)
	v_add_f32_e32 v107, v107, v116
	s_waitcnt lgkmcnt(2)
	v_add_f32_e32 v110, v117, v118
	s_waitcnt lgkmcnt(1)
	v_add_f32_e32 v108, v119, v108
	s_nop 1
	v_mov_b32_dpp v109, v107 quad_perm:[2,3,0,1] row_mask:0xf bank_mask:0xf
	s_nop 1
	v_mov_b32_dpp v111, v110 quad_perm:[2,3,0,1] row_mask:0xf bank_mask:0xf
	s_nop 1
	v_mov_b32_dpp v112, v108 quad_perm:[2,3,0,1] row_mask:0xf bank_mask:0xf
	ds_bpermute_b32 v100, v93, v99
	ds_bpermute_b32 v102, v93, v101
	s_waitcnt lgkmcnt(1)
	v_add_f32_e32 v107, v107, v109
	s_waitcnt lgkmcnt(0)
	v_add_f32_e32 v110, v110, v111
	s_waitcnt lgkmcnt(2)
	v_add_f32_e32 v108, v108, v112
	s_nop 1
	v_mov_b32_dpp v109, v107 row_half_mirror row_mask:0xf bank_mask:0xf
	s_nop 1
	v_mov_b32_dpp v111, v110 row_half_mirror row_mask:0xf bank_mask:0xf
	s_nop 1
	v_mov_b32_dpp v112, v108 row_half_mirror row_mask:0xf bank_mask:0xf
	ds_bpermute_b32 v104, v93, v103
	ds_bpermute_b32 v106, v93, v105
	s_waitcnt lgkmcnt(1)
	v_add_f32_e32 v107, v107, v109
	s_waitcnt lgkmcnt(0)
	v_add_f32_e32 v110, v110, v111
	s_waitcnt lgkmcnt(2)
	v_add_f32_e32 v108, v108, v112
	s_nop 1
	v_mov_b32_dpp v109, v107 row_mirror row_mask:0xf bank_mask:0xf
	s_nop 1
	v_mov_b32_dpp v111, v110 row_mirror row_mask:0xf bank_mask:0xf
	s_nop 1
	v_mov_b32_dpp v112, v108 row_mirror row_mask:0xf bank_mask:0xf
	v_perm_b32 v75, v94, v75, s36
	v_perm_b32 v94, v96, v95, s37
	s_waitcnt lgkmcnt(0)
	v_add_f32_e32 v107, v107, v109
	s_waitcnt lgkmcnt(1)
	v_add_f32_e32 v110, v110, v111
	s_waitcnt lgkmcnt(0)
	v_add_f32_e32 v112, v108, v112
	ds_bpermute_b32 v109, v92, v107
	ds_bpermute_b32 v111, v92, v110
	ds_bpermute_b32 v113, v92, v112
	v_or_b32_e32 v75, v75, v94
	global_store_dword v[80:81], v75, off offset:1792
	s_waitcnt lgkmcnt(2)
	v_add_f32_e32 v107, v107, v109
	s_waitcnt lgkmcnt(1)
	v_add_f32_e32 v109, v110, v111
	s_waitcnt lgkmcnt(0)
	v_add_f32_e32 v111, v112, v113
	ds_bpermute_b32 v108, v93, v107
	ds_bpermute_b32 v110, v93, v109
	ds_bpermute_b32 v112, v93, v111
	s_and_saveexec_b64 s[28:29], s[2:3]
	s_cbranch_execz .LBB0_991
; __device__ __forceinline__ void xprep_row(const f32x4 (&v)[8], const int m, LAS float* wf, bf16_t* XB, float* LOGF, const float* bfg, const int lane) {
;     ...
;         if (lane < 8) { float z = 0.f;
; #pragma unroll
;             for (int e = 0; e < 8; ++e) z = (lane == e) ? f[e] : z;
;             z += bfg[lane];
;             LOGF[(size_t)m * 8 + lane] = fminf(z, 0.f) - log1pf(expf(-fabsf(z))); }
	global_load_dword v75, v[70:71], off
	v_add_f32_e32 v97, v97, v98
	v_add_f32_e32 v99, v99, v100
	v_cndmask_b32_e64 v97, 0, v97, s[4:5]
	v_add_f32_e32 v101, v101, v102
	v_cndmask_b32_e64 v97, v97, v99, s[6:7]
	v_add_f32_e32 v96, v103, v104
	v_cndmask_b32_e64 v97, v97, v101, s[8:9]
	v_add_f32_e32 v95, v105, v106
	v_cndmask_b32_e64 v96, v97, v96, s[10:11]
	s_waitcnt lgkmcnt(2)
	v_add_f32_e32 v94, v107, v108
	v_cndmask_b32_e64 v95, v96, v95, s[12:13]
	s_waitcnt lgkmcnt(1)
	v_add_f32_e32 v81, v109, v110
	v_cndmask_b32_e64 v94, v95, v94, s[14:15]
	s_waitcnt lgkmcnt(0)
	v_add_f32_e32 v80, v111, v112
	v_cndmask_b32_e64 v81, v94, v81, s[16:17]
	v_cndmask_b32_e64 v80, v81, v80, s[18:19]
	s_waitcnt vmcnt(0)
	v_add_f32_e32 v75, v80, v75
	v_mul_f32_e64 v80, |v75|, s38
	v_fma_f32 v81, |v75|, s38, -v80
	v_rndne_f32_e32 v94, v80
	v_fma_f32 v81, |v75|, s39, v81
	v_sub_f32_e32 v80, v80, v94
	v_add_f32_e32 v80, v80, v81
	v_cvt_i32_f32_e32 v94, v94
	v_exp_f32_e32 v95, v80
	v_cmp_ngt_f32_e64 vcc, |v75|, s40
	v_lshlrev_b64 v[80:81], 5, v[78:79]
	v_min_f32_e32 v79, 0, v75
	v_ldexp_f32 v94, v95, v94
	v_cndmask_b32_e32 v94, 0, v94, vcc
	v_cmp_nlt_f32_e64 vcc, |v75|, s41
	v_lshl_add_u64 v[80:81], v[72:73], 0, v[80:81]
	s_nop 0
	v_cndmask_b32_e32 v108, v87, v94, vcc
	v_add_f32_e32 v75, 1.0, v108
	v_add_f32_e32 v96, -1.0, v75
	v_frexp_mant_f32_e32 v97, v75
	v_cvt_f64_f32_e32 v[94:95], v75
	v_sub_f32_e32 v98, v96, v75
	v_frexp_exp_i32_f64_e32 v94, v[94:95]
	v_cmp_gt_f32_e32 vcc, s43, v97
	v_sub_f32_e32 v96, v108, v96
	v_add_f32_e32 v95, 1.0, v98
	v_subbrev_co_u32_e32 v94, vcc, 0, v94, vcc
	v_add_f32_e32 v95, v96, v95
	v_sub_u32_e32 v96, 0, v94
	v_ldexp_f32 v75, v75, v96
	v_ldexp_f32 v95, v95, v96
	v_add_f32_e32 v96, -1.0, v75
	v_add_f32_e32 v98, 1.0, v75
	v_add_f32_e32 v97, 1.0, v96
	v_add_f32_e32 v99, -1.0, v98
	v_sub_f32_e32 v97, v75, v97
	v_sub_f32_e32 v75, v75, v99
	v_add_f32_e32 v75, v95, v75
	v_add_f32_e32 v99, v95, v97
	v_add_f32_e32 v95, v98, v75
	v_rcp_f32_e32 v102, v95
	v_add_f32_e32 v97, v96, v99
	v_sub_f32_e32 v98, v98, v95
	v_add_f32_e32 v75, v75, v98
	v_mul_f32_e32 v104, v97, v102
	v_mul_f32_e32 v98, v95, v104
	v_fma_f32 v100, v104, v95, -v98
	v_sub_f32_e32 v96, v96, v97
	v_fmac_f32_e32 v100, v104, v75
	v_add_f32_e32 v103, v99, v96
	v_add_f32_e32 v96, v98, v100
	v_sub_f32_e32 v99, v97, v96
	v_mov_b32_e32 v101, v96
	v_pk_add_f32 v[96:97], v[96:97], v[98:99] neg_lo:[0,1] neg_hi:[0,1]
	v_cvt_f32_i32_e32 v94, v94
	v_pk_add_f32 v[96:97], v[96:97], v[100:101] neg_lo:[0,1] neg_hi:[0,1]
	v_cmp_neq_f32_e32 vcc, s42, v108
	v_add_f32_e32 v97, v103, v97
	v_add_f32_e32 v96, v96, v97
	v_add_f32_e32 v97, v99, v96
	v_mul_f32_e32 v101, v102, v97
	v_mul_f32_e32 v98, v95, v101
	v_fma_f32 v100, v101, v95, -v98
	v_sub_f32_e32 v99, v99, v97
	v_fmac_f32_e32 v100, v101, v75
	v_add_f32_e32 v103, v96, v99
	v_add_f32_e32 v105, v104, v101
	v_add_f32_e32 v96, v98, v100
	v_sub_f32_e32 v95, v105, v104
	v_sub_f32_e32 v99, v97, v96
	v_sub_f32_e32 v75, v101, v95
	v_mov_b32_e32 v101, v96
	v_pk_add_f32 v[96:97], v[96:97], v[98:99] neg_lo:[0,1] neg_hi:[0,1]
	s_nop 0
	v_pk_add_f32 v[96:97], v[96:97], v[100:101] neg_lo:[0,1] neg_hi:[0,1]
	s_nop 0
	v_add_f32_e32 v95, v103, v97
	v_add_f32_e32 v95, v96, v95
	v_add_f32_e32 v95, v99, v95
	v_mul_f32_e32 v95, v102, v95
	v_add_f32_e32 v75, v75, v95
	v_add_f32_e32 v95, v105, v75
	v_mul_f32_e32 v96, v95, v95
	v_sub_f32_e32 v98, v95, v105
	v_fmamk_f32 v99, v96, 0x3e9b6dac, v84
	v_ldexp_f32 v97, v95, 1
	v_sub_f32_e32 v98, v75, v98
	v_mul_f32_e32 v95, v95, v96
	v_fmaak_f32 v75, v96, v99, 0x3f2aaada
	v_ldexp_f32 v101, v98, 1
	v_pk_mul_f32 v[98:99], v[94:95], v[74:75]
	s_nop 0
	v_fma_f32 v96, v94, s44, -v98
	v_fmac_f32_e32 v96, 0xb102e308, v94
	v_pk_add_f32 v[94:95], v[98:99], v[96:97]
	v_mov_b32_e32 v100, v98
	v_sub_f32_e32 v75, v95, v97
	v_sub_f32_e32 v75, v99, v75
	v_add_f32_e32 v101, v101, v75
	v_pk_add_f32 v[102:103], v[94:95], v[98:99] neg_lo:[0,1] neg_hi:[0,1]
	v_pk_add_f32 v[98:99], v[94:95], v[100:101]
	v_mov_b32_e32 v97, v94
	v_mov_b32_e32 v103, v99
	v_pk_add_f32 v[106:107], v[96:97], v[102:103] neg_lo:[0,1] neg_hi:[0,1]
	v_pk_add_f32 v[96:97], v[96:97], v[102:103]
	v_mov_b32_e32 v105, v94
	v_pk_add_f32 v[102:103], v[96:97], v[94:95] op_sel:[1,0] op_sel_hi:[0,1] neg_lo:[0,1] neg_hi:[0,1]
	v_mov_b32_e32 v104, v101
	v_mov_b32_e32 v100, v99
	v_mov_b32_e32 v101, v97
	v_pk_mov_b32 v[94:95], v[94:95], v[102:103] op_sel:[1,0]
	v_pk_add_f32 v[98:99], v[98:99], v[102:103] op_sel_hi:[1,0] neg_lo:[0,1] neg_hi:[0,1]
	v_pk_add_f32 v[94:95], v[100:101], v[94:95] neg_lo:[0,1] neg_hi:[0,1]
	v_mov_b32_e32 v98, v106
	v_pk_add_f32 v[94:95], v[104:105], v[94:95] neg_lo:[0,1] neg_hi:[0,1]
	v_mov_b32_e32 v107, v97
	v_pk_add_f32 v[98:99], v[98:99], v[94:95]
	s_nop 0
	v_pk_add_f32 v[100:101], v[98:99], v[98:99] op_sel:[0,1] op_sel_hi:[1,0]
	s_nop 0
	v_pk_add_f32 v[96:97], v[96:97], v[100:101] op_sel:[1,0] op_sel_hi:[0,1]
	v_mov_b32_e32 v99, v96
	v_mov_b32_e32 v95, v100
	v_pk_add_f32 v[100:101], v[98:99], v[106:107] neg_lo:[0,1] neg_hi:[0,1]
	s_nop 0
	v_sub_f32_e32 v75, v98, v100
	v_pk_add_f32 v[94:95], v[94:95], v[100:101] neg_lo:[0,1] neg_hi:[0,1]
	v_sub_f32_e32 v75, v106, v75
	v_add_f32_e32 v75, v94, v75
	v_add_f32_e32 v75, v75, v95
	v_add_f32_e32 v75, v96, v75
	v_cndmask_b32_e32 v75, v87, v75, vcc
	v_cmp_lt_f32_e64 vcc, |v108|, s45
	s_nop 1
	v_cndmask_b32_e32 v75, v75, v108, vcc
	v_sub_f32_e32 v75, v79, v75
	global_store_dword v[80:81], v75, off

; #define LAS __attribute__((address_space(3)))
; __device__ __forceinline__ void xprep_row(const f32x4 (&v)[8], const int m, LAS float* wf, bf16_t* XB, float* LOGF, const float* bfg, const int lane) {
;         unsigned* o4 = (unsigned*)((unsigned char*)XB + (size_t)m * DM) + lane;
; #pragma unroll
;         for (int j = 0; j < 8; ++j) o4[64 * j] = pg8::pack4i8(v[j] * ASC_XI8);
;         float f[8];
; #pragma unroll
;         for (int e = 0; e < 8; ++e) { float s = 0.f;
; #pragma unroll
;             for (int j = 0; j < 8; ++j) { const f32x4 w = *(const LAS f32x4*)(wf + e * 2048 + 256 * j + 4 * lane); s = fmaf(v[j][0], w[0], s); s = fmaf(v[j][1], w[1], s); s = fmaf(v[j][2], w[2], s); s = fmaf(v[j][3], w[3], s); }
;             f[e] = wave_sum(s); }
.LBB0_994:
	s_or_b64 exec, exec, s[30:31]
	v_pk_mul_f32 v[80:81], v[46:47], s[26:27] op_sel_hi:[1,0]
	v_pk_mul_f32 v[94:95], v[44:45], s[26:27] op_sel_hi:[1,0]
	v_med3_f32 v80, v80, s35, v85
	v_med3_f32 v75, v94, s35, v85
	v_med3_f32 v94, v95, s35, v85
	v_med3_f32 v81, v81, s35, v85
	v_add_f32_e32 v75, 0x4b400000, v75
	v_add_f32_e32 v94, 0x4b400000, v94
	v_add_f32_e32 v80, 0x4b400000, v80
	v_add_f32_e32 v81, 0x4b400000, v81
	v_lshlrev_b64 v[78:79], 11, v[76:77]
	v_perm_b32 v75, v94, v75, s36
	v_perm_b32 v80, v81, v80, s37
	v_lshl_add_u64 v[78:79], v[68:69], 0, v[78:79]
	v_or_b32_e32 v75, v75, v80
	v_pk_mul_f32 v[80:81], v[42:43], s[26:27] op_sel_hi:[1,0]
	v_pk_mul_f32 v[94:95], v[40:41], s[26:27] op_sel_hi:[1,0]
	global_store_dword v[78:79], v75, off
	v_med3_f32 v75, v94, s35, v85
	v_med3_f32 v94, v95, s35, v85
	v_med3_f32 v80, v80, s35, v85
	v_med3_f32 v81, v81, s35, v85
	v_add_f32_e32 v75, 0x4b400000, v75
	v_add_f32_e32 v94, 0x4b400000, v94
	v_add_f32_e32 v80, 0x4b400000, v80
	v_add_f32_e32 v81, 0x4b400000, v81
	v_perm_b32 v75, v94, v75, s36
	v_perm_b32 v80, v81, v80, s37
	v_or_b32_e32 v75, v75, v80
	v_pk_mul_f32 v[80:81], v[38:39], s[26:27] op_sel_hi:[1,0]
	v_pk_mul_f32 v[94:95], v[36:37], s[26:27] op_sel_hi:[1,0]
	global_store_dword v[78:79], v75, off offset:256
	v_med3_f32 v75, v94, s35, v85
	v_med3_f32 v94, v95, s35, v85
	v_med3_f32 v80, v80, s35, v85
	v_med3_f32 v81, v81, s35, v85
	v_add_f32_e32 v75, 0x4b400000, v75
	v_add_f32_e32 v94, 0x4b400000, v94
	v_add_f32_e32 v80, 0x4b400000, v80
	v_add_f32_e32 v81, 0x4b400000, v81
	v_perm_b32 v75, v94, v75, s36
	v_perm_b32 v80, v81, v80, s37
	v_or_b32_e32 v75, v75, v80
	v_pk_mul_f32 v[80:81], v[34:35], s[26:27] op_sel_hi:[1,0]
	v_pk_mul_f32 v[94:95], v[32:33], s[26:27] op_sel_hi:[1,0]
	global_store_dword v[78:79], v75, off offset:512
	v_med3_f32 v75, v94, s35, v85
	v_med3_f32 v94, v95, s35, v85
	v_med3_f32 v80, v80, s35, v85
	v_med3_f32 v81, v81, s35, v85
	v_add_f32_e32 v75, 0x4b400000, v75
	v_add_f32_e32 v94, 0x4b400000, v94
	v_add_f32_e32 v80, 0x4b400000, v80
	v_add_f32_e32 v81, 0x4b400000, v81
	v_perm_b32 v75, v94, v75, s36
	v_perm_b32 v80, v81, v80, s37
	v_or_b32_e32 v75, v75, v80
	v_pk_mul_f32 v[80:81], v[62:63], s[26:27] op_sel_hi:[1,0]
	v_pk_mul_f32 v[94:95], v[60:61], s[26:27] op_sel_hi:[1,0]
	global_store_dword v[78:79], v75, off offset:768
	v_med3_f32 v75, v94, s35, v85
	v_med3_f32 v94, v95, s35, v85
	v_med3_f32 v80, v80, s35, v85
	v_med3_f32 v81, v81, s35, v85
	v_add_f32_e32 v75, 0x4b400000, v75
	v_add_f32_e32 v94, 0x4b400000, v94
	v_add_f32_e32 v80, 0x4b400000, v80
	v_add_f32_e32 v81, 0x4b400000, v81
	v_perm_b32 v75, v94, v75, s36
	v_perm_b32 v80, v81, v80, s37
	v_or_b32_e32 v75, v75, v80
	v_pk_mul_f32 v[80:81], v[58:59], s[26:27] op_sel_hi:[1,0]
	v_pk_mul_f32 v[94:95], v[56:57], s[26:27] op_sel_hi:[1,0]
	global_store_dword v[78:79], v75, off offset:1024
	v_med3_f32 v75, v94, s35, v85
	v_med3_f32 v94, v95, s35, v85
	v_med3_f32 v80, v80, s35, v85
	v_med3_f32 v81, v81, s35, v85
	v_add_f32_e32 v75, 0x4b400000, v75
	v_add_f32_e32 v94, 0x4b400000, v94
	v_add_f32_e32 v80, 0x4b400000, v80
	v_add_f32_e32 v81, 0x4b400000, v81
	v_perm_b32 v75, v94, v75, s36
	v_perm_b32 v80, v81, v80, s37
	v_or_b32_e32 v75, v75, v80
	v_pk_mul_f32 v[94:95], v[52:53], s[26:27] op_sel_hi:[1,0]
	global_store_dword v[78:79], v75, off offset:1280
	v_med3_f32 v75, v94, s35, v85
	v_med3_f32 v94, v95, s35, v85
	v_add_f32_e32 v75, 0x4b400000, v75
	v_add_f32_e32 v94, 0x4b400000, v94
	v_perm_b32 v75, v94, v75, s36
	ds_read_b128 v[94:97], v65
	ds_read_b128 v[98:101], v65 offset:1024
	v_pk_mul_f32 v[80:81], v[54:55], s[26:27] op_sel_hi:[1,0]
	v_pk_mul_f32 v[102:103], v[50:51], s[26:27] op_sel_hi:[1,0]
	v_med3_f32 v80, v80, s35, v85
	s_waitcnt lgkmcnt(1)
	v_fma_f32 v104, v44, v94, 0
	v_fmac_f32_e32 v104, v45, v95
	v_fmac_f32_e32 v104, v46, v96
	v_fmac_f32_e32 v104, v47, v97
	ds_read_b128 v[94:97], v65 offset:2048
	s_waitcnt lgkmcnt(1)
	v_fmac_f32_e32 v104, v40, v98
	v_fmac_f32_e32 v104, v41, v99
	v_fmac_f32_e32 v104, v42, v100
	v_fmac_f32_e32 v104, v43, v101
	ds_read_b128 v[98:101], v65 offset:3072
	s_waitcnt lgkmcnt(1)
	v_fmac_f32_e32 v104, v36, v94
	v_fmac_f32_e32 v104, v37, v95
	v_fmac_f32_e32 v104, v38, v96
	v_fmac_f32_e32 v104, v39, v97
	ds_read_b128 v[94:97], v65 offset:4096
	s_waitcnt lgkmcnt(1)
	v_fmac_f32_e32 v104, v32, v98
	v_fmac_f32_e32 v104, v33, v99
	v_fmac_f32_e32 v104, v34, v100
	v_fmac_f32_e32 v104, v35, v101
	ds_read_b128 v[98:101], v65 offset:5120
	s_waitcnt lgkmcnt(1)
	v_fmac_f32_e32 v104, v60, v94
	v_fmac_f32_e32 v104, v61, v95
	v_fmac_f32_e32 v104, v62, v96
	v_fmac_f32_e32 v104, v63, v97
	ds_read_b128 v[94:97], v65 offset:6144
	s_waitcnt lgkmcnt(1)
	v_fmac_f32_e32 v104, v56, v98
	v_fmac_f32_e32 v104, v57, v99
	v_fmac_f32_e32 v104, v58, v100
	v_fmac_f32_e32 v104, v59, v101
	ds_read_b128 v[98:101], v65 offset:7168
	s_waitcnt lgkmcnt(1)
	v_fmac_f32_e32 v104, v52, v94
	v_fmac_f32_e32 v104, v53, v95
	v_fmac_f32_e32 v104, v54, v96
	v_fmac_f32_e32 v104, v55, v97
	s_waitcnt lgkmcnt(0)
	v_fmac_f32_e32 v104, v48, v98
	v_fmac_f32_e32 v104, v49, v99
	v_fmac_f32_e32 v104, v50, v100
	v_fmac_f32_e32 v104, v51, v101
	s_nop 1
	v_mov_b32_dpp v98, v104 quad_perm:[1,0,3,2] row_mask:0xf bank_mask:0xf
	v_med3_f32 v81, v81, s35, v85
	ds_read_b128 v[94:97], v65 offset:8192
	v_add_f32_e32 v80, 0x4b400000, v80
	v_add_f32_e32 v81, 0x4b400000, v81
	v_perm_b32 v80, v81, v80, s37
	v_or_b32_e32 v75, v75, v80
	v_pk_mul_f32 v[80:81], v[48:49], s[26:27] op_sel_hi:[1,0]
	global_store_dword v[78:79], v75, off offset:1536
	v_med3_f32 v75, v80, s35, v85
	v_med3_f32 v80, v81, s35, v85
	v_med3_f32 v81, v102, s35, v85
	s_waitcnt lgkmcnt(0)
; #define LAS __attribute__((address_space(3)))
; __device__ __forceinline__ float wave_sum(float v) {
; #pragma unroll
;     for (int o = 1; o < 64; o <<= 1) v += __shfl_xor(v, o);
;     return v;
; }
; __device__ __forceinline__ void xprep_row(const f32x4 (&v)[8], const int m, LAS float* wf, bf16_t* XB, float* LOGF, const float* bfg, const int lane) {
;     ...
;         for (int e = 0; e < 8; ++e) { float s = 0.f;
; #pragma unroll
;             for (int j = 0; j < 8; ++j) { const f32x4 w = *(const LAS f32x4*)(wf + e * 2048 + 256 * j + 4 * lane); s = fmaf(v[j][0], w[0], s); s = fmaf(v[j][1], w[1], s); s = fmaf(v[j][2], w[2], s); s = fmaf(v[j][3], w[3], s); }
;             f[e] = wave_sum(s); }
	v_add_f32_e32 v102, v104, v98
	ds_read_b128 v[98:101], v65 offset:9216
	s_waitcnt lgkmcnt(1)
	v_fma_f32 v105, v44, v94, 0
	v_fmac_f32_e32 v105, v45, v95
	v_fmac_f32_e32 v105, v46, v96
	v_fmac_f32_e32 v105, v47, v97
	ds_read_b128 v[94:97], v65 offset:10240
	s_waitcnt lgkmcnt(1)
	v_fmac_f32_e32 v105, v40, v98
	v_fmac_f32_e32 v105, v41, v99
	v_fmac_f32_e32 v105, v42, v100
	v_fmac_f32_e32 v105, v43, v101
	ds_read_b128 v[98:101], v65 offset:11264
	s_waitcnt lgkmcnt(1)
	v_fmac_f32_e32 v105, v36, v94
	v_fmac_f32_e32 v105, v37, v95
	v_fmac_f32_e32 v105, v38, v96
	v_fmac_f32_e32 v105, v39, v97
	ds_read_b128 v[94:97], v65 offset:12288
	s_waitcnt lgkmcnt(1)
	v_fmac_f32_e32 v105, v32, v98
	v_fmac_f32_e32 v105, v33, v99
	v_fmac_f32_e32 v105, v34, v100
	v_fmac_f32_e32 v105, v35, v101
	ds_read_b128 v[98:101], v65 offset:13312
	s_waitcnt lgkmcnt(1)
	v_fmac_f32_e32 v105, v60, v94
	v_fmac_f32_e32 v105, v61, v95
	v_fmac_f32_e32 v105, v62, v96
	v_fmac_f32_e32 v105, v63, v97
	ds_read_b128 v[94:97], v65 offset:14336
	s_waitcnt lgkmcnt(1)
	v_fmac_f32_e32 v105, v56, v98
	v_fmac_f32_e32 v105, v57, v99
	v_fmac_f32_e32 v105, v58, v100
	v_fmac_f32_e32 v105, v59, v101
	ds_read_b128 v[98:101], v65 offset:15360
	s_waitcnt lgkmcnt(1)
	v_fmac_f32_e32 v105, v52, v94
	v_fmac_f32_e32 v105, v53, v95
	v_fmac_f32_e32 v105, v54, v96
	v_fmac_f32_e32 v105, v55, v97
	s_nop 1
	v_mov_b32_dpp v104, v102 quad_perm:[2,3,0,1] row_mask:0xf bank_mask:0xf
	s_waitcnt lgkmcnt(0)
	v_fmac_f32_e32 v105, v48, v98
	v_fmac_f32_e32 v105, v49, v99
	v_fmac_f32_e32 v105, v50, v100
	v_fmac_f32_e32 v105, v51, v101
	s_nop 1
	v_mov_b32_dpp v94, v105 quad_perm:[1,0,3,2] row_mask:0xf bank_mask:0xf
	s_waitcnt lgkmcnt(0)
	v_add_f32_e32 v95, v102, v104
	s_nop 1
	v_mov_b32_dpp v96, v95 row_half_mirror row_mask:0xf bank_mask:0xf
	v_med3_f32 v97, v103, s35, v85
	v_add_f32_e32 v75, 0x4b400000, v75
	s_waitcnt lgkmcnt(0)
	v_add_f32_e32 v100, v105, v94
	s_nop 1
	v_mov_b32_dpp v101, v100 quad_perm:[2,3,0,1] row_mask:0xf bank_mask:0xf
	v_add_f32_e32 v94, 0x4b400000, v97
	s_waitcnt lgkmcnt(0)
	v_add_f32_e32 v95, v95, v96
	ds_read_b128 v[96:99], v65 offset:16384
	s_nop 1
	v_mov_b32_dpp v104, v95 row_mirror row_mask:0xf bank_mask:0xf
	s_waitcnt lgkmcnt(1)
	v_add_f32_e32 v105, v100, v101
	ds_read_b128 v[100:103], v65 offset:17408
	s_nop 1
	v_mov_b32_dpp v106, v105 row_half_mirror row_mask:0xf bank_mask:0xf
	s_waitcnt lgkmcnt(1)
	v_fma_f32 v107, v44, v96, 0
	v_fmac_f32_e32 v107, v45, v97
	v_fmac_f32_e32 v107, v46, v98
	v_fmac_f32_e32 v107, v47, v99
	ds_read_b128 v[96:99], v65 offset:18432
	s_waitcnt lgkmcnt(0)
	v_fmac_f32_e32 v107, v40, v100
	v_fmac_f32_e32 v107, v41, v101
	v_fmac_f32_e32 v107, v42, v102
	v_fmac_f32_e32 v107, v43, v103
	ds_read_b128 v[100:103], v65 offset:19456
	s_waitcnt lgkmcnt(1)
	v_fmac_f32_e32 v107, v36, v96
	v_fmac_f32_e32 v107, v37, v97
	v_fmac_f32_e32 v107, v38, v98
	v_fmac_f32_e32 v107, v39, v99
	ds_read_b128 v[96:99], v65 offset:20480
	s_waitcnt lgkmcnt(1)
	v_fmac_f32_e32 v107, v32, v100
	v_fmac_f32_e32 v107, v33, v101
	v_fmac_f32_e32 v107, v34, v102
	v_fmac_f32_e32 v107, v35, v103
	ds_read_b128 v[100:103], v65 offset:21504
	s_waitcnt lgkmcnt(1)
	v_fmac_f32_e32 v107, v60, v96
	v_fmac_f32_e32 v107, v61, v97
	v_fmac_f32_e32 v107, v62, v98
	v_fmac_f32_e32 v107, v63, v99
	ds_read_b128 v[96:99], v65 offset:22528
	s_waitcnt lgkmcnt(1)
	v_fmac_f32_e32 v107, v56, v100
	v_fmac_f32_e32 v107, v57, v101
	v_fmac_f32_e32 v107, v58, v102
	v_fmac_f32_e32 v107, v59, v103
	ds_read_b128 v[100:103], v65 offset:23552
	s_waitcnt lgkmcnt(1)
	v_fmac_f32_e32 v107, v52, v96
	v_fmac_f32_e32 v107, v53, v97
	v_fmac_f32_e32 v107, v54, v98
	v_fmac_f32_e32 v107, v55, v99
	s_waitcnt lgkmcnt(0)
	v_fmac_f32_e32 v107, v48, v100
	v_fmac_f32_e32 v107, v49, v101
	v_fmac_f32_e32 v107, v50, v102
	v_fmac_f32_e32 v107, v51, v103
	s_nop 1
	v_mov_b32_dpp v96, v107 quad_perm:[1,0,3,2] row_mask:0xf bank_mask:0xf
	v_add_f32_e32 v95, v95, v104
	v_add_f32_e32 v102, v105, v106
	ds_bpermute_b32 v97, v92, v95
	s_nop 1
	v_mov_b32_dpp v103, v102 row_mirror row_mask:0xf bank_mask:0xf
	s_waitcnt lgkmcnt(0)
	v_add_f32_e32 v104, v107, v96
	s_nop 1
	v_mov_b32_dpp v105, v104 quad_perm:[2,3,0,1] row_mask:0xf bank_mask:0xf
	ds_read_b128 v[98:101], v65 offset:24576
	s_waitcnt lgkmcnt(2)
	v_add_f32_e32 v95, v95, v97
	s_waitcnt lgkmcnt(1)
	v_add_f32_e32 v97, v102, v103
	ds_bpermute_b32 v96, v93, v95
	s_waitcnt lgkmcnt(1)
	v_add_f32_e32 v106, v104, v105
	ds_read_b128 v[102:105], v65 offset:25600
	s_waitcnt lgkmcnt(1)
	v_fma_f32 v108, v44, v98, 0
	v_fmac_f32_e32 v108, v45, v99
	v_fmac_f32_e32 v108, v46, v100
	v_fmac_f32_e32 v108, v47, v101
	ds_read_b128 v[98:101], v65 offset:26624
	s_waitcnt lgkmcnt(0)
	v_fmac_f32_e32 v108, v40, v102
	v_fmac_f32_e32 v108, v41, v103
	v_fmac_f32_e32 v108, v42, v104
	v_fmac_f32_e32 v108, v43, v105
	ds_read_b128 v[102:105], v65 offset:27648
	s_waitcnt lgkmcnt(1)
	v_fmac_f32_e32 v108, v36, v98
	v_fmac_f32_e32 v108, v37, v99
	v_fmac_f32_e32 v108, v38, v100
	v_fmac_f32_e32 v108, v39, v101
	ds_read_b128 v[98:101], v65 offset:28672
	s_waitcnt lgkmcnt(1)
	v_fmac_f32_e32 v108, v32, v102
	v_fmac_f32_e32 v108, v33, v103
	v_fmac_f32_e32 v108, v34, v104
	v_fmac_f32_e32 v108, v35, v105
	ds_read_b128 v[102:105], v65 offset:29696
	s_waitcnt lgkmcnt(1)
	v_fmac_f32_e32 v108, v60, v98
	v_fmac_f32_e32 v108, v61, v99
	v_fmac_f32_e32 v108, v62, v100
	v_fmac_f32_e32 v108, v63, v101
	ds_read_b128 v[98:101], v65 offset:30720
	s_waitcnt lgkmcnt(1)
	v_fmac_f32_e32 v108, v56, v102
	v_fmac_f32_e32 v108, v57, v103
	v_fmac_f32_e32 v108, v58, v104
	v_fmac_f32_e32 v108, v59, v105
	ds_read_b128 v[102:105], v65 offset:31744
	s_waitcnt lgkmcnt(1)
; #define LAS __attribute__((address_space(3)))
; __device__ __forceinline__ float wave_sum(float v) {
; #pragma unroll
;     for (int o = 1; o < 64; o <<= 1) v += __shfl_xor(v, o);
;     return v;
; }
; __device__ __forceinline__ void xprep_row(const f32x4 (&v)[8], const int m, LAS float* wf, bf16_t* XB, float* LOGF, const float* bfg, const int lane) {
;     ...
;         for (int e = 0; e < 8; ++e) { float s = 0.f;
; #pragma unroll
;             for (int j = 0; j < 8; ++j) { const f32x4 w = *(const LAS f32x4*)(wf + e * 2048 + 256 * j + 4 * lane); s = fmaf(v[j][0], w[0], s); s = fmaf(v[j][1], w[1], s); s = fmaf(v[j][2], w[2], s); s = fmaf(v[j][3], w[3], s); }
;             f[e] = wave_sum(s); }
	v_fmac_f32_e32 v108, v52, v98
	v_fmac_f32_e32 v108, v53, v99
	v_fmac_f32_e32 v108, v54, v100
	v_fmac_f32_e32 v108, v55, v101
	ds_read_b128 v[98:101], v65 offset:32768
	s_waitcnt lgkmcnt(1)
	v_fmac_f32_e32 v108, v48, v102
	v_fmac_f32_e32 v108, v49, v103
	v_fmac_f32_e32 v108, v50, v104
	v_fmac_f32_e32 v108, v51, v105
	ds_read_b128 v[102:105], v65 offset:33792
	s_waitcnt lgkmcnt(1)
	v_fma_f32 v110, v44, v98, 0
	v_fmac_f32_e32 v110, v45, v99
	v_fmac_f32_e32 v110, v46, v100
	v_fmac_f32_e32 v110, v47, v101
	ds_read_b128 v[98:101], v65 offset:34816
	s_waitcnt lgkmcnt(1)
	v_fmac_f32_e32 v110, v40, v102
	v_fmac_f32_e32 v110, v41, v103
	v_fmac_f32_e32 v110, v42, v104
	v_fmac_f32_e32 v110, v43, v105
	ds_read_b128 v[102:105], v65 offset:35840
	s_waitcnt lgkmcnt(1)
	v_fmac_f32_e32 v110, v36, v98
	v_fmac_f32_e32 v110, v37, v99
	v_fmac_f32_e32 v110, v38, v100
	v_fmac_f32_e32 v110, v39, v101
	ds_read_b128 v[98:101], v65 offset:36864
	s_waitcnt lgkmcnt(1)
	v_fmac_f32_e32 v110, v32, v102
	v_fmac_f32_e32 v110, v33, v103
	v_fmac_f32_e32 v110, v34, v104
	v_fmac_f32_e32 v110, v35, v105
	ds_read_b128 v[102:105], v65 offset:37888
	s_waitcnt lgkmcnt(1)
	v_fmac_f32_e32 v110, v60, v98
	v_fmac_f32_e32 v110, v61, v99
	v_fmac_f32_e32 v110, v62, v100
	v_fmac_f32_e32 v110, v63, v101
	ds_read_b128 v[98:101], v65 offset:38912
	s_waitcnt lgkmcnt(1)
	v_fmac_f32_e32 v110, v56, v102
	s_nop 1
	v_mov_b32_dpp v109, v108 quad_perm:[1,0,3,2] row_mask:0xf bank_mask:0xf
	v_fmac_f32_e32 v110, v57, v103
	v_fmac_f32_e32 v110, v58, v104
	v_fmac_f32_e32 v110, v59, v105
	ds_read_b128 v[102:105], v65 offset:39936
	s_waitcnt lgkmcnt(1)
	v_fmac_f32_e32 v110, v52, v98
	v_fmac_f32_e32 v110, v53, v99
	v_fmac_f32_e32 v110, v54, v100
	s_waitcnt lgkmcnt(0)
	v_add_f32_e32 v100, v108, v109
	v_fmac_f32_e32 v110, v55, v101
	s_nop 1
	v_mov_b32_dpp v101, v100 quad_perm:[2,3,0,1] row_mask:0xf bank_mask:0xf
	s_waitcnt lgkmcnt(0)
	v_fmac_f32_e32 v110, v48, v102
	v_fmac_f32_e32 v110, v49, v103
	v_fmac_f32_e32 v110, v50, v104
	v_fmac_f32_e32 v110, v51, v105
	s_nop 1
	v_mov_b32_dpp v98, v110 quad_perm:[1,0,3,2] row_mask:0xf bank_mask:0xf
	s_waitcnt lgkmcnt(0)
	v_add_f32_e32 v100, v100, v101
	s_nop 1
	v_mov_b32_dpp v101, v100 row_half_mirror row_mask:0xf bank_mask:0xf
	s_nop 1
	v_mov_b32_dpp v107, v106 row_half_mirror row_mask:0xf bank_mask:0xf
	ds_bpermute_b32 v99, v92, v97
	s_waitcnt lgkmcnt(1)
	v_add_f32_e32 v98, v110, v98
	s_nop 1
	v_mov_b32_dpp v103, v98 quad_perm:[2,3,0,1] row_mask:0xf bank_mask:0xf
	s_waitcnt lgkmcnt(0)
	v_add_f32_e32 v100, v100, v101
	s_nop 1
	v_mov_b32_dpp v101, v100 row_mirror row_mask:0xf bank_mask:0xf
	s_waitcnt lgkmcnt(2)
	v_add_f32_e32 v102, v106, v107
	s_nop 1
	v_mov_b32_dpp v104, v102 row_mirror row_mask:0xf bank_mask:0xf
	s_waitcnt lgkmcnt(0)
	v_add_f32_e32 v98, v98, v103
	v_add_f32_e32 v97, v97, v99
	s_nop 1
	v_mov_b32_dpp v99, v98 row_half_mirror row_mask:0xf bank_mask:0xf
	s_waitcnt lgkmcnt(1)
	v_add_f32_e32 v101, v100, v101
	ds_bpermute_b32 v106, v92, v101
	s_waitcnt lgkmcnt(1)
	v_add_f32_e32 v102, v102, v104
	ds_bpermute_b32 v103, v92, v102
	s_waitcnt lgkmcnt(1)
	v_add_f32_e32 v104, v98, v99
	s_nop 1
	v_mov_b32_dpp v105, v104 row_mirror row_mask:0xf bank_mask:0xf
	s_waitcnt lgkmcnt(0)
	v_add_f32_e32 v101, v101, v106
	ds_read_b128 v[106:109], v65 offset:40960
	ds_read_b128 v[110:113], v65 offset:41984
	s_waitcnt lgkmcnt(3)
	v_add_f32_e32 v99, v102, v103
	s_waitcnt lgkmcnt(2)
	v_add_f32_e32 v103, v104, v105
	ds_bpermute_b32 v104, v92, v103
	s_waitcnt lgkmcnt(2)
	v_fma_f32 v105, v44, v106, 0
	v_fmac_f32_e32 v105, v45, v107
	v_fmac_f32_e32 v105, v46, v108
	v_fmac_f32_e32 v105, v47, v109
	ds_read_b128 v[106:109], v65 offset:43008
	s_waitcnt lgkmcnt(2)
	v_fmac_f32_e32 v105, v40, v110
	v_fmac_f32_e32 v105, v41, v111
	v_fmac_f32_e32 v105, v42, v112
	v_fmac_f32_e32 v105, v43, v113
	ds_read_b128 v[110:113], v65 offset:44032
	s_waitcnt lgkmcnt(1)
	v_fmac_f32_e32 v105, v36, v106
	v_fmac_f32_e32 v105, v37, v107
	v_fmac_f32_e32 v105, v38, v108
	v_fmac_f32_e32 v105, v39, v109
	ds_read_b128 v[106:109], v65 offset:45056
	s_waitcnt lgkmcnt(1)
	v_fmac_f32_e32 v105, v32, v110
	v_fmac_f32_e32 v105, v33, v111
	v_fmac_f32_e32 v105, v34, v112
	v_fmac_f32_e32 v105, v35, v113
	ds_read_b128 v[110:113], v65 offset:46080
	s_waitcnt lgkmcnt(1)
	v_fmac_f32_e32 v105, v60, v106
	v_fmac_f32_e32 v105, v61, v107
	v_fmac_f32_e32 v105, v62, v108
	v_fmac_f32_e32 v105, v63, v109
	ds_read_b128 v[106:109], v65 offset:47104
	s_waitcnt lgkmcnt(1)
	v_fmac_f32_e32 v105, v56, v110
	v_fmac_f32_e32 v105, v57, v111
	v_fmac_f32_e32 v105, v58, v112
	v_fmac_f32_e32 v105, v59, v113
	ds_read_b128 v[110:113], v65 offset:48128
	s_waitcnt lgkmcnt(1)
	v_fmac_f32_e32 v105, v52, v106
	v_fmac_f32_e32 v105, v53, v107
	v_fmac_f32_e32 v105, v54, v108
	v_fmac_f32_e32 v105, v55, v109
	ds_read_b128 v[106:109], v65 offset:49152
	s_waitcnt lgkmcnt(1)
	v_fmac_f32_e32 v105, v48, v110
	v_fmac_f32_e32 v105, v49, v111
	v_fmac_f32_e32 v105, v50, v112
	v_fmac_f32_e32 v105, v51, v113
	ds_read_b128 v[110:113], v65 offset:50176
	s_waitcnt lgkmcnt(1)
	v_fma_f32 v115, v44, v106, 0
	v_fmac_f32_e32 v115, v45, v107
	v_fmac_f32_e32 v115, v46, v108
	v_fmac_f32_e32 v115, v47, v109
	ds_read_b128 v[106:109], v65 offset:51200
	s_waitcnt lgkmcnt(1)
	v_fmac_f32_e32 v115, v40, v110
	v_fmac_f32_e32 v115, v41, v111
	v_fmac_f32_e32 v115, v42, v112
	v_fmac_f32_e32 v115, v43, v113
	ds_read_b128 v[110:113], v65 offset:52224
	s_waitcnt lgkmcnt(1)
	v_fmac_f32_e32 v115, v36, v106
	v_fmac_f32_e32 v115, v37, v107
	v_fmac_f32_e32 v115, v38, v108
	v_fmac_f32_e32 v115, v39, v109
	ds_read_b128 v[106:109], v65 offset:53248
	s_waitcnt lgkmcnt(1)
; #define LAS __attribute__((address_space(3)))
; __device__ __forceinline__ float wave_sum(float v) {
; #pragma unroll
;     for (int o = 1; o < 64; o <<= 1) v += __shfl_xor(v, o);
;     return v;
; }
; __device__ __forceinline__ void xprep_row(const f32x4 (&v)[8], const int m, LAS float* wf, bf16_t* XB, float* LOGF, const float* bfg, const int lane) {
;     ...
;         for (int e = 0; e < 8; ++e) { float s = 0.f;
; #pragma unroll
;             for (int j = 0; j < 8; ++j) { const f32x4 w = *(const LAS f32x4*)(wf + e * 2048 + 256 * j + 4 * lane); s = fmaf(v[j][0], w[0], s); s = fmaf(v[j][1], w[1], s); s = fmaf(v[j][2], w[2], s); s = fmaf(v[j][3], w[3], s); }
;             f[e] = wave_sum(s); }
	v_fmac_f32_e32 v115, v32, v110
	v_fmac_f32_e32 v115, v33, v111
	v_fmac_f32_e32 v115, v34, v112
	v_fmac_f32_e32 v115, v35, v113
	ds_read_b128 v[110:113], v65 offset:54272
	s_waitcnt lgkmcnt(1)
	v_fmac_f32_e32 v115, v60, v106
	v_fmac_f32_e32 v115, v61, v107
	v_fmac_f32_e32 v115, v62, v108
	v_fmac_f32_e32 v115, v63, v109
	ds_read_b128 v[106:109], v65 offset:55296
	s_waitcnt lgkmcnt(1)
	v_fmac_f32_e32 v115, v56, v110
	v_fmac_f32_e32 v115, v57, v111
	v_fmac_f32_e32 v115, v58, v112
	v_fmac_f32_e32 v115, v59, v113
	ds_read_b128 v[110:113], v65 offset:56320
	s_waitcnt lgkmcnt(1)
	v_fmac_f32_e32 v115, v52, v106
	v_fmac_f32_e32 v115, v53, v107
	v_fmac_f32_e32 v115, v54, v108
	v_fmac_f32_e32 v115, v55, v109
	ds_read_b128 v[106:109], v65 offset:57344
	s_waitcnt lgkmcnt(1)
	v_fmac_f32_e32 v115, v48, v110
	v_fmac_f32_e32 v115, v49, v111
	v_fmac_f32_e32 v115, v50, v112
	v_fmac_f32_e32 v115, v51, v113
	ds_read_b128 v[110:113], v65 offset:58368
	s_waitcnt lgkmcnt(1)
	v_fma_f32 v117, v44, v106, 0
	v_fmac_f32_e32 v117, v45, v107
	v_fmac_f32_e32 v117, v46, v108
	v_fmac_f32_e32 v117, v47, v109
	ds_read_b128 v[106:109], v65 offset:59392
	s_waitcnt lgkmcnt(1)
	v_fmac_f32_e32 v117, v40, v110
	v_fmac_f32_e32 v117, v41, v111
	v_fmac_f32_e32 v117, v42, v112
	v_fmac_f32_e32 v117, v43, v113
	ds_read_b128 v[110:113], v65 offset:60416
	s_waitcnt lgkmcnt(1)
	v_fmac_f32_e32 v117, v36, v106
	v_fmac_f32_e32 v117, v37, v107
	v_fmac_f32_e32 v117, v38, v108
	v_fmac_f32_e32 v117, v39, v109
	ds_read_b128 v[106:109], v65 offset:61440
	s_waitcnt lgkmcnt(1)
	v_fmac_f32_e32 v117, v32, v110
	v_fmac_f32_e32 v117, v33, v111
	v_fmac_f32_e32 v117, v34, v112
	v_fmac_f32_e32 v117, v35, v113
	ds_read_b128 v[110:113], v65 offset:62464
	s_waitcnt lgkmcnt(1)
	v_fmac_f32_e32 v117, v60, v106
	v_fmac_f32_e32 v117, v61, v107
	v_fmac_f32_e32 v117, v62, v108
	v_fmac_f32_e32 v117, v63, v109
	ds_read_b128 v[106:109], v65 offset:63488
	s_waitcnt lgkmcnt(1)
	v_fmac_f32_e32 v117, v56, v110
	v_fmac_f32_e32 v117, v57, v111
	v_fmac_f32_e32 v117, v58, v112
	v_fmac_f32_e32 v117, v59, v113
	ds_read_b128 v[110:113], v65 offset:64512
	s_waitcnt lgkmcnt(1)
	v_fmac_f32_e32 v117, v52, v106
	v_fmac_f32_e32 v117, v53, v107
	v_fmac_f32_e32 v117, v54, v108
	v_fmac_f32_e32 v117, v55, v109
	s_waitcnt lgkmcnt(0)
	v_fmac_f32_e32 v117, v48, v110
	v_fmac_f32_e32 v117, v49, v111
	v_fmac_f32_e32 v117, v50, v112
	v_fmac_f32_e32 v117, v51, v113
	s_nop 1
	v_mov_b32_dpp v114, v105 quad_perm:[1,0,3,2] row_mask:0xf bank_mask:0xf
	s_nop 1
	v_mov_b32_dpp v116, v115 quad_perm:[1,0,3,2] row_mask:0xf bank_mask:0xf
	s_nop 1
	v_mov_b32_dpp v90, v117 quad_perm:[1,0,3,2] row_mask:0xf bank_mask:0xf
	v_add_f32_e32 v103, v103, v104
	ds_bpermute_b32 v98, v93, v97
	s_waitcnt lgkmcnt(0)
	v_add_f32_e32 v105, v105, v114
	s_waitcnt lgkmcnt(2)
	v_add_f32_e32 v107, v115, v116
	s_waitcnt lgkmcnt(1)
	v_add_f32_e32 v90, v117, v90
	s_nop 1
	v_mov_b32_dpp v106, v105 quad_perm:[2,3,0,1] row_mask:0xf bank_mask:0xf
	s_nop 1
	v_mov_b32_dpp v108, v107 quad_perm:[2,3,0,1] row_mask:0xf bank_mask:0xf
	s_nop 1
	v_mov_b32_dpp v89, v90 quad_perm:[2,3,0,1] row_mask:0xf bank_mask:0xf
	ds_bpermute_b32 v100, v93, v99
	ds_bpermute_b32 v102, v93, v101
	s_waitcnt lgkmcnt(1)
	v_add_f32_e32 v105, v105, v106
	s_waitcnt lgkmcnt(0)
	v_add_f32_e32 v107, v107, v108
	s_waitcnt lgkmcnt(2)
	v_add_f32_e32 v89, v90, v89
	s_nop 1
	v_mov_b32_dpp v106, v105 row_half_mirror row_mask:0xf bank_mask:0xf
	s_nop 1
	v_mov_b32_dpp v108, v107 row_half_mirror row_mask:0xf bank_mask:0xf
	s_nop 1
	v_mov_b32_dpp v88, v89 row_half_mirror row_mask:0xf bank_mask:0xf
	ds_bpermute_b32 v104, v93, v103
	v_add_f32_e32 v80, 0x4b400000, v80
	s_waitcnt lgkmcnt(0)
	v_add_f32_e32 v90, v105, v106
	s_waitcnt lgkmcnt(2)
	v_add_f32_e32 v106, v107, v108
	s_waitcnt lgkmcnt(1)
	v_add_f32_e32 v88, v89, v88
	s_nop 1
	v_mov_b32_dpp v105, v90 row_mirror row_mask:0xf bank_mask:0xf
	s_nop 1
	v_mov_b32_dpp v107, v106 row_mirror row_mask:0xf bank_mask:0xf
	s_nop 1
	v_mov_b32_dpp v89, v88 row_mirror row_mask:0xf bank_mask:0xf
	v_add_f32_e32 v81, 0x4b400000, v81
	v_perm_b32 v75, v80, v75, s36
	s_waitcnt lgkmcnt(0)
	v_add_f32_e32 v90, v90, v105
	s_waitcnt lgkmcnt(1)
	v_add_f32_e32 v105, v106, v107
	s_waitcnt lgkmcnt(0)
	v_add_f32_e32 v107, v88, v89
	ds_bpermute_b32 v91, v92, v90
	ds_bpermute_b32 v106, v92, v105
	ds_bpermute_b32 v92, v92, v107
	v_perm_b32 v80, v94, v81, s37
	v_or_b32_e32 v75, v75, v80
	s_waitcnt lgkmcnt(2)
	v_add_f32_e32 v88, v90, v91
	s_waitcnt lgkmcnt(1)
	v_add_f32_e32 v90, v105, v106
	s_waitcnt lgkmcnt(0)
	v_add_f32_e32 v92, v107, v92
	ds_bpermute_b32 v89, v93, v88
	ds_bpermute_b32 v91, v93, v90
	ds_bpermute_b32 v93, v93, v92
	global_store_dword v[78:79], v75, off offset:1792
	s_and_saveexec_b64 s[30:31], s[2:3]
	s_cbranch_execz .LBB0_985
; #define LAS __attribute__((address_space(3)))
; __device__ __forceinline__ void xprep_row(const f32x4 (&v)[8], const int m, LAS float* wf, bf16_t* XB, float* LOGF, const float* bfg, const int lane) {
;     ...
;         for (int e = 0; e < 8; ++e) { float s = 0.f;
; #pragma unroll
;             for (int j = 0; j < 8; ++j) { const f32x4 w = *(const LAS f32x4*)(wf + e * 2048 + 256 * j + 4 * lane); s = fmaf(v[j][0], w[0], s); s = fmaf(v[j][1], w[1], s); s = fmaf(v[j][2], w[2], s); s = fmaf(v[j][3], w[3], s); }
;             f[e] = wave_sum(s); }
;         if (lane < 8) { float z = 0.f;
; #pragma unroll
;             for (int e = 0; e < 8; ++e) z = (lane == e) ? f[e] : z;
;             z += bfg[lane];
;             LOGF[(size_t)m * 8 + lane] = fminf(z, 0.f) - log1pf(expf(-fabsf(z))); }
	global_load_dword v75, v[70:71], off
	s_waitcnt lgkmcnt(1)
	v_add_f32_e32 v79, v90, v91
	v_add_f32_e32 v91, v95, v96
	v_add_f32_e32 v90, v97, v98
	v_cndmask_b32_e64 v91, 0, v91, s[4:5]
	v_add_f32_e32 v80, v88, v89
	v_add_f32_e32 v89, v99, v100
	v_cndmask_b32_e64 v90, v91, v90, s[6:7]
	v_add_f32_e32 v88, v101, v102
	v_cndmask_b32_e64 v89, v90, v89, s[8:9]
	v_add_f32_e32 v81, v103, v104
	v_cndmask_b32_e64 v88, v89, v88, s[10:11]
	v_cndmask_b32_e64 v81, v88, v81, s[12:13]
	v_cndmask_b32_e64 v80, v81, v80, s[14:15]
	s_waitcnt lgkmcnt(0)
	v_add_f32_e32 v78, v92, v93
	v_cndmask_b32_e64 v79, v80, v79, s[16:17]
	v_cndmask_b32_e64 v78, v79, v78, s[18:19]
	s_waitcnt vmcnt(0)
	v_add_f32_e32 v75, v78, v75
	v_mul_f32_e64 v78, |v75|, s38
	v_fma_f32 v79, |v75|, s38, -v78
	v_rndne_f32_e32 v80, v78
	v_fma_f32 v79, |v75|, s39, v79
	v_sub_f32_e32 v78, v78, v80
	v_add_f32_e32 v78, v78, v79
	v_cvt_i32_f32_e32 v80, v80
	v_exp_f32_e32 v81, v78
	v_cmp_ngt_f32_e64 vcc, |v75|, s40
	v_lshlrev_b64 v[78:79], 5, v[76:77]
	v_min_f32_e32 v77, 0, v75
	v_ldexp_f32 v80, v81, v80
	v_cndmask_b32_e32 v80, 0, v80, vcc
	v_cmp_nlt_f32_e64 vcc, |v75|, s41
	v_lshl_add_u64 v[78:79], v[72:73], 0, v[78:79]
	s_nop 0
	v_cndmask_b32_e32 v100, v87, v80, vcc
	v_add_f32_e32 v75, 1.0, v100
	v_add_f32_e32 v88, -1.0, v75
	v_frexp_mant_f32_e32 v89, v75
	v_cvt_f64_f32_e32 v[80:81], v75
	v_sub_f32_e32 v90, v88, v75
	v_frexp_exp_i32_f64_e32 v80, v[80:81]
	v_cmp_gt_f32_e32 vcc, s43, v89
	v_sub_f32_e32 v88, v100, v88
	v_add_f32_e32 v81, 1.0, v90
	v_subbrev_co_u32_e32 v80, vcc, 0, v80, vcc
	v_add_f32_e32 v81, v88, v81
	v_sub_u32_e32 v88, 0, v80
	v_ldexp_f32 v75, v75, v88
	v_ldexp_f32 v81, v81, v88
	v_add_f32_e32 v88, -1.0, v75
	v_add_f32_e32 v90, 1.0, v75
	v_add_f32_e32 v89, 1.0, v88
	v_add_f32_e32 v91, -1.0, v90
	v_sub_f32_e32 v89, v75, v89
	v_sub_f32_e32 v75, v75, v91
	v_add_f32_e32 v75, v81, v75
	v_add_f32_e32 v91, v81, v89
	v_add_f32_e32 v81, v90, v75
	v_rcp_f32_e32 v94, v81
	v_add_f32_e32 v89, v88, v91
	v_sub_f32_e32 v90, v90, v81
	v_add_f32_e32 v75, v75, v90
	v_mul_f32_e32 v96, v89, v94
	v_mul_f32_e32 v90, v81, v96
	v_fma_f32 v92, v96, v81, -v90
	v_sub_f32_e32 v88, v88, v89
	v_fmac_f32_e32 v92, v96, v75
	v_add_f32_e32 v95, v91, v88
	v_add_f32_e32 v88, v90, v92
	v_sub_f32_e32 v91, v89, v88
	v_mov_b32_e32 v93, v88
	v_pk_add_f32 v[88:89], v[88:89], v[90:91] neg_lo:[0,1] neg_hi:[0,1]
	v_cvt_f32_i32_e32 v80, v80
	v_pk_add_f32 v[88:89], v[88:89], v[92:93] neg_lo:[0,1] neg_hi:[0,1]
	v_cmp_neq_f32_e32 vcc, s42, v100
	v_add_f32_e32 v89, v95, v89
	v_add_f32_e32 v88, v88, v89
	v_add_f32_e32 v89, v91, v88
	v_mul_f32_e32 v93, v94, v89
	v_mul_f32_e32 v90, v81, v93
	v_fma_f32 v92, v93, v81, -v90
	v_sub_f32_e32 v91, v91, v89
	v_fmac_f32_e32 v92, v93, v75
	v_add_f32_e32 v95, v88, v91
	v_add_f32_e32 v97, v96, v93
	v_add_f32_e32 v88, v90, v92
	v_sub_f32_e32 v81, v97, v96
	v_sub_f32_e32 v91, v89, v88
	v_sub_f32_e32 v75, v93, v81
	v_mov_b32_e32 v93, v88
	v_pk_add_f32 v[88:89], v[88:89], v[90:91] neg_lo:[0,1] neg_hi:[0,1]
	s_nop 0
	v_pk_add_f32 v[88:89], v[88:89], v[92:93] neg_lo:[0,1] neg_hi:[0,1]
	s_nop 0
	v_add_f32_e32 v81, v95, v89
	v_add_f32_e32 v81, v88, v81
	v_add_f32_e32 v81, v91, v81
	v_mul_f32_e32 v81, v94, v81
	v_add_f32_e32 v75, v75, v81
	v_add_f32_e32 v81, v97, v75
	v_mul_f32_e32 v88, v81, v81
	v_sub_f32_e32 v90, v81, v97
	v_fmamk_f32 v91, v88, 0x3e9b6dac, v84
	v_ldexp_f32 v89, v81, 1
	v_sub_f32_e32 v90, v75, v90
	v_mul_f32_e32 v81, v81, v88
	v_fmaak_f32 v75, v88, v91, 0x3f2aaada
	v_ldexp_f32 v93, v90, 1
	v_pk_mul_f32 v[90:91], v[80:81], v[74:75]
	s_nop 0
	v_fma_f32 v88, v80, s44, -v90
	v_fmac_f32_e32 v88, 0xb102e308, v80
	v_pk_add_f32 v[80:81], v[90:91], v[88:89]
	v_mov_b32_e32 v92, v90
	v_sub_f32_e32 v75, v81, v89
	v_sub_f32_e32 v75, v91, v75
	v_add_f32_e32 v93, v93, v75
	v_pk_add_f32 v[94:95], v[80:81], v[90:91] neg_lo:[0,1] neg_hi:[0,1]
	v_pk_add_f32 v[90:91], v[80:81], v[92:93]
	v_mov_b32_e32 v89, v80
	v_mov_b32_e32 v95, v91
	v_pk_add_f32 v[98:99], v[88:89], v[94:95] neg_lo:[0,1] neg_hi:[0,1]
	v_pk_add_f32 v[88:89], v[88:89], v[94:95]
	v_mov_b32_e32 v97, v80
	v_pk_add_f32 v[94:95], v[88:89], v[80:81] op_sel:[1,0] op_sel_hi:[0,1] neg_lo:[0,1] neg_hi:[0,1]
	v_mov_b32_e32 v96, v93
	v_mov_b32_e32 v92, v91
	v_mov_b32_e32 v93, v89
	v_pk_mov_b32 v[80:81], v[80:81], v[94:95] op_sel:[1,0]
	v_pk_add_f32 v[90:91], v[90:91], v[94:95] op_sel_hi:[1,0] neg_lo:[0,1] neg_hi:[0,1]
	v_pk_add_f32 v[80:81], v[92:93], v[80:81] neg_lo:[0,1] neg_hi:[0,1]
	v_mov_b32_e32 v90, v98
	v_pk_add_f32 v[80:81], v[96:97], v[80:81] neg_lo:[0,1] neg_hi:[0,1]
	v_mov_b32_e32 v99, v89
	v_pk_add_f32 v[90:91], v[90:91], v[80:81]
	s_nop 0
	v_pk_add_f32 v[92:93], v[90:91], v[90:91] op_sel:[0,1] op_sel_hi:[1,0]
	s_nop 0
	v_pk_add_f32 v[88:89], v[88:89], v[92:93] op_sel:[1,0] op_sel_hi:[0,1]
	v_mov_b32_e32 v91, v88
	v_mov_b32_e32 v81, v92
	v_pk_add_f32 v[92:93], v[90:91], v[98:99] neg_lo:[0,1] neg_hi:[0,1]
	s_nop 0
	v_sub_f32_e32 v75, v90, v92
	v_pk_add_f32 v[80:81], v[80:81], v[92:93] neg_lo:[0,1] neg_hi:[0,1]
	v_sub_f32_e32 v75, v98, v75
	v_add_f32_e32 v75, v80, v75
	v_add_f32_e32 v75, v75, v81
	v_add_f32_e32 v75, v88, v75
	v_cndmask_b32_e32 v75, v87, v75, vcc
	v_cmp_lt_f32_e64 vcc, |v100|, s45
	s_nop 1
	v_cndmask_b32_e32 v75, v75, v100, vcc
	v_sub_f32_e32 v75, v77, v75
	global_store_dword v[78:79], v75, off
	s_branch .LBB0_985

; __device__ __forceinline__ int crow(int r, int hi) { return (r & 3) + 8 * (r >> 2) + 4 * hi; }
; template <int MODE>
; __device__ __forceinline__ void attn_block(const AttnArgs& a, const BlockRef& cur, const BlockRef& nxt, char* lds, Seam<MODE>& S, const int tid) {
;     ...
;     if (a.o8 != 0.f) {
;         unsigned char* Ob = (unsigned char*)a.O + (size_t)(orow_ + wid * QBLK) * ldo + hcol_; const float os = a.o8;
; #pragma unroll
;         for (int r = 0; r < 16; ++r) { const int orow = crow(r, hi);
; #pragma unroll
;             for (int d0 = 0; d0 < 4; ++d0) { const float v = __builtin_amdgcn_fmed3f(o[d0][r] * rli[r] * os, -448.f, 448.f);
;                 const float vn = __shfl_xor(v, 1);
;                 const int pk = __builtin_amdgcn_cvt_pk_fp8_f32(v, vn, 0, false) & 0xffff; const int pk2 = __shfl_xor(pk, 2);
;                 if ((r32 & 3) == 0) *(unsigned*)(Ob + (size_t)orow * ldo + d0 * 32 + r32) = (unsigned)pk | ((unsigned)pk2 << 16); } }
.LBB0_3287:
	s_or_b64 exec, exec, s[6:7]
	v_mul_f32_e32 v48, v48, v0
	v_mul_f32_e32 v48, 0x41800000, v48
	v_med3_f32 v48, v48, s72, v224
	s_nop 1
	v_mov_b32_dpp v64, v48 quad_perm:[1,0,3,2] row_mask:0xf bank_mask:0xf
	s_waitcnt lgkmcnt(0)
	v_mov_b32_e32 v80, v1
	s_waitcnt lgkmcnt(0)
	v_cvt_pk_fp8_f32 v80, v48, v64
	v_and_b32_e32 v48, 0xffff, v80
	s_nop 1
	v_mov_b32_dpp v64, v48 quad_perm:[2,3,0,1] row_mask:0xf bank_mask:0xf
	s_and_saveexec_b64 s[6:7], vcc
	s_cbranch_execz .LBB0_3289
	s_waitcnt lgkmcnt(0)
	v_lshl_or_b32 v48, v64, 16, v48
	global_store_dword v[86:87], v48, off offset:32
.LBB0_3289:
	s_or_b64 exec, exec, s[6:7]
	v_mul_f32_e32 v32, v32, v0
	v_mul_f32_e32 v32, 0x41800000, v32
	v_med3_f32 v32, v32, s72, v224
	s_nop 1
	v_mov_b32_dpp v48, v32 quad_perm:[1,0,3,2] row_mask:0xf bank_mask:0xf
	s_waitcnt lgkmcnt(0)
	v_mov_b32_e32 v64, v1
	s_waitcnt lgkmcnt(0)
	v_cvt_pk_fp8_f32 v64, v32, v48
	v_and_b32_e32 v32, 0xffff, v64
	s_nop 1
	v_mov_b32_dpp v48, v32 quad_perm:[2,3,0,1] row_mask:0xf bank_mask:0xf
	s_and_saveexec_b64 s[6:7], vcc
	s_cbranch_execz .LBB0_3291
	s_waitcnt lgkmcnt(0)
	v_lshl_or_b32 v32, v48, 16, v32
	global_store_dword v[86:87], v32, off offset:64

; __device__ __forceinline__ int crow(int r, int hi) { return (r & 3) + 8 * (r >> 2) + 4 * hi; }
; template <int MODE>
; __device__ __forceinline__ void attn_block(const AttnArgs& a, const BlockRef& cur, const BlockRef& nxt, char* lds, Seam<MODE>& S, const int tid) {
;     ...
;     if (a.o8 != 0.f) {
;         unsigned char* Ob = (unsigned char*)a.O + (size_t)(orow_ + wid * QBLK) * ldo + hcol_; const float os = a.o8;
; #pragma unroll
;         for (int r = 0; r < 16; ++r) { const int orow = crow(r, hi);
; #pragma unroll
;             for (int d0 = 0; d0 < 4; ++d0) { const float v = __builtin_amdgcn_fmed3f(o[d0][r] * rli[r] * os, -448.f, 448.f);
;                 const float vn = __shfl_xor(v, 1);
;                 const int pk = __builtin_amdgcn_cvt_pk_fp8_f32(v, vn, 0, false) & 0xffff; const int pk2 = __shfl_xor(pk, 2);
;                 if ((r32 & 3) == 0) *(unsigned*)(Ob + (size_t)orow * ldo + d0 * 32 + r32) = (unsigned)pk | ((unsigned)pk2 << 16); } }
.LBB0_3323:
	s_or_b64 exec, exec, s[6:7]
	v_mul_f32_e32 v0, v20, v0
	v_mul_f32_e32 v0, 0x41800000, v0
	v_med3_f32 v0, v0, s72, v224
	s_nop 1
	v_mov_b32_dpp v10, v0 quad_perm:[1,0,3,2] row_mask:0xf bank_mask:0xf
	s_waitcnt lgkmcnt(0)
	v_mov_b32_e32 v18, v1
	s_waitcnt lgkmcnt(0)
	v_cvt_pk_fp8_f32 v18, v0, v10
	v_and_b32_e32 v0, 0xffff, v18
	s_nop 1
	v_mov_b32_dpp v10, v0 quad_perm:[2,3,0,1] row_mask:0xf bank_mask:0xf
	s_and_saveexec_b64 s[6:7], vcc
	s_cbranch_execz .LBB0_3325
	s_waitcnt lgkmcnt(0)
	v_lshl_or_b32 v0, v10, 16, v0
	global_store_dword v[16:17], v0, off offset:96

; __device__ __forceinline__ int crow(int r, int hi) { return (r & 3) + 8 * (r >> 2) + 4 * hi; }
; template <int MODE>
; __device__ __forceinline__ void attn_block(const AttnArgs& a, const BlockRef& cur, const BlockRef& nxt, char* lds, Seam<MODE>& S, const int tid) {
;     ...
;     if (a.o8 != 0.f) {
;         unsigned char* Ob = (unsigned char*)a.O + (size_t)(orow_ + wid * QBLK) * ldo + hcol_; const float os = a.o8;
; #pragma unroll
;         for (int r = 0; r < 16; ++r) { const int orow = crow(r, hi);
; #pragma unroll
;             for (int d0 = 0; d0 < 4; ++d0) { const float v = __builtin_amdgcn_fmed3f(o[d0][r] * rli[r] * os, -448.f, 448.f);
;                 const float vn = __shfl_xor(v, 1);
;                 const int pk = __builtin_amdgcn_cvt_pk_fp8_f32(v, vn, 0, false) & 0xffff; const int pk2 = __shfl_xor(pk, 2);
;                 if ((r32 & 3) == 0) *(unsigned*)(Ob + (size_t)orow * ldo + d0 * 32 + r32) = (unsigned)pk | ((unsigned)pk2 << 16); } }
.LBB0_3331:
	s_or_b64 exec, exec, s[6:7]
	v_mul_f32_e32 v0, v21, v0
	v_mul_f32_e32 v0, 0x41800000, v0
	v_med3_f32 v0, v0, s72, v224
	s_nop 1
	v_mov_b32_dpp v16, v0 quad_perm:[1,0,3,2] row_mask:0xf bank_mask:0xf
	s_waitcnt lgkmcnt(0)
	v_mov_b32_e32 v17, v1
	s_waitcnt lgkmcnt(0)
	v_cvt_pk_fp8_f32 v17, v0, v16
	v_and_b32_e32 v0, 0xffff, v17
	s_nop 1
	v_mov_b32_dpp v16, v0 quad_perm:[2,3,0,1] row_mask:0xf bank_mask:0xf
	s_and_saveexec_b64 s[6:7], vcc
	s_cbranch_execz .LBB0_3333
	s_waitcnt lgkmcnt(0)
	v_lshl_or_b32 v0, v16, 16, v0
	global_store_dword v[10:11], v0, off offset:96

; __device__ __forceinline__ int crow(int r, int hi) { return (r & 3) + 8 * (r >> 2) + 4 * hi; }
; template <int MODE>
; __device__ __forceinline__ void attn_block(const AttnArgs& a, const BlockRef& cur, const BlockRef& nxt, char* lds, Seam<MODE>& S, const int tid) {
;     ...
;     if (a.o8 != 0.f) {
;         unsigned char* Ob = (unsigned char*)a.O + (size_t)(orow_ + wid * QBLK) * ldo + hcol_; const float os = a.o8;
; #pragma unroll
;         for (int r = 0; r < 16; ++r) { const int orow = crow(r, hi);
; #pragma unroll
;             for (int d0 = 0; d0 < 4; ++d0) { const float v = __builtin_amdgcn_fmed3f(o[d0][r] * rli[r] * os, -448.f, 448.f);
;                 const float vn = __shfl_xor(v, 1);
;                 const int pk = __builtin_amdgcn_cvt_pk_fp8_f32(v, vn, 0, false) & 0xffff; const int pk2 = __shfl_xor(pk, 2);
;                 if ((r32 & 3) == 0) *(unsigned*)(Ob + (size_t)orow * ldo + d0 * 32 + r32) = (unsigned)pk | ((unsigned)pk2 << 16); } }
.LBB0_3339:
	s_or_b64 exec, exec, s[6:7]
	v_mul_f32_e32 v0, v22, v0
	v_mul_f32_e32 v0, 0x41800000, v0
	v_med3_f32 v0, v0, s72, v224
	s_nop 1
	v_mov_b32_dpp v12, v0 quad_perm:[1,0,3,2] row_mask:0xf bank_mask:0xf
	s_waitcnt lgkmcnt(0)
	v_mov_b32_e32 v16, v1
	s_waitcnt lgkmcnt(0)
	v_cvt_pk_fp8_f32 v16, v0, v12
	v_and_b32_e32 v0, 0xffff, v16
	s_nop 1
	v_mov_b32_dpp v12, v0 quad_perm:[2,3,0,1] row_mask:0xf bank_mask:0xf
	s_and_saveexec_b64 s[6:7], vcc
	s_cbranch_execz .LBB0_3341
	s_waitcnt lgkmcnt(0)
	v_lshl_or_b32 v0, v12, 16, v0
	global_store_dword v[10:11], v0, off offset:96

; __device__ __forceinline__ int crow(int r, int hi) { return (r & 3) + 8 * (r >> 2) + 4 * hi; }
; template <int MODE>
; __device__ __forceinline__ void attn_block(const AttnArgs& a, const BlockRef& cur, const BlockRef& nxt, char* lds, Seam<MODE>& S, const int tid) {
;     ...
;     if (a.o8 != 0.f) {
;         unsigned char* Ob = (unsigned char*)a.O + (size_t)(orow_ + wid * QBLK) * ldo + hcol_; const float os = a.o8;
; #pragma unroll
;         for (int r = 0; r < 16; ++r) { const int orow = crow(r, hi);
; #pragma unroll
;             for (int d0 = 0; d0 < 4; ++d0) { const float v = __builtin_amdgcn_fmed3f(o[d0][r] * rli[r] * os, -448.f, 448.f);
;                 const float vn = __shfl_xor(v, 1);
;                 const int pk = __builtin_amdgcn_cvt_pk_fp8_f32(v, vn, 0, false) & 0xffff; const int pk2 = __shfl_xor(pk, 2);
;                 if ((r32 & 3) == 0) *(unsigned*)(Ob + (size_t)orow * ldo + d0 * 32 + r32) = (unsigned)pk | ((unsigned)pk2 << 16); } }
.LBB0_3347:
	s_or_b64 exec, exec, s[6:7]
	v_mul_f32_e32 v0, v23, v0
	v_mul_f32_e32 v0, 0x41800000, v0
	v_med3_f32 v0, v0, s72, v224
	s_nop 1
	v_mov_b32_dpp v12, v0 quad_perm:[1,0,3,2] row_mask:0xf bank_mask:0xf
	s_waitcnt lgkmcnt(0)
	v_mov_b32_e32 v13, v1
	s_waitcnt lgkmcnt(0)
	v_cvt_pk_fp8_f32 v13, v0, v12
	v_and_b32_e32 v0, 0xffff, v13
	s_nop 1
	v_mov_b32_dpp v12, v0 quad_perm:[2,3,0,1] row_mask:0xf bank_mask:0xf
	s_and_saveexec_b64 s[6:7], vcc
	s_cbranch_execz .LBB0_3349
	s_waitcnt lgkmcnt(0)
	v_lshl_or_b32 v0, v12, 16, v0
	global_store_dword v[10:11], v0, off offset:96

; __device__ __forceinline__ int crow(int r, int hi) { return (r & 3) + 8 * (r >> 2) + 4 * hi; }
; template <int MODE>
; __device__ __forceinline__ void attn_block(const AttnArgs& a, const BlockRef& cur, const BlockRef& nxt, char* lds, Seam<MODE>& S, const int tid) {
;     ...
;     if (a.o8 != 0.f) {
;         unsigned char* Ob = (unsigned char*)a.O + (size_t)(orow_ + wid * QBLK) * ldo + hcol_; const float os = a.o8;
; #pragma unroll
;         for (int r = 0; r < 16; ++r) { const int orow = crow(r, hi);
; #pragma unroll
;             for (int d0 = 0; d0 < 4; ++d0) { const float v = __builtin_amdgcn_fmed3f(o[d0][r] * rli[r] * os, -448.f, 448.f);
;                 const float vn = __shfl_xor(v, 1);
;                 const int pk = __builtin_amdgcn_cvt_pk_fp8_f32(v, vn, 0, false) & 0xffff; const int pk2 = __shfl_xor(pk, 2);
;                 if ((r32 & 3) == 0) *(unsigned*)(Ob + (size_t)orow * ldo + d0 * 32 + r32) = (unsigned)pk | ((unsigned)pk2 << 16); } }
.LBB0_3355:
	s_or_b64 exec, exec, s[6:7]
	v_mul_f32_e32 v0, v24, v0
	v_mul_f32_e32 v0, 0x41800000, v0
	v_med3_f32 v0, v0, s72, v224
	s_nop 1
	v_mov_b32_dpp v6, v0 quad_perm:[1,0,3,2] row_mask:0xf bank_mask:0xf
	s_waitcnt lgkmcnt(0)
	v_mov_b32_e32 v12, v1
	s_waitcnt lgkmcnt(0)
	v_cvt_pk_fp8_f32 v12, v0, v6
	v_and_b32_e32 v0, 0xffff, v12
	s_nop 1
	v_mov_b32_dpp v6, v0 quad_perm:[2,3,0,1] row_mask:0xf bank_mask:0xf
	s_and_saveexec_b64 s[6:7], vcc
	s_cbranch_execz .LBB0_3357
	s_waitcnt lgkmcnt(0)
	v_lshl_or_b32 v0, v6, 16, v0
	global_store_dword v[10:11], v0, off offset:96

; __device__ __forceinline__ int crow(int r, int hi) { return (r & 3) + 8 * (r >> 2) + 4 * hi; }
; template <int MODE>
; __device__ __forceinline__ void attn_block(const AttnArgs& a, const BlockRef& cur, const BlockRef& nxt, char* lds, Seam<MODE>& S, const int tid) {
;     ...
;     if (a.o8 != 0.f) {
;         unsigned char* Ob = (unsigned char*)a.O + (size_t)(orow_ + wid * QBLK) * ldo + hcol_; const float os = a.o8;
; #pragma unroll
;         for (int r = 0; r < 16; ++r) { const int orow = crow(r, hi);
; #pragma unroll
;             for (int d0 = 0; d0 < 4; ++d0) { const float v = __builtin_amdgcn_fmed3f(o[d0][r] * rli[r] * os, -448.f, 448.f);
;                 const float vn = __shfl_xor(v, 1);
;                 const int pk = __builtin_amdgcn_cvt_pk_fp8_f32(v, vn, 0, false) & 0xffff; const int pk2 = __shfl_xor(pk, 2);
;                 if ((r32 & 3) == 0) *(unsigned*)(Ob + (size_t)orow * ldo + d0 * 32 + r32) = (unsigned)pk | ((unsigned)pk2 << 16); } }
.LBB0_3363:
	s_or_b64 exec, exec, s[6:7]
	v_mul_f32_e32 v0, v25, v0
	v_mul_f32_e32 v0, 0x41800000, v0
	v_med3_f32 v0, v0, s72, v224
	s_nop 1
	v_mov_b32_dpp v10, v0 quad_perm:[1,0,3,2] row_mask:0xf bank_mask:0xf
	s_waitcnt lgkmcnt(0)
	v_mov_b32_e32 v11, v1
	s_waitcnt lgkmcnt(0)
	v_cvt_pk_fp8_f32 v11, v0, v10
	v_and_b32_e32 v0, 0xffff, v11
	s_nop 1
	v_mov_b32_dpp v10, v0 quad_perm:[2,3,0,1] row_mask:0xf bank_mask:0xf
	s_and_saveexec_b64 s[6:7], vcc
	s_cbranch_execz .LBB0_3365
	s_waitcnt lgkmcnt(0)
	v_lshl_or_b32 v0, v10, 16, v0
	global_store_dword v[6:7], v0, off offset:96

; __device__ __forceinline__ int crow(int r, int hi) { return (r & 3) + 8 * (r >> 2) + 4 * hi; }
; template <int MODE>
; __device__ __forceinline__ void attn_block(const AttnArgs& a, const BlockRef& cur, const BlockRef& nxt, char* lds, Seam<MODE>& S, const int tid) {
;     ...
;     if (a.o8 != 0.f) {
;         unsigned char* Ob = (unsigned char*)a.O + (size_t)(orow_ + wid * QBLK) * ldo + hcol_; const float os = a.o8;
; #pragma unroll
;         for (int r = 0; r < 16; ++r) { const int orow = crow(r, hi);
; #pragma unroll
;             for (int d0 = 0; d0 < 4; ++d0) { const float v = __builtin_amdgcn_fmed3f(o[d0][r] * rli[r] * os, -448.f, 448.f);
;                 const float vn = __shfl_xor(v, 1);
;                 const int pk = __builtin_amdgcn_cvt_pk_fp8_f32(v, vn, 0, false) & 0xffff; const int pk2 = __shfl_xor(pk, 2);
;                 if ((r32 & 3) == 0) *(unsigned*)(Ob + (size_t)orow * ldo + d0 * 32 + r32) = (unsigned)pk | ((unsigned)pk2 << 16); } }
.LBB0_3371:
	s_or_b64 exec, exec, s[6:7]
	v_mul_f32_e32 v0, v26, v0
	v_mul_f32_e32 v0, 0x41800000, v0
	v_med3_f32 v0, v0, s72, v224
	s_nop 1
	v_mov_b32_dpp v8, v0 quad_perm:[1,0,3,2] row_mask:0xf bank_mask:0xf
	s_waitcnt lgkmcnt(0)
	v_mov_b32_e32 v10, v1
	s_waitcnt lgkmcnt(0)
	v_cvt_pk_fp8_f32 v10, v0, v8
	v_and_b32_e32 v0, 0xffff, v10
	s_nop 1
	v_mov_b32_dpp v8, v0 quad_perm:[2,3,0,1] row_mask:0xf bank_mask:0xf
	s_and_saveexec_b64 s[6:7], vcc
	s_cbranch_execz .LBB0_3373
	s_waitcnt lgkmcnt(0)
	v_lshl_or_b32 v0, v8, 16, v0
	global_store_dword v[6:7], v0, off offset:96

; __device__ __forceinline__ int crow(int r, int hi) { return (r & 3) + 8 * (r >> 2) + 4 * hi; }
; template <int MODE>
; __device__ __forceinline__ void attn_block(const AttnArgs& a, const BlockRef& cur, const BlockRef& nxt, char* lds, Seam<MODE>& S, const int tid) {
;     ...
;     if (a.o8 != 0.f) {
;         unsigned char* Ob = (unsigned char*)a.O + (size_t)(orow_ + wid * QBLK) * ldo + hcol_; const float os = a.o8;
; #pragma unroll
;         for (int r = 0; r < 16; ++r) { const int orow = crow(r, hi);
; #pragma unroll
;             for (int d0 = 0; d0 < 4; ++d0) { const float v = __builtin_amdgcn_fmed3f(o[d0][r] * rli[r] * os, -448.f, 448.f);
;                 const float vn = __shfl_xor(v, 1);
;                 const int pk = __builtin_amdgcn_cvt_pk_fp8_f32(v, vn, 0, false) & 0xffff; const int pk2 = __shfl_xor(pk, 2);
;                 if ((r32 & 3) == 0) *(unsigned*)(Ob + (size_t)orow * ldo + d0 * 32 + r32) = (unsigned)pk | ((unsigned)pk2 << 16); } }
.LBB0_3379:
	s_or_b64 exec, exec, s[6:7]
	v_mul_f32_e32 v0, v27, v0
	v_mul_f32_e32 v0, 0x41800000, v0
	v_med3_f32 v0, v0, s72, v224
	s_nop 1
	v_mov_b32_dpp v8, v0 quad_perm:[1,0,3,2] row_mask:0xf bank_mask:0xf
	s_waitcnt lgkmcnt(0)
	v_mov_b32_e32 v9, v1
	s_waitcnt lgkmcnt(0)
	v_cvt_pk_fp8_f32 v9, v0, v8
	v_and_b32_e32 v0, 0xffff, v9
	s_nop 1
	v_mov_b32_dpp v8, v0 quad_perm:[2,3,0,1] row_mask:0xf bank_mask:0xf
	s_and_saveexec_b64 s[6:7], vcc
	s_cbranch_execz .LBB0_3381
	s_waitcnt lgkmcnt(0)
	v_lshl_or_b32 v0, v8, 16, v0
	global_store_dword v[6:7], v0, off offset:96

; __device__ __forceinline__ int crow(int r, int hi) { return (r & 3) + 8 * (r >> 2) + 4 * hi; }
; template <int MODE>
; __device__ __forceinline__ void attn_block(const AttnArgs& a, const BlockRef& cur, const BlockRef& nxt, char* lds, Seam<MODE>& S, const int tid) {
;     ...
;     if (a.o8 != 0.f) {
;         unsigned char* Ob = (unsigned char*)a.O + (size_t)(orow_ + wid * QBLK) * ldo + hcol_; const float os = a.o8;
; #pragma unroll
;         for (int r = 0; r < 16; ++r) { const int orow = crow(r, hi);
; #pragma unroll
;             for (int d0 = 0; d0 < 4; ++d0) { const float v = __builtin_amdgcn_fmed3f(o[d0][r] * rli[r] * os, -448.f, 448.f);
;                 const float vn = __shfl_xor(v, 1);
;                 const int pk = __builtin_amdgcn_cvt_pk_fp8_f32(v, vn, 0, false) & 0xffff; const int pk2 = __shfl_xor(pk, 2);
;                 if ((r32 & 3) == 0) *(unsigned*)(Ob + (size_t)orow * ldo + d0 * 32 + r32) = (unsigned)pk | ((unsigned)pk2 << 16); } }
.LBB0_3387:
	s_or_b64 exec, exec, s[6:7]
	v_mul_f32_e32 v0, v28, v0
	v_mul_f32_e32 v0, 0x41800000, v0
	v_med3_f32 v0, v0, s72, v224
	s_nop 1
	v_mov_b32_dpp v2, v0 quad_perm:[1,0,3,2] row_mask:0xf bank_mask:0xf
	s_waitcnt lgkmcnt(0)
	v_mov_b32_e32 v8, v1
	s_waitcnt lgkmcnt(0)
	v_cvt_pk_fp8_f32 v8, v0, v2
	v_and_b32_e32 v0, 0xffff, v8
	s_nop 1
	v_mov_b32_dpp v2, v0 quad_perm:[2,3,0,1] row_mask:0xf bank_mask:0xf
	s_and_saveexec_b64 s[6:7], vcc
	s_cbranch_execz .LBB0_3389
	s_waitcnt lgkmcnt(0)
	v_lshl_or_b32 v0, v2, 16, v0
	global_store_dword v[6:7], v0, off offset:96

; __device__ __forceinline__ int crow(int r, int hi) { return (r & 3) + 8 * (r >> 2) + 4 * hi; }
; template <int MODE>
; __device__ __forceinline__ void attn_block(const AttnArgs& a, const BlockRef& cur, const BlockRef& nxt, char* lds, Seam<MODE>& S, const int tid) {
;     ...
;     if (a.o8 != 0.f) {
;         unsigned char* Ob = (unsigned char*)a.O + (size_t)(orow_ + wid * QBLK) * ldo + hcol_; const float os = a.o8;
; #pragma unroll
;         for (int r = 0; r < 16; ++r) { const int orow = crow(r, hi);
; #pragma unroll
;             for (int d0 = 0; d0 < 4; ++d0) { const float v = __builtin_amdgcn_fmed3f(o[d0][r] * rli[r] * os, -448.f, 448.f);
;                 const float vn = __shfl_xor(v, 1);
;                 const int pk = __builtin_amdgcn_cvt_pk_fp8_f32(v, vn, 0, false) & 0xffff; const int pk2 = __shfl_xor(pk, 2);
;                 if ((r32 & 3) == 0) *(unsigned*)(Ob + (size_t)orow * ldo + d0 * 32 + r32) = (unsigned)pk | ((unsigned)pk2 << 16); } }
.LBB0_3395:
	s_or_b64 exec, exec, s[6:7]
	v_mul_f32_e32 v0, v29, v0
	v_mul_f32_e32 v0, 0x41800000, v0
	v_med3_f32 v0, v0, s72, v224
	s_nop 1
	v_mov_b32_dpp v6, v0 quad_perm:[1,0,3,2] row_mask:0xf bank_mask:0xf
	s_waitcnt lgkmcnt(0)
	v_mov_b32_e32 v7, v1
	s_waitcnt lgkmcnt(0)
	v_cvt_pk_fp8_f32 v7, v0, v6
	v_and_b32_e32 v0, 0xffff, v7
	s_nop 1
	v_mov_b32_dpp v6, v0 quad_perm:[2,3,0,1] row_mask:0xf bank_mask:0xf
	s_and_saveexec_b64 s[6:7], vcc
	s_cbranch_execz .LBB0_3397
	s_waitcnt lgkmcnt(0)
	v_lshl_or_b32 v0, v6, 16, v0
	global_store_dword v[2:3], v0, off offset:96

; __device__ __forceinline__ int crow(int r, int hi) { return (r & 3) + 8 * (r >> 2) + 4 * hi; }
; template <int MODE>
; __device__ __forceinline__ void attn_block(const AttnArgs& a, const BlockRef& cur, const BlockRef& nxt, char* lds, Seam<MODE>& S, const int tid) {
;     ...
;     if (a.o8 != 0.f) {
;         unsigned char* Ob = (unsigned char*)a.O + (size_t)(orow_ + wid * QBLK) * ldo + hcol_; const float os = a.o8;
; #pragma unroll
;         for (int r = 0; r < 16; ++r) { const int orow = crow(r, hi);
; #pragma unroll
;             for (int d0 = 0; d0 < 4; ++d0) { const float v = __builtin_amdgcn_fmed3f(o[d0][r] * rli[r] * os, -448.f, 448.f);
;                 const float vn = __shfl_xor(v, 1);
;                 const int pk = __builtin_amdgcn_cvt_pk_fp8_f32(v, vn, 0, false) & 0xffff; const int pk2 = __shfl_xor(pk, 2);
;                 if ((r32 & 3) == 0) *(unsigned*)(Ob + (size_t)orow * ldo + d0 * 32 + r32) = (unsigned)pk | ((unsigned)pk2 << 16); } }
.LBB0_3403:
	s_or_b64 exec, exec, s[6:7]
	v_mul_f32_e32 v0, v30, v0
	v_mul_f32_e32 v0, 0x41800000, v0
	v_med3_f32 v0, v0, s72, v224
	s_nop 1
	v_mov_b32_dpp v4, v0 quad_perm:[1,0,3,2] row_mask:0xf bank_mask:0xf
	s_waitcnt lgkmcnt(0)
	v_mov_b32_e32 v6, v1
	s_waitcnt lgkmcnt(0)
	v_cvt_pk_fp8_f32 v6, v0, v4
	v_and_b32_e32 v0, 0xffff, v6
	s_nop 1
	v_mov_b32_dpp v4, v0 quad_perm:[2,3,0,1] row_mask:0xf bank_mask:0xf
	s_and_saveexec_b64 s[6:7], vcc
	s_cbranch_execz .LBB0_3405
	s_waitcnt lgkmcnt(0)
	v_lshl_or_b32 v0, v4, 16, v0
	global_store_dword v[2:3], v0, off offset:96

; __device__ __forceinline__ int crow(int r, int hi) { return (r & 3) + 8 * (r >> 2) + 4 * hi; }
; template <int MODE>
; __device__ __forceinline__ void attn_block(const AttnArgs& a, const BlockRef& cur, const BlockRef& nxt, char* lds, Seam<MODE>& S, const int tid) {
;     ...
;     if (a.o8 != 0.f) {
;         unsigned char* Ob = (unsigned char*)a.O + (size_t)(orow_ + wid * QBLK) * ldo + hcol_; const float os = a.o8;
; #pragma unroll
;         for (int r = 0; r < 16; ++r) { const int orow = crow(r, hi);
; #pragma unroll
;             for (int d0 = 0; d0 < 4; ++d0) { const float v = __builtin_amdgcn_fmed3f(o[d0][r] * rli[r] * os, -448.f, 448.f);
;                 const float vn = __shfl_xor(v, 1);
;                 const int pk = __builtin_amdgcn_cvt_pk_fp8_f32(v, vn, 0, false) & 0xffff; const int pk2 = __shfl_xor(pk, 2);
;                 if ((r32 & 3) == 0) *(unsigned*)(Ob + (size_t)orow * ldo + d0 * 32 + r32) = (unsigned)pk | ((unsigned)pk2 << 16); } }
.LBB0_3411:
	s_or_b64 exec, exec, s[6:7]
	v_mul_f32_e32 v0, v31, v0
	v_mul_f32_e32 v0, 0x41800000, v0
	v_med3_f32 v0, v0, s72, v224
	s_nop 1
	v_mov_b32_dpp v4, v0 quad_perm:[1,0,3,2] row_mask:0xf bank_mask:0xf
	s_waitcnt lgkmcnt(0)
	v_mov_b32_e32 v5, v1
	s_waitcnt lgkmcnt(0)
	v_cvt_pk_fp8_f32 v5, v0, v4
	v_and_b32_e32 v0, 0xffff, v5
	s_nop 1
	v_mov_b32_dpp v4, v0 quad_perm:[2,3,0,1] row_mask:0xf bank_mask:0xf
	s_and_saveexec_b64 s[6:7], vcc
	s_cbranch_execz .LBB0_3413
	s_waitcnt lgkmcnt(0)
	v_lshl_or_b32 v0, v4, 16, v0
	global_store_dword v[2:3], v0, off offset:96

; __device__ __forceinline__ int crow(int r, int hi) { return (r & 3) + 8 * (r >> 2) + 4 * hi; }
; template <int MODE>
; __device__ __forceinline__ void attn_block(const AttnArgs& a, const BlockRef& cur, const BlockRef& nxt, char* lds, Seam<MODE>& S, const int tid) {
;     ...
;     if (a.o8 != 0.f) {
;         unsigned char* Ob = (unsigned char*)a.O + (size_t)(orow_ + wid * QBLK) * ldo + hcol_; const float os = a.o8;
; #pragma unroll
;         for (int r = 0; r < 16; ++r) { const int orow = crow(r, hi);
; #pragma unroll
;             for (int d0 = 0; d0 < 4; ++d0) { const float v = __builtin_amdgcn_fmed3f(o[d0][r] * rli[r] * os, -448.f, 448.f);
;                 const float vn = __shfl_xor(v, 1);
;                 const int pk = __builtin_amdgcn_cvt_pk_fp8_f32(v, vn, 0, false) & 0xffff; const int pk2 = __shfl_xor(pk, 2);
;                 if ((r32 & 3) == 0) *(unsigned*)(Ob + (size_t)orow * ldo + d0 * 32 + r32) = (unsigned)pk | ((unsigned)pk2 << 16); } }
.LBB0_3491:
	s_or_b64 exec, exec, s[4:5]
	v_mul_f32_e32 v0, v48, v102
	v_mul_f32_e32 v0, 0x41800000, v0
	v_med3_f32 v0, v0, s65, v221
	s_nop 1
	v_mov_b32_dpp v48, v0 quad_perm:[1,0,3,2] row_mask:0xf bank_mask:0xf
	s_waitcnt lgkmcnt(0)
	v_mov_b32_e32 v64, v1
	s_waitcnt lgkmcnt(0)
	v_cvt_pk_fp8_f32 v64, v0, v48
	v_and_b32_e32 v0, 0xffff, v64
	s_nop 1
	v_mov_b32_dpp v48, v0 quad_perm:[2,3,0,1] row_mask:0xf bank_mask:0xf
	s_and_saveexec_b64 s[4:5], vcc
	s_cbranch_execz .LBB0_3493
	s_waitcnt lgkmcnt(0)
	v_lshl_or_b32 v0, v48, 16, v0
	global_store_dword v[100:101], v0, off offset:64
.LBB0_3493:
	s_or_b64 exec, exec, s[4:5]
	v_mul_f32_e32 v0, v32, v102
	v_mul_f32_e32 v0, 0x41800000, v0
	v_med3_f32 v0, v0, s65, v221
	s_nop 1
	v_mov_b32_dpp v32, v0 quad_perm:[1,0,3,2] row_mask:0xf bank_mask:0xf
	s_waitcnt lgkmcnt(0)
	v_mov_b32_e32 v48, v1
	s_waitcnt lgkmcnt(0)
	v_cvt_pk_fp8_f32 v48, v0, v32
	v_and_b32_e32 v0, 0xffff, v48
	s_nop 1
	v_mov_b32_dpp v32, v0 quad_perm:[2,3,0,1] row_mask:0xf bank_mask:0xf
	s_and_saveexec_b64 s[4:5], vcc
	s_cbranch_execz .LBB0_3495
	s_waitcnt lgkmcnt(0)
	v_lshl_or_b32 v0, v32, 16, v0
	global_store_dword v[100:101], v0, off offset:96

; __device__ __forceinline__ int crow(int r, int hi) { return (r & 3) + 8 * (r >> 2) + 4 * hi; }
; template <int MODE>
; __device__ __forceinline__ void attn_block(const AttnArgs& a, const BlockRef& cur, const BlockRef& nxt, char* lds, Seam<MODE>& S, const int tid) {
;     ...
;     if (a.o8 != 0.f) {
;         unsigned char* Ob = (unsigned char*)a.O + (size_t)(orow_ + wid * QBLK) * ldo + hcol_; const float os = a.o8;
; #pragma unroll
;         for (int r = 0; r < 16; ++r) { const int orow = crow(r, hi);
; #pragma unroll
;             for (int d0 = 0; d0 < 4; ++d0) { const float v = __builtin_amdgcn_fmed3f(o[d0][r] * rli[r] * os, -448.f, 448.f);
;                 const float vn = __shfl_xor(v, 1);
;                 const int pk = __builtin_amdgcn_cvt_pk_fp8_f32(v, vn, 0, false) & 0xffff; const int pk2 = __shfl_xor(pk, 2);
;                 if ((r32 & 3) == 0) *(unsigned*)(Ob + (size_t)orow * ldo + d0 * 32 + r32) = (unsigned)pk | ((unsigned)pk2 << 16); } }
.LBB0_3525:
	s_or_b64 exec, exec, s[4:5]
	v_mul_f32_e32 v0, v36, v0
	v_mul_f32_e32 v0, 0x41800000, v0
	v_med3_f32 v0, v0, s65, v221
	s_nop 1
	v_mov_b32_dpp v26, v0 quad_perm:[1,0,3,2] row_mask:0xf bank_mask:0xf
	s_waitcnt lgkmcnt(0)
	v_mov_b32_e32 v34, v1
	s_waitcnt lgkmcnt(0)
	v_cvt_pk_fp8_f32 v34, v0, v26
	v_and_b32_e32 v0, 0xffff, v34
	s_nop 1
	v_mov_b32_dpp v26, v0 quad_perm:[2,3,0,1] row_mask:0xf bank_mask:0xf
	s_and_saveexec_b64 s[4:5], vcc
	s_cbranch_execz .LBB0_3527
	s_waitcnt lgkmcnt(0)
	v_lshl_or_b32 v0, v26, 16, v0
	global_store_dword v[32:33], v0, off offset:96

; __device__ __forceinline__ int crow(int r, int hi) { return (r & 3) + 8 * (r >> 2) + 4 * hi; }
; template <int MODE>
; __device__ __forceinline__ void attn_block(const AttnArgs& a, const BlockRef& cur, const BlockRef& nxt, char* lds, Seam<MODE>& S, const int tid) {
;     ...
;     if (a.o8 != 0.f) {
;         unsigned char* Ob = (unsigned char*)a.O + (size_t)(orow_ + wid * QBLK) * ldo + hcol_; const float os = a.o8;
; #pragma unroll
;         for (int r = 0; r < 16; ++r) { const int orow = crow(r, hi);
; #pragma unroll
;             for (int d0 = 0; d0 < 4; ++d0) { const float v = __builtin_amdgcn_fmed3f(o[d0][r] * rli[r] * os, -448.f, 448.f);
;                 const float vn = __shfl_xor(v, 1);
;                 const int pk = __builtin_amdgcn_cvt_pk_fp8_f32(v, vn, 0, false) & 0xffff; const int pk2 = __shfl_xor(pk, 2);
;                 if ((r32 & 3) == 0) *(unsigned*)(Ob + (size_t)orow * ldo + d0 * 32 + r32) = (unsigned)pk | ((unsigned)pk2 << 16); } }
.LBB0_3533:
	s_or_b64 exec, exec, s[4:5]
	v_mul_f32_e32 v0, v37, v0
	v_mul_f32_e32 v0, 0x41800000, v0
	v_med3_f32 v0, v0, s65, v221
	s_nop 1
	v_mov_b32_dpp v32, v0 quad_perm:[1,0,3,2] row_mask:0xf bank_mask:0xf
	s_waitcnt lgkmcnt(0)
	v_mov_b32_e32 v33, v1
	s_waitcnt lgkmcnt(0)
	v_cvt_pk_fp8_f32 v33, v0, v32
	v_and_b32_e32 v0, 0xffff, v33
	s_nop 1
	v_mov_b32_dpp v32, v0 quad_perm:[2,3,0,1] row_mask:0xf bank_mask:0xf
	s_and_saveexec_b64 s[4:5], vcc
	s_cbranch_execz .LBB0_3535
	s_waitcnt lgkmcnt(0)
	v_lshl_or_b32 v0, v32, 16, v0
	global_store_dword v[26:27], v0, off offset:96

; __device__ __forceinline__ int crow(int r, int hi) { return (r & 3) + 8 * (r >> 2) + 4 * hi; }
; template <int MODE>
; __device__ __forceinline__ void attn_block(const AttnArgs& a, const BlockRef& cur, const BlockRef& nxt, char* lds, Seam<MODE>& S, const int tid) {
;     ...
;     if (a.o8 != 0.f) {
;         unsigned char* Ob = (unsigned char*)a.O + (size_t)(orow_ + wid * QBLK) * ldo + hcol_; const float os = a.o8;
; #pragma unroll
;         for (int r = 0; r < 16; ++r) { const int orow = crow(r, hi);
; #pragma unroll
;             for (int d0 = 0; d0 < 4; ++d0) { const float v = __builtin_amdgcn_fmed3f(o[d0][r] * rli[r] * os, -448.f, 448.f);
;                 const float vn = __shfl_xor(v, 1);
;                 const int pk = __builtin_amdgcn_cvt_pk_fp8_f32(v, vn, 0, false) & 0xffff; const int pk2 = __shfl_xor(pk, 2);
;                 if ((r32 & 3) == 0) *(unsigned*)(Ob + (size_t)orow * ldo + d0 * 32 + r32) = (unsigned)pk | ((unsigned)pk2 << 16); } }
.LBB0_3541:
	s_or_b64 exec, exec, s[4:5]
	v_mul_f32_e32 v0, v38, v0
	v_mul_f32_e32 v0, 0x41800000, v0
	v_med3_f32 v0, v0, s65, v221
	s_nop 1
	v_mov_b32_dpp v28, v0 quad_perm:[1,0,3,2] row_mask:0xf bank_mask:0xf
	s_waitcnt lgkmcnt(0)
	v_mov_b32_e32 v32, v1
	s_waitcnt lgkmcnt(0)
	v_cvt_pk_fp8_f32 v32, v0, v28
	v_and_b32_e32 v0, 0xffff, v32
	s_nop 1
	v_mov_b32_dpp v28, v0 quad_perm:[2,3,0,1] row_mask:0xf bank_mask:0xf
	s_and_saveexec_b64 s[4:5], vcc
	s_cbranch_execz .LBB0_3543
	s_waitcnt lgkmcnt(0)
	v_lshl_or_b32 v0, v28, 16, v0
	global_store_dword v[26:27], v0, off offset:96

; __device__ __forceinline__ int crow(int r, int hi) { return (r & 3) + 8 * (r >> 2) + 4 * hi; }
; template <int MODE>
; __device__ __forceinline__ void attn_block(const AttnArgs& a, const BlockRef& cur, const BlockRef& nxt, char* lds, Seam<MODE>& S, const int tid) {
;     ...
;     if (a.o8 != 0.f) {
;         unsigned char* Ob = (unsigned char*)a.O + (size_t)(orow_ + wid * QBLK) * ldo + hcol_; const float os = a.o8;
; #pragma unroll
;         for (int r = 0; r < 16; ++r) { const int orow = crow(r, hi);
; #pragma unroll
;             for (int d0 = 0; d0 < 4; ++d0) { const float v = __builtin_amdgcn_fmed3f(o[d0][r] * rli[r] * os, -448.f, 448.f);
;                 const float vn = __shfl_xor(v, 1);
;                 const int pk = __builtin_amdgcn_cvt_pk_fp8_f32(v, vn, 0, false) & 0xffff; const int pk2 = __shfl_xor(pk, 2);
;                 if ((r32 & 3) == 0) *(unsigned*)(Ob + (size_t)orow * ldo + d0 * 32 + r32) = (unsigned)pk | ((unsigned)pk2 << 16); } }
.LBB0_3549:
	s_or_b64 exec, exec, s[4:5]
	v_mul_f32_e32 v0, v39, v0
	v_mul_f32_e32 v0, 0x41800000, v0
	v_med3_f32 v0, v0, s65, v221
	s_nop 1
	v_mov_b32_dpp v28, v0 quad_perm:[1,0,3,2] row_mask:0xf bank_mask:0xf
	s_waitcnt lgkmcnt(0)
	v_mov_b32_e32 v29, v1
	s_waitcnt lgkmcnt(0)
	v_cvt_pk_fp8_f32 v29, v0, v28
	v_and_b32_e32 v0, 0xffff, v29
	s_nop 1
	v_mov_b32_dpp v28, v0 quad_perm:[2,3,0,1] row_mask:0xf bank_mask:0xf
	s_and_saveexec_b64 s[4:5], vcc
	s_cbranch_execz .LBB0_3551
	s_waitcnt lgkmcnt(0)
	v_lshl_or_b32 v0, v28, 16, v0
	global_store_dword v[26:27], v0, off offset:96

; __device__ __forceinline__ int crow(int r, int hi) { return (r & 3) + 8 * (r >> 2) + 4 * hi; }
; template <int MODE>
; __device__ __forceinline__ void attn_block(const AttnArgs& a, const BlockRef& cur, const BlockRef& nxt, char* lds, Seam<MODE>& S, const int tid) {
;     ...
;     if (a.o8 != 0.f) {
;         unsigned char* Ob = (unsigned char*)a.O + (size_t)(orow_ + wid * QBLK) * ldo + hcol_; const float os = a.o8;
; #pragma unroll
;         for (int r = 0; r < 16; ++r) { const int orow = crow(r, hi);
; #pragma unroll
;             for (int d0 = 0; d0 < 4; ++d0) { const float v = __builtin_amdgcn_fmed3f(o[d0][r] * rli[r] * os, -448.f, 448.f);
;                 const float vn = __shfl_xor(v, 1);
;                 const int pk = __builtin_amdgcn_cvt_pk_fp8_f32(v, vn, 0, false) & 0xffff; const int pk2 = __shfl_xor(pk, 2);
;                 if ((r32 & 3) == 0) *(unsigned*)(Ob + (size_t)orow * ldo + d0 * 32 + r32) = (unsigned)pk | ((unsigned)pk2 << 16); } }
.LBB0_3557:
	s_or_b64 exec, exec, s[4:5]
	v_mul_f32_e32 v0, v40, v0
	v_mul_f32_e32 v0, 0x41800000, v0
	v_med3_f32 v0, v0, s65, v221
	s_nop 1
	v_mov_b32_dpp v22, v0 quad_perm:[1,0,3,2] row_mask:0xf bank_mask:0xf
	s_waitcnt lgkmcnt(0)
	v_mov_b32_e32 v28, v1
	s_waitcnt lgkmcnt(0)
	v_cvt_pk_fp8_f32 v28, v0, v22
	v_and_b32_e32 v0, 0xffff, v28
	s_nop 1
	v_mov_b32_dpp v22, v0 quad_perm:[2,3,0,1] row_mask:0xf bank_mask:0xf
	s_and_saveexec_b64 s[4:5], vcc
	s_cbranch_execz .LBB0_3559
	s_waitcnt lgkmcnt(0)
	v_lshl_or_b32 v0, v22, 16, v0
	global_store_dword v[26:27], v0, off offset:96

; __device__ __forceinline__ int crow(int r, int hi) { return (r & 3) + 8 * (r >> 2) + 4 * hi; }
; template <int MODE>
; __device__ __forceinline__ void attn_block(const AttnArgs& a, const BlockRef& cur, const BlockRef& nxt, char* lds, Seam<MODE>& S, const int tid) {
;     ...
;     if (a.o8 != 0.f) {
;         unsigned char* Ob = (unsigned char*)a.O + (size_t)(orow_ + wid * QBLK) * ldo + hcol_; const float os = a.o8;
; #pragma unroll
;         for (int r = 0; r < 16; ++r) { const int orow = crow(r, hi);
; #pragma unroll
;             for (int d0 = 0; d0 < 4; ++d0) { const float v = __builtin_amdgcn_fmed3f(o[d0][r] * rli[r] * os, -448.f, 448.f);
;                 const float vn = __shfl_xor(v, 1);
;                 const int pk = __builtin_amdgcn_cvt_pk_fp8_f32(v, vn, 0, false) & 0xffff; const int pk2 = __shfl_xor(pk, 2);
;                 if ((r32 & 3) == 0) *(unsigned*)(Ob + (size_t)orow * ldo + d0 * 32 + r32) = (unsigned)pk | ((unsigned)pk2 << 16); } }
.LBB0_3565:
	s_or_b64 exec, exec, s[4:5]
	v_mul_f32_e32 v0, v41, v0
	v_mul_f32_e32 v0, 0x41800000, v0
	v_med3_f32 v0, v0, s65, v221
	s_nop 1
	v_mov_b32_dpp v26, v0 quad_perm:[1,0,3,2] row_mask:0xf bank_mask:0xf
	s_waitcnt lgkmcnt(0)
	v_mov_b32_e32 v27, v1
	s_waitcnt lgkmcnt(0)
	v_cvt_pk_fp8_f32 v27, v0, v26
	v_and_b32_e32 v0, 0xffff, v27
	s_nop 1
	v_mov_b32_dpp v26, v0 quad_perm:[2,3,0,1] row_mask:0xf bank_mask:0xf
	s_and_saveexec_b64 s[4:5], vcc
	s_cbranch_execz .LBB0_3567
	s_waitcnt lgkmcnt(0)
	v_lshl_or_b32 v0, v26, 16, v0
	global_store_dword v[22:23], v0, off offset:96

; __device__ __forceinline__ int crow(int r, int hi) { return (r & 3) + 8 * (r >> 2) + 4 * hi; }
; template <int MODE>
; __device__ __forceinline__ void attn_block(const AttnArgs& a, const BlockRef& cur, const BlockRef& nxt, char* lds, Seam<MODE>& S, const int tid) {
;     ...
;     if (a.o8 != 0.f) {
;         unsigned char* Ob = (unsigned char*)a.O + (size_t)(orow_ + wid * QBLK) * ldo + hcol_; const float os = a.o8;
; #pragma unroll
;         for (int r = 0; r < 16; ++r) { const int orow = crow(r, hi);
; #pragma unroll
;             for (int d0 = 0; d0 < 4; ++d0) { const float v = __builtin_amdgcn_fmed3f(o[d0][r] * rli[r] * os, -448.f, 448.f);
;                 const float vn = __shfl_xor(v, 1);
;                 const int pk = __builtin_amdgcn_cvt_pk_fp8_f32(v, vn, 0, false) & 0xffff; const int pk2 = __shfl_xor(pk, 2);
;                 if ((r32 & 3) == 0) *(unsigned*)(Ob + (size_t)orow * ldo + d0 * 32 + r32) = (unsigned)pk | ((unsigned)pk2 << 16); } }
.LBB0_3573:
	s_or_b64 exec, exec, s[4:5]
	v_mul_f32_e32 v0, v42, v0
	v_mul_f32_e32 v0, 0x41800000, v0
	v_med3_f32 v0, v0, s65, v221
	s_nop 1
	v_mov_b32_dpp v24, v0 quad_perm:[1,0,3,2] row_mask:0xf bank_mask:0xf
	s_waitcnt lgkmcnt(0)
	v_mov_b32_e32 v26, v1
	s_waitcnt lgkmcnt(0)
	v_cvt_pk_fp8_f32 v26, v0, v24
	v_and_b32_e32 v0, 0xffff, v26
	s_nop 1
	v_mov_b32_dpp v24, v0 quad_perm:[2,3,0,1] row_mask:0xf bank_mask:0xf
	s_and_saveexec_b64 s[4:5], vcc
	s_cbranch_execz .LBB0_3575
	s_waitcnt lgkmcnt(0)
	v_lshl_or_b32 v0, v24, 16, v0
	global_store_dword v[22:23], v0, off offset:96

; __device__ __forceinline__ int crow(int r, int hi) { return (r & 3) + 8 * (r >> 2) + 4 * hi; }
; template <int MODE>
; __device__ __forceinline__ void attn_block(const AttnArgs& a, const BlockRef& cur, const BlockRef& nxt, char* lds, Seam<MODE>& S, const int tid) {
;     ...
;     if (a.o8 != 0.f) {
;         unsigned char* Ob = (unsigned char*)a.O + (size_t)(orow_ + wid * QBLK) * ldo + hcol_; const float os = a.o8;
; #pragma unroll
;         for (int r = 0; r < 16; ++r) { const int orow = crow(r, hi);
; #pragma unroll
;             for (int d0 = 0; d0 < 4; ++d0) { const float v = __builtin_amdgcn_fmed3f(o[d0][r] * rli[r] * os, -448.f, 448.f);
;                 const float vn = __shfl_xor(v, 1);
;                 const int pk = __builtin_amdgcn_cvt_pk_fp8_f32(v, vn, 0, false) & 0xffff; const int pk2 = __shfl_xor(pk, 2);
;                 if ((r32 & 3) == 0) *(unsigned*)(Ob + (size_t)orow * ldo + d0 * 32 + r32) = (unsigned)pk | ((unsigned)pk2 << 16); } }
.LBB0_3581:
	s_or_b64 exec, exec, s[4:5]
	v_mul_f32_e32 v0, v43, v0
	v_mul_f32_e32 v0, 0x41800000, v0
	v_med3_f32 v0, v0, s65, v221
	s_nop 1
	v_mov_b32_dpp v24, v0 quad_perm:[1,0,3,2] row_mask:0xf bank_mask:0xf
	s_waitcnt lgkmcnt(0)
	v_mov_b32_e32 v25, v1
	s_waitcnt lgkmcnt(0)
	v_cvt_pk_fp8_f32 v25, v0, v24
	v_and_b32_e32 v0, 0xffff, v25
	s_nop 1
	v_mov_b32_dpp v24, v0 quad_perm:[2,3,0,1] row_mask:0xf bank_mask:0xf
	s_and_saveexec_b64 s[4:5], vcc
	s_cbranch_execz .LBB0_3583
	s_waitcnt lgkmcnt(0)
	v_lshl_or_b32 v0, v24, 16, v0
	global_store_dword v[22:23], v0, off offset:96

; __device__ __forceinline__ int crow(int r, int hi) { return (r & 3) + 8 * (r >> 2) + 4 * hi; }
; template <int MODE>
; __device__ __forceinline__ void attn_block(const AttnArgs& a, const BlockRef& cur, const BlockRef& nxt, char* lds, Seam<MODE>& S, const int tid) {
;     ...
;     if (a.o8 != 0.f) {
;         unsigned char* Ob = (unsigned char*)a.O + (size_t)(orow_ + wid * QBLK) * ldo + hcol_; const float os = a.o8;
; #pragma unroll
;         for (int r = 0; r < 16; ++r) { const int orow = crow(r, hi);
; #pragma unroll
;             for (int d0 = 0; d0 < 4; ++d0) { const float v = __builtin_amdgcn_fmed3f(o[d0][r] * rli[r] * os, -448.f, 448.f);
;                 const float vn = __shfl_xor(v, 1);
;                 const int pk = __builtin_amdgcn_cvt_pk_fp8_f32(v, vn, 0, false) & 0xffff; const int pk2 = __shfl_xor(pk, 2);
;                 if ((r32 & 3) == 0) *(unsigned*)(Ob + (size_t)orow * ldo + d0 * 32 + r32) = (unsigned)pk | ((unsigned)pk2 << 16); } }
.LBB0_3589:
	s_or_b64 exec, exec, s[4:5]
	v_mul_f32_e32 v0, v44, v0
	v_mul_f32_e32 v0, 0x41800000, v0
	v_med3_f32 v0, v0, s65, v221
	s_nop 1
	v_mov_b32_dpp v18, v0 quad_perm:[1,0,3,2] row_mask:0xf bank_mask:0xf
	s_waitcnt lgkmcnt(0)
	v_mov_b32_e32 v24, v1
	s_waitcnt lgkmcnt(0)
	v_cvt_pk_fp8_f32 v24, v0, v18
	v_and_b32_e32 v0, 0xffff, v24
	s_nop 1
	v_mov_b32_dpp v18, v0 quad_perm:[2,3,0,1] row_mask:0xf bank_mask:0xf
	s_and_saveexec_b64 s[4:5], vcc
	s_cbranch_execz .LBB0_3591
	s_waitcnt lgkmcnt(0)
	v_lshl_or_b32 v0, v18, 16, v0
	global_store_dword v[22:23], v0, off offset:96

; __device__ __forceinline__ int crow(int r, int hi) { return (r & 3) + 8 * (r >> 2) + 4 * hi; }
; template <int MODE>
; __device__ __forceinline__ void attn_block(const AttnArgs& a, const BlockRef& cur, const BlockRef& nxt, char* lds, Seam<MODE>& S, const int tid) {
;     ...
;     if (a.o8 != 0.f) {
;         unsigned char* Ob = (unsigned char*)a.O + (size_t)(orow_ + wid * QBLK) * ldo + hcol_; const float os = a.o8;
; #pragma unroll
;         for (int r = 0; r < 16; ++r) { const int orow = crow(r, hi);
; #pragma unroll
;             for (int d0 = 0; d0 < 4; ++d0) { const float v = __builtin_amdgcn_fmed3f(o[d0][r] * rli[r] * os, -448.f, 448.f);
;                 const float vn = __shfl_xor(v, 1);
;                 const int pk = __builtin_amdgcn_cvt_pk_fp8_f32(v, vn, 0, false) & 0xffff; const int pk2 = __shfl_xor(pk, 2);
;                 if ((r32 & 3) == 0) *(unsigned*)(Ob + (size_t)orow * ldo + d0 * 32 + r32) = (unsigned)pk | ((unsigned)pk2 << 16); } }
.LBB0_3597:
	s_or_b64 exec, exec, s[4:5]
	v_mul_f32_e32 v0, v45, v0
	v_mul_f32_e32 v0, 0x41800000, v0
	v_med3_f32 v0, v0, s65, v221
	s_nop 1
	v_mov_b32_dpp v22, v0 quad_perm:[1,0,3,2] row_mask:0xf bank_mask:0xf
	s_waitcnt lgkmcnt(0)
	v_mov_b32_e32 v23, v1
	s_waitcnt lgkmcnt(0)
	v_cvt_pk_fp8_f32 v23, v0, v22
	v_and_b32_e32 v0, 0xffff, v23
	s_nop 1
	v_mov_b32_dpp v22, v0 quad_perm:[2,3,0,1] row_mask:0xf bank_mask:0xf
	s_and_saveexec_b64 s[4:5], vcc
	s_cbranch_execz .LBB0_3599
	s_waitcnt lgkmcnt(0)
	v_lshl_or_b32 v0, v22, 16, v0
	global_store_dword v[18:19], v0, off offset:96

; __device__ __forceinline__ int crow(int r, int hi) { return (r & 3) + 8 * (r >> 2) + 4 * hi; }
; template <int MODE>
; __device__ __forceinline__ void attn_block(const AttnArgs& a, const BlockRef& cur, const BlockRef& nxt, char* lds, Seam<MODE>& S, const int tid) {
;     ...
;     if (a.o8 != 0.f) {
;         unsigned char* Ob = (unsigned char*)a.O + (size_t)(orow_ + wid * QBLK) * ldo + hcol_; const float os = a.o8;
; #pragma unroll
;         for (int r = 0; r < 16; ++r) { const int orow = crow(r, hi);
; #pragma unroll
;             for (int d0 = 0; d0 < 4; ++d0) { const float v = __builtin_amdgcn_fmed3f(o[d0][r] * rli[r] * os, -448.f, 448.f);
;                 const float vn = __shfl_xor(v, 1);
;                 const int pk = __builtin_amdgcn_cvt_pk_fp8_f32(v, vn, 0, false) & 0xffff; const int pk2 = __shfl_xor(pk, 2);
;                 if ((r32 & 3) == 0) *(unsigned*)(Ob + (size_t)orow * ldo + d0 * 32 + r32) = (unsigned)pk | ((unsigned)pk2 << 16); } }
.LBB0_3605:
	s_or_b64 exec, exec, s[4:5]
	v_mul_f32_e32 v0, v46, v0
	v_mul_f32_e32 v0, 0x41800000, v0
	v_med3_f32 v0, v0, s65, v221
	s_nop 1
	v_mov_b32_dpp v20, v0 quad_perm:[1,0,3,2] row_mask:0xf bank_mask:0xf
	s_waitcnt lgkmcnt(0)
	v_mov_b32_e32 v22, v1
	s_waitcnt lgkmcnt(0)
	v_cvt_pk_fp8_f32 v22, v0, v20
	v_and_b32_e32 v0, 0xffff, v22
	s_nop 1
	v_mov_b32_dpp v20, v0 quad_perm:[2,3,0,1] row_mask:0xf bank_mask:0xf
	s_and_saveexec_b64 s[4:5], vcc
	s_cbranch_execz .LBB0_3607
	s_waitcnt lgkmcnt(0)
	v_lshl_or_b32 v0, v20, 16, v0
	global_store_dword v[18:19], v0, off offset:96

; __device__ __forceinline__ u32x4 pack8bf(const f32x4 a, const f32x4 b) { u32x4 w; w.x = cvt_pk_bf16(a[0], a[1]); w.y = cvt_pk_bf16(a[2], a[3]); w.z = cvt_pk_bf16(b[0], b[1]); w.w = cvt_pk_bf16(b[2], b[3]); return w; }
;     ...
;         if constexpr (QM == 2) { const float qs0_ = g.qs * E.qscale(cur), qs1_ = qs0_ * g.qs_b1; _Pragma("unroll") for (int a = 0; a < 2; ++a) _Pragma("unroll") for (int b = 0; b < 2; ++b) _Pragma("unroll") for (int m = 0; m < 4; ++m) _Pragma("unroll") for (int n = 0; n < 2; ++n) { const v4i t_ = __builtin_bit_cast(v4i, acc[a][b][m][n]); acc[a][b][m][n] = (f32x4){(float)t_[0], (float)t_[1], (float)t_[2], (float)t_[3]} * (b == 0 ? qs0_ : qs1_); } }
;     __device__ __forceinline__ void operator()(EPI_ARGS) const {
;         const int row0 = u.pm * BM + wr * 64 + fr, col0 = u.pn * HALF + wc * 32 + 8 * fq, n0 = u.pn * BM + wc * 32 + 8 * fq;
;         f32x4 cg[2], dg[2], cu[2], du[2];
;         if constexpr (FOLD) {
; #pragma unroll
;             for (int n = 0; n < 2; ++n) { cg[n] = *(const f32x4*)(C + n0 + 4 * n); dg[n] = *(const f32x4*)(D + n0 + 4 * n); cu[n] = *(const f32x4*)(C + n0 + HALF + 4 * n); du[n] = *(const f32x4*)(D + n0 + HALF + 4 * n);
;                 if constexpr (PRE) { float os_ = oscale; asm volatile("" : "+s"(os_)); cu[n] = cu[n] * os_; du[n] = du[n] * os_; } } }
; #pragma unroll
;         for (int ai = 0; ai < 2; ++ai)
; #pragma unroll
;             for (int m = 0; m < 4; ++m) { const int row = row0 + ai * HALF + m * 16; f32x4 r[2];
;                 float mu = 0.f, rs = 1.f; if constexpr (FOLD) ln_stats(st, row, mu, rs);
; #pragma unroll
;                 for (int n = 0; n < 2; ++n) { f32x4 g = acc[ai][0][m][n], up = acc[ai][1][m][n];
;                     if constexpr (!PRE) { g = g * ascale; up = up * ascale; }
;                     if constexpr (FOLD) { g = (g - cg[n] * mu) * rs + dg[n]; up = (up - cu[n] * mu) * rs + du[n]; }
;                     if constexpr (!PRE) up = up * oscale;
; #pragma unroll
;                     for (int j = 0; j < 4; ++j) { const float e = __builtin_amdgcn_exp2f(g[j] * -1.4426950408889634f); r[n][j] = g[j] * __builtin_amdgcn_rcpf(1.0f + e) * up[j]; } }
;                 if constexpr (F8OUT) *(u32x2*)((unsigned char*)O + (size_t)row * ldc + col0) = pack8fp8(r[0], r[1]);
;                 else *(u32x4*)((bf16_t*)O + (size_t)row * ldc + col0) = pack8bf(r[0], r[1]); }
.LBB0_3779:
	v_lshl_or_b32 v84, s5, 8, v168
	v_lshl_add_u32 v160, s4, 8, v166
	v_ashrrev_i32_e32 v85, 31, v84
	v_lshlrev_b64 v[84:85], 2, v[84:85]
	v_ashrrev_i32_e32 v161, 31, v160
	v_lshl_add_u64 v[88:89], s[8:9], 0, v[84:85]
	v_lshl_add_u64 v[182:183], s[10:11], 0, v[84:85]
	s_mov_b32 s4, 0x41800000
	s_mov_b32 s40, 0x41800000
	v_lshl_add_u64 v[186:187], v[160:161], 3, s[14:15]
	global_load_dwordx4 v[96:99], v[88:89], off
	global_load_dwordx4 v[162:165], v[88:89], off offset:512
	global_load_dwordx4 v[100:103], v[182:183], off
	global_load_dwordx4 v[174:177], v[182:183], off offset:512
	global_load_dwordx4 v[84:87], v[88:89], off offset:16
	global_load_dwordx4 v[178:181], v[88:89], off offset:528
	s_nop 0
	global_load_dwordx4 v[88:91], v[182:183], off offset:16
	s_nop 0
	global_load_dwordx4 v[182:185], v[182:183], off offset:528
	global_load_dwordx2 v[226:227], v[186:187], off offset:128
	global_load_dwordx2 v[228:229], v[186:187], off offset:256
	global_load_dwordx2 v[230:231], v[186:187], off offset:384
	global_load_dwordx2 v[232:233], v[186:187], off offset:1024
	global_load_dwordx2 v[234:235], v[186:187], off offset:1152
	global_load_dwordx2 v[236:237], v[186:187], off offset:1280
	global_load_dwordx2 v[238:239], v[186:187], off offset:1408
	global_load_dwordx2 v[186:187], v[186:187], off
	v_cvt_f32_i32_e32 v131, v131
	v_cvt_f32_i32_e32 v130, v130
	v_cvt_f32_i32_e32 v137, v137
	v_cvt_f32_i32_e32 v136, v136
	v_cvt_f32_i32_e32 v141, v141
	v_pk_mul_f32 v[194:195], v[130:131], s[24:25] op_sel_hi:[1,0]
	v_cvt_f32_i32_e32 v140, v140
	v_cvt_f32_i32_e32 v133, v133
	v_cvt_f32_i32_e32 v132, v132
	v_pk_mul_f32 v[192:193], v[136:137], s[20:21] op_sel_hi:[1,0]
	v_cvt_f32_i32_e32 v139, v139
	v_cvt_f32_i32_e32 v138, v138
	v_cvt_f32_i32_e32 v135, v135
	v_cvt_f32_i32_e32 v134, v134
	v_pk_mul_f32 v[140:141], v[140:141], s[20:21] op_sel_hi:[1,0]
	v_pk_mul_f32 v[132:133], v[132:133], s[24:25] op_sel_hi:[1,0]
	v_pk_mul_f32 v[190:191], v[138:139], s[20:21] op_sel_hi:[1,0]
	v_pk_mul_f32 v[134:135], v[134:135], s[24:25] op_sel_hi:[1,0]
	v_mov_b32_e32 v138, v132
	v_mov_b32_e32 v139, v140
	v_mov_b32_e32 v140, v133
	v_cvt_f32_i32_e32 v188, v128
	v_lshl_or_b32 v128, s5, 7, v168
	v_mov_b32_e32 v196, v134
	v_cvt_f32_i32_e32 v143, v143
	v_cvt_f32_i32_e32 v142, v142
	v_cvt_f32_i32_e32 v189, v129
	v_ashrrev_i32_e32 v129, 31, v128
	v_cvt_f32_i32_e32 v125, v125
	v_pk_mul_f32 v[142:143], v[142:143], s[20:21] op_sel_hi:[1,0]
	v_pk_mul_f32 v[188:189], v[188:189], s[24:25] op_sel_hi:[1,0]
	v_mov_b32_e32 v197, v142
	v_mov_b32_e32 v142, v135
	v_cvt_f32_i32_e32 v124, v124
	v_cvt_f32_i32_e32 v117, v117
	v_cvt_f32_i32_e32 v116, v116
	v_cvt_f32_i32_e32 v127, v127
	v_pk_mul_f32 v[124:125], v[124:125], s[20:21] op_sel_hi:[1,0]
	v_cvt_f32_i32_e32 v126, v126
	v_pk_mul_f32 v[116:117], v[116:117], s[24:25] op_sel_hi:[1,0]
	v_cvt_f32_i32_e32 v119, v119
	v_cvt_f32_i32_e32 v118, v118
	v_pk_mul_f32 v[126:127], v[126:127], s[20:21] op_sel_hi:[1,0]
	v_cvt_f32_i32_e32 v121, v121
	v_cvt_f32_i32_e32 v120, v120
	v_pk_mul_f32 v[118:119], v[118:119], s[24:25] op_sel_hi:[1,0]
	v_cvt_f32_i32_e32 v113, v113
	v_cvt_f32_i32_e32 v112, v112
	v_pk_mul_f32 v[120:121], v[120:121], s[20:21] op_sel_hi:[1,0]
	v_cvt_f32_i32_e32 v123, v123
	v_cvt_f32_i32_e32 v122, v122
	v_pk_mul_f32 v[112:113], v[112:113], s[24:25] op_sel_hi:[1,0]
	v_cvt_f32_i32_e32 v115, v115
	v_cvt_f32_i32_e32 v114, v114
	v_pk_mul_f32 v[122:123], v[122:123], s[20:21] op_sel_hi:[1,0]
	v_cvt_f32_i32_e32 v109, v109
	v_cvt_f32_i32_e32 v108, v108
	v_pk_mul_f32 v[114:115], v[114:115], s[24:25] op_sel_hi:[1,0]
	v_cvt_f32_i32_e32 v93, v93
	v_cvt_f32_i32_e32 v92, v92
	v_pk_mul_f32 v[108:109], v[108:109], s[20:21] op_sel_hi:[1,0]
	v_cvt_f32_i32_e32 v111, v111
	v_cvt_f32_i32_e32 v110, v110
	v_pk_mul_f32 v[92:93], v[92:93], s[24:25] op_sel_hi:[1,0]
	v_cvt_f32_i32_e32 v95, v95
	v_cvt_f32_i32_e32 v94, v94
	v_pk_mul_f32 v[110:111], v[110:111], s[20:21] op_sel_hi:[1,0]
	v_cvt_f32_i32_e32 v105, v105
	v_cvt_f32_i32_e32 v104, v104
	v_pk_mul_f32 v[94:95], v[94:95], s[24:25] op_sel_hi:[1,0]
	v_cvt_f32_i32_e32 v81, v81
	v_cvt_f32_i32_e32 v80, v80
	s_waitcnt vmcnt(0)
	v_mov_b32_e32 v137, v96
	v_pk_mul_f32 v[162:163], v[162:163], s[4:5] op_sel_hi:[1,0]
	v_mov_b32_e32 v131, v102
	v_mov_b32_e32 v136, v162
	v_pk_mul_f32 v[164:165], v[164:165], s[4:5] op_sel_hi:[1,0]
	v_mov_b32_e32 v96, v163
	v_pk_mul_f32 v[174:175], v[174:175], s[4:5] op_sel_hi:[1,0]
	v_pk_mul_f32 v[186:187], v[186:187], s[26:27] op_sel_hi:[1,0]
	v_mov_b32_e32 v133, v98
	v_fma_f32 v102, -v186, v186, v187
	v_add_f32_e32 v102, 0x3727c5ac, v102
	v_rsq_f32_e32 v242, v102
	v_mov_b32_e32 v132, v164
	v_mov_b32_e32 v98, v165
	v_pk_mul_f32 v[176:177], v[176:177], s[4:5] op_sel_hi:[1,0]
	v_mov_b32_e32 v134, v174
	v_mov_b32_e32 v135, v100
	v_mov_b32_e32 v100, v175
	v_mov_b32_e32 v130, v176
	v_pk_fma_f32 v[138:139], v[136:137], v[186:187], v[138:139] op_sel_hi:[1,0,1] neg_lo:[1,0,0] neg_hi:[1,0,0]
	v_pk_fma_f32 v[140:141], v[96:97], v[186:187], v[140:141] op_sel_hi:[1,0,1] neg_lo:[1,0,0] neg_hi:[1,0,0]
	v_mov_b32_e32 v102, v177
	v_pk_fma_f32 v[142:143], v[98:99], v[186:187], v[142:143] op_sel_hi:[1,0,1] neg_lo:[1,0,0] neg_hi:[1,0,0]
	v_pk_fma_f32 v[162:163], v[132:133], v[186:187], v[196:197] op_sel_hi:[1,0,1] neg_lo:[1,0,0] neg_hi:[1,0,0]
	v_mov_b32_e32 v164, v242
	v_pk_fma_f32 v[138:139], v[138:139], v[164:165], v[134:135] op_sel_hi:[1,0,1]
	v_pk_fma_f32 v[140:141], v[140:141], v[164:165], v[100:101] op_sel_hi:[1,0,1]
	v_mul_f32_e32 v161, 0xbfb8aa3b, v139
	v_mul_f32_e32 v165, 0xbfb8aa3b, v141
	v_exp_f32_e32 v161, v161
	v_exp_f32_e32 v165, v165
	v_pk_mul_f32 v[178:179], v[178:179], s[40:41] op_sel_hi:[1,0]
; __device__ __forceinline__ float clamp448(float x) { return __builtin_amdgcn_fmed3f(x, -448.0f, 448.0f); }
; __device__ __forceinline__ u32x4 pack8bf(const f32x4 a, const f32x4 b) { u32x4 w; w.x = cvt_pk_bf16(a[0], a[1]); w.y = cvt_pk_bf16(a[2], a[3]); w.z = cvt_pk_bf16(b[0], b[1]); w.w = cvt_pk_bf16(b[2], b[3]); return w; }
; __device__ __forceinline__ void ln_stats(const float* st, int row, float& mu, float& rs) { const f32x2 s = *(const f32x2*)(st + 2 * (size_t)row); mu = s[0] * (1.0f / DM); rs = 1.0f / sqrtf(s[1] * (1.0f / DM) - mu * mu + LN_EPS); }
; __device__ __forceinline__ u32x2 pack8fp8(const f32x4 a, const f32x4 b) {
;     int lo = __builtin_amdgcn_cvt_pk_fp8_f32(clamp448(a[0]), clamp448(a[1]), 0, false); lo = __builtin_amdgcn_cvt_pk_fp8_f32(clamp448(a[2]), clamp448(a[3]), lo, true);
;     int hi = __builtin_amdgcn_cvt_pk_fp8_f32(clamp448(b[0]), clamp448(b[1]), 0, false); hi = __builtin_amdgcn_cvt_pk_fp8_f32(clamp448(b[2]), clamp448(b[3]), hi, true);
;     return (u32x2){(unsigned)lo, (unsigned)hi}; }
;     __device__ __forceinline__ void operator()(EPI_ARGS) const {
;     ...
;             for (int m = 0; m < 4; ++m) { const int row = row0 + ai * HALF + m * 16; f32x4 r[2];
;                 float mu = 0.f, rs = 1.f; if constexpr (FOLD) ln_stats(st, row, mu, rs);
; #pragma unroll
;                 for (int n = 0; n < 2; ++n) { f32x4 g = acc[ai][0][m][n], up = acc[ai][1][m][n];
;                     if constexpr (!PRE) { g = g * ascale; up = up * ascale; }
;                     if constexpr (FOLD) { g = (g - cg[n] * mu) * rs + dg[n]; up = (up - cu[n] * mu) * rs + du[n]; }
;                     if constexpr (!PRE) up = up * oscale;
; #pragma unroll
;                     for (int j = 0; j < 4; ++j) { const float e = __builtin_amdgcn_exp2f(g[j] * -1.4426950408889634f); r[n][j] = g[j] * __builtin_amdgcn_rcpf(1.0f + e) * up[j]; } }
;                 if constexpr (F8OUT) *(u32x2*)((unsigned char*)O + (size_t)row * ldc + col0) = pack8fp8(r[0], r[1]);
;                 else *(u32x4*)((bf16_t*)O + (size_t)row * ldc + col0) = pack8bf(r[0], r[1]); }
	v_pk_mul_f32 v[182:183], v[182:183], s[40:41] op_sel_hi:[1,0]
	v_add_f32_e32 v161, 1.0, v161
	v_pk_fma_f32 v[162:163], v[162:163], v[164:165], v[130:131] op_sel_hi:[1,0,1]
	v_add_f32_e32 v165, 1.0, v165
	v_rcp_f32_e32 v161, v161
	v_rcp_f32_e32 v165, v165
	v_mul_f32_e32 v174, 0xbfb8aa3b, v163
	v_exp_f32_e32 v174, v174
	v_mul_f32_e32 v139, v139, v161
	v_pk_fma_f32 v[142:143], v[142:143], v[164:165], v[102:103] op_sel_hi:[1,0,1]
	v_mul_f32_e32 v161, v138, v139
	v_mul_f32_e32 v138, 0xbfb8aa3b, v143
	v_exp_f32_e32 v138, v138
	v_add_f32_e32 v139, 1.0, v174
	v_mul_f32_e32 v141, v141, v165
	v_rcp_f32_e32 v165, v139
	v_add_f32_e32 v138, 1.0, v138
	v_mul_f32_e32 v196, v140, v141
	v_rcp_f32_e32 v176, v138
	v_mov_b32_e32 v138, v178
	v_mov_b32_e32 v139, v84
	v_mov_b32_e32 v140, v188
	v_mov_b32_e32 v141, v192
	v_pk_fma_f32 v[174:175], v[186:187], v[138:139], v[140:141] op_sel_hi:[0,1,1] neg_lo:[1,0,0] neg_hi:[1,0,0]
	v_mov_b32_e32 v140, v182
	v_mov_b32_e32 v141, v88
	v_pk_fma_f32 v[174:175], v[174:175], v[164:165], v[140:141] op_sel_hi:[1,0,1]
	v_mul_f32_e32 v88, v163, v165
	v_mul_f32_e32 v84, 0xbfb8aa3b, v175
	v_exp_f32_e32 v84, v84
	v_mov_b32_e32 v192, v189
	v_mul_f32_e32 v182, v162, v88
	v_mov_b32_e32 v88, v183
	v_add_f32_e32 v84, 1.0, v84
	v_rcp_f32_e32 v165, v84
	v_mov_b32_e32 v84, v179
	v_pk_fma_f32 v[162:163], v[186:187], v[84:85], v[192:193] op_sel_hi:[0,1,1] neg_lo:[1,0,0] neg_hi:[1,0,0]
	v_mul_f32_e32 v143, v143, v176
	v_pk_fma_f32 v[176:177], v[162:163], v[164:165], v[88:89] op_sel_hi:[1,0,1]
	v_mul_f32_e32 v183, v142, v143
	v_mul_f32_e32 v162, 0xbfb8aa3b, v177
	v_exp_f32_e32 v162, v162
	v_mul_f32_e32 v142, v175, v165
	v_pk_mul_f32 v[180:181], v[180:181], s[40:41] op_sel_hi:[1,0]
	v_mul_f32_e32 v188, v174, v142
	v_add_f32_e32 v142, 1.0, v162
	v_pk_mul_f32 v[184:185], v[184:185], s[40:41] op_sel_hi:[1,0]
	v_rcp_f32_e32 v189, v142
	v_mov_b32_e32 v142, v180
	v_mov_b32_e32 v143, v86
	v_mov_b32_e32 v162, v194
	v_mov_b32_e32 v163, v190
	v_pk_fma_f32 v[174:175], v[186:187], v[142:143], v[162:163] op_sel_hi:[0,1,1] neg_lo:[1,0,0] neg_hi:[1,0,0]
	v_mov_b32_e32 v162, v184
	v_mov_b32_e32 v163, v90
	v_pk_fma_f32 v[174:175], v[174:175], v[164:165], v[162:163] op_sel_hi:[1,0,1]
	v_mov_b32_e32 v190, v195
	v_mul_f32_e32 v86, 0xbfb8aa3b, v175
	v_exp_f32_e32 v180, v86
	v_mov_b32_e32 v86, v181
	v_pk_fma_f32 v[178:179], v[186:187], v[86:87], v[190:191] op_sel_hi:[0,1,1] neg_lo:[1,0,0] neg_hi:[1,0,0]
	v_mov_b32_e32 v90, v185
	v_pk_fma_f32 v[164:165], v[178:179], v[164:165], v[90:91] op_sel_hi:[1,0,1]
	v_add_f32_e32 v179, 1.0, v180
	v_mul_f32_e32 v178, 0xbfb8aa3b, v165
	v_exp_f32_e32 v178, v178
	v_rcp_f32_e32 v179, v179
	v_mul_f32_e32 v177, v177, v189
	v_mul_f32_e32 v176, v176, v177
	v_add_f32_e32 v178, 1.0, v178
	v_rcp_f32_e32 v178, v178
	v_mul_f32_e32 v175, v175, v179
	v_mul_f32_e32 v177, v174, v175
	v_med3_f32 v161, v161, s62, v173
	v_mul_f32_e32 v165, v165, v178
	v_mul_f32_e32 v164, v164, v165
	v_med3_f32 v165, v196, s62, v173
	v_cvt_pk_fp8_f32 v174, v161, v165
	v_med3_f32 v178, v188, s62, v173
	v_med3_f32 v176, v176, s62, v173
	v_cvt_pk_fp8_f32 v175, v178, v176
	v_med3_f32 v161, v182, s62, v173
	v_med3_f32 v165, v183, s62, v173
	v_cvt_pk_fp8_f32 v174, v161, v165 op_sel:[0,0,1]
	v_med3_f32 v161, v177, s62, v173
	v_med3_f32 v164, v164, s62, v173
	v_cvt_pk_fp8_f32 v175, v161, v164 op_sel:[0,0,1]
	v_mov_b64_e32 v[164:165], s[12:13]
	v_mad_i64_i32 v[176:177], s[4:5], v160, s63, v[164:165]
	v_lshl_add_u64 v[176:177], v[176:177], 0, v[128:129]
	global_store_dwordx2 v[176:177], v[174:175], off
	v_or_b32_e32 v174, 16, v160
	v_ashrrev_i32_e32 v175, 31, v174
	v_lshl_add_u64 v[176:177], v[174:175], 3, s[14:15]
	v_mov_b32_e32 v176, v226
	v_mov_b32_e32 v177, v227
	v_pk_mul_f32 v[104:105], v[104:105], s[20:21] op_sel_hi:[1,0]
	v_pk_mul_f32 v[80:81], v[80:81], s[24:25] op_sel_hi:[1,0]
	v_cvt_f32_i32_e32 v107, v107
	v_cvt_f32_i32_e32 v106, v106
	v_cvt_f32_i32_e32 v83, v83
	v_cvt_f32_i32_e32 v82, v82
	v_cvt_f32_i32_e32 v77, v77
	v_pk_mul_f32 v[106:107], v[106:107], s[20:21] op_sel_hi:[1,0]
	v_cvt_f32_i32_e32 v76, v76
	v_pk_mul_f32 v[82:83], v[82:83], s[24:25] op_sel_hi:[1,0]
	v_cvt_f32_i32_e32 v69, v69
	v_cvt_f32_i32_e32 v68, v68
	v_pk_mul_f32 v[76:77], v[76:77], s[20:21] op_sel_hi:[1,0]
	v_cvt_f32_i32_e32 v79, v79
	v_cvt_f32_i32_e32 v78, v78
	v_pk_mul_f32 v[68:69], v[68:69], s[24:25] op_sel_hi:[1,0]
	v_cvt_f32_i32_e32 v71, v71
	v_cvt_f32_i32_e32 v70, v70
	v_pk_mul_f32 v[78:79], v[78:79], s[20:21] op_sel_hi:[1,0]
	v_cvt_f32_i32_e32 v73, v73
	v_cvt_f32_i32_e32 v72, v72
	v_pk_mul_f32 v[70:71], v[70:71], s[24:25] op_sel_hi:[1,0]
	v_cvt_f32_i32_e32 v65, v65
	v_cvt_f32_i32_e32 v64, v64
	v_pk_mul_f32 v[72:73], v[72:73], s[20:21] op_sel_hi:[1,0]
	v_cvt_f32_i32_e32 v75, v75
	v_cvt_f32_i32_e32 v74, v74
	v_pk_mul_f32 v[64:65], v[64:65], s[24:25] op_sel_hi:[1,0]
	v_cvt_f32_i32_e32 v67, v67
	v_cvt_f32_i32_e32 v66, v66
	v_pk_mul_f32 v[74:75], v[74:75], s[20:21] op_sel_hi:[1,0]
	v_cvt_f32_i32_e32 v61, v61
	v_cvt_f32_i32_e32 v60, v60
	v_pk_mul_f32 v[66:67], v[66:67], s[24:25] op_sel_hi:[1,0]
	v_cvt_f32_i32_e32 v53, v53
	v_cvt_f32_i32_e32 v52, v52
	v_pk_mul_f32 v[60:61], v[60:61], s[20:21] op_sel_hi:[1,0]
	v_cvt_f32_i32_e32 v63, v63
	v_cvt_f32_i32_e32 v62, v62
	v_pk_mul_f32 v[52:53], v[52:53], s[24:25] op_sel_hi:[1,0]
	v_cvt_f32_i32_e32 v55, v55
	v_cvt_f32_i32_e32 v54, v54
	v_pk_mul_f32 v[62:63], v[62:63], s[20:21] op_sel_hi:[1,0]
	v_cvt_f32_i32_e32 v57, v57
	v_cvt_f32_i32_e32 v56, v56
	v_pk_mul_f32 v[54:55], v[54:55], s[24:25] op_sel_hi:[1,0]
	v_cvt_f32_i32_e32 v49, v49
	v_cvt_f32_i32_e32 v48, v48
	v_pk_mul_f32 v[56:57], v[56:57], s[20:21] op_sel_hi:[1,0]
	v_cvt_f32_i32_e32 v59, v59
; __device__ __forceinline__ u32x4 pack8bf(const f32x4 a, const f32x4 b) { u32x4 w; w.x = cvt_pk_bf16(a[0], a[1]); w.y = cvt_pk_bf16(a[2], a[3]); w.z = cvt_pk_bf16(b[0], b[1]); w.w = cvt_pk_bf16(b[2], b[3]); return w; }
;     __device__ __forceinline__ float qscale(const Unit& u) const { return ((u.pn >= 8 && u.pn <= 11) || u.pn == 17) ? 0.5f : 1.0f; }
; __device__ __forceinline__ void ln_stats(const float* st, int row, float& mu, float& rs) { const f32x2 s = *(const f32x2*)(st + 2 * (size_t)row); mu = s[0] * (1.0f / DM); rs = 1.0f / sqrtf(s[1] * (1.0f / DM) - mu * mu + LN_EPS); }
;     ...
;         if constexpr (QM == 2) { const float qs0_ = g.qs * E.qscale(cur), qs1_ = qs0_ * g.qs_b1; _Pragma("unroll") for (int a = 0; a < 2; ++a) _Pragma("unroll") for (int b = 0; b < 2; ++b) _Pragma("unroll") for (int m = 0; m < 4; ++m) _Pragma("unroll") for (int n = 0; n < 2; ++n) { const v4i t_ = __builtin_bit_cast(v4i, acc[a][b][m][n]); acc[a][b][m][n] = (f32x4){(float)t_[0], (float)t_[1], (float)t_[2], (float)t_[3]} * (b == 0 ? qs0_ : qs1_); } }
;     __device__ __forceinline__ void operator()(EPI_ARGS) const {
;     ...
;             for (int m = 0; m < 4; ++m) { const int row = row0 + ai * HALF + m * 16; f32x4 r[2];
;                 float mu = 0.f, rs = 1.f; if constexpr (FOLD) ln_stats(st, row, mu, rs);
; #pragma unroll
;                 for (int n = 0; n < 2; ++n) { f32x4 g = acc[ai][0][m][n], up = acc[ai][1][m][n];
;                     if constexpr (!PRE) { g = g * ascale; up = up * ascale; }
;                     if constexpr (FOLD) { g = (g - cg[n] * mu) * rs + dg[n]; up = (up - cu[n] * mu) * rs + du[n]; }
;                     if constexpr (!PRE) up = up * oscale;
; #pragma unroll
;                     for (int j = 0; j < 4; ++j) { const float e = __builtin_amdgcn_exp2f(g[j] * -1.4426950408889634f); r[n][j] = g[j] * __builtin_amdgcn_rcpf(1.0f + e) * up[j]; } }
;                 if constexpr (F8OUT) *(u32x2*)((unsigned char*)O + (size_t)row * ldc + col0) = pack8fp8(r[0], r[1]);
;                 else *(u32x4*)((bf16_t*)O + (size_t)row * ldc + col0) = pack8bf(r[0], r[1]); }
	v_cvt_f32_i32_e32 v58, v58
	v_pk_mul_f32 v[48:49], v[48:49], s[24:25] op_sel_hi:[1,0]
	v_cvt_f32_i32_e32 v51, v51
	v_cvt_f32_i32_e32 v50, v50
	v_pk_mul_f32 v[58:59], v[58:59], s[20:21] op_sel_hi:[1,0]
	v_cvt_f32_i32_e32 v45, v45
	v_cvt_f32_i32_e32 v44, v44
	v_pk_mul_f32 v[50:51], v[50:51], s[24:25] op_sel_hi:[1,0]
	v_cvt_f32_i32_e32 v37, v37
	v_cvt_f32_i32_e32 v36, v36
	v_pk_mul_f32 v[44:45], v[44:45], s[20:21] op_sel_hi:[1,0]
	v_cvt_f32_i32_e32 v47, v47
	v_cvt_f32_i32_e32 v46, v46
	v_pk_mul_f32 v[36:37], v[36:37], s[24:25] op_sel_hi:[1,0]
	v_cvt_f32_i32_e32 v39, v39
	v_cvt_f32_i32_e32 v38, v38
	v_pk_mul_f32 v[46:47], v[46:47], s[20:21] op_sel_hi:[1,0]
	v_cvt_f32_i32_e32 v41, v41
	v_cvt_f32_i32_e32 v40, v40
	v_pk_mul_f32 v[38:39], v[38:39], s[24:25] op_sel_hi:[1,0]
	v_cvt_f32_i32_e32 v33, v33
	v_cvt_f32_i32_e32 v32, v32
	v_pk_mul_f32 v[40:41], v[40:41], s[20:21] op_sel_hi:[1,0]
	v_cvt_f32_i32_e32 v43, v43
	v_cvt_f32_i32_e32 v42, v42
	v_pk_mul_f32 v[32:33], v[32:33], s[24:25] op_sel_hi:[1,0]
	v_cvt_f32_i32_e32 v35, v35
	v_cvt_f32_i32_e32 v34, v34
	v_pk_mul_f32 v[42:43], v[42:43], s[20:21] op_sel_hi:[1,0]
	v_pk_mul_f32 v[176:177], v[176:177], s[26:27] op_sel_hi:[1,0]
	v_cvt_f32_i32_e32 v29, v29
	v_fma_f32 v161, -v176, v176, v177
	v_add_f32_e32 v161, 0x3727c5ac, v161
	v_rsq_f32_e32 v242, v161
	v_pk_mul_f32 v[34:35], v[34:35], s[24:25] op_sel_hi:[1,0]
	v_cvt_f32_i32_e32 v28, v28
	v_cvt_f32_i32_e32 v21, v21
	v_cvt_f32_i32_e32 v20, v20
	v_pk_mul_f32 v[28:29], v[28:29], s[20:21] op_sel_hi:[1,0]
	v_pk_mul_f32 v[20:21], v[20:21], s[24:25] op_sel_hi:[1,0]
	v_cvt_f32_i32_e32 v31, v31
	v_cvt_f32_i32_e32 v30, v30
	v_cvt_f32_i32_e32 v23, v23
	v_cvt_f32_i32_e32 v22, v22
	v_pk_mul_f32 v[30:31], v[30:31], s[20:21] op_sel_hi:[1,0]
	v_pk_mul_f32 v[22:23], v[22:23], s[24:25] op_sel_hi:[1,0]
	v_cvt_f32_i32_e32 v25, v25
	v_mov_b32_e32 v180, v116
	v_mov_b32_e32 v181, v124
	v_mov_b32_e32 v178, v242
	v_pk_fma_f32 v[180:181], v[136:137], v[176:177], v[180:181] op_sel_hi:[1,0,1] neg_lo:[1,0,0] neg_hi:[1,0,0]
	v_mov_b32_e32 v124, v117
	v_pk_fma_f32 v[180:181], v[180:181], v[178:179], v[134:135] op_sel_hi:[1,0,1]
	v_cvt_f32_i32_e32 v24, v24
	v_mul_f32_e32 v116, 0xbfb8aa3b, v181
	v_exp_f32_e32 v161, v116
	v_pk_fma_f32 v[116:117], v[96:97], v[176:177], v[124:125] op_sel_hi:[1,0,1] neg_lo:[1,0,0] neg_hi:[1,0,0]
	v_cvt_f32_i32_e32 v17, v17
	v_pk_fma_f32 v[116:117], v[116:117], v[178:179], v[100:101] op_sel_hi:[1,0,1]
	v_add_f32_e32 v125, 1.0, v161
	v_mul_f32_e32 v124, 0xbfb8aa3b, v117
	v_exp_f32_e32 v124, v124
	v_rcp_f32_e32 v125, v125
	v_cvt_f32_i32_e32 v16, v16
	v_pk_mul_f32 v[24:25], v[24:25], s[20:21] op_sel_hi:[1,0]
	v_add_f32_e32 v124, 1.0, v124
	v_rcp_f32_e32 v124, v124
	v_mul_f32_e32 v125, v181, v125
	v_mul_f32_e32 v161, v180, v125
	v_mov_b32_e32 v125, v126
	v_mul_f32_e32 v117, v117, v124
	v_mov_b32_e32 v124, v118
	v_pk_fma_f32 v[124:125], v[132:133], v[176:177], v[124:125] op_sel_hi:[1,0,1] neg_lo:[1,0,0] neg_hi:[1,0,0]
	v_mov_b32_e32 v126, v119
	v_pk_fma_f32 v[124:125], v[124:125], v[178:179], v[130:131] op_sel_hi:[1,0,1]
	v_pk_mul_f32 v[16:17], v[16:17], s[24:25] op_sel_hi:[1,0]
	v_mul_f32_e32 v118, 0xbfb8aa3b, v125
	v_exp_f32_e32 v175, v118
	v_pk_fma_f32 v[118:119], v[98:99], v[176:177], v[126:127] op_sel_hi:[1,0,1] neg_lo:[1,0,0] neg_hi:[1,0,0]
	v_mul_f32_e32 v127, v116, v117
	v_pk_fma_f32 v[118:119], v[118:119], v[178:179], v[102:103] op_sel_hi:[1,0,1]
	v_add_f32_e32 v116, 1.0, v175
	v_mul_f32_e32 v126, 0xbfb8aa3b, v119
	v_exp_f32_e32 v126, v126
	v_rcp_f32_e32 v175, v116
	v_mov_b32_e32 v117, v120
	v_cvt_f32_i32_e32 v27, v27
	v_add_f32_e32 v116, 1.0, v126
	v_rcp_f32_e32 v126, v116
	v_mov_b32_e32 v116, v112
	v_pk_fma_f32 v[116:117], v[138:139], v[176:177], v[116:117] op_sel_hi:[1,0,1] neg_lo:[1,0,0] neg_hi:[1,0,0]
	v_mul_f32_e32 v120, v125, v175
	v_pk_fma_f32 v[116:117], v[116:117], v[178:179], v[140:141] op_sel_hi:[1,0,1]
	v_mul_f32_e32 v124, v124, v120
	v_mul_f32_e32 v112, 0xbfb8aa3b, v117
	v_exp_f32_e32 v112, v112
	v_mov_b32_e32 v120, v113
	v_mul_f32_e32 v119, v119, v126
	v_mul_f32_e32 v118, v118, v119
	v_add_f32_e32 v112, 1.0, v112
	v_rcp_f32_e32 v125, v112
	v_pk_fma_f32 v[112:113], v[84:85], v[176:177], v[120:121] op_sel_hi:[1,0,1] neg_lo:[1,0,0] neg_hi:[1,0,0]
	v_cvt_f32_i32_e32 v26, v26
	v_pk_fma_f32 v[112:113], v[112:113], v[178:179], v[88:89] op_sel_hi:[1,0,1]
	v_mul_f32_e32 v117, v117, v125
	v_mul_f32_e32 v120, 0xbfb8aa3b, v113
	v_exp_f32_e32 v120, v120
	v_mul_f32_e32 v119, v116, v117
	v_mov_b32_e32 v117, v122
	v_mov_b32_e32 v122, v115
	v_add_f32_e32 v116, 1.0, v120
	v_rcp_f32_e32 v120, v116
	v_mov_b32_e32 v116, v114
	v_pk_fma_f32 v[116:117], v[142:143], v[176:177], v[116:117] op_sel_hi:[1,0,1] neg_lo:[1,0,0] neg_hi:[1,0,0]
	v_cvt_f32_i32_e32 v19, v19
	v_pk_fma_f32 v[116:117], v[116:117], v[178:179], v[162:163] op_sel_hi:[1,0,1]
	v_mul_f32_e32 v113, v113, v120
	v_mul_f32_e32 v114, 0xbfb8aa3b, v117
	v_exp_f32_e32 v121, v114
	v_pk_fma_f32 v[114:115], v[86:87], v[176:177], v[122:123] op_sel_hi:[1,0,1] neg_lo:[1,0,0] neg_hi:[1,0,0]
	v_mul_f32_e32 v113, v112, v113
	v_pk_fma_f32 v[114:115], v[114:115], v[178:179], v[90:91] op_sel_hi:[1,0,1]
	v_add_f32_e32 v120, 1.0, v121
	v_mul_f32_e32 v122, 0xbfb8aa3b, v115
	v_exp_f32_e32 v122, v122
	v_rcp_f32_e32 v120, v120
	v_cvt_f32_i32_e32 v18, v18
	v_pk_mul_f32 v[26:27], v[26:27], s[20:21] op_sel_hi:[1,0]
	v_add_f32_e32 v121, 1.0, v122
	v_rcp_f32_e32 v121, v121
	v_mul_f32_e32 v112, v117, v120
	v_mul_f32_e32 v116, v116, v112
	v_med3_f32 v117, v127, s62, v173
	v_mul_f32_e32 v112, v115, v121
	v_mul_f32_e32 v114, v114, v112
	v_med3_f32 v115, v161, s62, v173
	v_cvt_pk_fp8_f32 v112, v115, v117
	v_med3_f32 v117, v118, s62, v173
; __device__ __forceinline__ float clamp448(float x) { return __builtin_amdgcn_fmed3f(x, -448.0f, 448.0f); }
; __device__ __forceinline__ u32x4 pack8bf(const f32x4 a, const f32x4 b) { u32x4 w; w.x = cvt_pk_bf16(a[0], a[1]); w.y = cvt_pk_bf16(a[2], a[3]); w.z = cvt_pk_bf16(b[0], b[1]); w.w = cvt_pk_bf16(b[2], b[3]); return w; }
; __device__ __forceinline__ void ln_stats(const float* st, int row, float& mu, float& rs) { const f32x2 s = *(const f32x2*)(st + 2 * (size_t)row); mu = s[0] * (1.0f / DM); rs = 1.0f / sqrtf(s[1] * (1.0f / DM) - mu * mu + LN_EPS); }
; __device__ __forceinline__ u32x2 pack8fp8(const f32x4 a, const f32x4 b) {
;     int lo = __builtin_amdgcn_cvt_pk_fp8_f32(clamp448(a[0]), clamp448(a[1]), 0, false); lo = __builtin_amdgcn_cvt_pk_fp8_f32(clamp448(a[2]), clamp448(a[3]), lo, true);
;     int hi = __builtin_amdgcn_cvt_pk_fp8_f32(clamp448(b[0]), clamp448(b[1]), 0, false); hi = __builtin_amdgcn_cvt_pk_fp8_f32(clamp448(b[2]), clamp448(b[3]), hi, true);
;     return (u32x2){(unsigned)lo, (unsigned)hi}; }
;     __device__ __forceinline__ void operator()(EPI_ARGS) const {
;     ...
;             for (int m = 0; m < 4; ++m) { const int row = row0 + ai * HALF + m * 16; f32x4 r[2];
;                 float mu = 0.f, rs = 1.f; if constexpr (FOLD) ln_stats(st, row, mu, rs);
; #pragma unroll
;                 for (int n = 0; n < 2; ++n) { f32x4 g = acc[ai][0][m][n], up = acc[ai][1][m][n];
;                     if constexpr (!PRE) { g = g * ascale; up = up * ascale; }
;                     if constexpr (FOLD) { g = (g - cg[n] * mu) * rs + dg[n]; up = (up - cu[n] * mu) * rs + du[n]; }
;                     if constexpr (!PRE) up = up * oscale;
; #pragma unroll
;                     for (int j = 0; j < 4; ++j) { const float e = __builtin_amdgcn_exp2f(g[j] * -1.4426950408889634f); r[n][j] = g[j] * __builtin_amdgcn_rcpf(1.0f + e) * up[j]; } }
;                 if constexpr (F8OUT) *(u32x2*)((unsigned char*)O + (size_t)row * ldc + col0) = pack8fp8(r[0], r[1]);
;                 else *(u32x4*)((bf16_t*)O + (size_t)row * ldc + col0) = pack8bf(r[0], r[1]); }
	v_med3_f32 v118, v119, s62, v173
	v_med3_f32 v119, v113, s62, v173
	v_cvt_pk_fp8_f32 v113, v118, v119
	v_med3_f32 v115, v124, s62, v173
	v_cvt_pk_fp8_f32 v112, v115, v117 op_sel:[0,0,1]
	v_med3_f32 v115, v116, s62, v173
	v_med3_f32 v114, v114, s62, v173
	v_cvt_pk_fp8_f32 v113, v115, v114 op_sel:[0,0,1]
	v_mad_i64_i32 v[114:115], s[4:5], v174, s63, v[164:165]
	v_lshl_add_u64 v[114:115], v[114:115], 0, v[128:129]
	global_store_dwordx2 v[114:115], v[112:113], off
	v_or_b32_e32 v112, 32, v160
	v_ashrrev_i32_e32 v113, 31, v112
	v_lshl_add_u64 v[114:115], v[112:113], 3, s[14:15]
	v_mov_b32_e32 v114, v228
	v_mov_b32_e32 v115, v229
	v_pk_mul_f32 v[18:19], v[18:19], s[24:25] op_sel_hi:[1,0]
	v_cvt_f32_i32_e32 v13, v13
	v_cvt_f32_i32_e32 v12, v12
	v_cvt_f32_i32_e32 v5, v5
	v_cvt_f32_i32_e32 v4, v4
	v_cvt_f32_i32_e32 v15, v15
	v_pk_mul_f32 v[12:13], v[12:13], s[20:21] op_sel_hi:[1,0]
	v_cvt_f32_i32_e32 v14, v14
	v_pk_mul_f32 v[4:5], v[4:5], s[24:25] op_sel_hi:[1,0]
	v_cvt_f32_i32_e32 v7, v7
	v_cvt_f32_i32_e32 v6, v6
	v_pk_mul_f32 v[14:15], v[14:15], s[20:21] op_sel_hi:[1,0]
	v_cvt_f32_i32_e32 v9, v9
	v_cvt_f32_i32_e32 v8, v8
	v_pk_mul_f32 v[6:7], v[6:7], s[24:25] op_sel_hi:[1,0]
	v_cvt_f32_i32_e32 v1, v1
	v_cvt_f32_i32_e32 v0, v0
	v_pk_mul_f32 v[8:9], v[8:9], s[20:21] op_sel_hi:[1,0]
	v_cvt_f32_i32_e32 v11, v11
	v_cvt_f32_i32_e32 v10, v10
	v_pk_mul_f32 v[0:1], v[0:1], s[24:25] op_sel_hi:[1,0]
	v_cvt_f32_i32_e32 v3, v3
	v_cvt_f32_i32_e32 v2, v2
	v_pk_mul_f32 v[10:11], v[10:11], s[20:21] op_sel_hi:[1,0]
	v_pk_mul_f32 v[2:3], v[2:3], s[24:25] op_sel_hi:[1,0]
	v_pk_mul_f32 v[114:115], v[114:115], s[26:27] op_sel_hi:[1,0]
	s_nop 0
	v_fma_f32 v113, -v114, v114, v115
	v_add_f32_e32 v113, 0x3727c5ac, v113
	v_rsq_f32_e32 v242, v113
	s_nop 1
	s_nop 0
	s_nop 0
	s_nop 1
	s_nop 1
	s_nop 0
	v_mov_b32_e32 v118, v92
	v_mov_b32_e32 v119, v108
	v_mov_b32_e32 v116, v242
	v_pk_fma_f32 v[118:119], v[136:137], v[114:115], v[118:119] op_sel_hi:[1,0,1] neg_lo:[1,0,0] neg_hi:[1,0,0]
	v_mov_b32_e32 v108, v93
	v_pk_fma_f32 v[118:119], v[118:119], v[116:117], v[134:135] op_sel_hi:[1,0,1]
	s_nop 0
	v_mul_f32_e32 v92, 0xbfb8aa3b, v119
	v_exp_f32_e32 v113, v92
	v_pk_fma_f32 v[92:93], v[96:97], v[114:115], v[108:109] op_sel_hi:[1,0,1] neg_lo:[1,0,0] neg_hi:[1,0,0]
	v_add_f32_e32 v109, 1.0, v113
	v_pk_fma_f32 v[92:93], v[92:93], v[116:117], v[100:101] op_sel_hi:[1,0,1]
	v_rcp_f32_e32 v109, v109
	v_mul_f32_e32 v108, 0xbfb8aa3b, v93
	v_exp_f32_e32 v108, v108
	v_mul_f32_e32 v109, v119, v109
	v_mul_f32_e32 v113, v118, v109
	v_add_f32_e32 v108, 1.0, v108
	v_rcp_f32_e32 v108, v108
	v_mov_b32_e32 v109, v110
	v_mov_b32_e32 v110, v95
	v_mul_f32_e32 v93, v93, v108
	v_mov_b32_e32 v108, v94
	v_pk_fma_f32 v[108:109], v[132:133], v[114:115], v[108:109] op_sel_hi:[1,0,1] neg_lo:[1,0,0] neg_hi:[1,0,0]
	s_nop 0
	v_pk_fma_f32 v[108:109], v[108:109], v[116:117], v[130:131] op_sel_hi:[1,0,1]
	s_nop 0
	v_mul_f32_e32 v94, 0xbfb8aa3b, v109
	v_exp_f32_e32 v117, v94
	v_pk_fma_f32 v[94:95], v[98:99], v[114:115], v[110:111] op_sel_hi:[1,0,1] neg_lo:[1,0,0] neg_hi:[1,0,0]
	v_mul_f32_e32 v111, v92, v93
	v_mov_b32_e32 v93, v104
	v_pk_fma_f32 v[94:95], v[94:95], v[116:117], v[102:103] op_sel_hi:[1,0,1]
	v_add_f32_e32 v92, 1.0, v117
	v_mul_f32_e32 v110, 0xbfb8aa3b, v95
	v_exp_f32_e32 v110, v110
	v_rcp_f32_e32 v117, v92
	v_add_f32_e32 v92, 1.0, v110
	v_rcp_f32_e32 v110, v92
	v_mov_b32_e32 v92, v80
	v_pk_fma_f32 v[92:93], v[138:139], v[114:115], v[92:93] op_sel_hi:[1,0,1] neg_lo:[1,0,0] neg_hi:[1,0,0]
	v_mul_f32_e32 v104, v109, v117
	v_pk_fma_f32 v[92:93], v[92:93], v[116:117], v[140:141] op_sel_hi:[1,0,1]
	v_mul_f32_e32 v108, v108, v104
	v_mul_f32_e32 v80, 0xbfb8aa3b, v93
	v_exp_f32_e32 v80, v80
	v_mov_b32_e32 v104, v81
	v_mul_f32_e32 v95, v95, v110
	v_mul_f32_e32 v94, v94, v95
	v_add_f32_e32 v80, 1.0, v80
	v_rcp_f32_e32 v109, v80
	v_pk_fma_f32 v[80:81], v[84:85], v[114:115], v[104:105] op_sel_hi:[1,0,1] neg_lo:[1,0,0] neg_hi:[1,0,0]
	v_mul_f32_e32 v93, v93, v109
	v_pk_fma_f32 v[80:81], v[80:81], v[116:117], v[88:89] op_sel_hi:[1,0,1]
	v_mul_f32_e32 v95, v92, v93
	v_mul_f32_e32 v104, 0xbfb8aa3b, v81
	v_exp_f32_e32 v104, v104
	v_mov_b32_e32 v93, v106
	v_mov_b32_e32 v106, v83
	v_add_f32_e32 v92, 1.0, v104
	v_rcp_f32_e32 v104, v92
	v_mov_b32_e32 v92, v82
	v_pk_fma_f32 v[92:93], v[142:143], v[114:115], v[92:93] op_sel_hi:[1,0,1] neg_lo:[1,0,0] neg_hi:[1,0,0]
	v_mul_f32_e32 v81, v81, v104
	v_pk_fma_f32 v[92:93], v[92:93], v[116:117], v[162:163] op_sel_hi:[1,0,1]
	v_mul_f32_e32 v81, v80, v81
	v_mul_f32_e32 v82, 0xbfb8aa3b, v93
	v_exp_f32_e32 v105, v82
	v_pk_fma_f32 v[82:83], v[86:87], v[114:115], v[106:107] op_sel_hi:[1,0,1] neg_lo:[1,0,0] neg_hi:[1,0,0]
	v_add_f32_e32 v104, 1.0, v105
	v_pk_fma_f32 v[82:83], v[82:83], v[116:117], v[90:91] op_sel_hi:[1,0,1]
	v_rcp_f32_e32 v104, v104
	v_mul_f32_e32 v106, 0xbfb8aa3b, v83
	v_exp_f32_e32 v106, v106
	v_mul_f32_e32 v80, v93, v104
	v_mul_f32_e32 v92, v92, v80
	v_add_f32_e32 v105, 1.0, v106
	v_rcp_f32_e32 v105, v105
	v_med3_f32 v93, v111, s62, v173
	v_mul_f32_e32 v80, v83, v105
	v_mul_f32_e32 v82, v82, v80
	v_med3_f32 v83, v113, s62, v173
	v_cvt_pk_fp8_f32 v80, v83, v93
	v_med3_f32 v93, v94, s62, v173
	v_med3_f32 v94, v95, s62, v173
	v_med3_f32 v95, v81, s62, v173
	v_cvt_pk_fp8_f32 v81, v94, v95
	v_med3_f32 v83, v108, s62, v173
	v_cvt_pk_fp8_f32 v80, v83, v93 op_sel:[0,0,1]
	v_med3_f32 v83, v92, s62, v173
	v_med3_f32 v82, v82, s62, v173
	v_cvt_pk_fp8_f32 v81, v83, v82 op_sel:[0,0,1]
	v_mad_i64_i32 v[82:83], s[4:5], v112, s63, v[164:165]
	v_lshl_add_u64 v[82:83], v[82:83], 0, v[128:129]
	global_store_dwordx2 v[82:83], v[80:81], off
	v_or_b32_e32 v80, 48, v160
; __device__ __forceinline__ float clamp448(float x) { return __builtin_amdgcn_fmed3f(x, -448.0f, 448.0f); }
; __device__ __forceinline__ u32x4 pack8bf(const f32x4 a, const f32x4 b) { u32x4 w; w.x = cvt_pk_bf16(a[0], a[1]); w.y = cvt_pk_bf16(a[2], a[3]); w.z = cvt_pk_bf16(b[0], b[1]); w.w = cvt_pk_bf16(b[2], b[3]); return w; }
; __device__ __forceinline__ void ln_stats(const float* st, int row, float& mu, float& rs) { const f32x2 s = *(const f32x2*)(st + 2 * (size_t)row); mu = s[0] * (1.0f / DM); rs = 1.0f / sqrtf(s[1] * (1.0f / DM) - mu * mu + LN_EPS); }
; __device__ __forceinline__ u32x2 pack8fp8(const f32x4 a, const f32x4 b) {
;     int lo = __builtin_amdgcn_cvt_pk_fp8_f32(clamp448(a[0]), clamp448(a[1]), 0, false); lo = __builtin_amdgcn_cvt_pk_fp8_f32(clamp448(a[2]), clamp448(a[3]), lo, true);
;     int hi = __builtin_amdgcn_cvt_pk_fp8_f32(clamp448(b[0]), clamp448(b[1]), 0, false); hi = __builtin_amdgcn_cvt_pk_fp8_f32(clamp448(b[2]), clamp448(b[3]), hi, true);
;     return (u32x2){(unsigned)lo, (unsigned)hi}; }
;     __device__ __forceinline__ void operator()(EPI_ARGS) const {
;     ...
;             for (int m = 0; m < 4; ++m) { const int row = row0 + ai * HALF + m * 16; f32x4 r[2];
;                 float mu = 0.f, rs = 1.f; if constexpr (FOLD) ln_stats(st, row, mu, rs);
; #pragma unroll
;                 for (int n = 0; n < 2; ++n) { f32x4 g = acc[ai][0][m][n], up = acc[ai][1][m][n];
;                     if constexpr (!PRE) { g = g * ascale; up = up * ascale; }
;                     if constexpr (FOLD) { g = (g - cg[n] * mu) * rs + dg[n]; up = (up - cu[n] * mu) * rs + du[n]; }
;                     if constexpr (!PRE) up = up * oscale;
; #pragma unroll
;                     for (int j = 0; j < 4; ++j) { const float e = __builtin_amdgcn_exp2f(g[j] * -1.4426950408889634f); r[n][j] = g[j] * __builtin_amdgcn_rcpf(1.0f + e) * up[j]; } }
;                 if constexpr (F8OUT) *(u32x2*)((unsigned char*)O + (size_t)row * ldc + col0) = pack8fp8(r[0], r[1]);
;                 else *(u32x4*)((bf16_t*)O + (size_t)row * ldc + col0) = pack8bf(r[0], r[1]); }
	v_ashrrev_i32_e32 v81, 31, v80
	v_lshl_add_u64 v[82:83], v[80:81], 3, s[14:15]
	v_mov_b32_e32 v82, v230
	v_mov_b32_e32 v83, v231
	v_pk_mul_f32 v[82:83], v[82:83], s[26:27] op_sel_hi:[1,0]
	s_nop 0
	v_fma_f32 v81, -v82, v82, v83
	v_add_f32_e32 v81, 0x3727c5ac, v81
	v_rsq_f32_e32 v242, v81
	s_nop 1
	s_nop 0
	s_nop 0
	s_nop 1
	s_nop 1
	s_nop 0
	v_mov_b32_e32 v94, v68
	v_mov_b32_e32 v95, v76
	v_mov_b32_e32 v92, v242
	v_pk_fma_f32 v[94:95], v[136:137], v[82:83], v[94:95] op_sel_hi:[1,0,1] neg_lo:[1,0,0] neg_hi:[1,0,0]
	v_mov_b32_e32 v76, v69
	v_pk_fma_f32 v[94:95], v[94:95], v[92:93], v[134:135] op_sel_hi:[1,0,1]
	s_nop 0
	v_mul_f32_e32 v68, 0xbfb8aa3b, v95
	v_exp_f32_e32 v81, v68
	v_pk_fma_f32 v[68:69], v[96:97], v[82:83], v[76:77] op_sel_hi:[1,0,1] neg_lo:[1,0,0] neg_hi:[1,0,0]
	v_add_f32_e32 v77, 1.0, v81
	v_pk_fma_f32 v[68:69], v[68:69], v[92:93], v[100:101] op_sel_hi:[1,0,1]
	v_rcp_f32_e32 v77, v77
	v_mul_f32_e32 v76, 0xbfb8aa3b, v69
	v_exp_f32_e32 v76, v76
	v_mul_f32_e32 v77, v95, v77
	v_mul_f32_e32 v81, v94, v77
	v_add_f32_e32 v76, 1.0, v76
	v_rcp_f32_e32 v76, v76
	v_mov_b32_e32 v77, v78
	v_mov_b32_e32 v78, v71
	v_mul_f32_e32 v69, v69, v76
	v_mov_b32_e32 v76, v70
	v_pk_fma_f32 v[76:77], v[132:133], v[82:83], v[76:77] op_sel_hi:[1,0,1] neg_lo:[1,0,0] neg_hi:[1,0,0]
	s_nop 0
	v_pk_fma_f32 v[76:77], v[76:77], v[92:93], v[130:131] op_sel_hi:[1,0,1]
	s_nop 0
	v_mul_f32_e32 v70, 0xbfb8aa3b, v77
	v_exp_f32_e32 v93, v70
	v_pk_fma_f32 v[70:71], v[98:99], v[82:83], v[78:79] op_sel_hi:[1,0,1] neg_lo:[1,0,0] neg_hi:[1,0,0]
	v_mul_f32_e32 v79, v68, v69
	v_mov_b32_e32 v69, v72
	v_pk_fma_f32 v[70:71], v[70:71], v[92:93], v[102:103] op_sel_hi:[1,0,1]
	v_add_f32_e32 v68, 1.0, v93
	v_mul_f32_e32 v78, 0xbfb8aa3b, v71
	v_exp_f32_e32 v78, v78
	v_rcp_f32_e32 v93, v68
	v_add_f32_e32 v68, 1.0, v78
	v_rcp_f32_e32 v78, v68
	v_mov_b32_e32 v68, v64
	v_pk_fma_f32 v[68:69], v[138:139], v[82:83], v[68:69] op_sel_hi:[1,0,1] neg_lo:[1,0,0] neg_hi:[1,0,0]
	v_mul_f32_e32 v72, v77, v93
	v_pk_fma_f32 v[68:69], v[68:69], v[92:93], v[140:141] op_sel_hi:[1,0,1]
	v_mul_f32_e32 v76, v76, v72
	v_mul_f32_e32 v64, 0xbfb8aa3b, v69
	v_exp_f32_e32 v64, v64
	v_mov_b32_e32 v72, v65
	v_mul_f32_e32 v71, v71, v78
	v_mul_f32_e32 v70, v70, v71
	v_add_f32_e32 v64, 1.0, v64
	v_rcp_f32_e32 v77, v64
	v_pk_fma_f32 v[64:65], v[84:85], v[82:83], v[72:73] op_sel_hi:[1,0,1] neg_lo:[1,0,0] neg_hi:[1,0,0]
	v_mul_f32_e32 v69, v69, v77
	v_pk_fma_f32 v[64:65], v[64:65], v[92:93], v[88:89] op_sel_hi:[1,0,1]
	v_mul_f32_e32 v71, v68, v69
	v_mul_f32_e32 v72, 0xbfb8aa3b, v65
	v_exp_f32_e32 v72, v72
	v_mov_b32_e32 v69, v74
	v_mov_b32_e32 v74, v67
	v_add_f32_e32 v68, 1.0, v72
	v_rcp_f32_e32 v72, v68
	v_mov_b32_e32 v68, v66
	v_pk_fma_f32 v[68:69], v[142:143], v[82:83], v[68:69] op_sel_hi:[1,0,1] neg_lo:[1,0,0] neg_hi:[1,0,0]
	v_mul_f32_e32 v65, v65, v72
	v_pk_fma_f32 v[68:69], v[68:69], v[92:93], v[162:163] op_sel_hi:[1,0,1]
	v_mul_f32_e32 v65, v64, v65
	v_mul_f32_e32 v66, 0xbfb8aa3b, v69
	v_exp_f32_e32 v73, v66
	v_pk_fma_f32 v[66:67], v[86:87], v[82:83], v[74:75] op_sel_hi:[1,0,1] neg_lo:[1,0,0] neg_hi:[1,0,0]
	v_add_f32_e32 v72, 1.0, v73
	v_pk_fma_f32 v[66:67], v[66:67], v[92:93], v[90:91] op_sel_hi:[1,0,1]
	v_rcp_f32_e32 v72, v72
	v_mul_f32_e32 v74, 0xbfb8aa3b, v67
	v_exp_f32_e32 v74, v74
	v_mul_f32_e32 v64, v69, v72
	v_mul_f32_e32 v68, v68, v64
	v_add_f32_e32 v73, 1.0, v74
	v_rcp_f32_e32 v73, v73
	v_med3_f32 v69, v79, s62, v173
	v_mul_f32_e32 v64, v67, v73
	v_mul_f32_e32 v66, v66, v64
	v_med3_f32 v67, v81, s62, v173
	v_cvt_pk_fp8_f32 v64, v67, v69
	v_med3_f32 v69, v70, s62, v173
	v_med3_f32 v70, v71, s62, v173
	v_med3_f32 v71, v65, s62, v173
	v_cvt_pk_fp8_f32 v65, v70, v71
	v_med3_f32 v67, v76, s62, v173
	v_cvt_pk_fp8_f32 v64, v67, v69 op_sel:[0,0,1]
	v_med3_f32 v67, v68, s62, v173
	v_med3_f32 v66, v66, s62, v173
	v_cvt_pk_fp8_f32 v65, v67, v66 op_sel:[0,0,1]
	v_mad_i64_i32 v[66:67], s[4:5], v80, s63, v[164:165]
	v_lshl_add_u64 v[66:67], v[66:67], 0, v[128:129]
	global_store_dwordx2 v[66:67], v[64:65], off
	v_add_u32_e32 v64, 0x80, v160
	v_ashrrev_i32_e32 v65, 31, v64
	v_lshl_add_u64 v[66:67], v[64:65], 3, s[14:15]
	v_mov_b32_e32 v66, v232
	v_mov_b32_e32 v67, v233
	v_pk_mul_f32 v[66:67], v[66:67], s[26:27] op_sel_hi:[1,0]
	s_nop 0
	v_fma_f32 v65, -v66, v66, v67
	v_add_f32_e32 v65, 0x3727c5ac, v65
	v_rsq_f32_e32 v242, v65
	s_nop 1
	s_nop 0
	s_nop 0
	s_nop 1
	s_nop 1
	s_nop 0
	v_mov_b32_e32 v70, v52
	v_mov_b32_e32 v71, v60
	v_mov_b32_e32 v68, v242
	v_pk_fma_f32 v[70:71], v[136:137], v[66:67], v[70:71] op_sel_hi:[1,0,1] neg_lo:[1,0,0] neg_hi:[1,0,0]
	v_mov_b32_e32 v60, v53
	v_pk_fma_f32 v[70:71], v[70:71], v[68:69], v[134:135] op_sel_hi:[1,0,1]
	s_nop 0
	v_mul_f32_e32 v52, 0xbfb8aa3b, v71
	v_exp_f32_e32 v65, v52
	v_pk_fma_f32 v[52:53], v[96:97], v[66:67], v[60:61] op_sel_hi:[1,0,1] neg_lo:[1,0,0] neg_hi:[1,0,0]
	v_add_f32_e32 v61, 1.0, v65
	v_pk_fma_f32 v[52:53], v[52:53], v[68:69], v[100:101] op_sel_hi:[1,0,1]
	v_rcp_f32_e32 v61, v61
	v_mul_f32_e32 v60, 0xbfb8aa3b, v53
	v_exp_f32_e32 v60, v60
	v_mul_f32_e32 v61, v71, v61
	v_mul_f32_e32 v65, v70, v61
	v_add_f32_e32 v60, 1.0, v60
	v_rcp_f32_e32 v60, v60
	v_mov_b32_e32 v61, v62
	v_mov_b32_e32 v62, v55
	v_mul_f32_e32 v53, v53, v60
	v_mov_b32_e32 v60, v54
	v_pk_fma_f32 v[60:61], v[132:133], v[66:67], v[60:61] op_sel_hi:[1,0,1] neg_lo:[1,0,0] neg_hi:[1,0,0]
	s_nop 0
	v_pk_fma_f32 v[60:61], v[60:61], v[68:69], v[130:131] op_sel_hi:[1,0,1]
	s_nop 0
	v_mul_f32_e32 v54, 0xbfb8aa3b, v61
	v_exp_f32_e32 v69, v54
	v_pk_fma_f32 v[54:55], v[98:99], v[66:67], v[62:63] op_sel_hi:[1,0,1] neg_lo:[1,0,0] neg_hi:[1,0,0]
	v_mul_f32_e32 v63, v52, v53
	v_mov_b32_e32 v53, v56
; __device__ __forceinline__ float clamp448(float x) { return __builtin_amdgcn_fmed3f(x, -448.0f, 448.0f); }
; __device__ __forceinline__ u32x4 pack8bf(const f32x4 a, const f32x4 b) { u32x4 w; w.x = cvt_pk_bf16(a[0], a[1]); w.y = cvt_pk_bf16(a[2], a[3]); w.z = cvt_pk_bf16(b[0], b[1]); w.w = cvt_pk_bf16(b[2], b[3]); return w; }
; __device__ __forceinline__ void ln_stats(const float* st, int row, float& mu, float& rs) { const f32x2 s = *(const f32x2*)(st + 2 * (size_t)row); mu = s[0] * (1.0f / DM); rs = 1.0f / sqrtf(s[1] * (1.0f / DM) - mu * mu + LN_EPS); }
; __device__ __forceinline__ u32x2 pack8fp8(const f32x4 a, const f32x4 b) {
;     int lo = __builtin_amdgcn_cvt_pk_fp8_f32(clamp448(a[0]), clamp448(a[1]), 0, false); lo = __builtin_amdgcn_cvt_pk_fp8_f32(clamp448(a[2]), clamp448(a[3]), lo, true);
;     int hi = __builtin_amdgcn_cvt_pk_fp8_f32(clamp448(b[0]), clamp448(b[1]), 0, false); hi = __builtin_amdgcn_cvt_pk_fp8_f32(clamp448(b[2]), clamp448(b[3]), hi, true);
;     return (u32x2){(unsigned)lo, (unsigned)hi}; }
;     __device__ __forceinline__ void operator()(EPI_ARGS) const {
;     ...
;             for (int m = 0; m < 4; ++m) { const int row = row0 + ai * HALF + m * 16; f32x4 r[2];
;                 float mu = 0.f, rs = 1.f; if constexpr (FOLD) ln_stats(st, row, mu, rs);
; #pragma unroll
;                 for (int n = 0; n < 2; ++n) { f32x4 g = acc[ai][0][m][n], up = acc[ai][1][m][n];
;                     if constexpr (!PRE) { g = g * ascale; up = up * ascale; }
;                     if constexpr (FOLD) { g = (g - cg[n] * mu) * rs + dg[n]; up = (up - cu[n] * mu) * rs + du[n]; }
;                     if constexpr (!PRE) up = up * oscale;
; #pragma unroll
;                     for (int j = 0; j < 4; ++j) { const float e = __builtin_amdgcn_exp2f(g[j] * -1.4426950408889634f); r[n][j] = g[j] * __builtin_amdgcn_rcpf(1.0f + e) * up[j]; } }
;                 if constexpr (F8OUT) *(u32x2*)((unsigned char*)O + (size_t)row * ldc + col0) = pack8fp8(r[0], r[1]);
;                 else *(u32x4*)((bf16_t*)O + (size_t)row * ldc + col0) = pack8bf(r[0], r[1]); }
	v_pk_fma_f32 v[54:55], v[54:55], v[68:69], v[102:103] op_sel_hi:[1,0,1]
	v_add_f32_e32 v52, 1.0, v69
	v_mul_f32_e32 v62, 0xbfb8aa3b, v55
	v_exp_f32_e32 v62, v62
	v_rcp_f32_e32 v69, v52
	v_add_f32_e32 v52, 1.0, v62
	v_rcp_f32_e32 v62, v52
	v_mov_b32_e32 v52, v48
	v_pk_fma_f32 v[52:53], v[138:139], v[66:67], v[52:53] op_sel_hi:[1,0,1] neg_lo:[1,0,0] neg_hi:[1,0,0]
	v_mul_f32_e32 v56, v61, v69
	v_pk_fma_f32 v[52:53], v[52:53], v[68:69], v[140:141] op_sel_hi:[1,0,1]
	v_mul_f32_e32 v60, v60, v56
	v_mul_f32_e32 v48, 0xbfb8aa3b, v53
	v_exp_f32_e32 v48, v48
	v_mov_b32_e32 v56, v49
	v_mul_f32_e32 v55, v55, v62
	v_mul_f32_e32 v54, v54, v55
	v_add_f32_e32 v48, 1.0, v48
	v_rcp_f32_e32 v61, v48
	v_pk_fma_f32 v[48:49], v[84:85], v[66:67], v[56:57] op_sel_hi:[1,0,1] neg_lo:[1,0,0] neg_hi:[1,0,0]
	v_mul_f32_e32 v53, v53, v61
	v_pk_fma_f32 v[48:49], v[48:49], v[68:69], v[88:89] op_sel_hi:[1,0,1]
	v_mul_f32_e32 v55, v52, v53
	v_mul_f32_e32 v56, 0xbfb8aa3b, v49
	v_exp_f32_e32 v56, v56
	v_mov_b32_e32 v53, v58
	v_mov_b32_e32 v58, v51
	v_add_f32_e32 v52, 1.0, v56
	v_rcp_f32_e32 v56, v52
	v_mov_b32_e32 v52, v50
	v_pk_fma_f32 v[52:53], v[142:143], v[66:67], v[52:53] op_sel_hi:[1,0,1] neg_lo:[1,0,0] neg_hi:[1,0,0]
	v_mul_f32_e32 v49, v49, v56
	v_pk_fma_f32 v[52:53], v[52:53], v[68:69], v[162:163] op_sel_hi:[1,0,1]
	v_mul_f32_e32 v49, v48, v49
	v_mul_f32_e32 v50, 0xbfb8aa3b, v53
	v_exp_f32_e32 v57, v50
	v_pk_fma_f32 v[50:51], v[86:87], v[66:67], v[58:59] op_sel_hi:[1,0,1] neg_lo:[1,0,0] neg_hi:[1,0,0]
	v_add_f32_e32 v56, 1.0, v57
	v_pk_fma_f32 v[50:51], v[50:51], v[68:69], v[90:91] op_sel_hi:[1,0,1]
	v_rcp_f32_e32 v56, v56
	v_mul_f32_e32 v58, 0xbfb8aa3b, v51
	v_exp_f32_e32 v58, v58
	v_mul_f32_e32 v48, v53, v56
	v_mul_f32_e32 v52, v52, v48
	v_add_f32_e32 v57, 1.0, v58
	v_rcp_f32_e32 v57, v57
	v_med3_f32 v53, v63, s62, v173
	v_mul_f32_e32 v48, v51, v57
	v_mul_f32_e32 v50, v50, v48
	v_med3_f32 v51, v65, s62, v173
	v_cvt_pk_fp8_f32 v48, v51, v53
	v_med3_f32 v53, v54, s62, v173
	v_med3_f32 v54, v55, s62, v173
	v_med3_f32 v55, v49, s62, v173
	v_cvt_pk_fp8_f32 v49, v54, v55
	v_med3_f32 v51, v60, s62, v173
	v_cvt_pk_fp8_f32 v48, v51, v53 op_sel:[0,0,1]
	v_med3_f32 v51, v52, s62, v173
	v_med3_f32 v50, v50, s62, v173
	v_cvt_pk_fp8_f32 v49, v51, v50 op_sel:[0,0,1]
	v_mad_i64_i32 v[50:51], s[4:5], v64, s63, v[164:165]
	v_lshl_add_u64 v[50:51], v[50:51], 0, v[128:129]
	global_store_dwordx2 v[50:51], v[48:49], off
	v_add_u32_e32 v48, 0x90, v160
	v_ashrrev_i32_e32 v49, 31, v48
	v_lshl_add_u64 v[50:51], v[48:49], 3, s[14:15]
	v_mov_b32_e32 v50, v234
	v_mov_b32_e32 v51, v235
	v_pk_mul_f32 v[50:51], v[50:51], s[26:27] op_sel_hi:[1,0]
	s_nop 0
	v_fma_f32 v49, -v50, v50, v51
	v_add_f32_e32 v49, 0x3727c5ac, v49
	v_rsq_f32_e32 v242, v49
	s_nop 1
	s_nop 0
	s_nop 0
	s_nop 1
	s_nop 1
	s_nop 0
	v_mov_b32_e32 v54, v36
	v_mov_b32_e32 v55, v44
	v_mov_b32_e32 v52, v242
	v_pk_fma_f32 v[54:55], v[136:137], v[50:51], v[54:55] op_sel_hi:[1,0,1] neg_lo:[1,0,0] neg_hi:[1,0,0]
	v_mov_b32_e32 v44, v37
	v_pk_fma_f32 v[54:55], v[54:55], v[52:53], v[134:135] op_sel_hi:[1,0,1]
	s_nop 0
	v_mul_f32_e32 v36, 0xbfb8aa3b, v55
	v_exp_f32_e32 v49, v36
	v_pk_fma_f32 v[36:37], v[96:97], v[50:51], v[44:45] op_sel_hi:[1,0,1] neg_lo:[1,0,0] neg_hi:[1,0,0]
	v_add_f32_e32 v45, 1.0, v49
	v_pk_fma_f32 v[36:37], v[36:37], v[52:53], v[100:101] op_sel_hi:[1,0,1]
	v_rcp_f32_e32 v45, v45
	v_mul_f32_e32 v44, 0xbfb8aa3b, v37
	v_exp_f32_e32 v44, v44
	v_mul_f32_e32 v45, v55, v45
	v_mul_f32_e32 v49, v54, v45
	v_add_f32_e32 v44, 1.0, v44
	v_rcp_f32_e32 v44, v44
	v_mov_b32_e32 v45, v46
	v_mov_b32_e32 v46, v39
	v_mul_f32_e32 v37, v37, v44
	v_mov_b32_e32 v44, v38
	v_pk_fma_f32 v[44:45], v[132:133], v[50:51], v[44:45] op_sel_hi:[1,0,1] neg_lo:[1,0,0] neg_hi:[1,0,0]
	s_nop 0
	v_pk_fma_f32 v[44:45], v[44:45], v[52:53], v[130:131] op_sel_hi:[1,0,1]
	s_nop 0
	v_mul_f32_e32 v38, 0xbfb8aa3b, v45
	v_exp_f32_e32 v53, v38
	v_pk_fma_f32 v[38:39], v[98:99], v[50:51], v[46:47] op_sel_hi:[1,0,1] neg_lo:[1,0,0] neg_hi:[1,0,0]
	v_mul_f32_e32 v47, v36, v37
	v_mov_b32_e32 v37, v40
	v_pk_fma_f32 v[38:39], v[38:39], v[52:53], v[102:103] op_sel_hi:[1,0,1]
	v_add_f32_e32 v36, 1.0, v53
	v_mul_f32_e32 v46, 0xbfb8aa3b, v39
	v_exp_f32_e32 v46, v46
	v_rcp_f32_e32 v53, v36
	v_add_f32_e32 v36, 1.0, v46
	v_rcp_f32_e32 v46, v36
	v_mov_b32_e32 v36, v32
	v_pk_fma_f32 v[36:37], v[138:139], v[50:51], v[36:37] op_sel_hi:[1,0,1] neg_lo:[1,0,0] neg_hi:[1,0,0]
	v_mul_f32_e32 v40, v45, v53
	v_pk_fma_f32 v[36:37], v[36:37], v[52:53], v[140:141] op_sel_hi:[1,0,1]
	v_mul_f32_e32 v44, v44, v40
	v_mul_f32_e32 v32, 0xbfb8aa3b, v37
	v_exp_f32_e32 v32, v32
	v_mov_b32_e32 v40, v33
	v_mul_f32_e32 v39, v39, v46
	v_mul_f32_e32 v38, v38, v39
	v_add_f32_e32 v32, 1.0, v32
	v_rcp_f32_e32 v45, v32
	v_pk_fma_f32 v[32:33], v[84:85], v[50:51], v[40:41] op_sel_hi:[1,0,1] neg_lo:[1,0,0] neg_hi:[1,0,0]
	v_mul_f32_e32 v37, v37, v45
	v_pk_fma_f32 v[32:33], v[32:33], v[52:53], v[88:89] op_sel_hi:[1,0,1]
	v_mul_f32_e32 v39, v36, v37
	v_mul_f32_e32 v40, 0xbfb8aa3b, v33
	v_exp_f32_e32 v40, v40
	v_mov_b32_e32 v37, v42
	v_mov_b32_e32 v42, v35
	v_add_f32_e32 v36, 1.0, v40
	v_rcp_f32_e32 v40, v36
	v_mov_b32_e32 v36, v34
	v_pk_fma_f32 v[36:37], v[142:143], v[50:51], v[36:37] op_sel_hi:[1,0,1] neg_lo:[1,0,0] neg_hi:[1,0,0]
	v_mul_f32_e32 v33, v33, v40
	v_pk_fma_f32 v[36:37], v[36:37], v[52:53], v[162:163] op_sel_hi:[1,0,1]
	v_mul_f32_e32 v33, v32, v33
	v_mul_f32_e32 v34, 0xbfb8aa3b, v37
	v_exp_f32_e32 v41, v34
	v_pk_fma_f32 v[34:35], v[86:87], v[50:51], v[42:43] op_sel_hi:[1,0,1] neg_lo:[1,0,0] neg_hi:[1,0,0]
	v_add_f32_e32 v40, 1.0, v41
	v_pk_fma_f32 v[34:35], v[34:35], v[52:53], v[90:91] op_sel_hi:[1,0,1]
; __device__ __forceinline__ float clamp448(float x) { return __builtin_amdgcn_fmed3f(x, -448.0f, 448.0f); }
; __device__ __forceinline__ u32x4 pack8bf(const f32x4 a, const f32x4 b) { u32x4 w; w.x = cvt_pk_bf16(a[0], a[1]); w.y = cvt_pk_bf16(a[2], a[3]); w.z = cvt_pk_bf16(b[0], b[1]); w.w = cvt_pk_bf16(b[2], b[3]); return w; }
; __device__ __forceinline__ void ln_stats(const float* st, int row, float& mu, float& rs) { const f32x2 s = *(const f32x2*)(st + 2 * (size_t)row); mu = s[0] * (1.0f / DM); rs = 1.0f / sqrtf(s[1] * (1.0f / DM) - mu * mu + LN_EPS); }
; __device__ __forceinline__ u32x2 pack8fp8(const f32x4 a, const f32x4 b) {
;     int lo = __builtin_amdgcn_cvt_pk_fp8_f32(clamp448(a[0]), clamp448(a[1]), 0, false); lo = __builtin_amdgcn_cvt_pk_fp8_f32(clamp448(a[2]), clamp448(a[3]), lo, true);
;     int hi = __builtin_amdgcn_cvt_pk_fp8_f32(clamp448(b[0]), clamp448(b[1]), 0, false); hi = __builtin_amdgcn_cvt_pk_fp8_f32(clamp448(b[2]), clamp448(b[3]), hi, true);
;     return (u32x2){(unsigned)lo, (unsigned)hi}; }
;     __device__ __forceinline__ void operator()(EPI_ARGS) const {
;     ...
;             for (int m = 0; m < 4; ++m) { const int row = row0 + ai * HALF + m * 16; f32x4 r[2];
;                 float mu = 0.f, rs = 1.f; if constexpr (FOLD) ln_stats(st, row, mu, rs);
; #pragma unroll
;                 for (int n = 0; n < 2; ++n) { f32x4 g = acc[ai][0][m][n], up = acc[ai][1][m][n];
;                     if constexpr (!PRE) { g = g * ascale; up = up * ascale; }
;                     if constexpr (FOLD) { g = (g - cg[n] * mu) * rs + dg[n]; up = (up - cu[n] * mu) * rs + du[n]; }
;                     if constexpr (!PRE) up = up * oscale;
; #pragma unroll
;                     for (int j = 0; j < 4; ++j) { const float e = __builtin_amdgcn_exp2f(g[j] * -1.4426950408889634f); r[n][j] = g[j] * __builtin_amdgcn_rcpf(1.0f + e) * up[j]; } }
;                 if constexpr (F8OUT) *(u32x2*)((unsigned char*)O + (size_t)row * ldc + col0) = pack8fp8(r[0], r[1]);
;                 else *(u32x4*)((bf16_t*)O + (size_t)row * ldc + col0) = pack8bf(r[0], r[1]); }
	v_rcp_f32_e32 v40, v40
	v_mul_f32_e32 v42, 0xbfb8aa3b, v35
	v_exp_f32_e32 v42, v42
	v_mul_f32_e32 v32, v37, v40
	v_mul_f32_e32 v36, v36, v32
	v_add_f32_e32 v41, 1.0, v42
	v_rcp_f32_e32 v41, v41
	v_med3_f32 v37, v47, s62, v173
	v_mul_f32_e32 v32, v35, v41
	v_mul_f32_e32 v34, v34, v32
	v_med3_f32 v35, v49, s62, v173
	v_cvt_pk_fp8_f32 v32, v35, v37
	v_med3_f32 v37, v38, s62, v173
	v_med3_f32 v38, v39, s62, v173
	v_med3_f32 v39, v33, s62, v173
	v_cvt_pk_fp8_f32 v33, v38, v39
	v_med3_f32 v35, v44, s62, v173
	v_cvt_pk_fp8_f32 v32, v35, v37 op_sel:[0,0,1]
	v_med3_f32 v35, v36, s62, v173
	v_med3_f32 v34, v34, s62, v173
	v_cvt_pk_fp8_f32 v33, v35, v34 op_sel:[0,0,1]
	v_mad_i64_i32 v[34:35], s[4:5], v48, s63, v[164:165]
	v_lshl_add_u64 v[34:35], v[34:35], 0, v[128:129]
	global_store_dwordx2 v[34:35], v[32:33], off
	v_add_u32_e32 v32, 0xa0, v160
	v_ashrrev_i32_e32 v33, 31, v32
	v_lshl_add_u64 v[34:35], v[32:33], 3, s[14:15]
	v_mov_b32_e32 v34, v236
	v_mov_b32_e32 v35, v237
	v_pk_mul_f32 v[34:35], v[34:35], s[26:27] op_sel_hi:[1,0]
	s_nop 0
	v_fma_f32 v33, -v34, v34, v35
	v_add_f32_e32 v33, 0x3727c5ac, v33
	v_rsq_f32_e32 v242, v33
	s_nop 1
	s_nop 0
	s_nop 0
	s_nop 1
	s_nop 1
	s_nop 0
	v_mov_b32_e32 v38, v20
	v_mov_b32_e32 v39, v28
	v_mov_b32_e32 v36, v242
	v_pk_fma_f32 v[38:39], v[136:137], v[34:35], v[38:39] op_sel_hi:[1,0,1] neg_lo:[1,0,0] neg_hi:[1,0,0]
	v_mov_b32_e32 v28, v21
	v_pk_fma_f32 v[38:39], v[38:39], v[36:37], v[134:135] op_sel_hi:[1,0,1]
	s_nop 0
	v_mul_f32_e32 v20, 0xbfb8aa3b, v39
	v_exp_f32_e32 v33, v20
	v_pk_fma_f32 v[20:21], v[96:97], v[34:35], v[28:29] op_sel_hi:[1,0,1] neg_lo:[1,0,0] neg_hi:[1,0,0]
	v_add_f32_e32 v29, 1.0, v33
	v_pk_fma_f32 v[20:21], v[20:21], v[36:37], v[100:101] op_sel_hi:[1,0,1]
	v_rcp_f32_e32 v29, v29
	v_mul_f32_e32 v28, 0xbfb8aa3b, v21
	v_exp_f32_e32 v28, v28
	v_mul_f32_e32 v29, v39, v29
	v_mul_f32_e32 v33, v38, v29
	v_add_f32_e32 v28, 1.0, v28
	v_rcp_f32_e32 v28, v28
	v_mov_b32_e32 v29, v30
	v_mov_b32_e32 v30, v23
	v_mul_f32_e32 v21, v21, v28
	v_mov_b32_e32 v28, v22
	v_pk_fma_f32 v[28:29], v[132:133], v[34:35], v[28:29] op_sel_hi:[1,0,1] neg_lo:[1,0,0] neg_hi:[1,0,0]
	s_nop 0
	v_pk_fma_f32 v[28:29], v[28:29], v[36:37], v[130:131] op_sel_hi:[1,0,1]
	s_nop 0
	v_mul_f32_e32 v22, 0xbfb8aa3b, v29
	v_exp_f32_e32 v37, v22
	v_pk_fma_f32 v[22:23], v[98:99], v[34:35], v[30:31] op_sel_hi:[1,0,1] neg_lo:[1,0,0] neg_hi:[1,0,0]
	v_mul_f32_e32 v31, v20, v21
	v_mov_b32_e32 v21, v24
	v_pk_fma_f32 v[22:23], v[22:23], v[36:37], v[102:103] op_sel_hi:[1,0,1]
	v_add_f32_e32 v20, 1.0, v37
	v_mul_f32_e32 v30, 0xbfb8aa3b, v23
	v_exp_f32_e32 v30, v30
	v_rcp_f32_e32 v37, v20
	v_add_f32_e32 v20, 1.0, v30
	v_rcp_f32_e32 v30, v20
	v_mov_b32_e32 v20, v16
	v_pk_fma_f32 v[20:21], v[138:139], v[34:35], v[20:21] op_sel_hi:[1,0,1] neg_lo:[1,0,0] neg_hi:[1,0,0]
	v_mul_f32_e32 v24, v29, v37
	v_pk_fma_f32 v[20:21], v[20:21], v[36:37], v[140:141] op_sel_hi:[1,0,1]
	v_mul_f32_e32 v28, v28, v24
	v_mul_f32_e32 v16, 0xbfb8aa3b, v21
	v_exp_f32_e32 v16, v16
	v_mov_b32_e32 v24, v17
	v_mul_f32_e32 v23, v23, v30
	v_mul_f32_e32 v22, v22, v23
	v_add_f32_e32 v16, 1.0, v16
	v_rcp_f32_e32 v29, v16
	v_pk_fma_f32 v[16:17], v[84:85], v[34:35], v[24:25] op_sel_hi:[1,0,1] neg_lo:[1,0,0] neg_hi:[1,0,0]
	v_mul_f32_e32 v21, v21, v29
	v_pk_fma_f32 v[16:17], v[16:17], v[36:37], v[88:89] op_sel_hi:[1,0,1]
	v_mul_f32_e32 v23, v20, v21
	v_mul_f32_e32 v24, 0xbfb8aa3b, v17
	v_exp_f32_e32 v24, v24
	v_mov_b32_e32 v21, v26
	v_mov_b32_e32 v26, v19
	v_add_f32_e32 v20, 1.0, v24
	v_rcp_f32_e32 v24, v20
	v_mov_b32_e32 v20, v18
	v_pk_fma_f32 v[20:21], v[142:143], v[34:35], v[20:21] op_sel_hi:[1,0,1] neg_lo:[1,0,0] neg_hi:[1,0,0]
	v_mul_f32_e32 v17, v17, v24
	v_pk_fma_f32 v[20:21], v[20:21], v[36:37], v[162:163] op_sel_hi:[1,0,1]
	v_mul_f32_e32 v17, v16, v17
	v_mul_f32_e32 v18, 0xbfb8aa3b, v21
	v_exp_f32_e32 v25, v18
	v_pk_fma_f32 v[18:19], v[86:87], v[34:35], v[26:27] op_sel_hi:[1,0,1] neg_lo:[1,0,0] neg_hi:[1,0,0]
	v_add_f32_e32 v24, 1.0, v25
	v_pk_fma_f32 v[18:19], v[18:19], v[36:37], v[90:91] op_sel_hi:[1,0,1]
	v_rcp_f32_e32 v24, v24
	v_mul_f32_e32 v26, 0xbfb8aa3b, v19
	v_exp_f32_e32 v26, v26
	v_mul_f32_e32 v16, v21, v24
	v_mul_f32_e32 v20, v20, v16
	v_add_f32_e32 v25, 1.0, v26
	v_rcp_f32_e32 v25, v25
	v_med3_f32 v21, v31, s62, v173
	v_mul_f32_e32 v16, v19, v25
	v_mul_f32_e32 v18, v18, v16
	v_med3_f32 v19, v33, s62, v173
	v_cvt_pk_fp8_f32 v16, v19, v21
	v_med3_f32 v21, v22, s62, v173
	v_med3_f32 v22, v23, s62, v173
; #define PG8_BAR __builtin_amdgcn_s_barrier()
; __device__ __forceinline__ u32x4 pack8bf(const f32x4 a, const f32x4 b) { u32x4 w; w.x = cvt_pk_bf16(a[0], a[1]); w.y = cvt_pk_bf16(a[2], a[3]); w.z = cvt_pk_bf16(b[0], b[1]); w.w = cvt_pk_bf16(b[2], b[3]); return w; }
; __device__ __forceinline__ void ln_stats(const float* st, int row, float& mu, float& rs) { const f32x2 s = *(const f32x2*)(st + 2 * (size_t)row); mu = s[0] * (1.0f / DM); rs = 1.0f / sqrtf(s[1] * (1.0f / DM) - mu * mu + LN_EPS); }
;     ...
;         if (wr == 0) PG8_BAR;
;         E(acc, cur, wr, wc, fr, fq);
;         if (!has_next) break;
; #pragma unroll
;         for (int a = 0; a < 2; ++a)
; #pragma unroll
;             for (int b = 0; b < 2; ++b)
; #pragma unroll
;                 for (int m = 0; m < 4; ++m)
; #pragma unroll
;                     for (int n = 0; n < 2; ++n) acc[a][b][m][n] = (f32x4){0.f, 0.f, 0.f, 0.f};
;         cur = nxt; cA = nA; cB = nB; ++ui;
;         if (wr == 1) PG8_BAR;
;     }
;     __device__ __forceinline__ void operator()(EPI_ARGS) const {
;     ...
;             for (int m = 0; m < 4; ++m) { const int row = row0 + ai * HALF + m * 16; f32x4 r[2];
;                 float mu = 0.f, rs = 1.f; if constexpr (FOLD) ln_stats(st, row, mu, rs);
; #pragma unroll
;                 for (int n = 0; n < 2; ++n) { f32x4 g = acc[ai][0][m][n], up = acc[ai][1][m][n];
;                     if constexpr (!PRE) { g = g * ascale; up = up * ascale; }
;                     if constexpr (FOLD) { g = (g - cg[n] * mu) * rs + dg[n]; up = (up - cu[n] * mu) * rs + du[n]; }
;                     if constexpr (!PRE) up = up * oscale;
; #pragma unroll
;                     for (int j = 0; j < 4; ++j) { const float e = __builtin_amdgcn_exp2f(g[j] * -1.4426950408889634f); r[n][j] = g[j] * __builtin_amdgcn_rcpf(1.0f + e) * up[j]; } }
;                 if constexpr (F8OUT) *(u32x2*)((unsigned char*)O + (size_t)row * ldc + col0) = pack8fp8(r[0], r[1]);
;                 else *(u32x4*)((bf16_t*)O + (size_t)row * ldc + col0) = pack8bf(r[0], r[1]); }
	v_med3_f32 v23, v17, s62, v173
	v_cvt_pk_fp8_f32 v17, v22, v23
	v_med3_f32 v19, v28, s62, v173
	v_cvt_pk_fp8_f32 v16, v19, v21 op_sel:[0,0,1]
	v_med3_f32 v19, v20, s62, v173
	v_med3_f32 v18, v18, s62, v173
	v_cvt_pk_fp8_f32 v17, v19, v18 op_sel:[0,0,1]
	v_mad_i64_i32 v[18:19], s[4:5], v32, s63, v[164:165]
	v_lshl_add_u64 v[18:19], v[18:19], 0, v[128:129]
	global_store_dwordx2 v[18:19], v[16:17], off
	v_add_u32_e32 v16, 0xb0, v160
	v_ashrrev_i32_e32 v17, 31, v16
	v_lshl_add_u64 v[18:19], v[16:17], 3, s[14:15]
	v_mov_b32_e32 v18, v238
	v_mov_b32_e32 v19, v239
	v_pk_mul_f32 v[18:19], v[18:19], s[26:27] op_sel_hi:[1,0]
	s_nop 0
	v_fma_f32 v17, -v18, v18, v19
	v_add_f32_e32 v17, 0x3727c5ac, v17
	v_rsq_f32_e32 v242, v17
	s_nop 1
	s_nop 0
	s_nop 0
	s_nop 1
	s_nop 1
	s_nop 0
	v_mov_b32_e32 v22, v4
	v_mov_b32_e32 v23, v12
	v_mov_b32_e32 v20, v242
	v_pk_fma_f32 v[22:23], v[136:137], v[18:19], v[22:23] op_sel_hi:[1,0,1] neg_lo:[1,0,0] neg_hi:[1,0,0]
	v_mov_b32_e32 v12, v5
	v_pk_fma_f32 v[22:23], v[22:23], v[20:21], v[134:135] op_sel_hi:[1,0,1]
	s_andn2_b64 vcc, exec, s[2:3]
	v_mul_f32_e32 v4, 0xbfb8aa3b, v23
	v_exp_f32_e32 v17, v4
	v_pk_fma_f32 v[4:5], v[96:97], v[18:19], v[12:13] op_sel_hi:[1,0,1] neg_lo:[1,0,0] neg_hi:[1,0,0]
	s_mov_b64 s[2:3], -1
	v_pk_fma_f32 v[4:5], v[4:5], v[20:21], v[100:101] op_sel_hi:[1,0,1]
	v_add_f32_e32 v13, 1.0, v17
	v_mul_f32_e32 v12, 0xbfb8aa3b, v5
	v_exp_f32_e32 v12, v12
	v_rcp_f32_e32 v13, v13
	v_add_f32_e32 v12, 1.0, v12
	v_rcp_f32_e32 v12, v12
	v_mul_f32_e32 v13, v23, v13
	v_mul_f32_e32 v17, v22, v13
	v_mov_b32_e32 v13, v14
	v_mul_f32_e32 v5, v5, v12
	v_mov_b32_e32 v12, v6
	v_pk_fma_f32 v[12:13], v[132:133], v[18:19], v[12:13] op_sel_hi:[1,0,1] neg_lo:[1,0,0] neg_hi:[1,0,0]
	v_mov_b32_e32 v14, v7
	v_pk_fma_f32 v[12:13], v[12:13], v[20:21], v[130:131] op_sel_hi:[1,0,1]
	s_nop 0
	v_mul_f32_e32 v6, 0xbfb8aa3b, v13
	v_exp_f32_e32 v21, v6
	v_pk_fma_f32 v[6:7], v[98:99], v[18:19], v[14:15] op_sel_hi:[1,0,1] neg_lo:[1,0,0] neg_hi:[1,0,0]
	v_mul_f32_e32 v15, v4, v5
	v_mov_b32_e32 v5, v8
	v_pk_fma_f32 v[6:7], v[6:7], v[20:21], v[102:103] op_sel_hi:[1,0,1]
	v_add_f32_e32 v4, 1.0, v21
	v_mul_f32_e32 v14, 0xbfb8aa3b, v7
	v_exp_f32_e32 v14, v14
	v_rcp_f32_e32 v21, v4
	v_add_f32_e32 v4, 1.0, v14
	v_rcp_f32_e32 v14, v4
	v_mov_b32_e32 v4, v0
	v_pk_fma_f32 v[4:5], v[138:139], v[18:19], v[4:5] op_sel_hi:[1,0,1] neg_lo:[1,0,0] neg_hi:[1,0,0]
	v_mul_f32_e32 v8, v13, v21
	v_pk_fma_f32 v[4:5], v[4:5], v[20:21], v[140:141] op_sel_hi:[1,0,1]
	v_mul_f32_e32 v12, v12, v8
	v_mul_f32_e32 v0, 0xbfb8aa3b, v5
	v_exp_f32_e32 v0, v0
	v_mov_b32_e32 v8, v1
	v_mul_f32_e32 v7, v7, v14
	v_mul_f32_e32 v6, v6, v7
	v_add_f32_e32 v0, 1.0, v0
	v_rcp_f32_e32 v13, v0
	v_pk_fma_f32 v[0:1], v[84:85], v[18:19], v[8:9] op_sel_hi:[1,0,1] neg_lo:[1,0,0] neg_hi:[1,0,0]
	v_mul_f32_e32 v5, v5, v13
	v_pk_fma_f32 v[0:1], v[0:1], v[20:21], v[88:89] op_sel_hi:[1,0,1]
	v_mul_f32_e32 v7, v4, v5
	v_mul_f32_e32 v8, 0xbfb8aa3b, v1
	v_exp_f32_e32 v8, v8
	v_mov_b32_e32 v5, v10
	v_mov_b32_e32 v10, v3
	v_add_f32_e32 v4, 1.0, v8
	v_rcp_f32_e32 v8, v4
	v_mov_b32_e32 v4, v2
	v_pk_fma_f32 v[4:5], v[142:143], v[18:19], v[4:5] op_sel_hi:[1,0,1] neg_lo:[1,0,0] neg_hi:[1,0,0]
	v_mul_f32_e32 v1, v1, v8
	v_pk_fma_f32 v[4:5], v[4:5], v[20:21], v[162:163] op_sel_hi:[1,0,1]
	v_mul_f32_e32 v1, v0, v1
	v_mul_f32_e32 v2, 0xbfb8aa3b, v5
	v_exp_f32_e32 v9, v2
	v_pk_fma_f32 v[2:3], v[86:87], v[18:19], v[10:11] op_sel_hi:[1,0,1] neg_lo:[1,0,0] neg_hi:[1,0,0]
	v_add_f32_e32 v8, 1.0, v9
	v_pk_fma_f32 v[2:3], v[2:3], v[20:21], v[90:91] op_sel_hi:[1,0,1]
	v_rcp_f32_e32 v8, v8
	v_mul_f32_e32 v10, 0xbfb8aa3b, v3
	v_exp_f32_e32 v10, v10
	v_mul_f32_e32 v0, v5, v8
	v_mul_f32_e32 v4, v4, v0
	v_add_f32_e32 v9, 1.0, v10
	v_rcp_f32_e32 v9, v9
	v_med3_f32 v5, v15, s62, v173
	v_mul_f32_e32 v0, v3, v9
	v_mul_f32_e32 v2, v2, v0
	v_med3_f32 v3, v17, s62, v173
	v_cvt_pk_fp8_f32 v0, v3, v5
	v_med3_f32 v5, v6, s62, v173
	v_med3_f32 v6, v7, s62, v173
	v_med3_f32 v7, v1, s62, v173
	v_cvt_pk_fp8_f32 v1, v6, v7
	v_med3_f32 v3, v12, s62, v173
	v_cvt_pk_fp8_f32 v0, v3, v5 op_sel:[0,0,1]
	v_med3_f32 v3, v4, s62, v173
	v_med3_f32 v2, v2, s62, v173
	v_cvt_pk_fp8_f32 v1, v3, v2 op_sel:[0,0,1]
	v_mad_i64_i32 v[2:3], s[4:5], v16, s63, v[164:165]
	v_lshl_add_u64 v[2:3], v[2:3], 0, v[128:129]
	global_store_dwordx2 v[2:3], v[0:1], off
	s_cbranch_vccnz .LBB0_3772
	s_andn2_b64 vcc, exec, s[6:7]
	s_cbranch_vccnz .LBB0_3771
	s_barrier
	s_branch .LBB0_3771

;     __device__ __forceinline__ float qscale(const Unit& u) const { return ((u.pn >= 8 && u.pn <= 11) || u.pn == 17) ? 0.5f : 1.0f; }
; __device__ __forceinline__ void ln_stats(const float* st, int row, float& mu, float& rs) { const f32x2 s = *(const f32x2*)(st + 2 * (size_t)row); mu = s[0] * (1.0f / DM); rs = 1.0f / sqrtf(s[1] * (1.0f / DM) - mu * mu + LN_EPS); }
;     ...
;         if constexpr (QM == 2) { const float qs0_ = g.qs * E.qscale(cur), qs1_ = qs0_ * g.qs_b1; _Pragma("unroll") for (int a = 0; a < 2; ++a) _Pragma("unroll") for (int b = 0; b < 2; ++b) _Pragma("unroll") for (int m = 0; m < 4; ++m) _Pragma("unroll") for (int n = 0; n < 2; ++n) { const v4i t_ = __builtin_bit_cast(v4i, acc[a][b][m][n]); acc[a][b][m][n] = (f32x4){(float)t_[0], (float)t_[1], (float)t_[2], (float)t_[3]} * (b == 0 ? qs0_ : qs1_); } }
;     __device__ __forceinline__ void operator()(EPI_ARGS) const {
;         if (wc >= 2) return;
;         const int row0 = u.pm * BM + wr * 64 + fr, n0 = 1024 + wc * 32 + 8 * fq, fi = 16 * wc + 4 * fq;
;         const f32x4 c0 = *(const f32x4*)(C + n0), c1 = *(const f32x4*)(C + n0 + 4), d0 = *(const f32x4*)(D + n0), d1 = *(const f32x4*)(D + n0 + 4);
; #pragma unroll
;         for (int ai = 0; ai < 2; ++ai)
; #pragma unroll
;             for (int m = 0; m < 4; ++m) { const int row = row0 + ai * HALF + m * 16; float mu, rs; ln_stats(st, row, mu, rs);
;                 const f32x4 c4 = *(const f32x4*)(cs + (size_t)row * 32 + fi), s4 = *(const f32x4*)(sn + (size_t)row * 32 + fi);
;                 const f32x4 v0 = (acc[ai][0][m][0] - c0 * mu) * rs + d0, v1 = (acc[ai][0][m][1] - c1 * mu) * rs + d1;
;                 *(u32x2*)((unsigned char*)KPE + (size_t)row * 64 + 32 * (fq & 1) + 8 * (2 * wc + (fq >> 1))) = pack8fp8(v0 * c4 - v1 * s4, v1 * c4 + v0 * s4); }
.LBB0_4117:
	v_lshl_add_u32 v102, s2, 8, v104
	v_ashrrev_i32_e32 v103, 31, v102
	v_lshl_add_u64 v[24:25], v[102:103], 3, s[12:13]
	global_load_dwordx2 v[118:119], v[24:25], off
	global_load_dwordx4 v[36:39], v[94:95], off
	global_load_dwordx4 v[32:35], v[94:95], off offset:16
	global_load_dwordx4 v[28:31], v[96:97], off
	s_nop 0
	global_load_dwordx4 v[24:27], v[96:97], off offset:16
	v_lshlrev_b64 v[114:115], 7, v[102:103]
	v_lshl_add_u64 v[110:111], v[90:91], 0, v[114:115]
	global_load_dwordx4 v[110:113], v[110:111], off
	v_lshl_add_u64 v[114:115], v[88:89], 0, v[114:115]
	global_load_dwordx4 v[114:117], v[114:115], off
	v_lshlrev_b64 v[124:125], 6, v[102:103]
	v_cvt_f32_i32_e32 v73, v73
	v_cvt_f32_i32_e32 v72, v72
	v_cvt_f32_i32_e32 v77, v77
	v_cvt_f32_i32_e32 v76, v76
	v_cvt_f32_i32_e32 v79, v79
	v_cvt_f32_i32_e32 v78, v78
	v_cvt_f32_i32_e32 v75, v75
	v_cvt_f32_i32_e32 v74, v74
	v_mov_b32_e32 v120, 0
	v_mov_b32_e32 v121, 0
	v_or_b32_e32 v122, 16, v102
	v_cvt_f32_i32_e32 v65, v65
	v_cvt_f32_i32_e32 v64, v64
	v_cvt_f32_i32_e32 v69, v69
	v_cvt_f32_i32_e32 v68, v68
	v_cvt_f32_i32_e32 v71, v71
	v_cvt_f32_i32_e32 v70, v70
	v_cvt_f32_i32_e32 v67, v67
	v_cvt_f32_i32_e32 v66, v66
	v_cvt_f32_i32_e32 v57, v57
	v_cvt_f32_i32_e32 v56, v56
	v_cvt_f32_i32_e32 v61, v61
	v_cvt_f32_i32_e32 v60, v60
	v_cvt_f32_i32_e32 v63, v63
	v_cvt_f32_i32_e32 v62, v62
	v_cvt_f32_i32_e32 v59, v59
	v_cvt_f32_i32_e32 v58, v58
	v_cvt_f32_i32_e32 v49, v49
	v_cvt_f32_i32_e32 v48, v48
	v_cvt_f32_i32_e32 v53, v53
	v_cvt_f32_i32_e32 v52, v52
	v_cvt_f32_i32_e32 v55, v55
	v_cvt_f32_i32_e32 v54, v54
	v_cvt_f32_i32_e32 v51, v51
	v_cvt_f32_i32_e32 v50, v50
	v_cvt_f32_i32_e32 v41, v41
	v_cvt_f32_i32_e32 v40, v40
	v_cvt_f32_i32_e32 v45, v45
	v_cvt_f32_i32_e32 v44, v44
	v_cvt_f32_i32_e32 v47, v47
	v_cvt_f32_i32_e32 v46, v46
	v_cvt_f32_i32_e32 v43, v43
	v_cvt_f32_i32_e32 v42, v42
	v_cvt_f32_i32_e32 v17, v17
	v_cvt_f32_i32_e32 v16, v16
	v_cvt_f32_i32_e32 v21, v21
	v_cvt_f32_i32_e32 v20, v20
	v_cvt_f32_i32_e32 v23, v23
	v_cvt_f32_i32_e32 v22, v22
	v_cvt_f32_i32_e32 v19, v19
	v_cvt_f32_i32_e32 v18, v18
	v_cvt_f32_i32_e32 v9, v9
	v_cvt_f32_i32_e32 v8, v8
	v_cvt_f32_i32_e32 v13, v13
	v_cvt_f32_i32_e32 v12, v12
	v_cvt_f32_i32_e32 v15, v15
	v_cvt_f32_i32_e32 v14, v14
	v_cvt_f32_i32_e32 v11, v11
	v_cvt_f32_i32_e32 v10, v10
	v_cvt_f32_i32_e32 v1, v1
	v_cvt_f32_i32_e32 v0, v0
	v_cvt_f32_i32_e32 v5, v5
	v_cvt_f32_i32_e32 v4, v4
	v_cvt_f32_i32_e32 v7, v7
	v_cvt_f32_i32_e32 v6, v6
	v_cvt_f32_i32_e32 v3, v3
	v_cvt_f32_i32_e32 v2, v2
	s_waitcnt vmcnt(0)
	v_pk_mul_f32 v[118:119], v[118:119], s[16:17] op_sel_hi:[1,0]
	s_nop 0
	v_fma_f32 v103, -v118, v118, v119
	v_add_f32_e32 v103, 0x3727c5ac, v103
	v_rsq_f32_e32 v254, v103
	v_pk_mul_f32 v[126:127], v[36:37], v[118:119] op_sel_hi:[1,0]
	v_pk_mul_f32 v[128:129], v[38:39], v[118:119] op_sel_hi:[1,0]
	v_pk_mul_f32 v[130:131], v[34:35], v[118:119] op_sel_hi:[1,0]
	v_pk_mul_f32 v[118:119], v[32:33], v[118:119] op_sel_hi:[1,0]
	v_pk_fma_f32 v[76:77], v[76:77], s[18:19], v[126:127] op_sel_hi:[1,0,1] neg_lo:[0,0,1] neg_hi:[0,0,1]
	v_pk_fma_f32 v[72:73], v[72:73], s[18:19], v[118:119] op_sel_hi:[1,0,1] neg_lo:[0,0,1] neg_hi:[0,0,1]
	v_pk_fma_f32 v[78:79], v[78:79], s[18:19], v[128:129] op_sel_hi:[1,0,1] neg_lo:[0,0,1] neg_hi:[0,0,1]
	v_pk_fma_f32 v[74:75], v[74:75], s[18:19], v[130:131] op_sel_hi:[1,0,1] neg_lo:[0,0,1] neg_hi:[0,0,1]
	s_nop 1
	s_nop 1
	v_mov_b32_e32 v118, v254
	v_pk_fma_f32 v[76:77], v[76:77], v[118:119], v[28:29] op_sel_hi:[1,0,1]
	v_pk_fma_f32 v[72:73], v[72:73], v[118:119], v[24:25] op_sel_hi:[1,0,1]
	v_pk_fma_f32 v[78:79], v[78:79], v[118:119], v[30:31] op_sel_hi:[1,0,1]
	v_pk_fma_f32 v[74:75], v[74:75], v[118:119], v[26:27] op_sel_hi:[1,0,1]
	v_pk_mul_f32 v[118:119], v[110:111], v[72:73]
	v_pk_mul_f32 v[110:111], v[110:111], v[76:77]
	v_pk_fma_f32 v[76:77], v[114:115], v[76:77], v[118:119] neg_lo:[0,0,1] neg_hi:[0,0,1]
	v_pk_fma_f32 v[72:73], v[114:115], v[72:73], v[110:111]
	v_med3_f32 v76, v76, s61, v109
	v_med3_f32 v77, v77, s61, v109
	v_med3_f32 v72, v72, s61, v109
	v_med3_f32 v73, v73, s61, v109
	v_cvt_pk_fp8_f32 v120, v76, v77
	v_cvt_pk_fp8_f32 v121, v72, v73
	v_pk_mul_f32 v[126:127], v[112:113], v[74:75]
	v_pk_mul_f32 v[112:113], v[112:113], v[78:79]
	v_pk_fma_f32 v[78:79], v[116:117], v[78:79], v[126:127] neg_lo:[0,0,1] neg_hi:[0,0,1]
	v_pk_fma_f32 v[74:75], v[116:117], v[74:75], v[112:113]
	v_med3_f32 v78, v78, s61, v109
	v_med3_f32 v79, v79, s61, v109
	v_med3_f32 v72, v74, s61, v109
	v_med3_f32 v73, v75, s61, v109
	v_cvt_pk_fp8_f32 v120, v78, v79 op_sel:[0,0,1]
	v_cvt_pk_fp8_f32 v121, v72, v73 op_sel:[0,0,1]
	v_ashrrev_i32_e32 v123, 31, v122
	v_lshl_add_u64 v[72:73], v[92:93], 0, v[124:125]
	v_lshl_add_u64 v[74:75], v[122:123], 3, s[12:13]
	global_store_dwordx2 v[72:73], v[120:121], off
	global_load_dwordx2 v[110:111], v[74:75], off
	v_lshlrev_b64 v[76:77], 7, v[122:123]
	v_lshl_add_u64 v[72:73], v[90:91], 0, v[76:77]
	global_load_dwordx4 v[72:75], v[72:73], off
	v_lshl_add_u64 v[76:77], v[88:89], 0, v[76:77]
	global_load_dwordx4 v[76:79], v[76:77], off
	v_or_b32_e32 v114, 32, v102
	v_ashrrev_i32_e32 v115, 31, v114
	s_waitcnt vmcnt(2)
; __device__ __forceinline__ void ln_stats(const float* st, int row, float& mu, float& rs) { const f32x2 s = *(const f32x2*)(st + 2 * (size_t)row); mu = s[0] * (1.0f / DM); rs = 1.0f / sqrtf(s[1] * (1.0f / DM) - mu * mu + LN_EPS); }
;     __device__ __forceinline__ void operator()(EPI_ARGS) const {
;         if (wc >= 2) return;
;         const int row0 = u.pm * BM + wr * 64 + fr, n0 = 1024 + wc * 32 + 8 * fq, fi = 16 * wc + 4 * fq;
;         const f32x4 c0 = *(const f32x4*)(C + n0), c1 = *(const f32x4*)(C + n0 + 4), d0 = *(const f32x4*)(D + n0), d1 = *(const f32x4*)(D + n0 + 4);
; #pragma unroll
;         for (int ai = 0; ai < 2; ++ai)
; #pragma unroll
;             for (int m = 0; m < 4; ++m) { const int row = row0 + ai * HALF + m * 16; float mu, rs; ln_stats(st, row, mu, rs);
;                 const f32x4 c4 = *(const f32x4*)(cs + (size_t)row * 32 + fi), s4 = *(const f32x4*)(sn + (size_t)row * 32 + fi);
;                 const f32x4 v0 = (acc[ai][0][m][0] - c0 * mu) * rs + d0, v1 = (acc[ai][0][m][1] - c1 * mu) * rs + d1;
;                 *(u32x2*)((unsigned char*)KPE + (size_t)row * 64 + 32 * (fq & 1) + 8 * (2 * wc + (fq >> 1))) = pack8fp8(v0 * c4 - v1 * s4, v1 * c4 + v0 * s4); }
	v_pk_mul_f32 v[110:111], v[110:111], s[16:17] op_sel_hi:[1,0]
	s_nop 0
	v_fma_f32 v103, -v110, v110, v111
	v_add_f32_e32 v103, 0x3727c5ac, v103
	v_rsq_f32_e32 v254, v103
	v_pk_mul_f32 v[116:117], v[36:37], v[110:111] op_sel_hi:[1,0]
	v_pk_mul_f32 v[118:119], v[38:39], v[110:111] op_sel_hi:[1,0]
	v_pk_mul_f32 v[120:121], v[34:35], v[110:111] op_sel_hi:[1,0]
	v_pk_mul_f32 v[110:111], v[32:33], v[110:111] op_sel_hi:[1,0]
	v_pk_fma_f32 v[68:69], v[68:69], s[18:19], v[116:117] op_sel_hi:[1,0,1] neg_lo:[0,0,1] neg_hi:[0,0,1]
	v_pk_fma_f32 v[64:65], v[64:65], s[18:19], v[110:111] op_sel_hi:[1,0,1] neg_lo:[0,0,1] neg_hi:[0,0,1]
	v_pk_fma_f32 v[70:71], v[70:71], s[18:19], v[118:119] op_sel_hi:[1,0,1] neg_lo:[0,0,1] neg_hi:[0,0,1]
	v_pk_fma_f32 v[66:67], v[66:67], s[18:19], v[120:121] op_sel_hi:[1,0,1] neg_lo:[0,0,1] neg_hi:[0,0,1]
	s_nop 1
	s_nop 1
	v_mov_b32_e32 v110, v254
	v_pk_fma_f32 v[68:69], v[68:69], v[110:111], v[28:29] op_sel_hi:[1,0,1]
	v_pk_fma_f32 v[64:65], v[64:65], v[110:111], v[24:25] op_sel_hi:[1,0,1]
	v_pk_fma_f32 v[70:71], v[70:71], v[110:111], v[30:31] op_sel_hi:[1,0,1]
	v_pk_fma_f32 v[66:67], v[66:67], v[110:111], v[26:27] op_sel_hi:[1,0,1]
	s_waitcnt vmcnt(1)
	v_pk_mul_f32 v[110:111], v[72:73], v[64:65]
	v_pk_mul_f32 v[72:73], v[72:73], v[68:69]
	s_waitcnt vmcnt(0)
	v_pk_fma_f32 v[68:69], v[76:77], v[68:69], v[110:111] neg_lo:[0,0,1] neg_hi:[0,0,1]
	v_pk_fma_f32 v[64:65], v[76:77], v[64:65], v[72:73]
	v_med3_f32 v68, v68, s61, v109
	v_med3_f32 v69, v69, s61, v109
	v_med3_f32 v64, v64, s61, v109
	v_med3_f32 v65, v65, s61, v109
	v_cvt_pk_fp8_f32 v112, v68, v69
	v_cvt_pk_fp8_f32 v113, v64, v65
	v_pk_mul_f32 v[116:117], v[74:75], v[66:67]
	v_pk_mul_f32 v[74:75], v[74:75], v[70:71]
	v_pk_fma_f32 v[70:71], v[78:79], v[70:71], v[116:117] neg_lo:[0,0,1] neg_hi:[0,0,1]
	v_pk_fma_f32 v[66:67], v[78:79], v[66:67], v[74:75]
	v_med3_f32 v70, v70, s61, v109
	v_med3_f32 v71, v71, s61, v109
	v_med3_f32 v64, v66, s61, v109
	v_med3_f32 v65, v67, s61, v109
	v_cvt_pk_fp8_f32 v112, v70, v71 op_sel:[0,0,1]
	v_cvt_pk_fp8_f32 v113, v64, v65 op_sel:[0,0,1]
	v_lshlrev_b64 v[64:65], 6, v[122:123]
	v_lshl_add_u64 v[64:65], v[92:93], 0, v[64:65]
	v_lshl_add_u64 v[66:67], v[114:115], 3, s[12:13]
	global_store_dwordx2 v[64:65], v[112:113], off
	global_load_dwordx2 v[72:73], v[66:67], off
	v_lshlrev_b64 v[68:69], 7, v[114:115]
	v_lshl_add_u64 v[64:65], v[90:91], 0, v[68:69]
	global_load_dwordx4 v[64:67], v[64:65], off
	v_lshl_add_u64 v[68:69], v[88:89], 0, v[68:69]
	global_load_dwordx4 v[68:71], v[68:69], off
	v_or_b32_e32 v76, 48, v102
	v_ashrrev_i32_e32 v77, 31, v76
	s_waitcnt vmcnt(2)
	v_pk_mul_f32 v[72:73], v[72:73], s[16:17] op_sel_hi:[1,0]
	s_nop 0
	v_fma_f32 v103, -v72, v72, v73
	v_add_f32_e32 v103, 0x3727c5ac, v103
	v_rsq_f32_e32 v254, v103
	v_pk_mul_f32 v[78:79], v[36:37], v[72:73] op_sel_hi:[1,0]
	v_pk_mul_f32 v[110:111], v[38:39], v[72:73] op_sel_hi:[1,0]
	v_pk_mul_f32 v[112:113], v[34:35], v[72:73] op_sel_hi:[1,0]
	v_pk_mul_f32 v[72:73], v[32:33], v[72:73] op_sel_hi:[1,0]
	v_pk_fma_f32 v[60:61], v[60:61], s[18:19], v[78:79] op_sel_hi:[1,0,1] neg_lo:[0,0,1] neg_hi:[0,0,1]
	v_pk_fma_f32 v[56:57], v[56:57], s[18:19], v[72:73] op_sel_hi:[1,0,1] neg_lo:[0,0,1] neg_hi:[0,0,1]
	v_pk_fma_f32 v[62:63], v[62:63], s[18:19], v[110:111] op_sel_hi:[1,0,1] neg_lo:[0,0,1] neg_hi:[0,0,1]
	v_pk_fma_f32 v[58:59], v[58:59], s[18:19], v[112:113] op_sel_hi:[1,0,1] neg_lo:[0,0,1] neg_hi:[0,0,1]
	s_nop 1
	s_nop 1
	v_mov_b32_e32 v72, v254
	v_pk_fma_f32 v[60:61], v[60:61], v[72:73], v[28:29] op_sel_hi:[1,0,1]
	v_pk_fma_f32 v[56:57], v[56:57], v[72:73], v[24:25] op_sel_hi:[1,0,1]
	v_pk_fma_f32 v[62:63], v[62:63], v[72:73], v[30:31] op_sel_hi:[1,0,1]
	v_pk_fma_f32 v[58:59], v[58:59], v[72:73], v[26:27] op_sel_hi:[1,0,1]
	s_waitcnt vmcnt(1)
	v_pk_mul_f32 v[72:73], v[64:65], v[56:57]
	v_pk_mul_f32 v[64:65], v[64:65], v[60:61]
	s_waitcnt vmcnt(0)
	v_pk_fma_f32 v[60:61], v[68:69], v[60:61], v[72:73] neg_lo:[0,0,1] neg_hi:[0,0,1]
	v_pk_fma_f32 v[56:57], v[68:69], v[56:57], v[64:65]
	v_med3_f32 v60, v60, s61, v109
	v_med3_f32 v61, v61, s61, v109
	v_med3_f32 v56, v56, s61, v109
	v_med3_f32 v57, v57, s61, v109
	v_cvt_pk_fp8_f32 v74, v60, v61
	v_cvt_pk_fp8_f32 v75, v56, v57
	v_pk_mul_f32 v[78:79], v[66:67], v[58:59]
	v_pk_mul_f32 v[66:67], v[66:67], v[62:63]
	v_pk_fma_f32 v[62:63], v[70:71], v[62:63], v[78:79] neg_lo:[0,0,1] neg_hi:[0,0,1]
	v_pk_fma_f32 v[58:59], v[70:71], v[58:59], v[66:67]
	v_med3_f32 v62, v62, s61, v109
	v_med3_f32 v63, v63, s61, v109
	v_med3_f32 v56, v58, s61, v109
	v_med3_f32 v57, v59, s61, v109
	v_cvt_pk_fp8_f32 v74, v62, v63 op_sel:[0,0,1]
	v_cvt_pk_fp8_f32 v75, v56, v57 op_sel:[0,0,1]
	v_lshlrev_b64 v[56:57], 6, v[114:115]
	v_lshl_add_u64 v[56:57], v[92:93], 0, v[56:57]
	v_lshl_add_u64 v[58:59], v[76:77], 3, s[12:13]
	global_store_dwordx2 v[56:57], v[74:75], off
	global_load_dwordx2 v[64:65], v[58:59], off
	v_lshlrev_b64 v[60:61], 7, v[76:77]
	v_lshl_add_u64 v[56:57], v[90:91], 0, v[60:61]
	global_load_dwordx4 v[56:59], v[56:57], off
	v_lshl_add_u64 v[60:61], v[88:89], 0, v[60:61]
	global_load_dwordx4 v[60:63], v[60:61], off
	v_add_u32_e32 v68, 0x80, v102
	v_ashrrev_i32_e32 v69, 31, v68
	s_waitcnt vmcnt(2)
; __device__ __forceinline__ void ln_stats(const float* st, int row, float& mu, float& rs) { const f32x2 s = *(const f32x2*)(st + 2 * (size_t)row); mu = s[0] * (1.0f / DM); rs = 1.0f / sqrtf(s[1] * (1.0f / DM) - mu * mu + LN_EPS); }
;     __device__ __forceinline__ void operator()(EPI_ARGS) const {
;         if (wc >= 2) return;
;         const int row0 = u.pm * BM + wr * 64 + fr, n0 = 1024 + wc * 32 + 8 * fq, fi = 16 * wc + 4 * fq;
;         const f32x4 c0 = *(const f32x4*)(C + n0), c1 = *(const f32x4*)(C + n0 + 4), d0 = *(const f32x4*)(D + n0), d1 = *(const f32x4*)(D + n0 + 4);
; #pragma unroll
;         for (int ai = 0; ai < 2; ++ai)
; #pragma unroll
;             for (int m = 0; m < 4; ++m) { const int row = row0 + ai * HALF + m * 16; float mu, rs; ln_stats(st, row, mu, rs);
;                 const f32x4 c4 = *(const f32x4*)(cs + (size_t)row * 32 + fi), s4 = *(const f32x4*)(sn + (size_t)row * 32 + fi);
;                 const f32x4 v0 = (acc[ai][0][m][0] - c0 * mu) * rs + d0, v1 = (acc[ai][0][m][1] - c1 * mu) * rs + d1;
;                 *(u32x2*)((unsigned char*)KPE + (size_t)row * 64 + 32 * (fq & 1) + 8 * (2 * wc + (fq >> 1))) = pack8fp8(v0 * c4 - v1 * s4, v1 * c4 + v0 * s4); }
	v_pk_mul_f32 v[64:65], v[64:65], s[16:17] op_sel_hi:[1,0]
	s_nop 0
	v_fma_f32 v78, -v64, v64, v65
	v_add_f32_e32 v78, 0x3727c5ac, v78
	v_rsq_f32_e32 v254, v78
	v_pk_mul_f32 v[70:71], v[36:37], v[64:65] op_sel_hi:[1,0]
	v_pk_mul_f32 v[72:73], v[38:39], v[64:65] op_sel_hi:[1,0]
	v_pk_mul_f32 v[74:75], v[34:35], v[64:65] op_sel_hi:[1,0]
	v_pk_mul_f32 v[64:65], v[32:33], v[64:65] op_sel_hi:[1,0]
	v_pk_fma_f32 v[52:53], v[52:53], s[18:19], v[70:71] op_sel_hi:[1,0,1] neg_lo:[0,0,1] neg_hi:[0,0,1]
	v_pk_fma_f32 v[48:49], v[48:49], s[18:19], v[64:65] op_sel_hi:[1,0,1] neg_lo:[0,0,1] neg_hi:[0,0,1]
	v_pk_fma_f32 v[54:55], v[54:55], s[18:19], v[72:73] op_sel_hi:[1,0,1] neg_lo:[0,0,1] neg_hi:[0,0,1]
	v_pk_fma_f32 v[50:51], v[50:51], s[18:19], v[74:75] op_sel_hi:[1,0,1] neg_lo:[0,0,1] neg_hi:[0,0,1]
	s_nop 1
	s_nop 1
	v_mov_b32_e32 v64, v254
	v_pk_fma_f32 v[52:53], v[52:53], v[64:65], v[28:29] op_sel_hi:[1,0,1]
	v_pk_fma_f32 v[48:49], v[48:49], v[64:65], v[24:25] op_sel_hi:[1,0,1]
	v_pk_fma_f32 v[54:55], v[54:55], v[64:65], v[30:31] op_sel_hi:[1,0,1]
	v_pk_fma_f32 v[50:51], v[50:51], v[64:65], v[26:27] op_sel_hi:[1,0,1]
	s_waitcnt vmcnt(1)
	v_pk_mul_f32 v[64:65], v[56:57], v[48:49]
	v_pk_mul_f32 v[56:57], v[56:57], v[52:53]
	s_waitcnt vmcnt(0)
	v_pk_fma_f32 v[52:53], v[60:61], v[52:53], v[64:65] neg_lo:[0,0,1] neg_hi:[0,0,1]
	v_pk_fma_f32 v[48:49], v[60:61], v[48:49], v[56:57]
	v_med3_f32 v52, v52, s61, v109
	v_med3_f32 v53, v53, s61, v109
	v_med3_f32 v48, v48, s61, v109
	v_med3_f32 v49, v49, s61, v109
	v_cvt_pk_fp8_f32 v66, v52, v53
	v_cvt_pk_fp8_f32 v67, v48, v49
	v_pk_mul_f32 v[70:71], v[58:59], v[50:51]
	v_pk_mul_f32 v[58:59], v[58:59], v[54:55]
	v_pk_fma_f32 v[54:55], v[62:63], v[54:55], v[70:71] neg_lo:[0,0,1] neg_hi:[0,0,1]
	v_pk_fma_f32 v[50:51], v[62:63], v[50:51], v[58:59]
	v_med3_f32 v54, v54, s61, v109
	v_med3_f32 v55, v55, s61, v109
	v_med3_f32 v48, v50, s61, v109
	v_med3_f32 v49, v51, s61, v109
	v_cvt_pk_fp8_f32 v66, v54, v55 op_sel:[0,0,1]
	v_cvt_pk_fp8_f32 v67, v48, v49 op_sel:[0,0,1]
	v_lshlrev_b64 v[48:49], 6, v[76:77]
	v_lshl_add_u64 v[48:49], v[92:93], 0, v[48:49]
	v_lshl_add_u64 v[50:51], v[68:69], 3, s[12:13]
	global_store_dwordx2 v[48:49], v[66:67], off
	global_load_dwordx2 v[56:57], v[50:51], off
	v_lshlrev_b64 v[52:53], 7, v[68:69]
	v_lshl_add_u64 v[48:49], v[90:91], 0, v[52:53]
	global_load_dwordx4 v[48:51], v[48:49], off
	v_lshl_add_u64 v[52:53], v[88:89], 0, v[52:53]
	global_load_dwordx4 v[52:55], v[52:53], off
	v_add_u32_e32 v60, 0x90, v102
	v_ashrrev_i32_e32 v61, 31, v60
	s_waitcnt vmcnt(2)
	v_pk_mul_f32 v[56:57], v[56:57], s[16:17] op_sel_hi:[1,0]
	s_nop 0
	v_fma_f32 v70, -v56, v56, v57
	v_add_f32_e32 v70, 0x3727c5ac, v70
	v_rsq_f32_e32 v254, v70
	v_pk_mul_f32 v[62:63], v[36:37], v[56:57] op_sel_hi:[1,0]
	v_pk_mul_f32 v[64:65], v[38:39], v[56:57] op_sel_hi:[1,0]
	v_pk_mul_f32 v[66:67], v[34:35], v[56:57] op_sel_hi:[1,0]
	v_pk_mul_f32 v[56:57], v[32:33], v[56:57] op_sel_hi:[1,0]
	v_pk_fma_f32 v[44:45], v[44:45], s[18:19], v[62:63] op_sel_hi:[1,0,1] neg_lo:[0,0,1] neg_hi:[0,0,1]
	v_pk_fma_f32 v[40:41], v[40:41], s[18:19], v[56:57] op_sel_hi:[1,0,1] neg_lo:[0,0,1] neg_hi:[0,0,1]
	v_pk_fma_f32 v[46:47], v[46:47], s[18:19], v[64:65] op_sel_hi:[1,0,1] neg_lo:[0,0,1] neg_hi:[0,0,1]
	v_pk_fma_f32 v[42:43], v[42:43], s[18:19], v[66:67] op_sel_hi:[1,0,1] neg_lo:[0,0,1] neg_hi:[0,0,1]
	s_nop 1
	s_nop 1
	v_mov_b32_e32 v56, v254
	v_pk_fma_f32 v[44:45], v[44:45], v[56:57], v[28:29] op_sel_hi:[1,0,1]
	v_pk_fma_f32 v[40:41], v[40:41], v[56:57], v[24:25] op_sel_hi:[1,0,1]
	v_pk_fma_f32 v[46:47], v[46:47], v[56:57], v[30:31] op_sel_hi:[1,0,1]
	v_pk_fma_f32 v[42:43], v[42:43], v[56:57], v[26:27] op_sel_hi:[1,0,1]
	s_waitcnt vmcnt(1)
	v_pk_mul_f32 v[56:57], v[48:49], v[40:41]
	v_pk_mul_f32 v[48:49], v[48:49], v[44:45]
	s_waitcnt vmcnt(0)
	v_pk_fma_f32 v[44:45], v[52:53], v[44:45], v[56:57] neg_lo:[0,0,1] neg_hi:[0,0,1]
	v_pk_fma_f32 v[40:41], v[52:53], v[40:41], v[48:49]
	v_med3_f32 v44, v44, s61, v109
	v_med3_f32 v45, v45, s61, v109
	v_med3_f32 v40, v40, s61, v109
	v_med3_f32 v41, v41, s61, v109
	v_cvt_pk_fp8_f32 v58, v44, v45
	v_cvt_pk_fp8_f32 v59, v40, v41
	v_pk_mul_f32 v[62:63], v[50:51], v[42:43]
	v_pk_mul_f32 v[50:51], v[50:51], v[46:47]
	v_pk_fma_f32 v[46:47], v[54:55], v[46:47], v[62:63] neg_lo:[0,0,1] neg_hi:[0,0,1]
	v_pk_fma_f32 v[42:43], v[54:55], v[42:43], v[50:51]
	v_med3_f32 v46, v46, s61, v109
	v_med3_f32 v47, v47, s61, v109
	v_med3_f32 v40, v42, s61, v109
	v_med3_f32 v41, v43, s61, v109
	v_cvt_pk_fp8_f32 v58, v46, v47 op_sel:[0,0,1]
	v_cvt_pk_fp8_f32 v59, v40, v41 op_sel:[0,0,1]
	v_lshlrev_b64 v[40:41], 6, v[68:69]
	v_lshl_add_u64 v[40:41], v[92:93], 0, v[40:41]
	v_lshl_add_u64 v[42:43], v[60:61], 3, s[12:13]
	global_store_dwordx2 v[40:41], v[58:59], off
	global_load_dwordx2 v[48:49], v[42:43], off
	v_lshlrev_b64 v[44:45], 7, v[60:61]
	v_lshl_add_u64 v[40:41], v[90:91], 0, v[44:45]
	global_load_dwordx4 v[40:43], v[40:41], off
	v_lshl_add_u64 v[44:45], v[88:89], 0, v[44:45]
	global_load_dwordx4 v[44:47], v[44:45], off
	v_add_u32_e32 v52, 0xa0, v102
	v_ashrrev_i32_e32 v53, 31, v52
	s_waitcnt vmcnt(2)
; __device__ __forceinline__ void ln_stats(const float* st, int row, float& mu, float& rs) { const f32x2 s = *(const f32x2*)(st + 2 * (size_t)row); mu = s[0] * (1.0f / DM); rs = 1.0f / sqrtf(s[1] * (1.0f / DM) - mu * mu + LN_EPS); }
;     __device__ __forceinline__ void operator()(EPI_ARGS) const {
;         if (wc >= 2) return;
;         const int row0 = u.pm * BM + wr * 64 + fr, n0 = 1024 + wc * 32 + 8 * fq, fi = 16 * wc + 4 * fq;
;         const f32x4 c0 = *(const f32x4*)(C + n0), c1 = *(const f32x4*)(C + n0 + 4), d0 = *(const f32x4*)(D + n0), d1 = *(const f32x4*)(D + n0 + 4);
; #pragma unroll
;         for (int ai = 0; ai < 2; ++ai)
; #pragma unroll
;             for (int m = 0; m < 4; ++m) { const int row = row0 + ai * HALF + m * 16; float mu, rs; ln_stats(st, row, mu, rs);
;                 const f32x4 c4 = *(const f32x4*)(cs + (size_t)row * 32 + fi), s4 = *(const f32x4*)(sn + (size_t)row * 32 + fi);
;                 const f32x4 v0 = (acc[ai][0][m][0] - c0 * mu) * rs + d0, v1 = (acc[ai][0][m][1] - c1 * mu) * rs + d1;
;                 *(u32x2*)((unsigned char*)KPE + (size_t)row * 64 + 32 * (fq & 1) + 8 * (2 * wc + (fq >> 1))) = pack8fp8(v0 * c4 - v1 * s4, v1 * c4 + v0 * s4); }
	v_pk_mul_f32 v[48:49], v[48:49], s[16:17] op_sel_hi:[1,0]
	s_nop 0
	v_fma_f32 v62, -v48, v48, v49
	v_add_f32_e32 v62, 0x3727c5ac, v62
	v_rsq_f32_e32 v254, v62
	v_pk_mul_f32 v[54:55], v[36:37], v[48:49] op_sel_hi:[1,0]
	v_pk_mul_f32 v[56:57], v[38:39], v[48:49] op_sel_hi:[1,0]
	v_pk_mul_f32 v[58:59], v[34:35], v[48:49] op_sel_hi:[1,0]
	v_pk_mul_f32 v[48:49], v[32:33], v[48:49] op_sel_hi:[1,0]
	v_pk_fma_f32 v[20:21], v[20:21], s[18:19], v[54:55] op_sel_hi:[1,0,1] neg_lo:[0,0,1] neg_hi:[0,0,1]
	v_pk_fma_f32 v[16:17], v[16:17], s[18:19], v[48:49] op_sel_hi:[1,0,1] neg_lo:[0,0,1] neg_hi:[0,0,1]
	v_pk_fma_f32 v[22:23], v[22:23], s[18:19], v[56:57] op_sel_hi:[1,0,1] neg_lo:[0,0,1] neg_hi:[0,0,1]
	v_pk_fma_f32 v[18:19], v[18:19], s[18:19], v[58:59] op_sel_hi:[1,0,1] neg_lo:[0,0,1] neg_hi:[0,0,1]
	s_nop 1
	s_nop 1
	v_mov_b32_e32 v48, v254
	v_pk_fma_f32 v[20:21], v[20:21], v[48:49], v[28:29] op_sel_hi:[1,0,1]
	v_pk_fma_f32 v[16:17], v[16:17], v[48:49], v[24:25] op_sel_hi:[1,0,1]
	v_pk_fma_f32 v[22:23], v[22:23], v[48:49], v[30:31] op_sel_hi:[1,0,1]
	v_pk_fma_f32 v[18:19], v[18:19], v[48:49], v[26:27] op_sel_hi:[1,0,1]
	s_waitcnt vmcnt(1)
	v_pk_mul_f32 v[48:49], v[40:41], v[16:17]
	v_pk_mul_f32 v[40:41], v[40:41], v[20:21]
	s_waitcnt vmcnt(0)
	v_pk_fma_f32 v[20:21], v[44:45], v[20:21], v[48:49] neg_lo:[0,0,1] neg_hi:[0,0,1]
	v_pk_fma_f32 v[16:17], v[44:45], v[16:17], v[40:41]
	v_med3_f32 v20, v20, s61, v109
	v_med3_f32 v21, v21, s61, v109
	v_med3_f32 v16, v16, s61, v109
	v_med3_f32 v17, v17, s61, v109
	v_cvt_pk_fp8_f32 v50, v20, v21
	v_cvt_pk_fp8_f32 v51, v16, v17
	v_pk_mul_f32 v[54:55], v[42:43], v[18:19]
	v_pk_mul_f32 v[42:43], v[42:43], v[22:23]
	v_pk_fma_f32 v[22:23], v[46:47], v[22:23], v[54:55] neg_lo:[0,0,1] neg_hi:[0,0,1]
	v_pk_fma_f32 v[18:19], v[46:47], v[18:19], v[42:43]
	v_med3_f32 v22, v22, s61, v109
	v_med3_f32 v23, v23, s61, v109
	v_med3_f32 v16, v18, s61, v109
	v_med3_f32 v17, v19, s61, v109
	v_cvt_pk_fp8_f32 v50, v22, v23 op_sel:[0,0,1]
	v_cvt_pk_fp8_f32 v51, v16, v17 op_sel:[0,0,1]
	v_lshlrev_b64 v[16:17], 6, v[60:61]
	v_lshl_add_u64 v[16:17], v[92:93], 0, v[16:17]
	v_lshl_add_u64 v[18:19], v[52:53], 3, s[12:13]
	global_store_dwordx2 v[16:17], v[50:51], off
	global_load_dwordx2 v[40:41], v[18:19], off
	v_lshlrev_b64 v[20:21], 7, v[52:53]
	v_lshl_add_u64 v[16:17], v[90:91], 0, v[20:21]
	global_load_dwordx4 v[16:19], v[16:17], off
	v_lshl_add_u64 v[20:21], v[88:89], 0, v[20:21]
	global_load_dwordx4 v[20:23], v[20:21], off
	v_add_u32_e32 v44, 0xb0, v102
	v_ashrrev_i32_e32 v45, 31, v44
	s_waitcnt vmcnt(2)
	v_pk_mul_f32 v[40:41], v[40:41], s[16:17] op_sel_hi:[1,0]
	s_nop 0
	v_fma_f32 v54, -v40, v40, v41
	v_add_f32_e32 v54, 0x3727c5ac, v54
	v_rsq_f32_e32 v254, v54
	v_pk_mul_f32 v[46:47], v[36:37], v[40:41] op_sel_hi:[1,0]
	v_pk_mul_f32 v[48:49], v[38:39], v[40:41] op_sel_hi:[1,0]
	v_pk_mul_f32 v[50:51], v[34:35], v[40:41] op_sel_hi:[1,0]
	v_pk_mul_f32 v[40:41], v[32:33], v[40:41] op_sel_hi:[1,0]
	v_pk_fma_f32 v[12:13], v[12:13], s[18:19], v[46:47] op_sel_hi:[1,0,1] neg_lo:[0,0,1] neg_hi:[0,0,1]
	v_pk_fma_f32 v[8:9], v[8:9], s[18:19], v[40:41] op_sel_hi:[1,0,1] neg_lo:[0,0,1] neg_hi:[0,0,1]
	v_pk_fma_f32 v[14:15], v[14:15], s[18:19], v[48:49] op_sel_hi:[1,0,1] neg_lo:[0,0,1] neg_hi:[0,0,1]
	v_pk_fma_f32 v[10:11], v[10:11], s[18:19], v[50:51] op_sel_hi:[1,0,1] neg_lo:[0,0,1] neg_hi:[0,0,1]
	s_nop 1
	s_nop 1
	v_mov_b32_e32 v40, v254
	v_pk_fma_f32 v[12:13], v[12:13], v[40:41], v[28:29] op_sel_hi:[1,0,1]
	v_pk_fma_f32 v[8:9], v[8:9], v[40:41], v[24:25] op_sel_hi:[1,0,1]
	v_pk_fma_f32 v[14:15], v[14:15], v[40:41], v[30:31] op_sel_hi:[1,0,1]
	v_pk_fma_f32 v[10:11], v[10:11], v[40:41], v[26:27] op_sel_hi:[1,0,1]
	s_waitcnt vmcnt(1)
	v_pk_mul_f32 v[40:41], v[16:17], v[8:9]
	v_pk_mul_f32 v[16:17], v[16:17], v[12:13]
	s_waitcnt vmcnt(0)
; __device__ __forceinline__ void ln_stats(const float* st, int row, float& mu, float& rs) { const f32x2 s = *(const f32x2*)(st + 2 * (size_t)row); mu = s[0] * (1.0f / DM); rs = 1.0f / sqrtf(s[1] * (1.0f / DM) - mu * mu + LN_EPS); }
;     __device__ __forceinline__ void operator()(EPI_ARGS) const {
;     ...
;             for (int m = 0; m < 4; ++m) { const int row = row0 + ai * HALF + m * 16; float mu, rs; ln_stats(st, row, mu, rs);
;                 const f32x4 c4 = *(const f32x4*)(cs + (size_t)row * 32 + fi), s4 = *(const f32x4*)(sn + (size_t)row * 32 + fi);
;                 const f32x4 v0 = (acc[ai][0][m][0] - c0 * mu) * rs + d0, v1 = (acc[ai][0][m][1] - c1 * mu) * rs + d1;
;                 *(u32x2*)((unsigned char*)KPE + (size_t)row * 64 + 32 * (fq & 1) + 8 * (2 * wc + (fq >> 1))) = pack8fp8(v0 * c4 - v1 * s4, v1 * c4 + v0 * s4); }
	v_pk_fma_f32 v[12:13], v[20:21], v[12:13], v[40:41] neg_lo:[0,0,1] neg_hi:[0,0,1]
	v_pk_fma_f32 v[8:9], v[20:21], v[8:9], v[16:17]
	v_med3_f32 v12, v12, s61, v109
	v_med3_f32 v13, v13, s61, v109
	v_med3_f32 v8, v8, s61, v109
	v_med3_f32 v9, v9, s61, v109
	v_cvt_pk_fp8_f32 v42, v12, v13
	v_cvt_pk_fp8_f32 v43, v8, v9
	v_pk_mul_f32 v[46:47], v[18:19], v[10:11]
	v_pk_mul_f32 v[18:19], v[18:19], v[14:15]
	v_pk_fma_f32 v[14:15], v[22:23], v[14:15], v[46:47] neg_lo:[0,0,1] neg_hi:[0,0,1]
	v_pk_fma_f32 v[10:11], v[22:23], v[10:11], v[18:19]
	v_med3_f32 v14, v14, s61, v109
	v_med3_f32 v15, v15, s61, v109
	v_med3_f32 v8, v10, s61, v109
	v_med3_f32 v9, v11, s61, v109
	v_cvt_pk_fp8_f32 v42, v14, v15 op_sel:[0,0,1]
	v_cvt_pk_fp8_f32 v43, v8, v9 op_sel:[0,0,1]
	v_lshlrev_b64 v[8:9], 6, v[52:53]
	v_lshl_add_u64 v[8:9], v[92:93], 0, v[8:9]
	v_lshl_add_u64 v[10:11], v[44:45], 3, s[12:13]
	global_store_dwordx2 v[8:9], v[42:43], off
	global_load_dwordx2 v[16:17], v[10:11], off
	v_lshlrev_b64 v[12:13], 7, v[44:45]
	v_lshl_add_u64 v[8:9], v[90:91], 0, v[12:13]
	global_load_dwordx4 v[8:11], v[8:9], off
	v_lshl_add_u64 v[12:13], v[88:89], 0, v[12:13]
	global_load_dwordx4 v[12:15], v[12:13], off
	v_mov_b32_e32 v18, 0
	v_mov_b32_e32 v19, 0
	s_waitcnt vmcnt(2)
	v_pk_mul_f32 v[16:17], v[16:17], s[16:17] op_sel_hi:[1,0]
	s_nop 0
	v_fma_f32 v40, -v16, v16, v17
	v_pk_mul_f32 v[20:21], v[36:37], v[16:17] op_sel_hi:[1,0]
	v_pk_mul_f32 v[22:23], v[38:39], v[16:17] op_sel_hi:[1,0]
	v_pk_mul_f32 v[34:35], v[34:35], v[16:17] op_sel_hi:[1,0]
	v_pk_mul_f32 v[16:17], v[32:33], v[16:17] op_sel_hi:[1,0]
	v_add_f32_e32 v32, 0x3727c5ac, v40
	v_mul_f32_e32 v33, 0x4f800000, v32
	v_cmp_gt_f32_e32 vcc, s60, v32
	v_pk_fma_f32 v[0:1], v[0:1], s[18:19], v[16:17] op_sel_hi:[1,0,1] neg_lo:[0,0,1] neg_hi:[0,0,1]
	v_pk_fma_f32 v[4:5], v[4:5], s[18:19], v[20:21] op_sel_hi:[1,0,1] neg_lo:[0,0,1] neg_hi:[0,0,1]
	v_cndmask_b32_e32 v32, v32, v33, vcc
	v_sqrt_f32_e32 v33, v32
	v_pk_fma_f32 v[6:7], v[6:7], s[18:19], v[22:23] op_sel_hi:[1,0,1] neg_lo:[0,0,1] neg_hi:[0,0,1]
	v_pk_fma_f32 v[2:3], v[2:3], s[18:19], v[34:35] op_sel_hi:[1,0,1] neg_lo:[0,0,1] neg_hi:[0,0,1]
	v_add_u32_e32 v16, -1, v33
	v_add_u32_e32 v17, 1, v33
	v_fma_f32 v20, -v16, v33, v32
	v_fma_f32 v21, -v17, v33, v32
	v_cmp_ge_f32_e64 s[2:3], 0, v20
	s_nop 1
	v_cndmask_b32_e64 v16, v33, v16, s[2:3]
	v_cmp_lt_f32_e64 s[2:3], 0, v21
	s_nop 1
	v_cndmask_b32_e64 v16, v16, v17, s[2:3]
	v_mul_f32_e32 v17, 0x37800000, v16
	v_cndmask_b32_e32 v16, v16, v17, vcc
	v_cmp_class_f32_e32 vcc, v32, v108
	s_nop 1
	v_cndmask_b32_e32 v16, v16, v32, vcc
	v_div_scale_f32 v17, s[2:3], v16, v16, 1.0
	v_rcp_f32_e32 v20, v17
	v_div_scale_f32 v21, vcc, 1.0, v16, 1.0
	v_fma_f32 v22, -v17, v20, 1.0
	v_fmac_f32_e32 v20, v22, v20
	v_mul_f32_e32 v22, v21, v20
	v_fma_f32 v23, -v17, v22, v21
	v_fmac_f32_e32 v22, v23, v20
	v_fma_f32 v17, -v17, v22, v21
	v_div_fmas_f32 v17, v17, v20, v22
	v_div_fixup_f32 v16, v17, v16, 1.0
	v_pk_fma_f32 v[4:5], v[4:5], v[16:17], v[28:29] op_sel_hi:[1,0,1]
	v_pk_fma_f32 v[0:1], v[0:1], v[16:17], v[24:25] op_sel_hi:[1,0,1]
	v_pk_fma_f32 v[6:7], v[6:7], v[16:17], v[30:31] op_sel_hi:[1,0,1]
	v_pk_fma_f32 v[2:3], v[2:3], v[16:17], v[26:27] op_sel_hi:[1,0,1]
	s_waitcnt vmcnt(1)
	v_pk_mul_f32 v[16:17], v[8:9], v[0:1]
	v_pk_mul_f32 v[8:9], v[8:9], v[4:5]
	s_waitcnt vmcnt(0)
	v_pk_fma_f32 v[4:5], v[12:13], v[4:5], v[16:17] neg_lo:[0,0,1] neg_hi:[0,0,1]
	v_pk_fma_f32 v[0:1], v[12:13], v[0:1], v[8:9]
	v_med3_f32 v4, v4, s61, v109
	v_med3_f32 v5, v5, s61, v109
	v_med3_f32 v0, v0, s61, v109
	v_med3_f32 v1, v1, s61, v109
	v_cvt_pk_fp8_f32 v18, v4, v5
	v_cvt_pk_fp8_f32 v19, v0, v1
	v_pk_mul_f32 v[20:21], v[10:11], v[2:3]
	v_pk_mul_f32 v[10:11], v[10:11], v[6:7]
	v_pk_fma_f32 v[6:7], v[14:15], v[6:7], v[20:21] neg_lo:[0,0,1] neg_hi:[0,0,1]
	v_pk_fma_f32 v[2:3], v[14:15], v[2:3], v[10:11]
	v_med3_f32 v6, v6, s61, v109
	v_med3_f32 v7, v7, s61, v109
	v_med3_f32 v0, v2, s61, v109
	v_med3_f32 v1, v3, s61, v109
	v_cvt_pk_fp8_f32 v18, v6, v7 op_sel:[0,0,1]
	v_cvt_pk_fp8_f32 v19, v0, v1 op_sel:[0,0,1]
	v_lshlrev_b64 v[0:1], 6, v[44:45]
	v_lshl_add_u64 v[0:1], v[92:93], 0, v[0:1]
	global_store_dwordx2 v[0:1], v[18:19], off
	s_andn2_b64 vcc, exec, s[20:21]
	s_mov_b64 s[2:3], -1
	s_cbranch_vccnz .LBB0_4104

;     __device__ __forceinline__ float qscale(const Unit& u) const { return ((u.pn >= 8 && u.pn <= 11) || u.pn == 17) ? 0.5f : 1.0f; }
;     ...
;         if constexpr (QM == 2) { const float qs0_ = g.qs * E.qscale(cur), qs1_ = qs0_ * g.qs_b1; _Pragma("unroll") for (int a = 0; a < 2; ++a) _Pragma("unroll") for (int b = 0; b < 2; ++b) _Pragma("unroll") for (int m = 0; m < 4; ++m) _Pragma("unroll") for (int n = 0; n < 2; ++n) { const v4i t_ = __builtin_bit_cast(v4i, acc[a][b][m][n]); acc[a][b][m][n] = (f32x4){(float)t_[0], (float)t_[1], (float)t_[2], (float)t_[3]} * (b == 0 ? qs0_ : qs1_); } }
; __device__ __forceinline__ float rms_scale(const float* ssq, int row, int which) {
;     const f32x4 a = *(const f32x4*)(ssq + (size_t)row * 16 + which * 8), b = *(const f32x4*)(ssq + (size_t)row * 16 + which * 8 + 4);
;     const float s = ((a[0] + a[1]) + (a[2] + a[3])) + ((b[0] + b[1]) + (b[2] + b[3]));
;     return 1.0f / sqrtf(s * (1.0f / 512.0f) + RMS_EPS);
; }
;     __device__ __forceinline__ void operator()(EPI_ARGS) const {
;         const int row0 = u.pm * BM + wr * 64 + fr; bf16_t* dst = (u.pn < 8) ? KN : V; const int h0 = 2 * (u.pn & 7);
; #pragma unroll
;         for (int ai = 0; ai < 2; ++ai)
; #pragma unroll
;             for (int m = 0; m < 4; ++m) { const int row = row0 + ai * HALF + m * 16; const float rs = rms_scale(ssq, row, 1);
; #pragma unroll
;                 for (int bj = 0; bj < 2; ++bj)
;                     *(u32x2*)((unsigned char*)dst + ((size_t)(h0 + bj) * NTOK + row) * 128 + 64 * (wc >> 1) + 32 * (fq & 1) + 8 * ((2 * wc + (fq >> 1)) & 3)) = pack8fp8(acc[ai][bj][m][0] * rs, acc[ai][bj][m][1] * rs); }
.LBB0_4141:
	v_lshl_add_u32 v144, s4, 8, v146
	v_ashrrev_i32_e32 v145, 31, v144
	v_lshlrev_b64 v[154:155], 6, v[144:145]
	v_lshl_add_u64 v[158:159], s[8:9], 0, v[154:155]
	global_load_dwordx4 v[198:201], v[158:159], off offset:1056
	global_load_dwordx4 v[202:205], v[158:159], off offset:1072
	global_load_dwordx4 v[206:209], v[158:159], off offset:2080
	global_load_dwordx4 v[210:213], v[158:159], off offset:2096
	global_load_dwordx4 v[214:217], v[158:159], off offset:3104
	global_load_dwordx4 v[218:221], v[158:159], off offset:3120
	v_mov_b32_e32 v252, 0x2000
	v_mov_b32_e32 v253, 0
	v_lshl_add_u64 v[252:253], v[158:159], 0, v[252:253]
	global_load_dwordx4 v[222:225], v[252:253], off offset:32
	global_load_dwordx4 v[226:229], v[252:253], off offset:48
	global_load_dwordx4 v[230:233], v[252:253], off offset:1056
	global_load_dwordx4 v[234:237], v[252:253], off offset:1072
	global_load_dwordx4 v[238:241], v[252:253], off offset:2080
	global_load_dwordx4 v[242:245], v[252:253], off offset:2096
	global_load_dwordx4 v[246:249], v[252:253], off offset:3104
	global_load_dwordx4 v[250:253], v[252:253], off offset:3120
	global_load_dwordx4 v[154:157], v[158:159], off offset:32
	s_nop 0
	global_load_dwordx4 v[158:161], v[158:159], off offset:48
	s_cmp_gt_i32 s5, 7
	v_cvt_f32_i32_e32 v113, v113
	v_cvt_f32_i32_e32 v112, v112
	s_cselect_b64 vcc, -1, 0
	s_cmp_lt_i32 s5, 8
	s_cselect_b32 s25, s67, s7
	s_cselect_b32 s4, s66, s6
	s_lshl_b32 s5, s5, 15
	v_cvt_f32_i32_e32 v162, v114
	v_cndmask_b32_e32 v114, v151, v152, vcc
	s_and_b32 s14, s5, 0x38000
	v_pk_mul_f32 v[168:169], v[114:115], v[112:113] op_sel_hi:[0,1]
	v_lshl_add_u64 v[112:113], v[144:145], 0, s[14:15]
	v_lshlrev_b64 v[170:171], 7, v[112:113]
	v_cvt_f32_i32_e32 v127, v127
	v_cvt_f32_i32_e32 v126, v126
	v_cvt_f32_i32_e32 v125, v125
	v_cvt_f32_i32_e32 v124, v124
	v_cvt_f32_i32_e32 v123, v123
	v_cvt_f32_i32_e32 v122, v122
	v_cvt_f32_i32_e32 v121, v121
	v_cvt_f32_i32_e32 v120, v120
	v_cvt_f32_i32_e32 v119, v119
	v_cvt_f32_i32_e32 v118, v118
	v_cvt_f32_i32_e32 v117, v117
	v_cvt_f32_i32_e32 v116, v116
	v_cvt_f32_i32_e32 v163, v115
	v_pk_mul_f32 v[124:125], v[114:115], v[124:125] op_sel_hi:[0,1]
	v_pk_mul_f32 v[126:127], v[114:115], v[126:127] op_sel_hi:[0,1]
	v_pk_mul_f32 v[120:121], v[114:115], v[120:121] op_sel_hi:[0,1]
	v_pk_mul_f32 v[122:123], v[114:115], v[122:123] op_sel_hi:[0,1]
	v_pk_mul_f32 v[116:117], v[114:115], v[116:117] op_sel_hi:[0,1]
	v_pk_mul_f32 v[118:119], v[114:115], v[118:119] op_sel_hi:[0,1]
	v_pk_mul_f32 v[162:163], v[114:115], v[162:163] op_sel_hi:[0,1]
	s_add_u32 s4, s4, s70
	s_mov_b32 s37, s15
	s_addc_u32 s5, s25, 0
	s_or_b32 s36, s14, 0x4000
	v_mov_b32_e32 v166, 0
	v_mov_b32_e32 v167, 0
	v_mov_b32_e32 v164, 0
	v_mov_b32_e32 v165, 0
	v_cvt_f32_i32_e32 v111, v111
	v_cvt_f32_i32_e32 v110, v110
	v_cvt_f32_i32_e32 v109, v109
	v_cvt_f32_i32_e32 v108, v108
	v_cvt_f32_i32_e32 v107, v107
	v_cvt_f32_i32_e32 v106, v106
	v_cvt_f32_i32_e32 v105, v105
	v_cvt_f32_i32_e32 v104, v104
	v_cvt_f32_i32_e32 v103, v103
	v_cvt_f32_i32_e32 v102, v102
	v_cvt_f32_i32_e32 v101, v101
	v_cvt_f32_i32_e32 v100, v100
	v_cvt_f32_i32_e32 v99, v99
	v_cvt_f32_i32_e32 v98, v98
	v_cvt_f32_i32_e32 v97, v97
	v_cvt_f32_i32_e32 v96, v96
	v_cvt_f32_i32_e32 v95, v95
	v_cvt_f32_i32_e32 v94, v94
	v_cvt_f32_i32_e32 v93, v93
	v_cvt_f32_i32_e32 v92, v92
	v_cvt_f32_i32_e32 v91, v91
	v_cvt_f32_i32_e32 v90, v90
	v_cvt_f32_i32_e32 v89, v89
	v_cvt_f32_i32_e32 v88, v88
	v_cvt_f32_i32_e32 v87, v87
	v_cvt_f32_i32_e32 v86, v86
	v_cvt_f32_i32_e32 v85, v85
	v_cvt_f32_i32_e32 v84, v84
	v_cvt_f32_i32_e32 v83, v83
	v_cvt_f32_i32_e32 v82, v82
	v_cvt_f32_i32_e32 v81, v81
	v_cvt_f32_i32_e32 v80, v80
	v_cvt_f32_i32_e32 v77, v77
	v_cvt_f32_i32_e32 v76, v76
	v_cvt_f32_i32_e32 v73, v73
	v_cvt_f32_i32_e32 v72, v72
	s_waitcnt vmcnt(0)
	v_mov_b32_e32 v112, v154
	v_mov_b32_e32 v113, v158
	v_mov_b32_e32 v158, v155
	v_mov_b32_e32 v154, v156
	v_mov_b32_e32 v155, v160
	v_mov_b32_e32 v160, v157
	v_pk_add_f32 v[112:113], v[112:113], v[158:159]
	v_pk_add_f32 v[154:155], v[154:155], v[160:161]
	v_cvt_f32_i32_e32 v69, v69
	v_pk_add_f32 v[112:113], v[112:113], v[154:155]
	v_lshl_add_u64 v[154:155], v[144:145], 0, s[36:37]
	v_add_f32_e32 v112, v112, v113
	v_fmamk_f32 v112, v112, 0x3b000000, v149
	v_rsq_f32_e32 v254, v112
	v_cvt_f32_i32_e32 v68, v68
	v_cvt_f32_i32_e32 v65, v65
	v_lshl_add_u64 v[112:113], s[4:5], 0, v[136:137]
	v_lshl_add_u64 v[112:113], v[112:113], 0, v[138:139]
	v_cvt_f32_i32_e32 v64, v64
	v_cvt_f32_i32_e32 v79, v79
	v_cvt_f32_i32_e32 v78, v78
	v_cvt_f32_i32_e32 v75, v75
	v_cvt_f32_i32_e32 v74, v74
	v_lshl_add_u64 v[156:157], v[112:113], 0, v[170:171]
	v_cvt_f32_i32_e32 v71, v71
	v_cvt_f32_i32_e32 v70, v70
	v_mov_b32_e32 v158, v254
	v_pk_mul_f32 v[126:127], v[126:127], v[158:159] op_sel_hi:[1,0]
	v_pk_mul_f32 v[124:125], v[124:125], v[158:159] op_sel_hi:[1,0]
	v_pk_mul_f32 v[122:123], v[122:123], v[158:159] op_sel_hi:[1,0]
	v_pk_mul_f32 v[120:121], v[120:121], v[158:159] op_sel_hi:[1,0]
	v_pk_mul_f32 v[118:119], v[118:119], v[158:159] op_sel_hi:[1,0]
	v_pk_mul_f32 v[116:117], v[116:117], v[158:159] op_sel_hi:[1,0]
	v_pk_mul_f32 v[160:161], v[162:163], v[158:159] op_sel_hi:[1,0]
	v_pk_mul_f32 v[158:159], v[168:169], v[158:159] op_sel_hi:[1,0]
	v_med3_f32 v115, v124, s74, v153
	v_med3_f32 v124, v125, s74, v153
	v_med3_f32 v125, v126, s74, v153
	v_med3_f32 v126, v127, s74, v153
	v_med3_f32 v116, v116, s74, v153
	v_med3_f32 v117, v117, s74, v153
	v_med3_f32 v127, v158, s74, v153
	v_med3_f32 v145, v159, s74, v153
	v_med3_f32 v120, v120, s74, v153
	v_med3_f32 v121, v121, s74, v153
	v_cvt_pk_fp8_f32 v166, v116, v117
	v_cvt_pk_fp8_f32 v167, v127, v145
; __device__ __forceinline__ float rms_scale(const float* ssq, int row, int which) {
;     const f32x4 a = *(const f32x4*)(ssq + (size_t)row * 16 + which * 8), b = *(const f32x4*)(ssq + (size_t)row * 16 + which * 8 + 4);
;     const float s = ((a[0] + a[1]) + (a[2] + a[3])) + ((b[0] + b[1]) + (b[2] + b[3]));
;     return 1.0f / sqrtf(s * (1.0f / 512.0f) + RMS_EPS);
; }
;     __device__ __forceinline__ void operator()(EPI_ARGS) const {
;     ...
;             for (int m = 0; m < 4; ++m) { const int row = row0 + ai * HALF + m * 16; const float rs = rms_scale(ssq, row, 1);
; #pragma unroll
;                 for (int bj = 0; bj < 2; ++bj)
;                     *(u32x2*)((unsigned char*)dst + ((size_t)(h0 + bj) * NTOK + row) * 128 + 64 * (wc >> 1) + 32 * (fq & 1) + 8 * ((2 * wc + (fq >> 1)) & 3)) = pack8fp8(acc[ai][bj][m][0] * rs, acc[ai][bj][m][1] * rs); }
	v_cvt_pk_fp8_f32 v164, v115, v124
	v_cvt_pk_fp8_f32 v165, v120, v121
	v_med3_f32 v118, v118, s74, v153
	v_med3_f32 v119, v119, s74, v153
	v_med3_f32 v158, v160, s74, v153
	v_med3_f32 v115, v161, s74, v153
	v_med3_f32 v122, v122, s74, v153
	v_med3_f32 v123, v123, s74, v153
	v_cvt_pk_fp8_f32 v166, v118, v119 op_sel:[0,0,1]
	v_cvt_pk_fp8_f32 v167, v158, v115 op_sel:[0,0,1]
	v_cvt_pk_fp8_f32 v164, v125, v126 op_sel:[0,0,1]
	v_cvt_pk_fp8_f32 v165, v122, v123 op_sel:[0,0,1]
	v_lshlrev_b64 v[116:117], 7, v[154:155]
	v_or_b32_e32 v124, 16, v144
	v_lshl_add_u64 v[116:117], v[112:113], 0, v[116:117]
	v_ashrrev_i32_e32 v125, 31, v124
	global_store_dwordx2 v[116:117], v[166:167], off
	v_lshlrev_b64 v[116:117], 6, v[124:125]
	global_store_dwordx2 v[156:157], v[164:165], off
	v_lshl_add_u64 v[120:121], s[8:9], 0, v[116:117]
	v_mov_b32_e32 v116, v198
	v_mov_b32_e32 v117, v199
	v_mov_b32_e32 v118, v200
	v_mov_b32_e32 v119, v201
	s_nop 0
	v_mov_b32_e32 v120, v202
	v_mov_b32_e32 v121, v203
	v_mov_b32_e32 v122, v204
	v_mov_b32_e32 v123, v205
	v_pk_mul_f32 v[108:109], v[114:115], v[108:109] op_sel_hi:[0,1]
	v_pk_mul_f32 v[110:111], v[114:115], v[110:111] op_sel_hi:[0,1]
	v_pk_mul_f32 v[104:105], v[114:115], v[104:105] op_sel_hi:[0,1]
	v_pk_mul_f32 v[106:107], v[114:115], v[106:107] op_sel_hi:[0,1]
	v_pk_mul_f32 v[100:101], v[114:115], v[100:101] op_sel_hi:[0,1]
	v_pk_mul_f32 v[102:103], v[114:115], v[102:103] op_sel_hi:[0,1]
	v_pk_mul_f32 v[96:97], v[114:115], v[96:97] op_sel_hi:[0,1]
	v_pk_mul_f32 v[98:99], v[114:115], v[98:99] op_sel_hi:[0,1]
	v_lshl_add_u64 v[160:161], v[124:125], 0, s[14:15]
	v_mov_b32_e32 v126, 0
	v_mov_b32_e32 v127, 0
	v_mov_b32_e32 v154, 0
	v_mov_b32_e32 v155, 0
	v_or_b32_e32 v156, 32, v144
	v_ashrrev_i32_e32 v157, 31, v156
	v_lshlrev_b64 v[158:159], 6, v[156:157]
	v_cvt_f32_i32_e32 v67, v67
	v_cvt_f32_i32_e32 v66, v66
	v_cvt_f32_i32_e32 v61, v61
	v_cvt_f32_i32_e32 v60, v60
	v_cvt_f32_i32_e32 v57, v57
	v_cvt_f32_i32_e32 v56, v56
	v_cvt_f32_i32_e32 v53, v53
	v_cvt_f32_i32_e32 v52, v52
	v_cvt_f32_i32_e32 v49, v49
	v_cvt_f32_i32_e32 v48, v48
	v_cvt_f32_i32_e32 v63, v63
	v_cvt_f32_i32_e32 v62, v62
	v_cvt_f32_i32_e32 v59, v59
	v_cvt_f32_i32_e32 v58, v58
	v_cvt_f32_i32_e32 v55, v55
	v_cvt_f32_i32_e32 v54, v54
	v_cvt_f32_i32_e32 v51, v51
	v_cvt_f32_i32_e32 v50, v50
	v_cvt_f32_i32_e32 v45, v45
	v_cvt_f32_i32_e32 v44, v44
	v_cvt_f32_i32_e32 v41, v41
	v_cvt_f32_i32_e32 v40, v40
	v_cvt_f32_i32_e32 v37, v37
	v_cvt_f32_i32_e32 v36, v36
	v_cvt_f32_i32_e32 v33, v33
	v_cvt_f32_i32_e32 v32, v32
	v_cvt_f32_i32_e32 v47, v47
	v_cvt_f32_i32_e32 v46, v46
	v_cvt_f32_i32_e32 v43, v43
	v_cvt_f32_i32_e32 v42, v42
	v_cvt_f32_i32_e32 v39, v39
	v_cvt_f32_i32_e32 v38, v38
	v_cvt_f32_i32_e32 v35, v35
	v_cvt_f32_i32_e32 v34, v34
	v_cvt_f32_i32_e32 v29, v29
	v_cvt_f32_i32_e32 v28, v28
	v_cvt_f32_i32_e32 v25, v25
	v_cvt_f32_i32_e32 v24, v24
	v_cvt_f32_i32_e32 v21, v21
	v_cvt_f32_i32_e32 v20, v20
	v_cvt_f32_i32_e32 v17, v17
	v_cvt_f32_i32_e32 v16, v16
	v_cvt_f32_i32_e32 v31, v31
	v_cvt_f32_i32_e32 v30, v30
	v_cvt_f32_i32_e32 v27, v27
	v_cvt_f32_i32_e32 v26, v26
	v_cvt_f32_i32_e32 v23, v23
	v_cvt_f32_i32_e32 v22, v22
	v_cvt_f32_i32_e32 v19, v19
	v_cvt_f32_i32_e32 v18, v18
	v_cvt_f32_i32_e32 v13, v13
	v_cvt_f32_i32_e32 v12, v12
	v_cvt_f32_i32_e32 v9, v9
	v_cvt_f32_i32_e32 v8, v8
	v_cvt_f32_i32_e32 v5, v5
	v_cvt_f32_i32_e32 v4, v4
	v_cvt_f32_i32_e32 v1, v1
	v_cvt_f32_i32_e32 v0, v0
	v_cvt_f32_i32_e32 v15, v15
	v_cvt_f32_i32_e32 v14, v14
	v_cvt_f32_i32_e32 v11, v11
	v_cvt_f32_i32_e32 v10, v10
	v_mov_b32_e32 v162, v116
	v_mov_b32_e32 v163, v120
	v_mov_b32_e32 v120, v117
	v_mov_b32_e32 v116, v118
	v_mov_b32_e32 v117, v122
	v_mov_b32_e32 v122, v119
	v_pk_add_f32 v[118:119], v[162:163], v[120:121]
	v_pk_add_f32 v[116:117], v[116:117], v[122:123]
	v_lshl_add_u64 v[120:121], v[124:125], 0, s[36:37]
	v_pk_add_f32 v[116:117], v[118:119], v[116:117]
	v_lshlrev_b64 v[118:119], 7, v[160:161]
	v_add_f32_e32 v115, v116, v117
	v_fmamk_f32 v115, v115, 0x3b000000, v149
	v_rsq_f32_e32 v254, v115
	v_lshlrev_b64 v[120:121], 7, v[120:121]
	v_cvt_f32_i32_e32 v7, v7
	v_lshl_add_u64 v[116:117], s[8:9], 0, v[158:159]
	v_cvt_f32_i32_e32 v6, v6
	v_cvt_f32_i32_e32 v3, v3
	v_cvt_f32_i32_e32 v2, v2
	s_nop 0
	s_nop 1
	s_nop 1
	v_pk_mul_f32 v[92:93], v[114:115], v[92:93] op_sel_hi:[0,1]
	v_mov_b32_e32 v122, v254
	v_pk_mul_f32 v[108:109], v[108:109], v[122:123] op_sel_hi:[1,0]
	v_pk_mul_f32 v[104:105], v[104:105], v[122:123] op_sel_hi:[1,0]
	v_pk_mul_f32 v[100:101], v[100:101], v[122:123] op_sel_hi:[1,0]
	v_pk_mul_f32 v[96:97], v[96:97], v[122:123] op_sel_hi:[1,0]
	v_med3_f32 v108, v108, s74, v153
	v_med3_f32 v109, v109, s74, v153
	v_med3_f32 v104, v104, s74, v153
	v_med3_f32 v105, v105, s74, v153
	v_med3_f32 v100, v100, s74, v153
	v_med3_f32 v101, v101, s74, v153
	v_med3_f32 v96, v96, s74, v153
	v_med3_f32 v97, v97, s74, v153
	v_cvt_pk_fp8_f32 v126, v108, v109
	v_cvt_pk_fp8_f32 v127, v104, v105
	v_cvt_pk_fp8_f32 v154, v100, v101
	v_cvt_pk_fp8_f32 v155, v96, v97
	v_pk_mul_f32 v[110:111], v[110:111], v[122:123] op_sel_hi:[1,0]
	v_pk_mul_f32 v[106:107], v[106:107], v[122:123] op_sel_hi:[1,0]
	v_pk_mul_f32 v[102:103], v[102:103], v[122:123] op_sel_hi:[1,0]
	v_pk_mul_f32 v[98:99], v[98:99], v[122:123] op_sel_hi:[1,0]
	v_med3_f32 v110, v110, s74, v153
	v_med3_f32 v111, v111, s74, v153
	v_med3_f32 v106, v106, s74, v153
	v_med3_f32 v107, v107, s74, v153
	v_med3_f32 v102, v102, s74, v153
	v_med3_f32 v103, v103, s74, v153
	v_med3_f32 v98, v98, s74, v153
	v_med3_f32 v99, v99, s74, v153
	v_cvt_pk_fp8_f32 v126, v110, v111 op_sel:[0,0,1]
	v_cvt_pk_fp8_f32 v127, v106, v107 op_sel:[0,0,1]
; __device__ __forceinline__ float rms_scale(const float* ssq, int row, int which) {
;     const f32x4 a = *(const f32x4*)(ssq + (size_t)row * 16 + which * 8), b = *(const f32x4*)(ssq + (size_t)row * 16 + which * 8 + 4);
;     const float s = ((a[0] + a[1]) + (a[2] + a[3])) + ((b[0] + b[1]) + (b[2] + b[3]));
;     return 1.0f / sqrtf(s * (1.0f / 512.0f) + RMS_EPS);
; }
;     __device__ __forceinline__ void operator()(EPI_ARGS) const {
;     ...
;             for (int m = 0; m < 4; ++m) { const int row = row0 + ai * HALF + m * 16; const float rs = rms_scale(ssq, row, 1);
; #pragma unroll
;                 for (int bj = 0; bj < 2; ++bj)
;                     *(u32x2*)((unsigned char*)dst + ((size_t)(h0 + bj) * NTOK + row) * 128 + 64 * (wc >> 1) + 32 * (fq & 1) + 8 * ((2 * wc + (fq >> 1)) & 3)) = pack8fp8(acc[ai][bj][m][0] * rs, acc[ai][bj][m][1] * rs); }
	v_cvt_pk_fp8_f32 v154, v102, v103 op_sel:[0,0,1]
	v_cvt_pk_fp8_f32 v155, v98, v99 op_sel:[0,0,1]
	v_lshl_add_u64 v[96:97], v[112:113], 0, v[118:119]
	v_lshl_add_u64 v[98:99], v[112:113], 0, v[120:121]
	global_store_dwordx2 v[96:97], v[126:127], off
	global_store_dwordx2 v[98:99], v[154:155], off
	v_mov_b32_e32 v96, v206
	v_mov_b32_e32 v97, v207
	v_mov_b32_e32 v98, v208
	v_mov_b32_e32 v99, v209
	s_nop 0
	v_mov_b32_e32 v100, v210
	v_mov_b32_e32 v101, v211
	v_mov_b32_e32 v102, v212
	v_mov_b32_e32 v103, v213
	v_or_b32_e32 v108, 48, v144
	v_ashrrev_i32_e32 v109, 31, v108
	v_lshlrev_b64 v[110:111], 6, v[108:109]
	v_pk_mul_f32 v[94:95], v[114:115], v[94:95] op_sel_hi:[0,1]
	v_pk_mul_f32 v[88:89], v[114:115], v[88:89] op_sel_hi:[0,1]
	v_pk_mul_f32 v[90:91], v[114:115], v[90:91] op_sel_hi:[0,1]
	v_pk_mul_f32 v[84:85], v[114:115], v[84:85] op_sel_hi:[0,1]
	v_pk_mul_f32 v[86:87], v[114:115], v[86:87] op_sel_hi:[0,1]
	v_pk_mul_f32 v[80:81], v[114:115], v[80:81] op_sel_hi:[0,1]
	v_pk_mul_f32 v[82:83], v[114:115], v[82:83] op_sel_hi:[0,1]
	v_lshl_add_u64 v[116:117], v[156:157], 0, s[14:15]
	v_mov_b32_e32 v118, v96
	v_mov_b32_e32 v119, v100
	v_mov_b32_e32 v100, v97
	v_mov_b32_e32 v96, v98
	v_mov_b32_e32 v97, v102
	v_mov_b32_e32 v102, v99
	v_pk_add_f32 v[98:99], v[118:119], v[100:101]
	v_pk_add_f32 v[96:97], v[96:97], v[102:103]
	v_lshl_add_u64 v[100:101], v[156:157], 0, s[36:37]
	v_pk_add_f32 v[96:97], v[98:99], v[96:97]
	v_lshlrev_b64 v[98:99], 7, v[116:117]
	v_add_f32_e32 v96, v96, v97
	v_fmamk_f32 v96, v96, 0x3b000000, v149
	v_rsq_f32_e32 v254, v96
	v_lshlrev_b64 v[100:101], 7, v[100:101]
	s_nop 0
	v_lshl_add_u64 v[96:97], s[8:9], 0, v[110:111]
	s_nop 1
	s_nop 1
	s_nop 1
	v_mov_b32_e32 v102, v254
	v_pk_mul_f32 v[92:93], v[92:93], v[102:103] op_sel_hi:[1,0]
	v_pk_mul_f32 v[88:89], v[88:89], v[102:103] op_sel_hi:[1,0]
	v_pk_mul_f32 v[84:85], v[84:85], v[102:103] op_sel_hi:[1,0]
	v_pk_mul_f32 v[80:81], v[80:81], v[102:103] op_sel_hi:[1,0]
	v_med3_f32 v92, v92, s74, v153
	v_med3_f32 v93, v93, s74, v153
	v_med3_f32 v88, v88, s74, v153
	v_med3_f32 v89, v89, s74, v153
	v_med3_f32 v84, v84, s74, v153
	v_med3_f32 v85, v85, s74, v153
	v_med3_f32 v80, v80, s74, v153
	v_med3_f32 v81, v81, s74, v153
	v_cvt_pk_fp8_f32 v104, v92, v93
	v_cvt_pk_fp8_f32 v105, v88, v89
	v_cvt_pk_fp8_f32 v106, v84, v85
	v_cvt_pk_fp8_f32 v107, v80, v81
	v_pk_mul_f32 v[94:95], v[94:95], v[102:103] op_sel_hi:[1,0]
	v_pk_mul_f32 v[90:91], v[90:91], v[102:103] op_sel_hi:[1,0]
	v_pk_mul_f32 v[86:87], v[86:87], v[102:103] op_sel_hi:[1,0]
	v_pk_mul_f32 v[82:83], v[82:83], v[102:103] op_sel_hi:[1,0]
	v_med3_f32 v94, v94, s74, v153
	v_med3_f32 v95, v95, s74, v153
	v_med3_f32 v90, v90, s74, v153
	v_med3_f32 v91, v91, s74, v153
	v_med3_f32 v86, v86, s74, v153
	v_med3_f32 v87, v87, s74, v153
	v_med3_f32 v82, v82, s74, v153
	v_med3_f32 v83, v83, s74, v153
	v_cvt_pk_fp8_f32 v104, v94, v95 op_sel:[0,0,1]
	v_cvt_pk_fp8_f32 v105, v90, v91 op_sel:[0,0,1]
	v_cvt_pk_fp8_f32 v106, v86, v87 op_sel:[0,0,1]
	v_cvt_pk_fp8_f32 v107, v82, v83 op_sel:[0,0,1]
	v_lshl_add_u64 v[80:81], v[112:113], 0, v[98:99]
	v_lshl_add_u64 v[82:83], v[112:113], 0, v[100:101]
	global_store_dwordx2 v[80:81], v[104:105], off
	global_store_dwordx2 v[82:83], v[106:107], off
	v_mov_b32_e32 v80, v214
	v_mov_b32_e32 v81, v215
	v_mov_b32_e32 v82, v216
	v_mov_b32_e32 v83, v217
	s_nop 0
	v_mov_b32_e32 v84, v218
	v_mov_b32_e32 v85, v219
	v_mov_b32_e32 v86, v220
	v_mov_b32_e32 v87, v221
	v_add_u32_e32 v92, 0x80, v144
	v_ashrrev_i32_e32 v93, 31, v92
	v_lshlrev_b64 v[94:95], 6, v[92:93]
	v_lshl_add_u64 v[96:97], v[108:109], 0, s[14:15]
	v_pk_mul_f32 v[76:77], v[114:115], v[76:77] op_sel_hi:[0,1]
	v_pk_mul_f32 v[72:73], v[114:115], v[72:73] op_sel_hi:[0,1]
	v_pk_mul_f32 v[68:69], v[114:115], v[68:69] op_sel_hi:[0,1]
	v_pk_mul_f32 v[64:65], v[114:115], v[64:65] op_sel_hi:[0,1]
	v_mov_b32_e32 v88, 0
	v_mov_b32_e32 v89, 0
	v_mov_b32_e32 v90, 0
	v_mov_b32_e32 v91, 0
	v_pk_mul_f32 v[78:79], v[114:115], v[78:79] op_sel_hi:[0,1]
	v_pk_mul_f32 v[74:75], v[114:115], v[74:75] op_sel_hi:[0,1]
	v_pk_mul_f32 v[70:71], v[114:115], v[70:71] op_sel_hi:[0,1]
	v_pk_mul_f32 v[66:67], v[114:115], v[66:67] op_sel_hi:[0,1]
	v_pk_mul_f32 v[60:61], v[114:115], v[60:61] op_sel_hi:[0,1]
	v_pk_mul_f32 v[56:57], v[114:115], v[56:57] op_sel_hi:[0,1]
	v_pk_mul_f32 v[52:53], v[114:115], v[52:53] op_sel_hi:[0,1]
	v_pk_mul_f32 v[48:49], v[114:115], v[48:49] op_sel_hi:[0,1]
	v_pk_mul_f32 v[62:63], v[114:115], v[62:63] op_sel_hi:[0,1]
	v_pk_mul_f32 v[58:59], v[114:115], v[58:59] op_sel_hi:[0,1]
	v_pk_mul_f32 v[54:55], v[114:115], v[54:55] op_sel_hi:[0,1]
	v_pk_mul_f32 v[50:51], v[114:115], v[50:51] op_sel_hi:[0,1]
	v_pk_mul_f32 v[44:45], v[114:115], v[44:45] op_sel_hi:[0,1]
	v_pk_mul_f32 v[40:41], v[114:115], v[40:41] op_sel_hi:[0,1]
	v_pk_mul_f32 v[36:37], v[114:115], v[36:37] op_sel_hi:[0,1]
	v_pk_mul_f32 v[32:33], v[114:115], v[32:33] op_sel_hi:[0,1]
	v_pk_mul_f32 v[46:47], v[114:115], v[46:47] op_sel_hi:[0,1]
	v_pk_mul_f32 v[42:43], v[114:115], v[42:43] op_sel_hi:[0,1]
	v_pk_mul_f32 v[38:39], v[114:115], v[38:39] op_sel_hi:[0,1]
	v_pk_mul_f32 v[34:35], v[114:115], v[34:35] op_sel_hi:[0,1]
	v_pk_mul_f32 v[28:29], v[114:115], v[28:29] op_sel_hi:[0,1]
	v_pk_mul_f32 v[24:25], v[114:115], v[24:25] op_sel_hi:[0,1]
	v_pk_mul_f32 v[20:21], v[114:115], v[20:21] op_sel_hi:[0,1]
	v_pk_mul_f32 v[16:17], v[114:115], v[16:17] op_sel_hi:[0,1]
	v_pk_mul_f32 v[30:31], v[114:115], v[30:31] op_sel_hi:[0,1]
	v_pk_mul_f32 v[26:27], v[114:115], v[26:27] op_sel_hi:[0,1]
	v_pk_mul_f32 v[22:23], v[114:115], v[22:23] op_sel_hi:[0,1]
	v_pk_mul_f32 v[18:19], v[114:115], v[18:19] op_sel_hi:[0,1]
; __device__ __forceinline__ float rms_scale(const float* ssq, int row, int which) {
;     const f32x4 a = *(const f32x4*)(ssq + (size_t)row * 16 + which * 8), b = *(const f32x4*)(ssq + (size_t)row * 16 + which * 8 + 4);
;     const float s = ((a[0] + a[1]) + (a[2] + a[3])) + ((b[0] + b[1]) + (b[2] + b[3]));
;     return 1.0f / sqrtf(s * (1.0f / 512.0f) + RMS_EPS);
; }
;     __device__ __forceinline__ void operator()(EPI_ARGS) const {
;     ...
;             for (int m = 0; m < 4; ++m) { const int row = row0 + ai * HALF + m * 16; const float rs = rms_scale(ssq, row, 1);
; #pragma unroll
;                 for (int bj = 0; bj < 2; ++bj)
;                     *(u32x2*)((unsigned char*)dst + ((size_t)(h0 + bj) * NTOK + row) * 128 + 64 * (wc >> 1) + 32 * (fq & 1) + 8 * ((2 * wc + (fq >> 1)) & 3)) = pack8fp8(acc[ai][bj][m][0] * rs, acc[ai][bj][m][1] * rs); }
	v_pk_mul_f32 v[12:13], v[114:115], v[12:13] op_sel_hi:[0,1]
	v_pk_mul_f32 v[8:9], v[114:115], v[8:9] op_sel_hi:[0,1]
	v_pk_mul_f32 v[4:5], v[114:115], v[4:5] op_sel_hi:[0,1]
	v_pk_mul_f32 v[0:1], v[114:115], v[0:1] op_sel_hi:[0,1]
	v_pk_mul_f32 v[14:15], v[114:115], v[14:15] op_sel_hi:[0,1]
	v_pk_mul_f32 v[10:11], v[114:115], v[10:11] op_sel_hi:[0,1]
	v_pk_mul_f32 v[6:7], v[114:115], v[6:7] op_sel_hi:[0,1]
	v_pk_mul_f32 v[2:3], v[114:115], v[2:3] op_sel_hi:[0,1]
	v_mov_b32_e32 v98, v80
	v_mov_b32_e32 v99, v84
	v_mov_b32_e32 v84, v81
	v_mov_b32_e32 v80, v82
	v_mov_b32_e32 v81, v86
	v_mov_b32_e32 v86, v83
	v_pk_add_f32 v[82:83], v[98:99], v[84:85]
	v_pk_add_f32 v[80:81], v[80:81], v[86:87]
	v_lshl_add_u64 v[84:85], v[108:109], 0, s[36:37]
	v_pk_add_f32 v[80:81], v[82:83], v[80:81]
	v_lshlrev_b64 v[82:83], 7, v[96:97]
	v_add_f32_e32 v80, v80, v81
	v_fmamk_f32 v80, v80, 0x3b000000, v149
	v_rsq_f32_e32 v254, v80
	v_lshlrev_b64 v[84:85], 7, v[84:85]
	s_nop 0
	v_lshl_add_u64 v[80:81], s[8:9], 0, v[94:95]
	s_nop 1
	s_nop 1
	s_nop 1
	v_mov_b32_e32 v86, v254
	v_pk_mul_f32 v[76:77], v[76:77], v[86:87] op_sel_hi:[1,0]
	v_pk_mul_f32 v[72:73], v[72:73], v[86:87] op_sel_hi:[1,0]
	v_pk_mul_f32 v[68:69], v[68:69], v[86:87] op_sel_hi:[1,0]
	v_pk_mul_f32 v[64:65], v[64:65], v[86:87] op_sel_hi:[1,0]
	v_med3_f32 v76, v76, s74, v153
	v_med3_f32 v77, v77, s74, v153
	v_med3_f32 v72, v72, s74, v153
	v_med3_f32 v73, v73, s74, v153
	v_med3_f32 v68, v68, s74, v153
	v_med3_f32 v69, v69, s74, v153
	v_med3_f32 v64, v64, s74, v153
	v_med3_f32 v65, v65, s74, v153
	v_cvt_pk_fp8_f32 v88, v76, v77
	v_cvt_pk_fp8_f32 v89, v72, v73
	v_cvt_pk_fp8_f32 v90, v68, v69
	v_cvt_pk_fp8_f32 v91, v64, v65
	v_pk_mul_f32 v[78:79], v[78:79], v[86:87] op_sel_hi:[1,0]
	v_pk_mul_f32 v[74:75], v[74:75], v[86:87] op_sel_hi:[1,0]
	v_pk_mul_f32 v[70:71], v[70:71], v[86:87] op_sel_hi:[1,0]
	v_pk_mul_f32 v[66:67], v[66:67], v[86:87] op_sel_hi:[1,0]
	v_med3_f32 v78, v78, s74, v153
	v_med3_f32 v79, v79, s74, v153
	v_med3_f32 v74, v74, s74, v153
	v_med3_f32 v75, v75, s74, v153
	v_med3_f32 v70, v70, s74, v153
	v_med3_f32 v71, v71, s74, v153
	v_med3_f32 v66, v66, s74, v153
	v_med3_f32 v67, v67, s74, v153
	v_cvt_pk_fp8_f32 v88, v78, v79 op_sel:[0,0,1]
	v_cvt_pk_fp8_f32 v89, v74, v75 op_sel:[0,0,1]
	v_cvt_pk_fp8_f32 v90, v70, v71 op_sel:[0,0,1]
	v_cvt_pk_fp8_f32 v91, v66, v67 op_sel:[0,0,1]
	v_lshl_add_u64 v[64:65], v[112:113], 0, v[82:83]
	v_lshl_add_u64 v[66:67], v[112:113], 0, v[84:85]
	global_store_dwordx2 v[64:65], v[88:89], off
	global_store_dwordx2 v[66:67], v[90:91], off
	v_mov_b32_e32 v64, v222
	v_mov_b32_e32 v65, v223
	v_mov_b32_e32 v66, v224
	v_mov_b32_e32 v67, v225
	s_nop 0
	v_mov_b32_e32 v68, v226
	v_mov_b32_e32 v69, v227
	v_mov_b32_e32 v70, v228
	v_mov_b32_e32 v71, v229
	v_add_u32_e32 v76, 0x90, v144
	v_ashrrev_i32_e32 v77, 31, v76
	v_lshlrev_b64 v[78:79], 6, v[76:77]
	v_lshl_add_u64 v[80:81], v[92:93], 0, s[14:15]
	v_mov_b32_e32 v82, v64
	v_mov_b32_e32 v83, v68
	v_mov_b32_e32 v68, v65
	v_mov_b32_e32 v64, v66
	v_mov_b32_e32 v65, v70
	v_mov_b32_e32 v70, v67
	v_pk_add_f32 v[66:67], v[82:83], v[68:69]
	v_pk_add_f32 v[64:65], v[64:65], v[70:71]
	v_lshl_add_u64 v[68:69], v[92:93], 0, s[36:37]
	v_pk_add_f32 v[64:65], v[66:67], v[64:65]
	v_lshlrev_b64 v[66:67], 7, v[80:81]
	v_add_f32_e32 v64, v64, v65
	v_fmamk_f32 v64, v64, 0x3b000000, v149
	v_rsq_f32_e32 v254, v64
	v_lshlrev_b64 v[68:69], 7, v[68:69]
	s_nop 0
	v_lshl_add_u64 v[64:65], s[8:9], 0, v[78:79]
	s_nop 1
	s_nop 1
	s_nop 1
	v_mov_b32_e32 v70, v254
	v_pk_mul_f32 v[60:61], v[60:61], v[70:71] op_sel_hi:[1,0]
	v_pk_mul_f32 v[56:57], v[56:57], v[70:71] op_sel_hi:[1,0]
	v_pk_mul_f32 v[52:53], v[52:53], v[70:71] op_sel_hi:[1,0]
	v_pk_mul_f32 v[48:49], v[48:49], v[70:71] op_sel_hi:[1,0]
	v_med3_f32 v60, v60, s74, v153
	v_med3_f32 v61, v61, s74, v153
	v_med3_f32 v56, v56, s74, v153
	v_med3_f32 v57, v57, s74, v153
	v_med3_f32 v52, v52, s74, v153
	v_med3_f32 v53, v53, s74, v153
	v_med3_f32 v48, v48, s74, v153
	v_med3_f32 v49, v49, s74, v153
	v_cvt_pk_fp8_f32 v72, v60, v61
	v_cvt_pk_fp8_f32 v73, v56, v57
	v_cvt_pk_fp8_f32 v74, v52, v53
	v_cvt_pk_fp8_f32 v75, v48, v49
	v_pk_mul_f32 v[62:63], v[62:63], v[70:71] op_sel_hi:[1,0]
	v_pk_mul_f32 v[58:59], v[58:59], v[70:71] op_sel_hi:[1,0]
	v_pk_mul_f32 v[54:55], v[54:55], v[70:71] op_sel_hi:[1,0]
	v_pk_mul_f32 v[50:51], v[50:51], v[70:71] op_sel_hi:[1,0]
	v_med3_f32 v62, v62, s74, v153
	v_med3_f32 v63, v63, s74, v153
	v_med3_f32 v58, v58, s74, v153
	v_med3_f32 v59, v59, s74, v153
	v_med3_f32 v54, v54, s74, v153
	v_med3_f32 v55, v55, s74, v153
	v_med3_f32 v50, v50, s74, v153
	v_med3_f32 v51, v51, s74, v153
	v_cvt_pk_fp8_f32 v72, v62, v63 op_sel:[0,0,1]
	v_cvt_pk_fp8_f32 v73, v58, v59 op_sel:[0,0,1]
	v_cvt_pk_fp8_f32 v74, v54, v55 op_sel:[0,0,1]
	v_cvt_pk_fp8_f32 v75, v50, v51 op_sel:[0,0,1]
	v_lshl_add_u64 v[48:49], v[112:113], 0, v[66:67]
	v_lshl_add_u64 v[50:51], v[112:113], 0, v[68:69]
	global_store_dwordx2 v[48:49], v[72:73], off
	global_store_dwordx2 v[50:51], v[74:75], off
	v_mov_b32_e32 v48, v230
	v_mov_b32_e32 v49, v231
	v_mov_b32_e32 v50, v232
	v_mov_b32_e32 v51, v233
	s_nop 0
	v_mov_b32_e32 v52, v234
	v_mov_b32_e32 v53, v235
	v_mov_b32_e32 v54, v236
	v_mov_b32_e32 v55, v237
	v_add_u32_e32 v60, 0xa0, v144
	v_ashrrev_i32_e32 v61, 31, v60
	v_lshlrev_b64 v[62:63], 6, v[60:61]
	v_lshl_add_u64 v[64:65], v[76:77], 0, s[14:15]
	v_mov_b32_e32 v66, v48
	v_mov_b32_e32 v67, v52
	v_mov_b32_e32 v52, v49
	v_mov_b32_e32 v48, v50
	v_mov_b32_e32 v49, v54
	v_mov_b32_e32 v54, v51
	v_pk_add_f32 v[50:51], v[66:67], v[52:53]
	v_pk_add_f32 v[48:49], v[48:49], v[54:55]
	v_lshl_add_u64 v[52:53], v[76:77], 0, s[36:37]
; #define PG8_BAR __builtin_amdgcn_s_barrier()
;     ...
;         if (wr == 0) PG8_BAR;
;         E(acc, cur, wr, wc, fr, fq);
;         if (!has_next) break;
; #pragma unroll
;         for (int a = 0; a < 2; ++a)
; #pragma unroll
;             for (int b = 0; b < 2; ++b)
; #pragma unroll
;                 for (int m = 0; m < 4; ++m)
; #pragma unroll
;                     for (int n = 0; n < 2; ++n) acc[a][b][m][n] = (f32x4){0.f, 0.f, 0.f, 0.f};
;         cur = nxt; cA = nA; cB = nB; ++ui;
;         if (wr == 1) PG8_BAR;
;     }
; __device__ __forceinline__ float rms_scale(const float* ssq, int row, int which) {
;     const f32x4 a = *(const f32x4*)(ssq + (size_t)row * 16 + which * 8), b = *(const f32x4*)(ssq + (size_t)row * 16 + which * 8 + 4);
;     const float s = ((a[0] + a[1]) + (a[2] + a[3])) + ((b[0] + b[1]) + (b[2] + b[3]));
;     return 1.0f / sqrtf(s * (1.0f / 512.0f) + RMS_EPS);
; }
;     __device__ __forceinline__ void operator()(EPI_ARGS) const {
;     ...
;             for (int m = 0; m < 4; ++m) { const int row = row0 + ai * HALF + m * 16; const float rs = rms_scale(ssq, row, 1);
; #pragma unroll
;                 for (int bj = 0; bj < 2; ++bj)
;                     *(u32x2*)((unsigned char*)dst + ((size_t)(h0 + bj) * NTOK + row) * 128 + 64 * (wc >> 1) + 32 * (fq & 1) + 8 * ((2 * wc + (fq >> 1)) & 3)) = pack8fp8(acc[ai][bj][m][0] * rs, acc[ai][bj][m][1] * rs); }
	v_pk_add_f32 v[48:49], v[50:51], v[48:49]
	v_lshlrev_b64 v[50:51], 7, v[64:65]
	v_add_f32_e32 v48, v48, v49
	v_fmamk_f32 v48, v48, 0x3b000000, v149
	v_rsq_f32_e32 v254, v48
	v_lshlrev_b64 v[52:53], 7, v[52:53]
	s_nop 0
	v_lshl_add_u64 v[48:49], s[8:9], 0, v[62:63]
	s_nop 1
	s_nop 1
	s_nop 1
	v_mov_b32_e32 v54, v254
	v_pk_mul_f32 v[44:45], v[44:45], v[54:55] op_sel_hi:[1,0]
	v_pk_mul_f32 v[40:41], v[40:41], v[54:55] op_sel_hi:[1,0]
	v_pk_mul_f32 v[36:37], v[36:37], v[54:55] op_sel_hi:[1,0]
	v_pk_mul_f32 v[32:33], v[32:33], v[54:55] op_sel_hi:[1,0]
	v_med3_f32 v44, v44, s74, v153
	v_med3_f32 v45, v45, s74, v153
	v_med3_f32 v40, v40, s74, v153
	v_med3_f32 v41, v41, s74, v153
	v_med3_f32 v36, v36, s74, v153
	v_med3_f32 v37, v37, s74, v153
	v_med3_f32 v32, v32, s74, v153
	v_med3_f32 v33, v33, s74, v153
	v_cvt_pk_fp8_f32 v56, v44, v45
	v_cvt_pk_fp8_f32 v57, v40, v41
	v_cvt_pk_fp8_f32 v58, v36, v37
	v_cvt_pk_fp8_f32 v59, v32, v33
	v_pk_mul_f32 v[46:47], v[46:47], v[54:55] op_sel_hi:[1,0]
	v_pk_mul_f32 v[42:43], v[42:43], v[54:55] op_sel_hi:[1,0]
	v_pk_mul_f32 v[38:39], v[38:39], v[54:55] op_sel_hi:[1,0]
	v_pk_mul_f32 v[34:35], v[34:35], v[54:55] op_sel_hi:[1,0]
	v_med3_f32 v46, v46, s74, v153
	v_med3_f32 v47, v47, s74, v153
	v_med3_f32 v42, v42, s74, v153
	v_med3_f32 v43, v43, s74, v153
	v_med3_f32 v38, v38, s74, v153
	v_med3_f32 v39, v39, s74, v153
	v_med3_f32 v34, v34, s74, v153
	v_med3_f32 v35, v35, s74, v153
	v_cvt_pk_fp8_f32 v56, v46, v47 op_sel:[0,0,1]
	v_cvt_pk_fp8_f32 v57, v42, v43 op_sel:[0,0,1]
	v_cvt_pk_fp8_f32 v58, v38, v39 op_sel:[0,0,1]
	v_cvt_pk_fp8_f32 v59, v34, v35 op_sel:[0,0,1]
	v_lshl_add_u64 v[32:33], v[112:113], 0, v[50:51]
	v_lshl_add_u64 v[34:35], v[112:113], 0, v[52:53]
	global_store_dwordx2 v[32:33], v[56:57], off
	global_store_dwordx2 v[34:35], v[58:59], off
	v_mov_b32_e32 v32, v238
	v_mov_b32_e32 v33, v239
	v_mov_b32_e32 v34, v240
	v_mov_b32_e32 v35, v241
	s_nop 0
	v_mov_b32_e32 v36, v242
	v_mov_b32_e32 v37, v243
	v_mov_b32_e32 v38, v244
	v_mov_b32_e32 v39, v245
	v_add_u32_e32 v44, 0xb0, v144
	v_ashrrev_i32_e32 v45, 31, v44
	v_lshlrev_b64 v[46:47], 6, v[44:45]
	v_lshl_add_u64 v[48:49], v[60:61], 0, s[14:15]
	v_mov_b32_e32 v50, v32
	v_mov_b32_e32 v51, v36
	v_mov_b32_e32 v36, v33
	v_mov_b32_e32 v32, v34
	v_mov_b32_e32 v33, v38
	v_mov_b32_e32 v38, v35
	v_pk_add_f32 v[34:35], v[50:51], v[36:37]
	v_pk_add_f32 v[32:33], v[32:33], v[38:39]
	v_lshl_add_u64 v[36:37], v[60:61], 0, s[36:37]
	v_pk_add_f32 v[32:33], v[34:35], v[32:33]
	v_lshlrev_b64 v[34:35], 7, v[48:49]
	v_add_f32_e32 v32, v32, v33
	v_fmamk_f32 v32, v32, 0x3b000000, v149
	v_rsq_f32_e32 v254, v32
	v_lshlrev_b64 v[36:37], 7, v[36:37]
	s_nop 0
	v_lshl_add_u64 v[32:33], s[8:9], 0, v[46:47]
	s_nop 1
	s_nop 1
	s_nop 1
	v_mov_b32_e32 v38, v254
	v_pk_mul_f32 v[28:29], v[28:29], v[38:39] op_sel_hi:[1,0]
	v_pk_mul_f32 v[24:25], v[24:25], v[38:39] op_sel_hi:[1,0]
	v_pk_mul_f32 v[20:21], v[20:21], v[38:39] op_sel_hi:[1,0]
	v_pk_mul_f32 v[16:17], v[16:17], v[38:39] op_sel_hi:[1,0]
	v_med3_f32 v28, v28, s74, v153
	v_med3_f32 v29, v29, s74, v153
	v_med3_f32 v24, v24, s74, v153
	v_med3_f32 v25, v25, s74, v153
	v_med3_f32 v20, v20, s74, v153
	v_med3_f32 v21, v21, s74, v153
	v_med3_f32 v16, v16, s74, v153
	v_med3_f32 v17, v17, s74, v153
	v_cvt_pk_fp8_f32 v40, v28, v29
	v_cvt_pk_fp8_f32 v41, v24, v25
	v_cvt_pk_fp8_f32 v42, v20, v21
	v_cvt_pk_fp8_f32 v43, v16, v17
	v_pk_mul_f32 v[30:31], v[30:31], v[38:39] op_sel_hi:[1,0]
	v_pk_mul_f32 v[26:27], v[26:27], v[38:39] op_sel_hi:[1,0]
	v_pk_mul_f32 v[22:23], v[22:23], v[38:39] op_sel_hi:[1,0]
	v_pk_mul_f32 v[18:19], v[18:19], v[38:39] op_sel_hi:[1,0]
	v_med3_f32 v30, v30, s74, v153
	v_med3_f32 v31, v31, s74, v153
	v_med3_f32 v26, v26, s74, v153
	v_med3_f32 v27, v27, s74, v153
	v_med3_f32 v22, v22, s74, v153
	v_med3_f32 v23, v23, s74, v153
	v_med3_f32 v18, v18, s74, v153
	v_med3_f32 v19, v19, s74, v153
	v_cvt_pk_fp8_f32 v40, v30, v31 op_sel:[0,0,1]
	v_cvt_pk_fp8_f32 v41, v26, v27 op_sel:[0,0,1]
	v_cvt_pk_fp8_f32 v42, v22, v23 op_sel:[0,0,1]
	v_cvt_pk_fp8_f32 v43, v18, v19 op_sel:[0,0,1]
	v_lshl_add_u64 v[16:17], v[112:113], 0, v[34:35]
	v_lshl_add_u64 v[18:19], v[112:113], 0, v[36:37]
	global_store_dwordx2 v[16:17], v[40:41], off
	global_store_dwordx2 v[18:19], v[42:43], off
	v_mov_b32_e32 v16, v246
	v_mov_b32_e32 v17, v247
	v_mov_b32_e32 v18, v248
	v_mov_b32_e32 v19, v249
	s_nop 0
	v_mov_b32_e32 v20, v250
	v_mov_b32_e32 v21, v251
	v_mov_b32_e32 v22, v252
	v_mov_b32_e32 v23, v253
	v_lshl_add_u64 v[28:29], v[44:45], 0, s[14:15]
	v_mov_b32_e32 v30, v16
	v_mov_b32_e32 v31, v20
	v_mov_b32_e32 v20, v17
	v_mov_b32_e32 v16, v18
	v_mov_b32_e32 v17, v22
	v_mov_b32_e32 v22, v19
	v_pk_add_f32 v[18:19], v[30:31], v[20:21]
	v_pk_add_f32 v[16:17], v[16:17], v[22:23]
	s_nop 0
	v_pk_add_f32 v[16:17], v[18:19], v[16:17]
	v_lshl_add_u64 v[18:19], v[44:45], 0, s[36:37]
	v_add_f32_e32 v16, v16, v17
	v_fmamk_f32 v16, v16, 0x3b000000, v149
	v_rsq_f32_e32 v254, v16
	v_lshlrev_b64 v[18:19], 7, v[18:19]
	s_nop 0
	v_lshlrev_b64 v[16:17], 7, v[28:29]
	v_lshl_add_u64 v[16:17], v[112:113], 0, v[16:17]
	s_nop 1
	s_nop 1
	s_nop 1
	v_mov_b32_e32 v20, v254
	v_pk_mul_f32 v[12:13], v[12:13], v[20:21] op_sel_hi:[1,0]
	v_pk_mul_f32 v[8:9], v[8:9], v[20:21] op_sel_hi:[1,0]
	v_pk_mul_f32 v[4:5], v[4:5], v[20:21] op_sel_hi:[1,0]
	v_pk_mul_f32 v[0:1], v[0:1], v[20:21] op_sel_hi:[1,0]
	v_med3_f32 v12, v12, s74, v153
	v_med3_f32 v13, v13, s74, v153
	v_med3_f32 v8, v8, s74, v153
	v_med3_f32 v9, v9, s74, v153
	v_med3_f32 v4, v4, s74, v153
	v_med3_f32 v5, v5, s74, v153
	v_med3_f32 v0, v0, s74, v153
	v_med3_f32 v1, v1, s74, v153
	v_cvt_pk_fp8_f32 v24, v12, v13
	v_cvt_pk_fp8_f32 v25, v8, v9
	v_cvt_pk_fp8_f32 v26, v4, v5
	v_cvt_pk_fp8_f32 v27, v0, v1
	v_pk_mul_f32 v[14:15], v[14:15], v[20:21] op_sel_hi:[1,0]
	v_pk_mul_f32 v[10:11], v[10:11], v[20:21] op_sel_hi:[1,0]
	v_pk_mul_f32 v[6:7], v[6:7], v[20:21] op_sel_hi:[1,0]
	v_pk_mul_f32 v[2:3], v[2:3], v[20:21] op_sel_hi:[1,0]
	v_med3_f32 v14, v14, s74, v153
	v_med3_f32 v15, v15, s74, v153
	v_med3_f32 v10, v10, s74, v153
	v_med3_f32 v11, v11, s74, v153
	v_med3_f32 v6, v6, s74, v153
	v_med3_f32 v7, v7, s74, v153
	v_med3_f32 v2, v2, s74, v153
	v_med3_f32 v3, v3, s74, v153
	v_cvt_pk_fp8_f32 v24, v14, v15 op_sel:[0,0,1]
	v_cvt_pk_fp8_f32 v25, v10, v11 op_sel:[0,0,1]
	v_cvt_pk_fp8_f32 v26, v6, v7 op_sel:[0,0,1]
	v_cvt_pk_fp8_f32 v27, v2, v3 op_sel:[0,0,1]
	s_andn2_b64 vcc, exec, s[2:3]
	s_mov_b64 s[2:3], -1
	v_lshl_add_u64 v[0:1], v[112:113], 0, v[18:19]
	global_store_dwordx2 v[16:17], v[24:25], off
	global_store_dwordx2 v[0:1], v[26:27], off
	s_cbranch_vccnz .LBB0_4130
	s_andn2_b64 vcc, exec, s[16:17]
	s_cbranch_vccnz .LBB0_4129
	s_barrier
	s_branch .LBB0_4129

;     __device__ __forceinline__ float qscale(const Unit& u) const { return ((u.pn >= 8 && u.pn <= 11) || u.pn == 17) ? 0.5f : 1.0f; }
;     ...
;         if constexpr (QM == 2) { const float qs0_ = g.qs * E.qscale(cur), qs1_ = qs0_ * g.qs_b1; _Pragma("unroll") for (int a = 0; a < 2; ++a) _Pragma("unroll") for (int b = 0; b < 2; ++b) _Pragma("unroll") for (int m = 0; m < 4; ++m) _Pragma("unroll") for (int n = 0; n < 2; ++n) { const v4i t_ = __builtin_bit_cast(v4i, acc[a][b][m][n]); acc[a][b][m][n] = (f32x4){(float)t_[0], (float)t_[1], (float)t_[2], (float)t_[3]} * (b == 0 ? qs0_ : qs1_); } }
; __device__ __forceinline__ float rms_scale(const float* ssq, int row, int which) {
;     const f32x4 a = *(const f32x4*)(ssq + (size_t)row * 16 + which * 8), b = *(const f32x4*)(ssq + (size_t)row * 16 + which * 8 + 4);
;     const float s = ((a[0] + a[1]) + (a[2] + a[3])) + ((b[0] + b[1]) + (b[2] + b[3]));
;     return 1.0f / sqrtf(s * (1.0f / 512.0f) + RMS_EPS);
; }
.LBB0_4165:
	s_lshl_b32 s4, s4, 8
	s_add_i32 s36, s4, s63
	v_or_b32_e32 v142, s36, v145
	v_ashrrev_i32_e32 v143, 31, v142
	v_lshlrev_b64 v[152:153], 6, v[142:143]
	v_or_b32_e32 v160, 1, v142
	v_lshl_add_u64 v[156:157], s[8:9], 0, v[152:153]
	v_ashrrev_i32_e32 v161, 31, v160
	global_load_dwordx4 v[152:155], v[156:157], off offset:32
	s_nop 0
	global_load_dwordx4 v[156:159], v[156:157], off offset:48
	v_lshlrev_b64 v[160:161], 6, v[160:161]
	v_lshl_add_u64 v[164:165], s[8:9], 0, v[160:161]
	global_load_dwordx4 v[160:163], v[164:165], off offset:32
	s_nop 0
	global_load_dwordx4 v[164:167], v[164:165], off offset:48
	v_cvt_f32_i32_e32 v115, v115
	v_cvt_f32_i32_e32 v114, v114
	v_cvt_f32_i32_e32 v113, v113
	v_cvt_f32_i32_e32 v112, v112
	v_cvt_f32_i32_e32 v169, v119
	v_cvt_f32_i32_e32 v168, v118
	v_cvt_f32_i32_e32 v117, v117
	v_cvt_f32_i32_e32 v116, v116
	v_cvt_f32_i32_e32 v127, v127
	v_cvt_f32_i32_e32 v126, v126
	v_cvt_f32_i32_e32 v125, v125
	v_cvt_f32_i32_e32 v124, v124
	v_cvt_f32_i32_e32 v123, v123
	v_cvt_f32_i32_e32 v122, v122
	v_cvt_f32_i32_e32 v121, v121
	v_cvt_f32_i32_e32 v120, v120
	v_or_b32_e32 v170, 2, v142
	v_or_b32_e32 v172, 3, v142
	v_ashrrev_i32_e32 v171, 31, v170
	v_ashrrev_i32_e32 v173, 31, v172
	v_pk_mul_f32 v[186:187], v[112:113], s[18:19] op_sel_hi:[1,0]
	v_pk_mul_f32 v[188:189], v[114:115], s[18:19] op_sel_hi:[1,0]
	v_lshlrev_b64 v[112:113], 6, v[170:171]
	v_lshlrev_b64 v[114:115], 6, v[172:173]
	v_pk_mul_f32 v[182:183], v[116:117], s[18:19] op_sel_hi:[1,0]
	v_pk_mul_f32 v[184:185], v[168:169], s[18:19] op_sel_hi:[1,0]
	v_lshl_add_u64 v[116:117], s[8:9], 0, v[112:113]
	v_lshl_add_u64 v[168:169], s[8:9], 0, v[114:115]
	v_pk_mul_f32 v[174:175], v[124:125], s[18:19] op_sel_hi:[1,0]
	v_pk_mul_f32 v[176:177], v[126:127], s[18:19] op_sel_hi:[1,0]
	v_pk_mul_f32 v[178:179], v[120:121], s[18:19] op_sel_hi:[1,0]
	v_pk_mul_f32 v[180:181], v[122:123], s[18:19] op_sel_hi:[1,0]
	global_load_dwordx4 v[112:115], v[116:117], off offset:32
	global_load_dwordx4 v[120:123], v[116:117], off offset:48
	global_load_dwordx4 v[124:127], v[168:169], off offset:32
	s_nop 0
	global_load_dwordx4 v[168:171], v[168:169], off offset:48
	v_lshl_or_b32 v118, s5, 8, v146
	s_ashr_i32 s37, s36, 31
	v_cvt_f32_i32_e32 v109, v109
	v_cvt_f32_i32_e32 v108, v108
	v_cvt_f32_i32_e32 v105, v105
	v_cvt_f32_i32_e32 v104, v104
	v_cvt_f32_i32_e32 v97, v97
	v_cvt_f32_i32_e32 v96, v96
	v_cvt_f32_i32_e32 v99, v99
	v_cvt_f32_i32_e32 v98, v98
	v_cvt_f32_i32_e32 v101, v101
	v_pk_mul_f32 v[172:173], v[96:97], s[18:19] op_sel_hi:[1,0]
	v_cvt_f32_i32_e32 v100, v100
	v_cvt_f32_i32_e32 v103, v103
	v_cvt_f32_i32_e32 v102, v102
	v_cvt_f32_i32_e32 v93, v93
	v_pk_mul_f32 v[100:101], v[100:101], s[18:19] op_sel_hi:[1,0]
	v_cvt_f32_i32_e32 v92, v92
	v_pk_mul_f32 v[102:103], v[102:103], s[18:19] op_sel_hi:[1,0]
	v_cvt_f32_i32_e32 v89, v89
	v_cvt_f32_i32_e32 v88, v88
	v_cvt_f32_i32_e32 v81, v81
	v_cvt_f32_i32_e32 v80, v80
	v_cvt_f32_i32_e32 v83, v83
	v_cvt_f32_i32_e32 v82, v82
	v_cvt_f32_i32_e32 v85, v85
	v_cvt_f32_i32_e32 v84, v84
	v_cvt_f32_i32_e32 v87, v87
	v_cvt_f32_i32_e32 v86, v86
	v_cvt_f32_i32_e32 v77, v77
	v_pk_mul_f32 v[84:85], v[84:85], s[18:19] op_sel_hi:[1,0]
	v_cvt_f32_i32_e32 v76, v76
	v_pk_mul_f32 v[86:87], v[86:87], s[18:19] op_sel_hi:[1,0]
	v_cvt_f32_i32_e32 v73, v73
	v_cvt_f32_i32_e32 v72, v72
	v_cvt_f32_i32_e32 v65, v65
	v_cvt_f32_i32_e32 v64, v64
	v_cvt_f32_i32_e32 v67, v67
	v_cvt_f32_i32_e32 v66, v66
	v_cvt_f32_i32_e32 v69, v69
	v_cvt_f32_i32_e32 v68, v68
	v_cvt_f32_i32_e32 v71, v71
	s_waitcnt vmcnt(0)
	v_mov_b32_e32 v116, v152
	v_mov_b32_e32 v117, v156
	v_mov_b32_e32 v156, v153
	v_mov_b32_e32 v152, v154
	v_mov_b32_e32 v153, v158
	v_mov_b32_e32 v158, v155
	v_pk_add_f32 v[116:117], v[116:117], v[156:157]
	v_pk_add_f32 v[152:153], v[152:153], v[158:159]
	v_mov_b32_e32 v154, v160
	v_mov_b32_e32 v155, v164
	v_mov_b32_e32 v164, v161
	v_mov_b32_e32 v156, v162
	v_mov_b32_e32 v157, v166
	v_mov_b32_e32 v166, v163
	v_pk_add_f32 v[116:117], v[116:117], v[152:153]
	v_pk_add_f32 v[152:153], v[154:155], v[164:165]
	v_pk_add_f32 v[154:155], v[156:157], v[166:167]
	v_add_f32_e32 v119, v116, v117
	v_pk_add_f32 v[116:117], v[152:153], v[154:155]
	v_fmamk_f32 v119, v119, 0x3b000000, v148
	v_add_f32_e32 v116, v116, v117
	v_mul_f32_e32 v117, 0x4f800000, v119
	v_cmp_gt_f32_e32 vcc, s68, v119
	v_fmamk_f32 v116, v116, 0x3b000000, v148
	v_cmp_gt_f32_e64 s[4:5], s68, v116
	v_cndmask_b32_e32 v117, v119, v117, vcc
	v_sqrt_f32_e32 v143, v117
	v_mul_f32_e32 v119, 0x4f800000, v116
	v_cndmask_b32_e64 v116, v116, v119, s[4:5]
	v_sqrt_f32_e32 v119, v116
	v_add_u32_e32 v151, -1, v143
	v_add_u32_e32 v152, 1, v143
	v_fma_f32 v153, -v151, v143, v117
	v_fma_f32 v154, -v152, v143, v117
	v_cmp_ge_f32_e64 s[6:7], 0, v153
	v_add_u32_e32 v155, -1, v119
	v_add_u32_e32 v156, 1, v119
	v_cndmask_b32_e64 v143, v143, v151, s[6:7]
	v_cmp_lt_f32_e64 s[6:7], 0, v154
	v_fma_f32 v151, -v155, v119, v116
	v_fma_f32 v153, -v156, v119, v116
	v_cndmask_b32_e64 v143, v143, v152, s[6:7]
	v_cmp_ge_f32_e64 s[6:7], 0, v151
	v_mul_f32_e32 v151, 0x37800000, v143
	v_cndmask_b32_e32 v143, v143, v151, vcc
	v_cmp_class_f32_e32 vcc, v117, v149
	v_cndmask_b32_e64 v119, v119, v155, s[6:7]
	v_cmp_lt_f32_e64 s[6:7], 0, v153
	v_cndmask_b32_e32 v117, v143, v117, vcc
	v_or_b32_e32 v160, 17, v142
	v_cndmask_b32_e64 v119, v119, v156, s[6:7]
	v_div_scale_f32 v143, s[6:7], v117, v117, 1.0
	v_rcp_f32_e32 v152, v143
	v_mul_f32_e32 v151, 0x37800000, v119
	v_cndmask_b32_e64 v119, v119, v151, s[4:5]
	v_div_scale_f32 v151, vcc, 1.0, v117, 1.0
	v_fma_f32 v153, -v143, v152, 1.0
	v_fmac_f32_e32 v152, v153, v152
	v_mul_f32_e32 v153, v151, v152
; __device__ __forceinline__ float clamp448(float x) { return __builtin_amdgcn_fmed3f(x, -448.0f, 448.0f); }
; __device__ __forceinline__ float rms_scale(const float* ssq, int row, int which) {
;     const f32x4 a = *(const f32x4*)(ssq + (size_t)row * 16 + which * 8), b = *(const f32x4*)(ssq + (size_t)row * 16 + which * 8 + 4);
;     const float s = ((a[0] + a[1]) + (a[2] + a[3])) + ((b[0] + b[1]) + (b[2] + b[3]));
;     return 1.0f / sqrtf(s * (1.0f / 512.0f) + RMS_EPS);
; }
;     __device__ __forceinline__ void operator()(EPI_ARGS) const {
;     ...
;             for (int m = 0; m < 4; ++m) { const int t0 = u.pm * BM + ai * HALF + wr * 64 + 16 * m + 4 * fq, q = 4 * m + fq;
;                 const f32x4 rs = (f32x4){rms_scale(ssq, t0, 1), rms_scale(ssq, t0 + 1, 1), rms_scale(ssq, t0 + 2, 1), rms_scale(ssq, t0 + 3, 1)} * osc;
;                 const size_t tpos = (size_t)(t0 & ~63) + 32 * (q & 1) + 16 * (q >> 3) + 4 * ((q >> 1) & 3);
; #pragma unroll
;                 for (int bj = 0; bj < 2; ++bj)
; #pragma unroll
;                     for (int n = 0; n < 2; ++n) { const f32x4 v = acc[ai][bj][m][n] * rs;
;                         int w = __builtin_amdgcn_cvt_pk_fp8_f32(clamp448(v[0]), clamp448(v[1]), 0, false); w = __builtin_amdgcn_cvt_pk_fp8_f32(clamp448(v[2]), clamp448(v[3]), w, true);
;                         *(unsigned*)(VT + ((size_t)((2 * u.pn + bj) * 128 + dcol + 4 * n)) * NTOK + tpos) = (unsigned)w; } }
	v_fma_f32 v154, -v143, v153, v151
	v_fmac_f32_e32 v153, v154, v152
	v_fma_f32 v143, -v143, v153, v151
	v_cmp_class_f32_e64 s[4:5], v116, v149
	v_ashrrev_i32_e32 v161, 31, v160
	v_lshlrev_b64 v[160:161], 6, v[160:161]
	v_cndmask_b32_e64 v119, v119, v116, s[4:5]
	v_div_fmas_f32 v116, v143, v152, v153
	v_mov_b32_e32 v152, v112
	v_mov_b32_e32 v153, v120
	v_mov_b32_e32 v120, v113
	v_pk_add_f32 v[112:113], v[152:153], v[120:121]
	v_mov_b32_e32 v120, v114
	v_mov_b32_e32 v121, v122
	v_mov_b32_e32 v122, v115
	v_pk_add_f32 v[114:115], v[120:121], v[122:123]
	v_div_scale_f32 v151, s[4:5], v119, v119, 1.0
	v_pk_add_f32 v[112:113], v[112:113], v[114:115]
	v_rcp_f32_e32 v154, v151
	v_add_f32_e32 v112, v112, v113
	v_fmamk_f32 v112, v112, 0x3b000000, v148
	v_mul_f32_e32 v113, 0x4f800000, v112
	v_cmp_gt_f32_e64 s[4:5], s68, v112
	v_div_fixup_f32 v116, v116, v117, 1.0
	v_fma_f32 v117, -v151, v154, 1.0
	v_cndmask_b32_e64 v112, v112, v113, s[4:5]
	v_sqrt_f32_e32 v113, v112
	v_fmac_f32_e32 v154, v117, v154
	v_div_scale_f32 v117, vcc, 1.0, v119, 1.0
	v_mul_f32_e32 v143, v117, v154
	v_fma_f32 v114, -v151, v143, v117
	v_fmac_f32_e32 v143, v114, v154
	v_add_u32_e32 v115, -1, v113
	v_fma_f32 v114, -v151, v143, v117
	v_fma_f32 v117, -v115, v113, v112
	v_cmp_ge_f32_e64 s[6:7], 0, v117
	v_add_u32_e32 v117, 1, v113
	v_lshl_add_u64 v[164:165], s[8:9], 0, v[160:161]
	v_cndmask_b32_e64 v115, v113, v115, s[6:7]
	v_fma_f32 v113, -v117, v113, v112
	v_cmp_lt_f32_e64 s[6:7], 0, v113
	v_cvt_f32_i32_e32 v70, v70
	v_pk_mul_f32 v[68:69], v[68:69], s[18:19] op_sel_hi:[1,0]
	v_cndmask_b32_e64 v113, v115, v117, s[6:7]
	v_mul_f32_e32 v115, 0x37800000, v113
	v_cndmask_b32_e64 v113, v113, v115, s[4:5]
	v_cmp_class_f32_e64 s[4:5], v112, v149
	v_mov_b32_e32 v115, v170
	v_mov_b32_e32 v170, v127
	v_cndmask_b32_e64 v120, v113, v112, s[4:5]
	v_div_scale_f32 v121, s[4:5], v120, v120, 1.0
	v_rcp_f32_e32 v122, v121
	v_div_fmas_f32 v112, v114, v154, v143
	v_div_fixup_f32 v117, v112, v119, 1.0
	v_mov_b32_e32 v113, v168
	v_fma_f32 v112, -v121, v122, 1.0
	v_fmac_f32_e32 v122, v112, v122
	v_mov_b32_e32 v112, v124
	v_mov_b32_e32 v168, v125
	v_mov_b32_e32 v114, v126
	v_pk_add_f32 v[112:113], v[112:113], v[168:169]
	v_pk_add_f32 v[114:115], v[114:115], v[170:171]
	v_div_scale_f32 v119, vcc, 1.0, v120, 1.0
	v_pk_add_f32 v[112:113], v[112:113], v[114:115]
	v_mul_f32_e32 v123, v119, v122
	v_add_f32_e32 v112, v112, v113
	v_fmamk_f32 v112, v112, 0x3b000000, v148
	v_mul_f32_e32 v113, 0x4f800000, v112
	v_cmp_gt_f32_e64 s[4:5], s68, v112
	v_fma_f32 v114, -v121, v123, v119
	v_fmac_f32_e32 v123, v114, v122
	v_cndmask_b32_e64 v112, v112, v113, s[4:5]
	v_sqrt_f32_e32 v113, v112
	v_fma_f32 v114, -v121, v123, v119
	v_pk_mul_f32 v[126:127], v[116:117], s[20:21] op_sel_hi:[1,0]
	v_lshl_add_u64 v[154:155], v[136:137], 0, s[36:37]
	v_add_u32_e32 v115, -1, v113
	v_fma_f32 v119, -v115, v113, v112
	v_cmp_ge_f32_e64 s[6:7], 0, v119
	v_add_u32_e32 v119, 1, v113
	v_pk_mul_f32 v[124:125], v[182:183], v[126:127]
	v_cndmask_b32_e64 v115, v113, v115, s[6:7]
	v_fma_f32 v113, -v119, v113, v112
	v_cmp_lt_f32_e64 s[6:7], 0, v113
	v_mov_b32_e32 v143, 0
	v_cvt_f32_i32_e32 v169, v111
	v_cndmask_b32_e64 v113, v115, v119, s[6:7]
	v_mul_f32_e32 v115, 0x37800000, v113
	v_cndmask_b32_e64 v113, v113, v115, s[4:5]
	v_cmp_class_f32_e64 s[4:5], v112, v149
	v_cvt_f32_i32_e32 v168, v110
	v_pk_mul_f32 v[110:111], v[108:109], s[18:19] op_sel_hi:[1,0]
	v_cndmask_b32_e64 v113, v113, v112, s[4:5]
	v_div_scale_f32 v115, s[4:5], v113, v113, 1.0
	v_rcp_f32_e32 v119, v115
	v_div_fmas_f32 v112, v114, v122, v123
	v_div_fixup_f32 v112, v112, v120, 1.0
	v_pk_mul_f32 v[108:109], v[168:169], s[18:19] op_sel_hi:[1,0]
	v_fma_f32 v114, -v115, v119, 1.0
	v_fmac_f32_e32 v119, v114, v119
	v_div_scale_f32 v114, vcc, 1.0, v113, 1.0
	v_mul_f32_e32 v120, v114, v119
	v_fma_f32 v121, -v115, v120, v114
	v_fmac_f32_e32 v120, v121, v119
	v_fma_f32 v114, -v115, v120, v114
	v_div_fmas_f32 v114, v114, v119, v120
	v_div_fixup_f32 v113, v114, v113, 1.0
	v_pk_mul_f32 v[152:153], v[112:113], s[20:21] op_sel_hi:[1,0]
	v_pk_mul_f32 v[112:113], v[174:175], v[126:127]
	v_med3_f32 v112, v112, s69, v150
	v_med3_f32 v113, v113, s69, v150
	v_cvt_pk_fp8_f32 v114, v112, v113
	v_pk_mul_f32 v[112:113], v[176:177], v[152:153]
	v_ashrrev_i32_e32 v119, 31, v118
	v_med3_f32 v112, v112, s69, v150
	v_med3_f32 v113, v113, s69, v150
	v_cvt_pk_fp8_f32 v114, v112, v113 op_sel:[0,0,1]
	v_lshlrev_b64 v[112:113], 14, v[118:119]
	v_lshl_add_u64 v[120:121], v[154:155], 0, v[112:113]
	global_store_dword v[120:121], v114, off
	v_pk_mul_f32 v[114:115], v[178:179], v[126:127]
	v_pk_mul_f32 v[126:127], v[186:187], v[126:127]
	v_med3_f32 v114, v114, s69, v150
	v_med3_f32 v115, v115, s69, v150
	v_cvt_pk_fp8_f32 v119, v114, v115
	v_pk_mul_f32 v[114:115], v[180:181], v[152:153]
	v_cvt_f32_i32_e32 v169, v107
	v_med3_f32 v114, v114, s69, v150
	v_med3_f32 v115, v115, s69, v150
	v_cvt_pk_fp8_f32 v119, v114, v115 op_sel:[0,0,1]
	v_or_b32_e32 v114, 4, v118
	v_ashrrev_i32_e32 v115, 31, v114
	v_lshlrev_b64 v[116:117], 14, v[114:115]
	v_lshl_add_u64 v[122:123], v[154:155], 0, v[116:117]
	global_store_dword v[122:123], v119, off
	v_med3_f32 v115, v124, s69, v150
	v_med3_f32 v119, v125, s69, v150
	v_cvt_pk_fp8_f32 v143, v115, v119
	v_pk_mul_f32 v[124:125], v[184:185], v[152:153]
	v_or_b32_e32 v114, 0x80, v118
	v_med3_f32 v115, v124, s69, v150
	v_med3_f32 v119, v125, s69, v150
	v_cvt_pk_fp8_f32 v143, v115, v119 op_sel:[0,0,1]
	v_ashrrev_i32_e32 v115, 31, v114
	v_lshlrev_b64 v[114:115], 14, v[114:115]
	v_lshl_add_u64 v[124:125], v[154:155], 0, v[114:115]
	global_store_dword v[124:125], v143, off
	v_med3_f32 v119, v126, s69, v150
; __device__ __forceinline__ float clamp448(float x) { return __builtin_amdgcn_fmed3f(x, -448.0f, 448.0f); }
; __device__ __forceinline__ float rms_scale(const float* ssq, int row, int which) {
;     const f32x4 a = *(const f32x4*)(ssq + (size_t)row * 16 + which * 8), b = *(const f32x4*)(ssq + (size_t)row * 16 + which * 8 + 4);
;     const float s = ((a[0] + a[1]) + (a[2] + a[3])) + ((b[0] + b[1]) + (b[2] + b[3]));
;     return 1.0f / sqrtf(s * (1.0f / 512.0f) + RMS_EPS);
; }
;     __device__ __forceinline__ void operator()(EPI_ARGS) const {
;     ...
;             for (int m = 0; m < 4; ++m) { const int t0 = u.pm * BM + ai * HALF + wr * 64 + 16 * m + 4 * fq, q = 4 * m + fq;
;                 const f32x4 rs = (f32x4){rms_scale(ssq, t0, 1), rms_scale(ssq, t0 + 1, 1), rms_scale(ssq, t0 + 2, 1), rms_scale(ssq, t0 + 3, 1)} * osc;
;                 const size_t tpos = (size_t)(t0 & ~63) + 32 * (q & 1) + 16 * (q >> 3) + 4 * ((q >> 1) & 3);
; #pragma unroll
;                 for (int bj = 0; bj < 2; ++bj)
; #pragma unroll
;                     for (int n = 0; n < 2; ++n) { const f32x4 v = acc[ai][bj][m][n] * rs;
;                         int w = __builtin_amdgcn_cvt_pk_fp8_f32(clamp448(v[0]), clamp448(v[1]), 0, false); w = __builtin_amdgcn_cvt_pk_fp8_f32(clamp448(v[2]), clamp448(v[3]), w, true);
;                         *(unsigned*)(VT + ((size_t)((2 * u.pn + bj) * 128 + dcol + 4 * n)) * NTOK + tpos) = (unsigned)w; } }
	v_med3_f32 v126, v127, s69, v150
	v_cvt_pk_fp8_f32 v143, v119, v126
	v_pk_mul_f32 v[126:127], v[188:189], v[152:153]
	v_or_b32_e32 v118, 0x84, v118
	v_med3_f32 v119, v126, s69, v150
	v_med3_f32 v126, v127, s69, v150
	v_cvt_pk_fp8_f32 v143, v119, v126 op_sel:[0,0,1]
	v_ashrrev_i32_e32 v119, 31, v118
	v_or_b32_e32 v152, 16, v142
	v_lshlrev_b64 v[118:119], 14, v[118:119]
	v_ashrrev_i32_e32 v153, 31, v152
	v_lshl_add_u64 v[126:127], v[154:155], 0, v[118:119]
	v_lshlrev_b64 v[152:153], 6, v[152:153]
	global_store_dword v[126:127], v143, off
	v_lshl_add_u64 v[156:157], s[8:9], 0, v[152:153]
	global_load_dwordx4 v[152:155], v[156:157], off offset:32
	s_nop 0
	global_load_dwordx4 v[156:159], v[156:157], off offset:48
	s_nop 0
	global_load_dwordx4 v[160:163], v[164:165], off offset:32
	s_nop 0
	global_load_dwordx4 v[164:167], v[164:165], off offset:48
	v_cvt_f32_i32_e32 v168, v106
	v_pk_mul_f32 v[106:107], v[104:105], s[18:19] op_sel_hi:[1,0]
	v_pk_mul_f32 v[174:175], v[98:99], s[18:19] op_sel_hi:[1,0]
	v_pk_mul_f32 v[70:71], v[70:71], s[18:19] op_sel_hi:[1,0]
	v_pk_mul_f32 v[104:105], v[168:169], s[18:19] op_sel_hi:[1,0]
	s_addk_i32 s36, 0x80
	v_cvt_f32_i32_e32 v61, v61
	v_cvt_f32_i32_e32 v60, v60
	v_cvt_f32_i32_e32 v57, v57
	v_cvt_f32_i32_e32 v56, v56
	v_cvt_f32_i32_e32 v53, v53
	v_cvt_f32_i32_e32 v52, v52
	v_cvt_f32_i32_e32 v49, v49
	v_cvt_f32_i32_e32 v48, v48
	v_cvt_f32_i32_e32 v51, v51
	v_cvt_f32_i32_e32 v50, v50
	s_ashr_i32 s37, s36, 31
	v_cvt_f32_i32_e32 v45, v45
	v_cvt_f32_i32_e32 v44, v44
	v_cvt_f32_i32_e32 v41, v41
	v_cvt_f32_i32_e32 v40, v40
	v_cvt_f32_i32_e32 v33, v33
	v_cvt_f32_i32_e32 v32, v32
	v_cvt_f32_i32_e32 v35, v35
	v_cvt_f32_i32_e32 v34, v34
	v_cvt_f32_i32_e32 v37, v37
	v_cvt_f32_i32_e32 v36, v36
	v_cvt_f32_i32_e32 v39, v39
	v_cvt_f32_i32_e32 v38, v38
	v_cvt_f32_i32_e32 v29, v29
	v_pk_mul_f32 v[36:37], v[36:37], s[18:19] op_sel_hi:[1,0]
	v_cvt_f32_i32_e32 v28, v28
	v_pk_mul_f32 v[38:39], v[38:39], s[18:19] op_sel_hi:[1,0]
	v_cvt_f32_i32_e32 v25, v25
	v_cvt_f32_i32_e32 v24, v24
	v_cvt_f32_i32_e32 v17, v17
	v_cvt_f32_i32_e32 v16, v16
	v_cvt_f32_i32_e32 v19, v19
	v_cvt_f32_i32_e32 v18, v18
	v_cvt_f32_i32_e32 v21, v21
	v_cvt_f32_i32_e32 v20, v20
	v_cvt_f32_i32_e32 v23, v23
	v_cvt_f32_i32_e32 v22, v22
	v_cvt_f32_i32_e32 v13, v13
	v_pk_mul_f32 v[20:21], v[20:21], s[18:19] op_sel_hi:[1,0]
	v_cvt_f32_i32_e32 v12, v12
	v_pk_mul_f32 v[22:23], v[22:23], s[18:19] op_sel_hi:[1,0]
	v_cvt_f32_i32_e32 v9, v9
	v_cvt_f32_i32_e32 v8, v8
	v_cvt_f32_i32_e32 v1, v1
	v_cvt_f32_i32_e32 v0, v0
	v_cvt_f32_i32_e32 v3, v3
	v_cvt_f32_i32_e32 v2, v2
	v_cvt_f32_i32_e32 v5, v5
	v_cvt_f32_i32_e32 v4, v4
	v_cvt_f32_i32_e32 v7, v7
	v_cvt_f32_i32_e32 v6, v6
	v_pk_mul_f32 v[4:5], v[4:5], s[18:19] op_sel_hi:[1,0]
	v_pk_mul_f32 v[6:7], v[6:7], s[18:19] op_sel_hi:[1,0]
	s_waitcnt vmcnt(3)
	v_mov_b32_e32 v168, v152
	s_waitcnt vmcnt(2)
	v_mov_b32_e32 v169, v156
	v_mov_b32_e32 v156, v153
	v_pk_add_f32 v[152:153], v[168:169], v[156:157]
	v_mov_b32_e32 v156, v154
	v_mov_b32_e32 v157, v158
	v_mov_b32_e32 v158, v155
	v_pk_add_f32 v[154:155], v[156:157], v[158:159]
	s_waitcnt vmcnt(0)
	v_mov_b32_e32 v97, v164
	v_pk_add_f32 v[152:153], v[152:153], v[154:155]
	v_mov_b32_e32 v164, v161
	v_add_f32_e32 v143, v152, v153
	v_fmamk_f32 v143, v143, 0x3b000000, v148
	v_mul_f32_e32 v151, 0x4f800000, v143
	v_cmp_gt_f32_e32 vcc, s68, v143
	v_or_b32_e32 v152, 18, v142
	v_ashrrev_i32_e32 v153, 31, v152
	v_cndmask_b32_e32 v143, v143, v151, vcc
	v_sqrt_f32_e32 v151, v143
	v_lshlrev_b64 v[152:153], 6, v[152:153]
	v_lshl_add_u64 v[156:157], s[8:9], 0, v[152:153]
	global_load_dwordx4 v[152:155], v[156:157], off offset:32
	s_nop 0
	global_load_dwordx4 v[156:159], v[156:157], off offset:48
	v_add_u32_e32 v168, -1, v151
	v_fma_f32 v169, -v168, v151, v143
	v_cmp_ge_f32_e64 s[4:5], 0, v169
	v_add_u32_e32 v169, 1, v151
	s_nop 0
	v_cndmask_b32_e64 v168, v151, v168, s[4:5]
	v_fma_f32 v151, -v169, v151, v143
	v_cmp_lt_f32_e64 s[4:5], 0, v151
	s_nop 1
	v_cndmask_b32_e64 v151, v168, v169, s[4:5]
	v_mul_f32_e32 v168, 0x37800000, v151
	v_cndmask_b32_e32 v151, v151, v168, vcc
	v_cmp_class_f32_e32 vcc, v143, v149
	s_nop 1
	v_cndmask_b32_e32 v143, v151, v143, vcc
	v_div_scale_f32 v151, s[4:5], v143, v143, 1.0
	v_rcp_f32_e32 v176, v151
	v_div_scale_f32 v177, vcc, 1.0, v143, 1.0
	v_fma_f32 v96, -v151, v176, 1.0
	v_fmac_f32_e32 v176, v96, v176
	v_mov_b32_e32 v96, v160
	v_pk_add_f32 v[160:161], v[96:97], v[164:165]
	v_or_b32_e32 v96, 19, v142
	v_ashrrev_i32_e32 v97, 31, v96
	v_lshlrev_b64 v[96:97], 6, v[96:97]
	v_lshl_add_u64 v[164:165], s[8:9], 0, v[96:97]
	global_load_dwordx4 v[96:99], v[164:165], off offset:32
	global_load_dwordx4 v[168:171], v[164:165], off offset:48
	v_mov_b32_e32 v164, v162
	v_mov_b32_e32 v165, v166
	v_mov_b32_e32 v166, v163
	v_pk_add_f32 v[162:163], v[164:165], v[166:167]
	v_mul_f32_e32 v178, v177, v176
	v_pk_add_f32 v[160:161], v[160:161], v[162:163]
	v_fma_f32 v162, -v151, v178, v177
	v_add_f32_e32 v160, v160, v161
	v_fmamk_f32 v160, v160, 0x3b000000, v148
	v_mul_f32_e32 v161, 0x4f800000, v160
	v_cmp_gt_f32_e64 s[4:5], s68, v160
	v_fmac_f32_e32 v178, v162, v176
	v_fma_f32 v151, -v151, v178, v177
	v_cndmask_b32_e64 v160, v160, v161, s[4:5]
	v_sqrt_f32_e32 v161, v160
	v_div_fmas_f32 v151, v151, v176, v178
	v_add_u32_e32 v162, -1, v161
	v_fma_f32 v163, -v162, v161, v160
	v_cmp_ge_f32_e64 s[6:7], 0, v163
	v_add_u32_e32 v163, 1, v161
	s_nop 0
	v_cndmask_b32_e64 v162, v161, v162, s[6:7]
	v_fma_f32 v161, -v163, v161, v160
	v_cmp_lt_f32_e64 s[6:7], 0, v161
	s_nop 1
	v_cndmask_b32_e64 v161, v162, v163, s[6:7]
	v_mul_f32_e32 v162, 0x37800000, v161
	v_cndmask_b32_e64 v161, v161, v162, s[4:5]
	v_cmp_class_f32_e64 s[4:5], v160, v149
	s_waitcnt vmcnt(3)
; __device__ __forceinline__ float clamp448(float x) { return __builtin_amdgcn_fmed3f(x, -448.0f, 448.0f); }
; __device__ __forceinline__ float rms_scale(const float* ssq, int row, int which) {
;     const f32x4 a = *(const f32x4*)(ssq + (size_t)row * 16 + which * 8), b = *(const f32x4*)(ssq + (size_t)row * 16 + which * 8 + 4);
;     const float s = ((a[0] + a[1]) + (a[2] + a[3])) + ((b[0] + b[1]) + (b[2] + b[3]));
;     return 1.0f / sqrtf(s * (1.0f / 512.0f) + RMS_EPS);
; }
;     __device__ __forceinline__ void operator()(EPI_ARGS) const {
;     ...
;             for (int m = 0; m < 4; ++m) { const int t0 = u.pm * BM + ai * HALF + wr * 64 + 16 * m + 4 * fq, q = 4 * m + fq;
;                 const f32x4 rs = (f32x4){rms_scale(ssq, t0, 1), rms_scale(ssq, t0 + 1, 1), rms_scale(ssq, t0 + 2, 1), rms_scale(ssq, t0 + 3, 1)} * osc;
;                 const size_t tpos = (size_t)(t0 & ~63) + 32 * (q & 1) + 16 * (q >> 3) + 4 * ((q >> 1) & 3);
; #pragma unroll
;                 for (int bj = 0; bj < 2; ++bj)
; #pragma unroll
;                     for (int n = 0; n < 2; ++n) { const f32x4 v = acc[ai][bj][m][n] * rs;
;                         int w = __builtin_amdgcn_cvt_pk_fp8_f32(clamp448(v[0]), clamp448(v[1]), 0, false); w = __builtin_amdgcn_cvt_pk_fp8_f32(clamp448(v[2]), clamp448(v[3]), w, true);
;                         *(unsigned*)(VT + ((size_t)((2 * u.pn + bj) * 128 + dcol + 4 * n)) * NTOK + tpos) = (unsigned)w; } }
	v_mov_b32_e32 v162, v152
	s_waitcnt vmcnt(2)
	v_mov_b32_e32 v163, v156
	v_mov_b32_e32 v156, v153
	v_pk_add_f32 v[152:153], v[162:163], v[156:157]
	v_mov_b32_e32 v156, v154
	v_mov_b32_e32 v157, v158
	v_mov_b32_e32 v158, v155
	v_cndmask_b32_e64 v161, v161, v160, s[4:5]
	v_pk_add_f32 v[154:155], v[156:157], v[158:159]
	v_div_scale_f32 v164, s[4:5], v161, v161, 1.0
	v_pk_add_f32 v[152:153], v[152:153], v[154:155]
	v_rcp_f32_e32 v165, v164
	v_add_f32_e32 v152, v152, v153
	v_fmamk_f32 v152, v152, 0x3b000000, v148
	v_mul_f32_e32 v153, 0x4f800000, v152
	v_cmp_gt_f32_e64 s[4:5], s68, v152
	v_div_fixup_f32 v160, v151, v143, 1.0
	v_fma_f32 v143, -v164, v165, 1.0
	v_cndmask_b32_e64 v152, v152, v153, s[4:5]
	v_sqrt_f32_e32 v153, v152
	v_fmac_f32_e32 v165, v143, v165
	v_div_scale_f32 v143, vcc, 1.0, v161, 1.0
	v_mul_f32_e32 v151, v143, v165
	v_fma_f32 v154, -v164, v151, v143
	v_fmac_f32_e32 v151, v154, v165
	v_add_u32_e32 v154, -1, v153
	v_fma_f32 v155, -v154, v153, v152
	v_cmp_ge_f32_e64 s[6:7], 0, v155
	v_add_u32_e32 v155, 1, v153
	v_fma_f32 v143, -v164, v151, v143
	v_cndmask_b32_e64 v154, v153, v154, s[6:7]
	v_fma_f32 v153, -v155, v153, v152
	v_cmp_lt_f32_e64 s[6:7], 0, v153
	v_div_fmas_f32 v143, v143, v165, v151
	v_div_fixup_f32 v161, v143, v161, 1.0
	v_cndmask_b32_e64 v153, v154, v155, s[6:7]
	v_mul_f32_e32 v154, 0x37800000, v153
	v_cndmask_b32_e64 v153, v153, v154, s[4:5]
	v_cmp_class_f32_e64 s[4:5], v152, v149
	v_pk_mul_f32 v[158:159], v[82:83], s[18:19] op_sel_hi:[1,0]
	s_nop 0
	v_cndmask_b32_e64 v154, v153, v152, s[4:5]
	s_waitcnt vmcnt(1)
	v_mov_b32_e32 v152, v96
	s_waitcnt vmcnt(0)
	v_mov_b32_e32 v153, v168
	v_mov_b32_e32 v168, v97
	v_pk_add_f32 v[96:97], v[152:153], v[168:169]
	v_mov_b32_e32 v152, v98
	v_mov_b32_e32 v153, v170
	v_mov_b32_e32 v170, v99
	v_pk_add_f32 v[98:99], v[152:153], v[170:171]
	v_div_scale_f32 v155, s[4:5], v154, v154, 1.0
	v_pk_add_f32 v[96:97], v[96:97], v[98:99]
	v_rcp_f32_e32 v156, v155
	v_add_f32_e32 v96, v96, v97
	v_fmamk_f32 v96, v96, 0x3b000000, v148
	v_mul_f32_e32 v97, 0x4f800000, v96
	v_cmp_gt_f32_e64 s[4:5], s68, v96
	v_fma_f32 v143, -v155, v156, 1.0
	v_fmac_f32_e32 v156, v143, v156
	v_cndmask_b32_e64 v96, v96, v97, s[4:5]
	v_sqrt_f32_e32 v97, v96
	v_div_scale_f32 v143, vcc, 1.0, v154, 1.0
	v_mul_f32_e32 v151, v143, v156
	v_fma_f32 v98, -v155, v151, v143
	v_fmac_f32_e32 v151, v98, v156
	v_add_u32_e32 v99, -1, v97
	v_fma_f32 v98, -v155, v151, v143
	v_fma_f32 v143, -v99, v97, v96
	v_cmp_ge_f32_e64 s[6:7], 0, v143
	v_add_u32_e32 v143, 1, v97
	v_cvt_f32_i32_e32 v153, v95
	v_cndmask_b32_e64 v99, v97, v99, s[6:7]
	v_fma_f32 v97, -v143, v97, v96
	v_cmp_lt_f32_e64 s[6:7], 0, v97
	s_nop 1
	v_cndmask_b32_e64 v97, v99, v143, s[6:7]
	v_mul_f32_e32 v99, 0x37800000, v97
	v_cndmask_b32_e64 v97, v97, v99, s[4:5]
	v_cmp_class_f32_e64 s[4:5], v96, v149
	s_nop 1
	v_cndmask_b32_e64 v97, v97, v96, s[4:5]
	v_div_scale_f32 v99, s[4:5], v97, v97, 1.0
	v_rcp_f32_e32 v143, v99
	v_div_fmas_f32 v96, v98, v156, v151
	v_div_fixup_f32 v96, v96, v154, 1.0
	v_pk_mul_f32 v[156:157], v[80:81], s[18:19] op_sel_hi:[1,0]
	v_fma_f32 v98, -v99, v143, 1.0
	v_fmac_f32_e32 v143, v98, v143
	v_div_scale_f32 v98, vcc, 1.0, v97, 1.0
	v_mul_f32_e32 v151, v98, v143
	v_fma_f32 v152, -v99, v151, v98
	v_fmac_f32_e32 v151, v152, v143
	v_fma_f32 v98, -v99, v151, v98
	v_div_fmas_f32 v98, v98, v143, v151
	v_div_fixup_f32 v97, v98, v97, 1.0
	v_pk_mul_f32 v[98:99], v[160:161], s[20:21] op_sel_hi:[1,0]
	v_pk_mul_f32 v[110:111], v[110:111], v[98:99]
	v_pk_mul_f32 v[96:97], v[96:97], s[20:21] op_sel_hi:[1,0]
	v_med3_f32 v110, v110, s69, v150
	v_med3_f32 v111, v111, s69, v150
	v_cvt_pk_fp8_f32 v143, v110, v111
	v_pk_mul_f32 v[108:109], v[108:109], v[96:97]
	v_pk_mul_f32 v[106:107], v[106:107], v[98:99]
	v_med3_f32 v108, v108, s69, v150
	v_med3_f32 v109, v109, s69, v150
	v_cvt_pk_fp8_f32 v143, v108, v109 op_sel:[0,0,1]
	v_med3_f32 v106, v106, s69, v150
	v_med3_f32 v107, v107, s69, v150
	v_cvt_pk_fp8_f32 v108, v106, v107
	v_pk_mul_f32 v[104:105], v[104:105], v[96:97]
	v_pk_mul_f32 v[100:101], v[100:101], v[98:99]
	v_med3_f32 v104, v104, s69, v150
	v_med3_f32 v105, v105, s69, v150
	v_cvt_pk_fp8_f32 v108, v104, v105 op_sel:[0,0,1]
	v_med3_f32 v100, v100, s69, v150
	v_med3_f32 v101, v101, s69, v150
	v_cvt_pk_fp8_f32 v104, v100, v101
	v_pk_mul_f32 v[100:101], v[102:103], v[96:97]
	v_pk_mul_f32 v[98:99], v[172:173], v[98:99]
	v_med3_f32 v100, v100, s69, v150
	v_med3_f32 v101, v101, s69, v150
	v_cvt_pk_fp8_f32 v104, v100, v101 op_sel:[0,0,1]
	v_med3_f32 v98, v98, s69, v150
	v_med3_f32 v99, v99, s69, v150
	v_cvt_pk_fp8_f32 v100, v98, v99
	v_pk_mul_f32 v[96:97], v[174:175], v[96:97]
	v_cvt_f32_i32_e32 v152, v94
	v_med3_f32 v96, v96, s69, v150
	v_med3_f32 v97, v97, s69, v150
	v_cvt_pk_fp8_f32 v100, v96, v97 op_sel:[0,0,1]
	v_or_b32_e32 v96, 32, v142
	v_ashrrev_i32_e32 v97, 31, v96
	v_lshlrev_b64 v[96:97], 6, v[96:97]
	global_store_dword v[120:121], v143, off offset:8
	global_store_dword v[122:123], v108, off offset:8
	global_store_dword v[124:125], v104, off offset:8
	global_store_dword v[126:127], v100, off offset:8
	v_lshl_add_u64 v[100:101], s[8:9], 0, v[96:97]
	global_load_dwordx4 v[96:99], v[100:101], off offset:32
	s_nop 0
	global_load_dwordx4 v[100:103], v[100:101], off offset:48
	v_or_b32_e32 v104, 33, v142
	v_ashrrev_i32_e32 v105, 31, v104
	v_lshlrev_b64 v[104:105], 6, v[104:105]
	v_lshl_add_u64 v[108:109], s[8:9], 0, v[104:105]
	global_load_dwordx4 v[104:107], v[108:109], off offset:32
	s_nop 0
	global_load_dwordx4 v[108:111], v[108:109], off offset:48
	v_pk_mul_f32 v[94:95], v[92:93], s[18:19] op_sel_hi:[1,0]
	v_pk_mul_f32 v[92:93], v[152:153], s[18:19] op_sel_hi:[1,0]
	v_cvt_f32_i32_e32 v153, v91
	v_cvt_f32_i32_e32 v152, v90
	v_pk_mul_f32 v[90:91], v[88:89], s[18:19] op_sel_hi:[1,0]
	v_pk_mul_f32 v[88:89], v[152:153], s[18:19] op_sel_hi:[1,0]
	s_waitcnt vmcnt(3)
; __device__ __forceinline__ float rms_scale(const float* ssq, int row, int which) {
;     const f32x4 a = *(const f32x4*)(ssq + (size_t)row * 16 + which * 8), b = *(const f32x4*)(ssq + (size_t)row * 16 + which * 8 + 4);
;     const float s = ((a[0] + a[1]) + (a[2] + a[3])) + ((b[0] + b[1]) + (b[2] + b[3]));
;     return 1.0f / sqrtf(s * (1.0f / 512.0f) + RMS_EPS);
; }
	v_mov_b32_e32 v152, v96
	s_waitcnt vmcnt(2)
	v_mov_b32_e32 v153, v100
	v_mov_b32_e32 v100, v97
	v_pk_add_f32 v[96:97], v[152:153], v[100:101]
	v_mov_b32_e32 v100, v98
	v_mov_b32_e32 v101, v102
	v_mov_b32_e32 v102, v99
	v_pk_add_f32 v[98:99], v[100:101], v[102:103]
	s_waitcnt vmcnt(0)
	v_mov_b32_e32 v81, v108
	v_pk_add_f32 v[96:97], v[96:97], v[98:99]
	v_mov_b32_e32 v108, v105
	v_add_f32_e32 v143, v96, v97
	v_or_b32_e32 v96, 34, v142
	v_ashrrev_i32_e32 v97, 31, v96
	v_lshlrev_b64 v[96:97], 6, v[96:97]
	v_lshl_add_u64 v[100:101], s[8:9], 0, v[96:97]
	global_load_dwordx4 v[96:99], v[100:101], off offset:32
	s_nop 0
	global_load_dwordx4 v[100:103], v[100:101], off offset:48
	v_fmamk_f32 v143, v143, 0x3b000000, v148
	v_mul_f32_e32 v151, 0x4f800000, v143
	v_cmp_gt_f32_e32 vcc, s68, v143
	s_nop 1
	v_cndmask_b32_e32 v143, v143, v151, vcc
	v_sqrt_f32_e32 v151, v143
	s_nop 0
	v_add_u32_e32 v152, -1, v151
	v_fma_f32 v153, -v152, v151, v143
	v_cmp_ge_f32_e64 s[4:5], 0, v153
	v_add_u32_e32 v153, 1, v151
	s_nop 0
	v_cndmask_b32_e64 v152, v151, v152, s[4:5]
	v_fma_f32 v151, -v153, v151, v143
	v_cmp_lt_f32_e64 s[4:5], 0, v151
	s_nop 1
	v_cndmask_b32_e64 v151, v152, v153, s[4:5]
	v_mul_f32_e32 v152, 0x37800000, v151
	v_cndmask_b32_e32 v151, v151, v152, vcc
	v_cmp_class_f32_e32 vcc, v143, v149
	s_nop 1
	v_cndmask_b32_e32 v143, v151, v143, vcc
	v_div_scale_f32 v151, s[4:5], v143, v143, 1.0
	v_rcp_f32_e32 v160, v151
	v_div_scale_f32 v161, vcc, 1.0, v143, 1.0
	v_fma_f32 v80, -v151, v160, 1.0
	v_fmac_f32_e32 v160, v80, v160
	v_mov_b32_e32 v80, v104
	v_pk_add_f32 v[104:105], v[80:81], v[108:109]
	v_or_b32_e32 v80, 35, v142
	v_ashrrev_i32_e32 v81, 31, v80
	v_lshlrev_b64 v[80:81], 6, v[80:81]
	v_lshl_add_u64 v[108:109], s[8:9], 0, v[80:81]
	global_load_dwordx4 v[80:83], v[108:109], off offset:32
	global_load_dwordx4 v[152:155], v[108:109], off offset:48
	v_mov_b32_e32 v108, v106
	v_mov_b32_e32 v109, v110
	v_mov_b32_e32 v110, v107
	v_pk_add_f32 v[106:107], v[108:109], v[110:111]
	v_mul_f32_e32 v162, v161, v160
	v_pk_add_f32 v[104:105], v[104:105], v[106:107]
	v_fma_f32 v106, -v151, v162, v161
	v_add_f32_e32 v104, v104, v105
	v_fmamk_f32 v104, v104, 0x3b000000, v148
	v_mul_f32_e32 v105, 0x4f800000, v104
	v_cmp_gt_f32_e64 s[4:5], s68, v104
	v_fmac_f32_e32 v162, v106, v160
	v_fma_f32 v106, -v151, v162, v161
	v_cndmask_b32_e64 v104, v104, v105, s[4:5]
	v_sqrt_f32_e32 v105, v104
	s_nop 0
	v_add_u32_e32 v107, -1, v105
	v_fma_f32 v108, -v107, v105, v104
	v_cmp_ge_f32_e64 s[6:7], 0, v108
	v_add_u32_e32 v108, 1, v105
	s_nop 0
	v_cndmask_b32_e64 v107, v105, v107, s[6:7]
	v_fma_f32 v105, -v108, v105, v104
	v_cmp_lt_f32_e64 s[6:7], 0, v105
	s_nop 1
	v_cndmask_b32_e64 v105, v107, v108, s[6:7]
	v_mul_f32_e32 v107, 0x37800000, v105
	v_cndmask_b32_e64 v105, v105, v107, s[4:5]
	v_cmp_class_f32_e64 s[4:5], v104, v149
	s_waitcnt vmcnt(2)
	v_mov_b32_e32 v107, v100
	v_cndmask_b32_e64 v105, v105, v104, s[4:5]
	v_div_scale_f32 v108, s[4:5], v105, v105, 1.0
	v_rcp_f32_e32 v109, v108
	v_div_fmas_f32 v104, v106, v160, v162
	v_mov_b32_e32 v100, v97
	v_div_scale_f32 v110, vcc, 1.0, v105, 1.0
	v_fma_f32 v106, -v108, v109, 1.0
	v_fmac_f32_e32 v109, v106, v109
	v_mov_b32_e32 v106, v96
	v_pk_add_f32 v[96:97], v[106:107], v[100:101]
	v_mov_b32_e32 v100, v98
	v_mov_b32_e32 v101, v102
	v_mov_b32_e32 v102, v99
	v_pk_add_f32 v[98:99], v[100:101], v[102:103]
	v_mul_f32_e32 v111, v110, v109
	v_pk_add_f32 v[96:97], v[96:97], v[98:99]
	v_fma_f32 v98, -v108, v111, v110
	v_add_f32_e32 v96, v96, v97
	v_fmamk_f32 v96, v96, 0x3b000000, v148
	v_mul_f32_e32 v97, 0x4f800000, v96
	v_cmp_gt_f32_e64 s[4:5], s68, v96
	v_fmac_f32_e32 v111, v98, v109
	v_fma_f32 v98, -v108, v111, v110
	v_cndmask_b32_e64 v96, v96, v97, s[4:5]
	v_sqrt_f32_e32 v97, v96
	v_div_fixup_f32 v104, v104, v143, 1.0
	v_add_u32_e32 v99, -1, v97
	v_fma_f32 v100, -v99, v97, v96
	v_cmp_ge_f32_e64 s[6:7], 0, v100
	v_add_u32_e32 v100, 1, v97
	s_nop 0
	v_cndmask_b32_e64 v99, v97, v99, s[6:7]
	v_fma_f32 v97, -v100, v97, v96
	v_cmp_lt_f32_e64 s[6:7], 0, v97
	s_nop 1
	v_cndmask_b32_e64 v97, v99, v100, s[6:7]
	v_mul_f32_e32 v99, 0x37800000, v97
	v_cndmask_b32_e64 v97, v97, v99, s[4:5]
	v_cmp_class_f32_e64 s[4:5], v96, v149
	s_nop 1
	v_cndmask_b32_e64 v99, v97, v96, s[4:5]
	v_div_scale_f32 v100, s[4:5], v99, v99, 1.0
	v_rcp_f32_e32 v101, v100
	v_div_fmas_f32 v96, v98, v109, v111
	v_div_fixup_f32 v105, v96, v105, 1.0
	s_waitcnt vmcnt(0)
; __device__ __forceinline__ float clamp448(float x) { return __builtin_amdgcn_fmed3f(x, -448.0f, 448.0f); }
; __device__ __forceinline__ float rms_scale(const float* ssq, int row, int which) {
;     const f32x4 a = *(const f32x4*)(ssq + (size_t)row * 16 + which * 8), b = *(const f32x4*)(ssq + (size_t)row * 16 + which * 8 + 4);
;     const float s = ((a[0] + a[1]) + (a[2] + a[3])) + ((b[0] + b[1]) + (b[2] + b[3]));
;     return 1.0f / sqrtf(s * (1.0f / 512.0f) + RMS_EPS);
; }
;     __device__ __forceinline__ void operator()(EPI_ARGS) const {
;     ...
;             for (int m = 0; m < 4; ++m) { const int t0 = u.pm * BM + ai * HALF + wr * 64 + 16 * m + 4 * fq, q = 4 * m + fq;
;                 const f32x4 rs = (f32x4){rms_scale(ssq, t0, 1), rms_scale(ssq, t0 + 1, 1), rms_scale(ssq, t0 + 2, 1), rms_scale(ssq, t0 + 3, 1)} * osc;
;                 const size_t tpos = (size_t)(t0 & ~63) + 32 * (q & 1) + 16 * (q >> 3) + 4 * ((q >> 1) & 3);
; #pragma unroll
;                 for (int bj = 0; bj < 2; ++bj)
; #pragma unroll
;                     for (int n = 0; n < 2; ++n) { const f32x4 v = acc[ai][bj][m][n] * rs;
;                         int w = __builtin_amdgcn_cvt_pk_fp8_f32(clamp448(v[0]), clamp448(v[1]), 0, false); w = __builtin_amdgcn_cvt_pk_fp8_f32(clamp448(v[2]), clamp448(v[3]), w, true);
;                         *(unsigned*)(VT + ((size_t)((2 * u.pn + bj) * 128 + dcol + 4 * n)) * NTOK + tpos) = (unsigned)w; } }
	v_mov_b32_e32 v97, v152
	v_fma_f32 v96, -v100, v101, 1.0
	v_fmac_f32_e32 v101, v96, v101
	v_mov_b32_e32 v96, v80
	v_mov_b32_e32 v152, v81
	v_pk_add_f32 v[80:81], v[96:97], v[152:153]
	v_mov_b32_e32 v96, v82
	v_mov_b32_e32 v97, v154
	v_mov_b32_e32 v154, v83
	v_pk_add_f32 v[82:83], v[96:97], v[154:155]
	v_div_scale_f32 v98, vcc, 1.0, v99, 1.0
	v_pk_add_f32 v[80:81], v[80:81], v[82:83]
	v_mul_f32_e32 v102, v98, v101
	v_add_f32_e32 v80, v80, v81
	v_fmamk_f32 v80, v80, 0x3b000000, v148
	v_mul_f32_e32 v81, 0x4f800000, v80
	v_cmp_gt_f32_e64 s[4:5], s68, v80
	v_fma_f32 v82, -v100, v102, v98
	v_fmac_f32_e32 v102, v82, v101
	v_cndmask_b32_e64 v80, v80, v81, s[4:5]
	v_sqrt_f32_e32 v81, v80
	v_fma_f32 v82, -v100, v102, v98
	v_add_u32_e32 v83, -1, v81
	v_fma_f32 v96, -v83, v81, v80
	v_cmp_ge_f32_e64 s[6:7], 0, v96
	v_add_u32_e32 v96, 1, v81
	s_nop 0
	v_cndmask_b32_e64 v83, v81, v83, s[6:7]
	v_fma_f32 v81, -v96, v81, v80
	v_cmp_lt_f32_e64 s[6:7], 0, v81
	s_nop 1
	v_cndmask_b32_e64 v81, v83, v96, s[6:7]
	v_mul_f32_e32 v83, 0x37800000, v81
	v_cndmask_b32_e64 v81, v81, v83, s[4:5]
	v_cmp_class_f32_e64 s[4:5], v80, v149
	s_nop 1
	v_cndmask_b32_e64 v81, v81, v80, s[4:5]
	v_div_scale_f32 v83, s[4:5], v81, v81, 1.0
	v_rcp_f32_e32 v96, v83
	v_div_fmas_f32 v80, v82, v101, v102
	v_div_fixup_f32 v80, v80, v99, 1.0
	v_pk_mul_f32 v[100:101], v[64:65], s[18:19] op_sel_hi:[1,0]
	v_fma_f32 v82, -v83, v96, 1.0
	v_fmac_f32_e32 v96, v82, v96
	v_div_scale_f32 v82, vcc, 1.0, v81, 1.0
	v_mul_f32_e32 v97, v82, v96
	v_fma_f32 v98, -v83, v97, v82
	v_fmac_f32_e32 v97, v98, v96
	v_fma_f32 v82, -v83, v97, v82
	v_div_fmas_f32 v82, v82, v96, v97
	v_div_fixup_f32 v81, v82, v81, 1.0
	v_pk_mul_f32 v[82:83], v[104:105], s[20:21] op_sel_hi:[1,0]
	v_pk_mul_f32 v[94:95], v[94:95], v[82:83]
	v_pk_mul_f32 v[80:81], v[80:81], s[20:21] op_sel_hi:[1,0]
	v_med3_f32 v94, v94, s69, v150
	v_med3_f32 v95, v95, s69, v150
	v_cvt_pk_fp8_f32 v96, v94, v95
	v_pk_mul_f32 v[92:93], v[92:93], v[80:81]
	v_pk_mul_f32 v[90:91], v[90:91], v[82:83]
	v_med3_f32 v92, v92, s69, v150
	v_med3_f32 v93, v93, s69, v150
	v_cvt_pk_fp8_f32 v96, v92, v93 op_sel:[0,0,1]
	v_med3_f32 v90, v90, s69, v150
	v_med3_f32 v91, v91, s69, v150
	v_cvt_pk_fp8_f32 v92, v90, v91
	v_pk_mul_f32 v[88:89], v[88:89], v[80:81]
	v_pk_mul_f32 v[84:85], v[84:85], v[82:83]
	v_med3_f32 v88, v88, s69, v150
	v_med3_f32 v89, v89, s69, v150
	v_cvt_pk_fp8_f32 v92, v88, v89 op_sel:[0,0,1]
	v_med3_f32 v84, v84, s69, v150
	v_med3_f32 v85, v85, s69, v150
	v_cvt_pk_fp8_f32 v88, v84, v85
	v_pk_mul_f32 v[84:85], v[86:87], v[80:81]
	v_pk_mul_f32 v[82:83], v[156:157], v[82:83]
	v_med3_f32 v84, v84, s69, v150
	v_med3_f32 v85, v85, s69, v150
	v_cvt_pk_fp8_f32 v88, v84, v85 op_sel:[0,0,1]
	v_med3_f32 v82, v82, s69, v150
	v_med3_f32 v83, v83, s69, v150
	v_cvt_pk_fp8_f32 v84, v82, v83
	v_pk_mul_f32 v[80:81], v[158:159], v[80:81]
	v_cvt_f32_i32_e32 v97, v79
	v_med3_f32 v80, v80, s69, v150
	v_med3_f32 v81, v81, s69, v150
	v_cvt_pk_fp8_f32 v84, v80, v81 op_sel:[0,0,1]
	v_or_b32_e32 v80, 48, v142
	v_ashrrev_i32_e32 v81, 31, v80
	v_lshlrev_b64 v[80:81], 6, v[80:81]
	global_store_dword v[120:121], v96, off offset:16
	global_store_dword v[122:123], v92, off offset:16
	global_store_dword v[124:125], v88, off offset:16
	global_store_dword v[126:127], v84, off offset:16
	v_lshl_add_u64 v[84:85], s[8:9], 0, v[80:81]
	global_load_dwordx4 v[80:83], v[84:85], off offset:32
	s_nop 0
	global_load_dwordx4 v[84:87], v[84:85], off offset:48
	v_or_b32_e32 v88, 49, v142
	v_ashrrev_i32_e32 v89, 31, v88
	v_lshlrev_b64 v[88:89], 6, v[88:89]
	v_lshl_add_u64 v[92:93], s[8:9], 0, v[88:89]
	global_load_dwordx4 v[88:91], v[92:93], off offset:32
	s_nop 0
	global_load_dwordx4 v[92:95], v[92:93], off offset:48
	v_cvt_f32_i32_e32 v96, v78
	v_pk_mul_f32 v[78:79], v[76:77], s[18:19] op_sel_hi:[1,0]
	v_pk_mul_f32 v[102:103], v[66:67], s[18:19] op_sel_hi:[1,0]
	v_pk_mul_f32 v[76:77], v[96:97], s[18:19] op_sel_hi:[1,0]
	v_cvt_f32_i32_e32 v97, v75
	v_cvt_f32_i32_e32 v96, v74
	v_pk_mul_f32 v[74:75], v[72:73], s[18:19] op_sel_hi:[1,0]
	v_pk_mul_f32 v[72:73], v[96:97], s[18:19] op_sel_hi:[1,0]
	s_waitcnt vmcnt(3)
	v_mov_b32_e32 v96, v80
	s_waitcnt vmcnt(2)
	v_mov_b32_e32 v97, v84
	v_mov_b32_e32 v84, v81
	v_pk_add_f32 v[80:81], v[96:97], v[84:85]
	v_mov_b32_e32 v84, v82
	v_mov_b32_e32 v85, v86
	v_mov_b32_e32 v86, v83
	v_pk_add_f32 v[82:83], v[84:85], v[86:87]
	s_waitcnt vmcnt(0)
	v_mov_b32_e32 v65, v92
	v_pk_add_f32 v[80:81], v[80:81], v[82:83]
	v_mov_b32_e32 v92, v89
	v_add_f32_e32 v96, v80, v81
	v_or_b32_e32 v80, 50, v142
	v_ashrrev_i32_e32 v81, 31, v80
	v_lshlrev_b64 v[80:81], 6, v[80:81]
	v_lshl_add_u64 v[84:85], s[8:9], 0, v[80:81]
	global_load_dwordx4 v[80:83], v[84:85], off offset:32
	s_nop 0
	global_load_dwordx4 v[84:87], v[84:85], off offset:48
	v_fmamk_f32 v96, v96, 0x3b000000, v148
	v_mul_f32_e32 v97, 0x4f800000, v96
	v_cmp_gt_f32_e32 vcc, s68, v96
	s_nop 1
	v_cndmask_b32_e32 v96, v96, v97, vcc
	v_sqrt_f32_e32 v97, v96
	s_nop 0
	v_add_u32_e32 v98, -1, v97
	v_fma_f32 v99, -v98, v97, v96
	v_cmp_ge_f32_e64 s[4:5], 0, v99
	v_add_u32_e32 v99, 1, v97
	s_nop 0
	v_cndmask_b32_e64 v98, v97, v98, s[4:5]
	v_fma_f32 v97, -v99, v97, v96
	v_cmp_lt_f32_e64 s[4:5], 0, v97
	s_nop 1
	v_cndmask_b32_e64 v97, v98, v99, s[4:5]
	v_mul_f32_e32 v98, 0x37800000, v97
	v_cndmask_b32_e32 v97, v97, v98, vcc
	v_cmp_class_f32_e32 vcc, v96, v149
	s_nop 1
	v_cndmask_b32_e32 v104, v97, v96, vcc
	v_div_scale_f32 v105, s[4:5], v104, v104, 1.0
	v_rcp_f32_e32 v106, v105
	v_div_scale_f32 v107, vcc, 1.0, v104, 1.0
	v_fma_f32 v64, -v105, v106, 1.0
	v_fmac_f32_e32 v106, v64, v106
	v_mov_b32_e32 v64, v88
	v_pk_add_f32 v[88:89], v[64:65], v[92:93]
	v_or_b32_e32 v64, 51, v142
	v_ashrrev_i32_e32 v65, 31, v64
	v_lshlrev_b64 v[64:65], 6, v[64:65]
	v_lshl_add_u64 v[92:93], s[8:9], 0, v[64:65]
	global_load_dwordx4 v[64:67], v[92:93], off offset:32
	global_load_dwordx4 v[96:99], v[92:93], off offset:48
	v_mov_b32_e32 v92, v90
	v_mov_b32_e32 v93, v94
	v_mov_b32_e32 v94, v91
	v_pk_add_f32 v[90:91], v[92:93], v[94:95]
	v_mul_f32_e32 v108, v107, v106
	v_pk_add_f32 v[88:89], v[88:89], v[90:91]
	v_fma_f32 v90, -v105, v108, v107
	v_add_f32_e32 v88, v88, v89
	v_fmamk_f32 v88, v88, 0x3b000000, v148
	v_mul_f32_e32 v89, 0x4f800000, v88
	v_cmp_gt_f32_e64 s[4:5], s68, v88
	v_fmac_f32_e32 v108, v90, v106
	v_fma_f32 v90, -v105, v108, v107
	v_cndmask_b32_e64 v88, v88, v89, s[4:5]
	v_sqrt_f32_e32 v89, v88
	s_nop 0
	v_add_u32_e32 v91, -1, v89
	v_fma_f32 v92, -v91, v89, v88
	v_cmp_ge_f32_e64 s[6:7], 0, v92
	v_add_u32_e32 v92, 1, v89
	s_nop 0
	v_cndmask_b32_e64 v91, v89, v91, s[6:7]
	v_fma_f32 v89, -v92, v89, v88
	v_cmp_lt_f32_e64 s[6:7], 0, v89
	s_nop 1
	v_cndmask_b32_e64 v89, v91, v92, s[6:7]
	v_mul_f32_e32 v91, 0x37800000, v89
	v_cndmask_b32_e64 v89, v89, v91, s[4:5]
	v_cmp_class_f32_e64 s[4:5], v88, v149
	s_waitcnt vmcnt(2)
; __device__ __forceinline__ float clamp448(float x) { return __builtin_amdgcn_fmed3f(x, -448.0f, 448.0f); }
; __device__ __forceinline__ float rms_scale(const float* ssq, int row, int which) {
;     const f32x4 a = *(const f32x4*)(ssq + (size_t)row * 16 + which * 8), b = *(const f32x4*)(ssq + (size_t)row * 16 + which * 8 + 4);
;     const float s = ((a[0] + a[1]) + (a[2] + a[3])) + ((b[0] + b[1]) + (b[2] + b[3]));
;     return 1.0f / sqrtf(s * (1.0f / 512.0f) + RMS_EPS);
; }
;     __device__ __forceinline__ void operator()(EPI_ARGS) const {
;     ...
;             for (int m = 0; m < 4; ++m) { const int t0 = u.pm * BM + ai * HALF + wr * 64 + 16 * m + 4 * fq, q = 4 * m + fq;
;                 const f32x4 rs = (f32x4){rms_scale(ssq, t0, 1), rms_scale(ssq, t0 + 1, 1), rms_scale(ssq, t0 + 2, 1), rms_scale(ssq, t0 + 3, 1)} * osc;
;                 const size_t tpos = (size_t)(t0 & ~63) + 32 * (q & 1) + 16 * (q >> 3) + 4 * ((q >> 1) & 3);
; #pragma unroll
;                 for (int bj = 0; bj < 2; ++bj)
; #pragma unroll
;                     for (int n = 0; n < 2; ++n) { const f32x4 v = acc[ai][bj][m][n] * rs;
;                         int w = __builtin_amdgcn_cvt_pk_fp8_f32(clamp448(v[0]), clamp448(v[1]), 0, false); w = __builtin_amdgcn_cvt_pk_fp8_f32(clamp448(v[2]), clamp448(v[3]), w, true);
;                         *(unsigned*)(VT + ((size_t)((2 * u.pn + bj) * 128 + dcol + 4 * n)) * NTOK + tpos) = (unsigned)w; } }
	v_mov_b32_e32 v91, v84
	v_cndmask_b32_e64 v89, v89, v88, s[4:5]
	v_div_scale_f32 v92, s[4:5], v89, v89, 1.0
	v_rcp_f32_e32 v93, v92
	v_div_fmas_f32 v88, v90, v106, v108
	v_mov_b32_e32 v84, v81
	v_div_scale_f32 v94, vcc, 1.0, v89, 1.0
	v_fma_f32 v90, -v92, v93, 1.0
	v_fmac_f32_e32 v93, v90, v93
	v_mov_b32_e32 v90, v80
	v_pk_add_f32 v[80:81], v[90:91], v[84:85]
	v_mov_b32_e32 v84, v82
	v_mov_b32_e32 v85, v86
	v_mov_b32_e32 v86, v83
	v_pk_add_f32 v[82:83], v[84:85], v[86:87]
	v_mul_f32_e32 v95, v94, v93
	v_pk_add_f32 v[80:81], v[80:81], v[82:83]
	v_fma_f32 v82, -v92, v95, v94
	v_add_f32_e32 v80, v80, v81
	v_fmamk_f32 v80, v80, 0x3b000000, v148
	v_mul_f32_e32 v81, 0x4f800000, v80
	v_cmp_gt_f32_e64 s[4:5], s68, v80
	v_fmac_f32_e32 v95, v82, v93
	v_fma_f32 v82, -v92, v95, v94
	v_cndmask_b32_e64 v80, v80, v81, s[4:5]
	v_sqrt_f32_e32 v81, v80
	v_div_fixup_f32 v88, v88, v104, 1.0
	v_add_u32_e32 v83, -1, v81
	v_fma_f32 v84, -v83, v81, v80
	v_cmp_ge_f32_e64 s[6:7], 0, v84
	v_add_u32_e32 v84, 1, v81
	s_nop 0
	v_cndmask_b32_e64 v83, v81, v83, s[6:7]
	v_fma_f32 v81, -v84, v81, v80
	v_cmp_lt_f32_e64 s[6:7], 0, v81
	s_nop 1
	v_cndmask_b32_e64 v81, v83, v84, s[6:7]
	v_mul_f32_e32 v83, 0x37800000, v81
	v_cndmask_b32_e64 v81, v81, v83, s[4:5]
	v_cmp_class_f32_e64 s[4:5], v80, v149
	s_nop 1
	v_cndmask_b32_e64 v83, v81, v80, s[4:5]
	v_div_scale_f32 v84, s[4:5], v83, v83, 1.0
	v_rcp_f32_e32 v85, v84
	v_div_fmas_f32 v80, v82, v93, v95
	v_div_fixup_f32 v89, v80, v89, 1.0
	s_waitcnt vmcnt(0)
	v_mov_b32_e32 v81, v96
	v_fma_f32 v80, -v84, v85, 1.0
	v_fmac_f32_e32 v85, v80, v85
	v_mov_b32_e32 v80, v64
	v_mov_b32_e32 v96, v65
	v_pk_add_f32 v[64:65], v[80:81], v[96:97]
	v_mov_b32_e32 v80, v66
	v_mov_b32_e32 v81, v98
	v_mov_b32_e32 v98, v67
	v_pk_add_f32 v[66:67], v[80:81], v[98:99]
	v_div_scale_f32 v82, vcc, 1.0, v83, 1.0
	v_pk_add_f32 v[64:65], v[64:65], v[66:67]
	v_mul_f32_e32 v86, v82, v85
	v_add_f32_e32 v64, v64, v65
	v_fmamk_f32 v64, v64, 0x3b000000, v148
	v_mul_f32_e32 v65, 0x4f800000, v64
	v_cmp_gt_f32_e64 s[4:5], s68, v64
	v_fma_f32 v66, -v84, v86, v82
	v_fmac_f32_e32 v86, v66, v85
	v_cndmask_b32_e64 v64, v64, v65, s[4:5]
	v_sqrt_f32_e32 v65, v64
	v_fma_f32 v66, -v84, v86, v82
	v_cvt_f32_i32_e32 v84, v54
	v_add_u32_e32 v67, -1, v65
	v_fma_f32 v80, -v67, v65, v64
	v_cmp_ge_f32_e64 s[6:7], 0, v80
	v_add_u32_e32 v80, 1, v65
	s_nop 0
	v_cndmask_b32_e64 v67, v65, v67, s[6:7]
	v_fma_f32 v65, -v80, v65, v64
	v_cmp_lt_f32_e64 s[6:7], 0, v65
	s_nop 1
	v_cndmask_b32_e64 v65, v67, v80, s[6:7]
	v_mul_f32_e32 v67, 0x37800000, v65
	v_cndmask_b32_e64 v65, v65, v67, s[4:5]
	v_cmp_class_f32_e64 s[4:5], v64, v149
	s_nop 1
	v_cndmask_b32_e64 v65, v65, v64, s[4:5]
	v_div_scale_f32 v67, s[4:5], v65, v65, 1.0
	v_rcp_f32_e32 v80, v67
	v_div_fmas_f32 v64, v66, v85, v86
	v_div_fixup_f32 v64, v64, v83, 1.0
	v_cvt_f32_i32_e32 v83, v63
	v_fma_f32 v66, -v67, v80, 1.0
	v_fmac_f32_e32 v80, v66, v80
	v_div_scale_f32 v66, vcc, 1.0, v65, 1.0
	v_mul_f32_e32 v81, v66, v80
	v_fma_f32 v82, -v67, v81, v66
	v_fmac_f32_e32 v81, v82, v80
	v_fma_f32 v66, -v67, v81, v66
	v_div_fmas_f32 v66, v66, v80, v81
	v_div_fixup_f32 v65, v66, v65, 1.0
	v_pk_mul_f32 v[66:67], v[88:89], s[20:21] op_sel_hi:[1,0]
	v_pk_mul_f32 v[78:79], v[78:79], v[66:67]
	v_pk_mul_f32 v[64:65], v[64:65], s[20:21] op_sel_hi:[1,0]
	v_med3_f32 v78, v78, s69, v150
	v_med3_f32 v79, v79, s69, v150
	v_cvt_pk_fp8_f32 v80, v78, v79
	v_pk_mul_f32 v[76:77], v[76:77], v[64:65]
	v_pk_mul_f32 v[74:75], v[74:75], v[66:67]
	v_med3_f32 v76, v76, s69, v150
	v_med3_f32 v77, v77, s69, v150
	v_cvt_pk_fp8_f32 v80, v76, v77 op_sel:[0,0,1]
	v_med3_f32 v74, v74, s69, v150
	v_med3_f32 v75, v75, s69, v150
	v_cvt_pk_fp8_f32 v76, v74, v75
	v_pk_mul_f32 v[72:73], v[72:73], v[64:65]
	v_pk_mul_f32 v[68:69], v[68:69], v[66:67]
	v_med3_f32 v72, v72, s69, v150
	v_med3_f32 v73, v73, s69, v150
	v_cvt_pk_fp8_f32 v76, v72, v73 op_sel:[0,0,1]
	v_med3_f32 v68, v68, s69, v150
	v_med3_f32 v69, v69, s69, v150
	v_cvt_pk_fp8_f32 v72, v68, v69
	v_pk_mul_f32 v[68:69], v[70:71], v[64:65]
	v_pk_mul_f32 v[66:67], v[100:101], v[66:67]
	v_med3_f32 v68, v68, s69, v150
	v_med3_f32 v69, v69, s69, v150
	v_cvt_pk_fp8_f32 v72, v68, v69 op_sel:[0,0,1]
	v_med3_f32 v66, v66, s69, v150
	v_med3_f32 v67, v67, s69, v150
	v_cvt_pk_fp8_f32 v68, v66, v67
	v_pk_mul_f32 v[64:65], v[102:103], v[64:65]
	v_cvt_f32_i32_e32 v82, v62
	v_med3_f32 v64, v64, s69, v150
	v_med3_f32 v65, v65, s69, v150
	v_cvt_pk_fp8_f32 v68, v64, v65 op_sel:[0,0,1]
	v_or_b32_e32 v64, s36, v145
	v_ashrrev_i32_e32 v65, 31, v64
	v_lshlrev_b64 v[66:67], 6, v[64:65]
	global_store_dword v[120:121], v80, off offset:24
	global_store_dword v[122:123], v76, off offset:24
	global_store_dword v[124:125], v72, off offset:24
	global_store_dword v[126:127], v68, off offset:24
	v_lshl_add_u64 v[70:71], s[8:9], 0, v[66:67]
	global_load_dwordx4 v[66:69], v[70:71], off offset:32
	s_nop 0
	global_load_dwordx4 v[70:73], v[70:71], off offset:48
	v_or_b32_e32 v74, 1, v64
	v_ashrrev_i32_e32 v75, 31, v74
	v_lshlrev_b64 v[74:75], 6, v[74:75]
	v_lshl_add_u64 v[78:79], s[8:9], 0, v[74:75]
	global_load_dwordx4 v[74:77], v[78:79], off offset:32
	s_nop 0
	global_load_dwordx4 v[78:81], v[78:79], off offset:48
	v_pk_mul_f32 v[62:63], v[60:61], s[18:19] op_sel_hi:[1,0]
	v_pk_mul_f32 v[60:61], v[82:83], s[18:19] op_sel_hi:[1,0]
	v_cvt_f32_i32_e32 v83, v59
	v_cvt_f32_i32_e32 v82, v58
	v_pk_mul_f32 v[58:59], v[56:57], s[18:19] op_sel_hi:[1,0]
	v_cvt_f32_i32_e32 v85, v55
	v_pk_mul_f32 v[54:55], v[52:53], s[18:19] op_sel_hi:[1,0]
	v_pk_mul_f32 v[56:57], v[82:83], s[18:19] op_sel_hi:[1,0]
	v_pk_mul_f32 v[86:87], v[48:49], s[18:19] op_sel_hi:[1,0]
	v_pk_mul_f32 v[52:53], v[84:85], s[18:19] op_sel_hi:[1,0]
	v_pk_mul_f32 v[88:89], v[50:51], s[18:19] op_sel_hi:[1,0]
	s_waitcnt vmcnt(3)
; __device__ __forceinline__ float rms_scale(const float* ssq, int row, int which) {
;     const f32x4 a = *(const f32x4*)(ssq + (size_t)row * 16 + which * 8), b = *(const f32x4*)(ssq + (size_t)row * 16 + which * 8 + 4);
;     const float s = ((a[0] + a[1]) + (a[2] + a[3])) + ((b[0] + b[1]) + (b[2] + b[3]));
;     return 1.0f / sqrtf(s * (1.0f / 512.0f) + RMS_EPS);
; }
;     __device__ __forceinline__ void operator()(EPI_ARGS) const {
;     ...
;             for (int m = 0; m < 4; ++m) { const int t0 = u.pm * BM + ai * HALF + wr * 64 + 16 * m + 4 * fq, q = 4 * m + fq;
;                 const f32x4 rs = (f32x4){rms_scale(ssq, t0, 1), rms_scale(ssq, t0 + 1, 1), rms_scale(ssq, t0 + 2, 1), rms_scale(ssq, t0 + 3, 1)} * osc;
;                 const size_t tpos = (size_t)(t0 & ~63) + 32 * (q & 1) + 16 * (q >> 3) + 4 * ((q >> 1) & 3);
	v_mov_b32_e32 v82, v66
	s_waitcnt vmcnt(2)
	v_mov_b32_e32 v83, v70
	v_mov_b32_e32 v70, v67
	v_pk_add_f32 v[66:67], v[82:83], v[70:71]
	v_mov_b32_e32 v70, v68
	v_mov_b32_e32 v71, v72
	v_mov_b32_e32 v72, v69
	v_pk_add_f32 v[68:69], v[70:71], v[72:73]
	s_waitcnt vmcnt(0)
	v_mov_b32_e32 v49, v78
	v_pk_add_f32 v[66:67], v[66:67], v[68:69]
	v_mov_b32_e32 v78, v75
	v_add_f32_e32 v65, v66, v67
	v_fmamk_f32 v65, v65, 0x3b000000, v148
	v_mul_f32_e32 v82, 0x4f800000, v65
	v_cmp_gt_f32_e32 vcc, s68, v65
	v_or_b32_e32 v66, 2, v64
	v_ashrrev_i32_e32 v67, 31, v66
	v_cndmask_b32_e32 v65, v65, v82, vcc
	v_sqrt_f32_e32 v82, v65
	v_lshlrev_b64 v[66:67], 6, v[66:67]
	v_lshl_add_u64 v[70:71], s[8:9], 0, v[66:67]
	global_load_dwordx4 v[66:69], v[70:71], off offset:32
	s_nop 0
	global_load_dwordx4 v[70:73], v[70:71], off offset:48
	v_add_u32_e32 v83, -1, v82
	v_fma_f32 v84, -v83, v82, v65
	v_cmp_ge_f32_e64 s[4:5], 0, v84
	v_add_u32_e32 v84, 1, v82
	s_nop 0
	v_cndmask_b32_e64 v83, v82, v83, s[4:5]
	v_fma_f32 v82, -v84, v82, v65
	v_cmp_lt_f32_e64 s[4:5], 0, v82
	s_nop 1
	v_cndmask_b32_e64 v82, v83, v84, s[4:5]
	v_mul_f32_e32 v83, 0x37800000, v82
	v_cndmask_b32_e32 v82, v82, v83, vcc
	v_cmp_class_f32_e32 vcc, v65, v149
	s_nop 1
	v_cndmask_b32_e32 v65, v82, v65, vcc
	v_div_scale_f32 v90, s[4:5], v65, v65, 1.0
	v_rcp_f32_e32 v91, v90
	v_div_scale_f32 v92, vcc, 1.0, v65, 1.0
	v_fma_f32 v48, -v90, v91, 1.0
	v_fmac_f32_e32 v91, v48, v91
	v_mov_b32_e32 v48, v74
	v_pk_add_f32 v[74:75], v[48:49], v[78:79]
	v_or_b32_e32 v48, 3, v64
	v_ashrrev_i32_e32 v49, 31, v48
	v_lshlrev_b64 v[48:49], 6, v[48:49]
	v_lshl_add_u64 v[78:79], s[8:9], 0, v[48:49]
	global_load_dwordx4 v[48:51], v[78:79], off offset:32
	global_load_dwordx4 v[82:85], v[78:79], off offset:48
	v_mov_b32_e32 v78, v76
	v_mov_b32_e32 v79, v80
	v_mov_b32_e32 v80, v77
	v_pk_add_f32 v[76:77], v[78:79], v[80:81]
	v_mul_f32_e32 v93, v92, v91
	v_pk_add_f32 v[74:75], v[74:75], v[76:77]
	v_fma_f32 v76, -v90, v93, v92
	v_add_f32_e32 v74, v74, v75
	v_fmamk_f32 v74, v74, 0x3b000000, v148
	v_mul_f32_e32 v75, 0x4f800000, v74
	v_cmp_gt_f32_e64 s[4:5], s68, v74
	v_fmac_f32_e32 v93, v76, v91
	v_fma_f32 v76, -v90, v93, v92
	v_cndmask_b32_e64 v74, v74, v75, s[4:5]
	v_sqrt_f32_e32 v75, v74
	s_nop 0
	v_add_u32_e32 v77, -1, v75
	v_fma_f32 v78, -v77, v75, v74
	v_cmp_ge_f32_e64 s[6:7], 0, v78
	v_add_u32_e32 v78, 1, v75
	s_nop 0
	v_cndmask_b32_e64 v77, v75, v77, s[6:7]
	v_fma_f32 v75, -v78, v75, v74
	v_cmp_lt_f32_e64 s[6:7], 0, v75
	s_nop 1
	v_cndmask_b32_e64 v75, v77, v78, s[6:7]
	v_mul_f32_e32 v77, 0x37800000, v75
	v_cndmask_b32_e64 v75, v75, v77, s[4:5]
	v_cmp_class_f32_e64 s[4:5], v74, v149
	s_waitcnt vmcnt(2)
	v_mov_b32_e32 v77, v70
	v_cndmask_b32_e64 v75, v75, v74, s[4:5]
	v_div_fmas_f32 v74, v76, v91, v93
	v_mov_b32_e32 v76, v66
	v_mov_b32_e32 v70, v67
	v_pk_add_f32 v[66:67], v[76:77], v[70:71]
	v_mov_b32_e32 v70, v68
	v_mov_b32_e32 v71, v72
	v_mov_b32_e32 v72, v69
	v_pk_add_f32 v[68:69], v[70:71], v[72:73]
	v_div_scale_f32 v78, s[4:5], v75, v75, 1.0
	v_pk_add_f32 v[66:67], v[66:67], v[68:69]
	v_rcp_f32_e32 v79, v78
	v_add_f32_e32 v66, v66, v67
	v_fmamk_f32 v66, v66, 0x3b000000, v148
	v_mul_f32_e32 v67, 0x4f800000, v66
	v_cmp_gt_f32_e64 s[4:5], s68, v66
	v_div_fixup_f32 v74, v74, v65, 1.0
	v_fma_f32 v65, -v78, v79, 1.0
	v_cndmask_b32_e64 v66, v66, v67, s[4:5]
	v_sqrt_f32_e32 v67, v66
	v_fmac_f32_e32 v79, v65, v79
	v_div_scale_f32 v65, vcc, 1.0, v75, 1.0
	v_mul_f32_e32 v80, v65, v79
	v_fma_f32 v68, -v78, v80, v65
	v_fmac_f32_e32 v80, v68, v79
	v_add_u32_e32 v68, -1, v67
	v_fma_f32 v69, -v68, v67, v66
	v_cmp_ge_f32_e64 s[6:7], 0, v69
	v_add_u32_e32 v69, 1, v67
	v_fma_f32 v65, -v78, v80, v65
	v_cndmask_b32_e64 v68, v67, v68, s[6:7]
	v_fma_f32 v67, -v69, v67, v66
	v_cmp_lt_f32_e64 s[6:7], 0, v67
	v_div_fmas_f32 v65, v65, v79, v80
	v_div_fixup_f32 v75, v65, v75, 1.0
	v_cndmask_b32_e64 v67, v68, v69, s[6:7]
	v_mul_f32_e32 v68, 0x37800000, v67
	v_cndmask_b32_e64 v67, v67, v68, s[4:5]
	v_cmp_class_f32_e64 s[4:5], v66, v149
	v_pk_mul_f32 v[78:79], v[32:33], s[18:19] op_sel_hi:[1,0]
	v_pk_mul_f32 v[80:81], v[34:35], s[18:19] op_sel_hi:[1,0]
	v_cndmask_b32_e64 v68, v67, v66, s[4:5]
	s_waitcnt vmcnt(1)
	v_mov_b32_e32 v66, v48
	s_waitcnt vmcnt(0)
	v_mov_b32_e32 v67, v82
	v_mov_b32_e32 v82, v49
	v_pk_add_f32 v[48:49], v[66:67], v[82:83]
	v_mov_b32_e32 v66, v50
	v_mov_b32_e32 v67, v84
	v_mov_b32_e32 v84, v51
	v_pk_add_f32 v[50:51], v[66:67], v[84:85]
	v_div_scale_f32 v69, s[4:5], v68, v68, 1.0
	v_pk_add_f32 v[48:49], v[48:49], v[50:51]
	v_rcp_f32_e32 v70, v69
	v_add_f32_e32 v48, v48, v49
	v_fmamk_f32 v48, v48, 0x3b000000, v148
	v_mul_f32_e32 v49, 0x4f800000, v48
	v_cmp_gt_f32_e64 s[4:5], s68, v48
	v_fma_f32 v65, -v69, v70, 1.0
	v_fmac_f32_e32 v70, v65, v70
	v_cndmask_b32_e64 v48, v48, v49, s[4:5]
	v_sqrt_f32_e32 v49, v48
	v_div_scale_f32 v65, vcc, 1.0, v68, 1.0
	v_mul_f32_e32 v71, v65, v70
	v_fma_f32 v50, -v69, v71, v65
	v_fmac_f32_e32 v71, v50, v70
	v_add_u32_e32 v51, -1, v49
	v_fma_f32 v50, -v69, v71, v65
	v_fma_f32 v65, -v51, v49, v48
	v_cmp_ge_f32_e64 s[6:7], 0, v65
	v_add_u32_e32 v65, 1, v49
	s_nop 0
	v_cndmask_b32_e64 v51, v49, v51, s[6:7]
	v_fma_f32 v49, -v65, v49, v48
	v_cmp_lt_f32_e64 s[6:7], 0, v49
	s_nop 1
	v_cndmask_b32_e64 v49, v51, v65, s[6:7]
	v_mul_f32_e32 v51, 0x37800000, v49
	v_cndmask_b32_e64 v49, v49, v51, s[4:5]
	v_cmp_class_f32_e64 s[4:5], v48, v149
	s_nop 1
	v_cndmask_b32_e64 v49, v49, v48, s[4:5]
	v_div_scale_f32 v51, s[4:5], v49, v49, 1.0
	v_rcp_f32_e32 v65, v51
	v_div_fmas_f32 v48, v50, v70, v71
	v_div_fixup_f32 v48, v48, v68, 1.0
	v_lshl_add_u64 v[70:71], v[136:137], 0, s[36:37]
	v_fma_f32 v50, -v51, v65, 1.0
; __device__ __forceinline__ float clamp448(float x) { return __builtin_amdgcn_fmed3f(x, -448.0f, 448.0f); }
; __device__ __forceinline__ float rms_scale(const float* ssq, int row, int which) {
;     const f32x4 a = *(const f32x4*)(ssq + (size_t)row * 16 + which * 8), b = *(const f32x4*)(ssq + (size_t)row * 16 + which * 8 + 4);
;     const float s = ((a[0] + a[1]) + (a[2] + a[3])) + ((b[0] + b[1]) + (b[2] + b[3]));
;     return 1.0f / sqrtf(s * (1.0f / 512.0f) + RMS_EPS);
; }
;     __device__ __forceinline__ void operator()(EPI_ARGS) const {
;     ...
;             for (int m = 0; m < 4; ++m) { const int t0 = u.pm * BM + ai * HALF + wr * 64 + 16 * m + 4 * fq, q = 4 * m + fq;
;                 const f32x4 rs = (f32x4){rms_scale(ssq, t0, 1), rms_scale(ssq, t0 + 1, 1), rms_scale(ssq, t0 + 2, 1), rms_scale(ssq, t0 + 3, 1)} * osc;
;                 const size_t tpos = (size_t)(t0 & ~63) + 32 * (q & 1) + 16 * (q >> 3) + 4 * ((q >> 1) & 3);
; #pragma unroll
;                 for (int bj = 0; bj < 2; ++bj)
; #pragma unroll
;                     for (int n = 0; n < 2; ++n) { const f32x4 v = acc[ai][bj][m][n] * rs;
;                         int w = __builtin_amdgcn_cvt_pk_fp8_f32(clamp448(v[0]), clamp448(v[1]), 0, false); w = __builtin_amdgcn_cvt_pk_fp8_f32(clamp448(v[2]), clamp448(v[3]), w, true);
;                         *(unsigned*)(VT + ((size_t)((2 * u.pn + bj) * 128 + dcol + 4 * n)) * NTOK + tpos) = (unsigned)w; } }
	v_fmac_f32_e32 v65, v50, v65
	v_div_scale_f32 v50, vcc, 1.0, v49, 1.0
	v_mul_f32_e32 v66, v50, v65
	v_fma_f32 v67, -v51, v66, v50
	v_fmac_f32_e32 v66, v67, v65
	v_fma_f32 v50, -v51, v66, v50
	v_div_fmas_f32 v50, v50, v65, v66
	v_div_fixup_f32 v49, v50, v49, 1.0
	v_pk_mul_f32 v[66:67], v[74:75], s[20:21] op_sel_hi:[1,0]
	v_pk_mul_f32 v[68:69], v[48:49], s[20:21] op_sel_hi:[1,0]
	v_pk_mul_f32 v[48:49], v[62:63], v[66:67]
	v_med3_f32 v48, v48, s69, v150
	v_med3_f32 v49, v49, s69, v150
	v_cvt_pk_fp8_f32 v50, v48, v49
	v_pk_mul_f32 v[48:49], v[60:61], v[68:69]
	v_pk_mul_f32 v[54:55], v[54:55], v[66:67]
	v_med3_f32 v48, v48, s69, v150
	v_med3_f32 v49, v49, s69, v150
	v_cvt_pk_fp8_f32 v50, v48, v49 op_sel:[0,0,1]
	v_pk_mul_f32 v[48:49], v[58:59], v[66:67]
	v_med3_f32 v48, v48, s69, v150
	v_med3_f32 v49, v49, s69, v150
	v_cvt_pk_fp8_f32 v58, v48, v49
	v_pk_mul_f32 v[48:49], v[56:57], v[68:69]
	v_med3_f32 v54, v54, s69, v150
	v_med3_f32 v55, v55, s69, v150
	v_cvt_pk_fp8_f32 v56, v54, v55
	v_pk_mul_f32 v[52:53], v[52:53], v[68:69]
	v_med3_f32 v52, v52, s69, v150
	v_med3_f32 v53, v53, s69, v150
	v_cvt_pk_fp8_f32 v56, v52, v53 op_sel:[0,0,1]
	v_pk_mul_f32 v[52:53], v[86:87], v[66:67]
	v_med3_f32 v48, v48, s69, v150
	v_med3_f32 v52, v52, s69, v150
	v_med3_f32 v53, v53, s69, v150
	v_cvt_pk_fp8_f32 v57, v52, v53
	v_pk_mul_f32 v[52:53], v[88:89], v[68:69]
	v_med3_f32 v49, v49, s69, v150
	v_med3_f32 v52, v52, s69, v150
	v_med3_f32 v53, v53, s69, v150
	v_cvt_pk_fp8_f32 v57, v52, v53 op_sel:[0,0,1]
	v_cvt_pk_fp8_f32 v58, v48, v49 op_sel:[0,0,1]
	v_lshl_add_u64 v[52:53], v[70:71], 0, v[114:115]
	global_store_dword v[52:53], v56, off
	v_lshl_add_u64 v[54:55], v[70:71], 0, v[118:119]
	v_or_b32_e32 v56, 16, v64
	v_lshl_add_u64 v[48:49], v[70:71], 0, v[112:113]
	global_store_dword v[54:55], v57, off
	v_ashrrev_i32_e32 v57, 31, v56
	global_store_dword v[48:49], v50, off
	v_lshl_add_u64 v[50:51], v[70:71], 0, v[116:117]
	v_lshlrev_b64 v[56:57], 6, v[56:57]
	global_store_dword v[50:51], v58, off
	v_lshl_add_u64 v[60:61], s[8:9], 0, v[56:57]
	global_load_dwordx4 v[56:59], v[60:61], off offset:32
	s_nop 0
	global_load_dwordx4 v[60:63], v[60:61], off offset:48
	v_or_b32_e32 v66, 17, v64
	v_ashrrev_i32_e32 v67, 31, v66
	v_lshlrev_b64 v[66:67], 6, v[66:67]
	v_lshl_add_u64 v[70:71], s[8:9], 0, v[66:67]
	global_load_dwordx4 v[66:69], v[70:71], off offset:32
	s_nop 0
	global_load_dwordx4 v[70:73], v[70:71], off offset:48
	v_cvt_f32_i32_e32 v75, v47
	v_cvt_f32_i32_e32 v74, v46
	v_pk_mul_f32 v[46:47], v[44:45], s[18:19] op_sel_hi:[1,0]
	v_pk_mul_f32 v[44:45], v[74:75], s[18:19] op_sel_hi:[1,0]
	v_cvt_f32_i32_e32 v75, v43
	v_cvt_f32_i32_e32 v74, v42
	v_pk_mul_f32 v[42:43], v[40:41], s[18:19] op_sel_hi:[1,0]
	v_pk_mul_f32 v[40:41], v[74:75], s[18:19] op_sel_hi:[1,0]
	s_waitcnt vmcnt(3)
	v_mov_b32_e32 v74, v56
	s_waitcnt vmcnt(2)
	v_mov_b32_e32 v75, v60
	v_mov_b32_e32 v60, v57
	v_pk_add_f32 v[56:57], v[74:75], v[60:61]
	v_mov_b32_e32 v60, v58
	v_mov_b32_e32 v61, v62
	v_mov_b32_e32 v62, v59
	v_pk_add_f32 v[58:59], v[60:61], v[62:63]
	s_waitcnt vmcnt(0)
	v_mov_b32_e32 v33, v70
	v_pk_add_f32 v[56:57], v[56:57], v[58:59]
	v_mov_b32_e32 v70, v67
	v_add_f32_e32 v65, v56, v57
	v_or_b32_e32 v56, 18, v64
	v_ashrrev_i32_e32 v57, 31, v56
	v_lshlrev_b64 v[56:57], 6, v[56:57]
	v_lshl_add_u64 v[60:61], s[8:9], 0, v[56:57]
	global_load_dwordx4 v[56:59], v[60:61], off offset:32
	s_nop 0
	global_load_dwordx4 v[60:63], v[60:61], off offset:48
	v_fmamk_f32 v65, v65, 0x3b000000, v148
	v_mul_f32_e32 v74, 0x4f800000, v65
	v_cmp_gt_f32_e32 vcc, s68, v65
	s_nop 1
	v_cndmask_b32_e32 v65, v65, v74, vcc
	v_sqrt_f32_e32 v74, v65
	s_nop 0
	v_add_u32_e32 v75, -1, v74
	v_fma_f32 v76, -v75, v74, v65
	v_cmp_ge_f32_e64 s[4:5], 0, v76
	v_add_u32_e32 v76, 1, v74
	s_nop 0
	v_cndmask_b32_e64 v75, v74, v75, s[4:5]
	v_fma_f32 v74, -v76, v74, v65
	v_cmp_lt_f32_e64 s[4:5], 0, v74
	s_nop 1
	v_cndmask_b32_e64 v74, v75, v76, s[4:5]
	v_mul_f32_e32 v75, 0x37800000, v74
	v_cndmask_b32_e32 v74, v74, v75, vcc
	v_cmp_class_f32_e32 vcc, v65, v149
	s_nop 1
	v_cndmask_b32_e32 v65, v74, v65, vcc
	v_div_scale_f32 v82, s[4:5], v65, v65, 1.0
	v_rcp_f32_e32 v83, v82
	v_div_scale_f32 v84, vcc, 1.0, v65, 1.0
	v_fma_f32 v32, -v82, v83, 1.0
	v_fmac_f32_e32 v83, v32, v83
	v_mov_b32_e32 v32, v66
	v_pk_add_f32 v[66:67], v[32:33], v[70:71]
	v_or_b32_e32 v32, 19, v64
	v_ashrrev_i32_e32 v33, 31, v32
	v_lshlrev_b64 v[32:33], 6, v[32:33]
	v_lshl_add_u64 v[70:71], s[8:9], 0, v[32:33]
	global_load_dwordx4 v[32:35], v[70:71], off offset:32
	global_load_dwordx4 v[74:77], v[70:71], off offset:48
	v_mov_b32_e32 v70, v68
	v_mov_b32_e32 v71, v72
	v_mov_b32_e32 v72, v69
	v_pk_add_f32 v[68:69], v[70:71], v[72:73]
	v_mul_f32_e32 v85, v84, v83
	v_pk_add_f32 v[66:67], v[66:67], v[68:69]
	v_fma_f32 v68, -v82, v85, v84
	v_add_f32_e32 v66, v66, v67
	v_fmamk_f32 v66, v66, 0x3b000000, v148
	v_mul_f32_e32 v67, 0x4f800000, v66
	v_cmp_gt_f32_e64 s[4:5], s68, v66
	v_fmac_f32_e32 v85, v68, v83
	v_fma_f32 v68, -v82, v85, v84
	v_cndmask_b32_e64 v66, v66, v67, s[4:5]
	v_sqrt_f32_e32 v67, v66
	s_nop 0
	v_add_u32_e32 v69, -1, v67
	v_fma_f32 v70, -v69, v67, v66
	v_cmp_ge_f32_e64 s[6:7], 0, v70
	v_add_u32_e32 v70, 1, v67
	s_nop 0
	v_cndmask_b32_e64 v69, v67, v69, s[6:7]
	v_fma_f32 v67, -v70, v67, v66
	v_cmp_lt_f32_e64 s[6:7], 0, v67
	s_nop 1
	v_cndmask_b32_e64 v67, v69, v70, s[6:7]
	v_mul_f32_e32 v69, 0x37800000, v67
	v_cndmask_b32_e64 v67, v67, v69, s[4:5]
	v_cmp_class_f32_e64 s[4:5], v66, v149
	s_waitcnt vmcnt(2)
; __device__ __forceinline__ float clamp448(float x) { return __builtin_amdgcn_fmed3f(x, -448.0f, 448.0f); }
; __device__ __forceinline__ float rms_scale(const float* ssq, int row, int which) {
;     const f32x4 a = *(const f32x4*)(ssq + (size_t)row * 16 + which * 8), b = *(const f32x4*)(ssq + (size_t)row * 16 + which * 8 + 4);
;     const float s = ((a[0] + a[1]) + (a[2] + a[3])) + ((b[0] + b[1]) + (b[2] + b[3]));
;     return 1.0f / sqrtf(s * (1.0f / 512.0f) + RMS_EPS);
; }
;     __device__ __forceinline__ void operator()(EPI_ARGS) const {
;     ...
;             for (int m = 0; m < 4; ++m) { const int t0 = u.pm * BM + ai * HALF + wr * 64 + 16 * m + 4 * fq, q = 4 * m + fq;
;                 const f32x4 rs = (f32x4){rms_scale(ssq, t0, 1), rms_scale(ssq, t0 + 1, 1), rms_scale(ssq, t0 + 2, 1), rms_scale(ssq, t0 + 3, 1)} * osc;
;                 const size_t tpos = (size_t)(t0 & ~63) + 32 * (q & 1) + 16 * (q >> 3) + 4 * ((q >> 1) & 3);
; #pragma unroll
;                 for (int bj = 0; bj < 2; ++bj)
; #pragma unroll
;                     for (int n = 0; n < 2; ++n) { const f32x4 v = acc[ai][bj][m][n] * rs;
;                         int w = __builtin_amdgcn_cvt_pk_fp8_f32(clamp448(v[0]), clamp448(v[1]), 0, false); w = __builtin_amdgcn_cvt_pk_fp8_f32(clamp448(v[2]), clamp448(v[3]), w, true);
;                         *(unsigned*)(VT + ((size_t)((2 * u.pn + bj) * 128 + dcol + 4 * n)) * NTOK + tpos) = (unsigned)w; } }
	v_mov_b32_e32 v69, v60
	v_cndmask_b32_e64 v67, v67, v66, s[4:5]
	v_div_fmas_f32 v66, v68, v83, v85
	v_mov_b32_e32 v68, v56
	v_mov_b32_e32 v60, v57
	v_pk_add_f32 v[56:57], v[68:69], v[60:61]
	v_mov_b32_e32 v60, v58
	v_mov_b32_e32 v61, v62
	v_mov_b32_e32 v62, v59
	v_pk_add_f32 v[58:59], v[60:61], v[62:63]
	v_div_scale_f32 v70, s[4:5], v67, v67, 1.0
	v_pk_add_f32 v[56:57], v[56:57], v[58:59]
	v_rcp_f32_e32 v71, v70
	v_add_f32_e32 v56, v56, v57
	v_fmamk_f32 v56, v56, 0x3b000000, v148
	v_mul_f32_e32 v57, 0x4f800000, v56
	v_cmp_gt_f32_e64 s[4:5], s68, v56
	v_div_fixup_f32 v66, v66, v65, 1.0
	v_fma_f32 v65, -v70, v71, 1.0
	v_cndmask_b32_e64 v56, v56, v57, s[4:5]
	v_sqrt_f32_e32 v57, v56
	v_fmac_f32_e32 v71, v65, v71
	v_div_scale_f32 v65, vcc, 1.0, v67, 1.0
	v_add_u32_e32 v59, -1, v57
	v_fma_f32 v60, -v59, v57, v56
	v_cmp_ge_f32_e64 s[6:7], 0, v60
	v_add_u32_e32 v60, 1, v57
	v_mul_f32_e32 v72, v65, v71
	v_cndmask_b32_e64 v59, v57, v59, s[6:7]
	v_fma_f32 v57, -v60, v57, v56
	v_cmp_lt_f32_e64 s[6:7], 0, v57
	v_fma_f32 v58, -v70, v72, v65
	v_fmac_f32_e32 v72, v58, v71
	v_cndmask_b32_e64 v57, v59, v60, s[6:7]
	v_mul_f32_e32 v59, 0x37800000, v57
	v_cndmask_b32_e64 v57, v57, v59, s[4:5]
	v_cmp_class_f32_e64 s[4:5], v56, v149
	v_fma_f32 v58, -v70, v72, v65
	s_nop 0
	v_cndmask_b32_e64 v59, v57, v56, s[4:5]
	v_div_scale_f32 v60, s[4:5], v59, v59, 1.0
	v_rcp_f32_e32 v61, v60
	v_div_fmas_f32 v56, v58, v71, v72
	v_div_fixup_f32 v67, v56, v67, 1.0
	s_waitcnt vmcnt(0)
	v_mov_b32_e32 v57, v74
	v_fma_f32 v56, -v60, v61, 1.0
	v_fmac_f32_e32 v61, v56, v61
	v_mov_b32_e32 v56, v32
	v_mov_b32_e32 v74, v33
	v_pk_add_f32 v[32:33], v[56:57], v[74:75]
	v_mov_b32_e32 v56, v34
	v_mov_b32_e32 v57, v76
	v_mov_b32_e32 v76, v35
	v_pk_add_f32 v[34:35], v[56:57], v[76:77]
	v_div_scale_f32 v58, vcc, 1.0, v59, 1.0
	v_pk_add_f32 v[32:33], v[32:33], v[34:35]
	v_mul_f32_e32 v62, v58, v61
	v_add_f32_e32 v32, v32, v33
	v_fmamk_f32 v32, v32, 0x3b000000, v148
	v_mul_f32_e32 v33, 0x4f800000, v32
	v_cmp_gt_f32_e64 s[4:5], s68, v32
	v_fma_f32 v34, -v60, v62, v58
	v_fmac_f32_e32 v62, v34, v61
	v_cndmask_b32_e64 v32, v32, v33, s[4:5]
	v_sqrt_f32_e32 v33, v32
	v_fma_f32 v34, -v60, v62, v58
	v_add_u32_e32 v35, -1, v33
	v_fma_f32 v56, -v35, v33, v32
	v_cmp_ge_f32_e64 s[6:7], 0, v56
	v_add_u32_e32 v56, 1, v33
	s_nop 0
	v_cndmask_b32_e64 v35, v33, v35, s[6:7]
	v_fma_f32 v33, -v56, v33, v32
	v_cmp_lt_f32_e64 s[6:7], 0, v33
	s_nop 1
	v_cndmask_b32_e64 v33, v35, v56, s[6:7]
	v_mul_f32_e32 v35, 0x37800000, v33
	v_cndmask_b32_e64 v33, v33, v35, s[4:5]
	v_cmp_class_f32_e64 s[4:5], v32, v149
	s_nop 1
	v_cndmask_b32_e64 v33, v33, v32, s[4:5]
	v_div_scale_f32 v35, s[4:5], v33, v33, 1.0
	v_rcp_f32_e32 v56, v35
	v_div_fmas_f32 v32, v34, v61, v62
	v_div_fixup_f32 v32, v32, v59, 1.0
	v_pk_mul_f32 v[60:61], v[16:17], s[18:19] op_sel_hi:[1,0]
	v_fma_f32 v34, -v35, v56, 1.0
	v_fmac_f32_e32 v56, v34, v56
	v_div_scale_f32 v34, vcc, 1.0, v33, 1.0
	v_mul_f32_e32 v57, v34, v56
	v_fma_f32 v58, -v35, v57, v34
	v_fmac_f32_e32 v57, v58, v56
	v_fma_f32 v34, -v35, v57, v34
	v_div_fmas_f32 v34, v34, v56, v57
	v_div_fixup_f32 v33, v34, v33, 1.0
	v_pk_mul_f32 v[34:35], v[66:67], s[20:21] op_sel_hi:[1,0]
	v_pk_mul_f32 v[46:47], v[46:47], v[34:35]
	v_pk_mul_f32 v[32:33], v[32:33], s[20:21] op_sel_hi:[1,0]
	v_med3_f32 v46, v46, s69, v150
	v_med3_f32 v47, v47, s69, v150
	v_cvt_pk_fp8_f32 v56, v46, v47
	v_pk_mul_f32 v[44:45], v[44:45], v[32:33]
	v_pk_mul_f32 v[42:43], v[42:43], v[34:35]
	v_med3_f32 v44, v44, s69, v150
	v_med3_f32 v45, v45, s69, v150
	v_cvt_pk_fp8_f32 v56, v44, v45 op_sel:[0,0,1]
	v_med3_f32 v42, v42, s69, v150
	v_med3_f32 v43, v43, s69, v150
	v_cvt_pk_fp8_f32 v44, v42, v43
	v_pk_mul_f32 v[40:41], v[40:41], v[32:33]
	v_pk_mul_f32 v[36:37], v[36:37], v[34:35]
	v_med3_f32 v40, v40, s69, v150
	v_med3_f32 v41, v41, s69, v150
	v_cvt_pk_fp8_f32 v44, v40, v41 op_sel:[0,0,1]
	v_med3_f32 v36, v36, s69, v150
	v_med3_f32 v37, v37, s69, v150
	v_cvt_pk_fp8_f32 v40, v36, v37
	v_pk_mul_f32 v[36:37], v[38:39], v[32:33]
	v_pk_mul_f32 v[34:35], v[78:79], v[34:35]
	v_med3_f32 v36, v36, s69, v150
	v_med3_f32 v37, v37, s69, v150
	v_cvt_pk_fp8_f32 v40, v36, v37 op_sel:[0,0,1]
	v_med3_f32 v34, v34, s69, v150
	v_med3_f32 v35, v35, s69, v150
	v_cvt_pk_fp8_f32 v36, v34, v35
	v_pk_mul_f32 v[32:33], v[80:81], v[32:33]
	v_cvt_f32_i32_e32 v57, v31
	v_med3_f32 v32, v32, s69, v150
	v_med3_f32 v33, v33, s69, v150
	v_cvt_pk_fp8_f32 v36, v32, v33 op_sel:[0,0,1]
	v_or_b32_e32 v32, 32, v64
	v_ashrrev_i32_e32 v33, 31, v32
	v_lshlrev_b64 v[32:33], 6, v[32:33]
	global_store_dword v[48:49], v56, off offset:8
	global_store_dword v[50:51], v44, off offset:8
	global_store_dword v[52:53], v40, off offset:8
	global_store_dword v[54:55], v36, off offset:8
	v_lshl_add_u64 v[36:37], s[8:9], 0, v[32:33]
	global_load_dwordx4 v[32:35], v[36:37], off offset:32
	s_nop 0
	global_load_dwordx4 v[36:39], v[36:37], off offset:48
	v_or_b32_e32 v40, 33, v64
	v_ashrrev_i32_e32 v41, 31, v40
	v_lshlrev_b64 v[40:41], 6, v[40:41]
	v_lshl_add_u64 v[44:45], s[8:9], 0, v[40:41]
	global_load_dwordx4 v[40:43], v[44:45], off offset:32
	s_nop 0
	global_load_dwordx4 v[44:47], v[44:45], off offset:48
	v_cvt_f32_i32_e32 v56, v30
	v_pk_mul_f32 v[30:31], v[28:29], s[18:19] op_sel_hi:[1,0]
	v_pk_mul_f32 v[62:63], v[18:19], s[18:19] op_sel_hi:[1,0]
	v_pk_mul_f32 v[28:29], v[56:57], s[18:19] op_sel_hi:[1,0]
	v_cvt_f32_i32_e32 v57, v27
	v_cvt_f32_i32_e32 v56, v26
	v_pk_mul_f32 v[26:27], v[24:25], s[18:19] op_sel_hi:[1,0]
	v_pk_mul_f32 v[24:25], v[56:57], s[18:19] op_sel_hi:[1,0]
	s_waitcnt vmcnt(3)
	v_mov_b32_e32 v56, v32
	s_waitcnt vmcnt(2)
; __device__ __forceinline__ float rms_scale(const float* ssq, int row, int which) {
;     const f32x4 a = *(const f32x4*)(ssq + (size_t)row * 16 + which * 8), b = *(const f32x4*)(ssq + (size_t)row * 16 + which * 8 + 4);
;     const float s = ((a[0] + a[1]) + (a[2] + a[3])) + ((b[0] + b[1]) + (b[2] + b[3]));
;     return 1.0f / sqrtf(s * (1.0f / 512.0f) + RMS_EPS);
; }
	v_mov_b32_e32 v57, v36
	v_mov_b32_e32 v36, v33
	v_pk_add_f32 v[32:33], v[56:57], v[36:37]
	v_mov_b32_e32 v36, v34
	v_mov_b32_e32 v37, v38
	v_mov_b32_e32 v38, v35
	v_pk_add_f32 v[34:35], v[36:37], v[38:39]
	s_waitcnt vmcnt(0)
	v_mov_b32_e32 v17, v44
	v_pk_add_f32 v[32:33], v[32:33], v[34:35]
	v_mov_b32_e32 v44, v41
	v_add_f32_e32 v56, v32, v33
	v_or_b32_e32 v32, 34, v64
	v_ashrrev_i32_e32 v33, 31, v32
	v_lshlrev_b64 v[32:33], 6, v[32:33]
	v_lshl_add_u64 v[36:37], s[8:9], 0, v[32:33]
	global_load_dwordx4 v[32:35], v[36:37], off offset:32
	s_nop 0
	global_load_dwordx4 v[36:39], v[36:37], off offset:48
	v_fmamk_f32 v56, v56, 0x3b000000, v148
	v_mul_f32_e32 v57, 0x4f800000, v56
	v_cmp_gt_f32_e32 vcc, s68, v56
	s_nop 1
	v_cndmask_b32_e32 v56, v56, v57, vcc
	v_sqrt_f32_e32 v57, v56
	s_nop 0
	v_add_u32_e32 v58, -1, v57
	v_fma_f32 v59, -v58, v57, v56
	v_cmp_ge_f32_e64 s[4:5], 0, v59
	v_add_u32_e32 v59, 1, v57
	s_nop 0
	v_cndmask_b32_e64 v58, v57, v58, s[4:5]
	v_fma_f32 v57, -v59, v57, v56
	v_cmp_lt_f32_e64 s[4:5], 0, v57
	s_nop 1
	v_cndmask_b32_e64 v57, v58, v59, s[4:5]
	v_mul_f32_e32 v58, 0x37800000, v57
	v_cndmask_b32_e32 v57, v57, v58, vcc
	v_cmp_class_f32_e32 vcc, v56, v149
	s_nop 1
	v_cndmask_b32_e32 v65, v57, v56, vcc
	v_div_scale_f32 v66, s[4:5], v65, v65, 1.0
	v_rcp_f32_e32 v67, v66
	v_div_scale_f32 v68, vcc, 1.0, v65, 1.0
	v_fma_f32 v16, -v66, v67, 1.0
	v_fmac_f32_e32 v67, v16, v67
	v_mov_b32_e32 v16, v40
	v_pk_add_f32 v[40:41], v[16:17], v[44:45]
	v_or_b32_e32 v16, 35, v64
	v_ashrrev_i32_e32 v17, 31, v16
	v_lshlrev_b64 v[16:17], 6, v[16:17]
	v_lshl_add_u64 v[44:45], s[8:9], 0, v[16:17]
	global_load_dwordx4 v[16:19], v[44:45], off offset:32
	global_load_dwordx4 v[56:59], v[44:45], off offset:48
	v_mov_b32_e32 v44, v42
	v_mov_b32_e32 v45, v46
	v_mov_b32_e32 v46, v43
	v_pk_add_f32 v[42:43], v[44:45], v[46:47]
	v_mul_f32_e32 v69, v68, v67
	v_pk_add_f32 v[40:41], v[40:41], v[42:43]
	v_fma_f32 v42, -v66, v69, v68
	v_add_f32_e32 v40, v40, v41
	v_fmamk_f32 v40, v40, 0x3b000000, v148
	v_mul_f32_e32 v41, 0x4f800000, v40
	v_cmp_gt_f32_e64 s[4:5], s68, v40
	v_fmac_f32_e32 v69, v42, v67
	v_fma_f32 v42, -v66, v69, v68
	v_cndmask_b32_e64 v40, v40, v41, s[4:5]
	v_sqrt_f32_e32 v41, v40
	s_nop 0
	v_add_u32_e32 v43, -1, v41
	v_fma_f32 v44, -v43, v41, v40
	v_cmp_ge_f32_e64 s[6:7], 0, v44
	v_add_u32_e32 v44, 1, v41
	s_nop 0
	v_cndmask_b32_e64 v43, v41, v43, s[6:7]
	v_fma_f32 v41, -v44, v41, v40
	v_cmp_lt_f32_e64 s[6:7], 0, v41
	s_nop 1
	v_cndmask_b32_e64 v41, v43, v44, s[6:7]
	v_mul_f32_e32 v43, 0x37800000, v41
	v_cndmask_b32_e64 v41, v41, v43, s[4:5]
	v_cmp_class_f32_e64 s[4:5], v40, v149
	s_waitcnt vmcnt(2)
	v_mov_b32_e32 v43, v36
	v_cndmask_b32_e64 v41, v41, v40, s[4:5]
	v_div_scale_f32 v44, s[4:5], v41, v41, 1.0
	v_rcp_f32_e32 v45, v44
	v_div_fmas_f32 v40, v42, v67, v69
	v_mov_b32_e32 v36, v33
	v_div_scale_f32 v46, vcc, 1.0, v41, 1.0
	v_fma_f32 v42, -v44, v45, 1.0
	v_fmac_f32_e32 v45, v42, v45
	v_mov_b32_e32 v42, v32
	v_pk_add_f32 v[32:33], v[42:43], v[36:37]
	v_mov_b32_e32 v36, v34
	v_mov_b32_e32 v37, v38
	v_mov_b32_e32 v38, v35
	v_pk_add_f32 v[34:35], v[36:37], v[38:39]
	v_mul_f32_e32 v47, v46, v45
	v_pk_add_f32 v[32:33], v[32:33], v[34:35]
	v_fma_f32 v34, -v44, v47, v46
	v_add_f32_e32 v32, v32, v33
	v_fmamk_f32 v32, v32, 0x3b000000, v148
	v_mul_f32_e32 v33, 0x4f800000, v32
	v_cmp_gt_f32_e64 s[4:5], s68, v32
	v_fmac_f32_e32 v47, v34, v45
	v_fma_f32 v34, -v44, v47, v46
	v_cndmask_b32_e64 v32, v32, v33, s[4:5]
	v_sqrt_f32_e32 v33, v32
	v_div_fixup_f32 v40, v40, v65, 1.0
	v_add_u32_e32 v35, -1, v33
	v_fma_f32 v36, -v35, v33, v32
	v_cmp_ge_f32_e64 s[6:7], 0, v36
	v_add_u32_e32 v36, 1, v33
	s_nop 0
	v_cndmask_b32_e64 v35, v33, v35, s[6:7]
	v_fma_f32 v33, -v36, v33, v32
	v_cmp_lt_f32_e64 s[6:7], 0, v33
	s_nop 1
	v_cndmask_b32_e64 v33, v35, v36, s[6:7]
	v_mul_f32_e32 v35, 0x37800000, v33
	v_cndmask_b32_e64 v33, v33, v35, s[4:5]
	v_cmp_class_f32_e64 s[4:5], v32, v149
	s_nop 1
	v_cndmask_b32_e64 v35, v33, v32, s[4:5]
	v_div_scale_f32 v36, s[4:5], v35, v35, 1.0
	v_rcp_f32_e32 v37, v36
	v_div_fmas_f32 v32, v34, v45, v47
	v_div_fixup_f32 v41, v32, v41, 1.0
	s_waitcnt vmcnt(0)
	v_mov_b32_e32 v33, v56
	v_fma_f32 v32, -v36, v37, 1.0
	v_fmac_f32_e32 v37, v32, v37
	v_mov_b32_e32 v32, v16
	v_mov_b32_e32 v56, v17
	v_pk_add_f32 v[16:17], v[32:33], v[56:57]
	v_mov_b32_e32 v32, v18
	v_mov_b32_e32 v33, v58
	v_mov_b32_e32 v58, v19
	v_pk_add_f32 v[18:19], v[32:33], v[58:59]
	v_div_scale_f32 v34, vcc, 1.0, v35, 1.0
	v_pk_add_f32 v[16:17], v[16:17], v[18:19]
	v_mul_f32_e32 v38, v34, v37
	v_add_f32_e32 v16, v16, v17
	v_fmamk_f32 v16, v16, 0x3b000000, v148
	v_mul_f32_e32 v17, 0x4f800000, v16
	v_cmp_gt_f32_e64 s[4:5], s68, v16
	v_fma_f32 v18, -v36, v38, v34
	v_fmac_f32_e32 v38, v18, v37
	v_cndmask_b32_e64 v16, v16, v17, s[4:5]
	v_sqrt_f32_e32 v17, v16
	v_fma_f32 v18, -v36, v38, v34
	v_add_u32_e32 v19, -1, v17
	v_fma_f32 v32, -v19, v17, v16
	v_cmp_ge_f32_e64 s[6:7], 0, v32
	v_add_u32_e32 v32, 1, v17
	s_nop 0
	v_cndmask_b32_e64 v19, v17, v19, s[6:7]
	v_fma_f32 v17, -v32, v17, v16
	v_cmp_lt_f32_e64 s[6:7], 0, v17
	s_nop 1
	v_cndmask_b32_e64 v17, v19, v32, s[6:7]
	v_mul_f32_e32 v19, 0x37800000, v17
	v_cndmask_b32_e64 v17, v17, v19, s[4:5]
	v_cmp_class_f32_e64 s[4:5], v16, v149
	s_nop 1
	v_cndmask_b32_e64 v17, v17, v16, s[4:5]
	v_div_scale_f32 v19, s[4:5], v17, v17, 1.0
	v_rcp_f32_e32 v32, v19
	v_div_fmas_f32 v16, v18, v37, v38
	v_div_fixup_f32 v16, v16, v35, 1.0
	v_pk_mul_f32 v[36:37], v[0:1], s[18:19] op_sel_hi:[1,0]
	v_fma_f32 v18, -v19, v32, 1.0
	v_fmac_f32_e32 v32, v18, v32
	v_div_scale_f32 v18, vcc, 1.0, v17, 1.0
	v_mul_f32_e32 v33, v18, v32
	v_fma_f32 v34, -v19, v33, v18
; __device__ __forceinline__ float clamp448(float x) { return __builtin_amdgcn_fmed3f(x, -448.0f, 448.0f); }
; __device__ __forceinline__ float rms_scale(const float* ssq, int row, int which) {
;     const f32x4 a = *(const f32x4*)(ssq + (size_t)row * 16 + which * 8), b = *(const f32x4*)(ssq + (size_t)row * 16 + which * 8 + 4);
;     const float s = ((a[0] + a[1]) + (a[2] + a[3])) + ((b[0] + b[1]) + (b[2] + b[3]));
;     return 1.0f / sqrtf(s * (1.0f / 512.0f) + RMS_EPS);
; }
;     __device__ __forceinline__ void operator()(EPI_ARGS) const {
;     ...
;             for (int m = 0; m < 4; ++m) { const int t0 = u.pm * BM + ai * HALF + wr * 64 + 16 * m + 4 * fq, q = 4 * m + fq;
;                 const f32x4 rs = (f32x4){rms_scale(ssq, t0, 1), rms_scale(ssq, t0 + 1, 1), rms_scale(ssq, t0 + 2, 1), rms_scale(ssq, t0 + 3, 1)} * osc;
;                 const size_t tpos = (size_t)(t0 & ~63) + 32 * (q & 1) + 16 * (q >> 3) + 4 * ((q >> 1) & 3);
; #pragma unroll
;                 for (int bj = 0; bj < 2; ++bj)
; #pragma unroll
;                     for (int n = 0; n < 2; ++n) { const f32x4 v = acc[ai][bj][m][n] * rs;
;                         int w = __builtin_amdgcn_cvt_pk_fp8_f32(clamp448(v[0]), clamp448(v[1]), 0, false); w = __builtin_amdgcn_cvt_pk_fp8_f32(clamp448(v[2]), clamp448(v[3]), w, true);
;                         *(unsigned*)(VT + ((size_t)((2 * u.pn + bj) * 128 + dcol + 4 * n)) * NTOK + tpos) = (unsigned)w; } }
	v_fmac_f32_e32 v33, v34, v32
	v_fma_f32 v18, -v19, v33, v18
	v_div_fmas_f32 v18, v18, v32, v33
	v_div_fixup_f32 v17, v18, v17, 1.0
	v_pk_mul_f32 v[18:19], v[40:41], s[20:21] op_sel_hi:[1,0]
	v_pk_mul_f32 v[30:31], v[30:31], v[18:19]
	v_pk_mul_f32 v[16:17], v[16:17], s[20:21] op_sel_hi:[1,0]
	v_med3_f32 v30, v30, s69, v150
	v_med3_f32 v31, v31, s69, v150
	v_cvt_pk_fp8_f32 v32, v30, v31
	v_pk_mul_f32 v[28:29], v[28:29], v[16:17]
	v_pk_mul_f32 v[26:27], v[26:27], v[18:19]
	v_med3_f32 v28, v28, s69, v150
	v_med3_f32 v29, v29, s69, v150
	v_cvt_pk_fp8_f32 v32, v28, v29 op_sel:[0,0,1]
	v_med3_f32 v26, v26, s69, v150
	v_med3_f32 v27, v27, s69, v150
	v_cvt_pk_fp8_f32 v28, v26, v27
	v_pk_mul_f32 v[24:25], v[24:25], v[16:17]
	v_pk_mul_f32 v[20:21], v[20:21], v[18:19]
	v_med3_f32 v24, v24, s69, v150
	v_med3_f32 v25, v25, s69, v150
	v_cvt_pk_fp8_f32 v28, v24, v25 op_sel:[0,0,1]
	v_med3_f32 v20, v20, s69, v150
	v_med3_f32 v21, v21, s69, v150
	v_cvt_pk_fp8_f32 v24, v20, v21
	v_pk_mul_f32 v[20:21], v[22:23], v[16:17]
	v_pk_mul_f32 v[18:19], v[60:61], v[18:19]
	v_med3_f32 v20, v20, s69, v150
	v_med3_f32 v21, v21, s69, v150
	v_cvt_pk_fp8_f32 v24, v20, v21 op_sel:[0,0,1]
	v_med3_f32 v18, v18, s69, v150
	v_med3_f32 v19, v19, s69, v150
	v_cvt_pk_fp8_f32 v20, v18, v19
	v_pk_mul_f32 v[16:17], v[62:63], v[16:17]
	v_cvt_f32_i32_e32 v33, v15
	v_med3_f32 v16, v16, s69, v150
	v_med3_f32 v17, v17, s69, v150
	v_cvt_pk_fp8_f32 v20, v16, v17 op_sel:[0,0,1]
	v_or_b32_e32 v16, 48, v64
	v_ashrrev_i32_e32 v17, 31, v16
	v_lshlrev_b64 v[16:17], 6, v[16:17]
	global_store_dword v[48:49], v32, off offset:16
	global_store_dword v[50:51], v28, off offset:16
	global_store_dword v[52:53], v24, off offset:16
	global_store_dword v[54:55], v20, off offset:16
	v_lshl_add_u64 v[20:21], s[8:9], 0, v[16:17]
	global_load_dwordx4 v[16:19], v[20:21], off offset:32
	s_nop 0
	global_load_dwordx4 v[20:23], v[20:21], off offset:48
	v_or_b32_e32 v24, 49, v64
	v_ashrrev_i32_e32 v25, 31, v24
	v_lshlrev_b64 v[24:25], 6, v[24:25]
	v_lshl_add_u64 v[28:29], s[8:9], 0, v[24:25]
	global_load_dwordx4 v[24:27], v[28:29], off offset:32
	s_nop 0
	global_load_dwordx4 v[28:31], v[28:29], off offset:48
	v_cvt_f32_i32_e32 v32, v14
	v_pk_mul_f32 v[14:15], v[12:13], s[18:19] op_sel_hi:[1,0]
	v_pk_mul_f32 v[38:39], v[2:3], s[18:19] op_sel_hi:[1,0]
	v_pk_mul_f32 v[12:13], v[32:33], s[18:19] op_sel_hi:[1,0]
	v_cvt_f32_i32_e32 v33, v11
	v_cvt_f32_i32_e32 v32, v10
	v_pk_mul_f32 v[10:11], v[8:9], s[18:19] op_sel_hi:[1,0]
	v_pk_mul_f32 v[8:9], v[32:33], s[18:19] op_sel_hi:[1,0]
	s_waitcnt vmcnt(3)
	v_mov_b32_e32 v32, v16
	s_waitcnt vmcnt(2)
	v_mov_b32_e32 v33, v20
	v_mov_b32_e32 v20, v17
	v_pk_add_f32 v[16:17], v[32:33], v[20:21]
	v_mov_b32_e32 v20, v18
	v_mov_b32_e32 v21, v22
	v_mov_b32_e32 v22, v19
	v_pk_add_f32 v[18:19], v[20:21], v[22:23]
	s_waitcnt vmcnt(0)
	v_mov_b32_e32 v1, v28
	v_pk_add_f32 v[16:17], v[16:17], v[18:19]
	v_mov_b32_e32 v28, v25
	v_add_f32_e32 v32, v16, v17
	v_or_b32_e32 v16, 50, v64
	v_ashrrev_i32_e32 v17, 31, v16
	v_lshlrev_b64 v[16:17], 6, v[16:17]
	v_lshl_add_u64 v[20:21], s[8:9], 0, v[16:17]
	global_load_dwordx4 v[16:19], v[20:21], off offset:32
	s_nop 0
	global_load_dwordx4 v[20:23], v[20:21], off offset:48
	v_fmamk_f32 v32, v32, 0x3b000000, v148
	v_mul_f32_e32 v33, 0x4f800000, v32
	v_cmp_gt_f32_e32 vcc, s68, v32
	s_nop 1
	v_cndmask_b32_e32 v32, v32, v33, vcc
	v_sqrt_f32_e32 v33, v32
	s_nop 0
	v_add_u32_e32 v34, -1, v33
	v_fma_f32 v35, -v34, v33, v32
	v_cmp_ge_f32_e64 s[4:5], 0, v35
	v_add_u32_e32 v35, 1, v33
	s_nop 0
	v_cndmask_b32_e64 v34, v33, v34, s[4:5]
	v_fma_f32 v33, -v35, v33, v32
	v_cmp_lt_f32_e64 s[4:5], 0, v33
	s_nop 1
	v_cndmask_b32_e64 v33, v34, v35, s[4:5]
	v_mul_f32_e32 v34, 0x37800000, v33
	v_cndmask_b32_e32 v33, v33, v34, vcc
	v_cmp_class_f32_e32 vcc, v32, v149
	s_nop 1
	v_cndmask_b32_e32 v40, v33, v32, vcc
	v_div_scale_f32 v41, s[4:5], v40, v40, 1.0
	v_rcp_f32_e32 v42, v41
	v_div_scale_f32 v43, vcc, 1.0, v40, 1.0
	v_fma_f32 v0, -v41, v42, 1.0
	v_fmac_f32_e32 v42, v0, v42
	v_mov_b32_e32 v0, v24
	v_pk_add_f32 v[24:25], v[0:1], v[28:29]
	v_or_b32_e32 v0, 51, v64
	v_ashrrev_i32_e32 v1, 31, v0
	v_lshlrev_b64 v[0:1], 6, v[0:1]
	v_lshl_add_u64 v[28:29], s[8:9], 0, v[0:1]
	global_load_dwordx4 v[0:3], v[28:29], off offset:32
	global_load_dwordx4 v[32:35], v[28:29], off offset:48
	v_mov_b32_e32 v28, v26
	v_mov_b32_e32 v29, v30
	v_mov_b32_e32 v30, v27
	v_pk_add_f32 v[26:27], v[28:29], v[30:31]
	v_mul_f32_e32 v44, v43, v42
	v_pk_add_f32 v[24:25], v[24:25], v[26:27]
	v_fma_f32 v26, -v41, v44, v43
	v_add_f32_e32 v24, v24, v25
	v_fmamk_f32 v24, v24, 0x3b000000, v148
	v_mul_f32_e32 v25, 0x4f800000, v24
	v_cmp_gt_f32_e64 s[4:5], s68, v24
	v_fmac_f32_e32 v44, v26, v42
	v_fma_f32 v26, -v41, v44, v43
	v_cndmask_b32_e64 v24, v24, v25, s[4:5]
	v_sqrt_f32_e32 v25, v24
	s_nop 0
	v_add_u32_e32 v27, -1, v25
	v_fma_f32 v28, -v27, v25, v24
	v_cmp_ge_f32_e64 s[6:7], 0, v28
	v_add_u32_e32 v28, 1, v25
	s_nop 0
	v_cndmask_b32_e64 v27, v25, v27, s[6:7]
	v_fma_f32 v25, -v28, v25, v24
	v_cmp_lt_f32_e64 s[6:7], 0, v25
	s_nop 1
	v_cndmask_b32_e64 v25, v27, v28, s[6:7]
	v_mul_f32_e32 v27, 0x37800000, v25
	v_cndmask_b32_e64 v25, v25, v27, s[4:5]
	v_cmp_class_f32_e64 s[4:5], v24, v149
	s_waitcnt vmcnt(2)
; __device__ __forceinline__ float clamp448(float x) { return __builtin_amdgcn_fmed3f(x, -448.0f, 448.0f); }
; __device__ __forceinline__ float rms_scale(const float* ssq, int row, int which) {
;     const f32x4 a = *(const f32x4*)(ssq + (size_t)row * 16 + which * 8), b = *(const f32x4*)(ssq + (size_t)row * 16 + which * 8 + 4);
;     const float s = ((a[0] + a[1]) + (a[2] + a[3])) + ((b[0] + b[1]) + (b[2] + b[3]));
;     return 1.0f / sqrtf(s * (1.0f / 512.0f) + RMS_EPS);
; }
;     __device__ __forceinline__ void operator()(EPI_ARGS) const {
;     ...
;             for (int m = 0; m < 4; ++m) { const int t0 = u.pm * BM + ai * HALF + wr * 64 + 16 * m + 4 * fq, q = 4 * m + fq;
;                 const f32x4 rs = (f32x4){rms_scale(ssq, t0, 1), rms_scale(ssq, t0 + 1, 1), rms_scale(ssq, t0 + 2, 1), rms_scale(ssq, t0 + 3, 1)} * osc;
;                 const size_t tpos = (size_t)(t0 & ~63) + 32 * (q & 1) + 16 * (q >> 3) + 4 * ((q >> 1) & 3);
; #pragma unroll
;                 for (int bj = 0; bj < 2; ++bj)
; #pragma unroll
;                     for (int n = 0; n < 2; ++n) { const f32x4 v = acc[ai][bj][m][n] * rs;
;                         int w = __builtin_amdgcn_cvt_pk_fp8_f32(clamp448(v[0]), clamp448(v[1]), 0, false); w = __builtin_amdgcn_cvt_pk_fp8_f32(clamp448(v[2]), clamp448(v[3]), w, true);
;                         *(unsigned*)(VT + ((size_t)((2 * u.pn + bj) * 128 + dcol + 4 * n)) * NTOK + tpos) = (unsigned)w; } }
	v_mov_b32_e32 v27, v20
	v_cndmask_b32_e64 v25, v25, v24, s[4:5]
	v_div_scale_f32 v28, s[4:5], v25, v25, 1.0
	v_rcp_f32_e32 v29, v28
	v_div_fmas_f32 v24, v26, v42, v44
	v_mov_b32_e32 v20, v17
	v_div_scale_f32 v30, vcc, 1.0, v25, 1.0
	v_fma_f32 v26, -v28, v29, 1.0
	v_fmac_f32_e32 v29, v26, v29
	v_mov_b32_e32 v26, v16
	v_pk_add_f32 v[16:17], v[26:27], v[20:21]
	v_mov_b32_e32 v20, v18
	v_mov_b32_e32 v21, v22
	v_mov_b32_e32 v22, v19
	v_pk_add_f32 v[18:19], v[20:21], v[22:23]
	v_mul_f32_e32 v31, v30, v29
	v_pk_add_f32 v[16:17], v[16:17], v[18:19]
	v_fma_f32 v18, -v28, v31, v30
	v_add_f32_e32 v16, v16, v17
	v_fmamk_f32 v16, v16, 0x3b000000, v148
	v_mul_f32_e32 v17, 0x4f800000, v16
	v_cmp_gt_f32_e64 s[4:5], s68, v16
	v_fmac_f32_e32 v31, v18, v29
	v_fma_f32 v18, -v28, v31, v30
	v_cndmask_b32_e64 v16, v16, v17, s[4:5]
	v_sqrt_f32_e32 v17, v16
	v_div_fixup_f32 v24, v24, v40, 1.0
	v_add_u32_e32 v19, -1, v17
	v_fma_f32 v20, -v19, v17, v16
	v_cmp_ge_f32_e64 s[6:7], 0, v20
	v_add_u32_e32 v20, 1, v17
	s_nop 0
	v_cndmask_b32_e64 v19, v17, v19, s[6:7]
	v_fma_f32 v17, -v20, v17, v16
	v_cmp_lt_f32_e64 s[6:7], 0, v17
	s_nop 1
	v_cndmask_b32_e64 v17, v19, v20, s[6:7]
	v_mul_f32_e32 v19, 0x37800000, v17
	v_cndmask_b32_e64 v17, v17, v19, s[4:5]
	v_cmp_class_f32_e64 s[4:5], v16, v149
	s_nop 1
	v_cndmask_b32_e64 v19, v17, v16, s[4:5]
	v_div_scale_f32 v20, s[4:5], v19, v19, 1.0
	v_rcp_f32_e32 v21, v20
	v_div_fmas_f32 v16, v18, v29, v31
	v_div_fixup_f32 v25, v16, v25, 1.0
	s_waitcnt vmcnt(0)
	v_mov_b32_e32 v17, v32
	v_fma_f32 v16, -v20, v21, 1.0
	v_fmac_f32_e32 v21, v16, v21
	v_mov_b32_e32 v16, v0
	v_mov_b32_e32 v32, v1
	v_pk_add_f32 v[0:1], v[16:17], v[32:33]
	v_mov_b32_e32 v16, v2
	v_mov_b32_e32 v17, v34
	v_mov_b32_e32 v34, v3
	v_pk_add_f32 v[2:3], v[16:17], v[34:35]
	v_div_scale_f32 v18, vcc, 1.0, v19, 1.0
	v_pk_add_f32 v[0:1], v[0:1], v[2:3]
	v_mul_f32_e32 v22, v18, v21
	v_add_f32_e32 v0, v0, v1
	v_fmamk_f32 v0, v0, 0x3b000000, v148
	v_mul_f32_e32 v1, 0x4f800000, v0
	v_cmp_gt_f32_e64 s[4:5], s68, v0
	v_fma_f32 v2, -v20, v22, v18
	v_fmac_f32_e32 v22, v2, v21
	v_cndmask_b32_e64 v0, v0, v1, s[4:5]
	v_sqrt_f32_e32 v1, v0
	v_fma_f32 v2, -v20, v22, v18
	v_add_u32_e32 v3, -1, v1
	v_fma_f32 v16, -v3, v1, v0
	v_cmp_ge_f32_e64 s[6:7], 0, v16
	v_add_u32_e32 v16, 1, v1
	s_nop 0
	v_cndmask_b32_e64 v3, v1, v3, s[6:7]
	v_fma_f32 v1, -v16, v1, v0
	v_cmp_lt_f32_e64 s[6:7], 0, v1
	s_nop 1
	v_cndmask_b32_e64 v1, v3, v16, s[6:7]
	v_mul_f32_e32 v3, 0x37800000, v1
	v_cndmask_b32_e64 v1, v1, v3, s[4:5]
	v_cmp_class_f32_e64 s[4:5], v0, v149
	s_nop 1
	v_cndmask_b32_e64 v1, v1, v0, s[4:5]
	v_div_scale_f32 v3, s[4:5], v1, v1, 1.0
	v_rcp_f32_e32 v16, v3
	v_div_fmas_f32 v0, v2, v21, v22
	v_div_fixup_f32 v0, v0, v19, 1.0
	v_fma_f32 v2, -v3, v16, 1.0
	v_fmac_f32_e32 v16, v2, v16
	v_div_scale_f32 v2, vcc, 1.0, v1, 1.0
	v_mul_f32_e32 v17, v2, v16
	v_fma_f32 v18, -v3, v17, v2
	v_fmac_f32_e32 v17, v18, v16
	v_fma_f32 v2, -v3, v17, v2
	v_div_fmas_f32 v2, v2, v16, v17
	v_div_fixup_f32 v1, v2, v1, 1.0
	v_pk_mul_f32 v[2:3], v[24:25], s[20:21] op_sel_hi:[1,0]
	v_pk_mul_f32 v[14:15], v[14:15], v[2:3]
	v_pk_mul_f32 v[0:1], v[0:1], s[20:21] op_sel_hi:[1,0]
	v_med3_f32 v14, v14, s69, v150
	v_med3_f32 v15, v15, s69, v150
	v_cvt_pk_fp8_f32 v16, v14, v15
	v_pk_mul_f32 v[12:13], v[12:13], v[0:1]
	v_pk_mul_f32 v[10:11], v[10:11], v[2:3]
	v_med3_f32 v12, v12, s69, v150
	v_med3_f32 v13, v13, s69, v150
	v_cvt_pk_fp8_f32 v16, v12, v13 op_sel:[0,0,1]
	v_med3_f32 v10, v10, s69, v150
	v_med3_f32 v11, v11, s69, v150
	v_cvt_pk_fp8_f32 v12, v10, v11
	v_pk_mul_f32 v[8:9], v[8:9], v[0:1]
	v_pk_mul_f32 v[4:5], v[4:5], v[2:3]
	v_med3_f32 v8, v8, s69, v150
	v_med3_f32 v9, v9, s69, v150
	v_cvt_pk_fp8_f32 v12, v8, v9 op_sel:[0,0,1]
	v_med3_f32 v4, v4, s69, v150
	v_med3_f32 v5, v5, s69, v150
	v_cvt_pk_fp8_f32 v8, v4, v5
	v_pk_mul_f32 v[4:5], v[6:7], v[0:1]
	v_pk_mul_f32 v[2:3], v[36:37], v[2:3]
	v_med3_f32 v4, v4, s69, v150
	v_med3_f32 v5, v5, s69, v150
	v_cvt_pk_fp8_f32 v8, v4, v5 op_sel:[0,0,1]
	v_med3_f32 v2, v2, s69, v150
	v_med3_f32 v3, v3, s69, v150
	v_cvt_pk_fp8_f32 v4, v2, v3
	v_pk_mul_f32 v[0:1], v[38:39], v[0:1]
	s_andn2_b64 vcc, exec, s[2:3]
	v_med3_f32 v0, v0, s69, v150
	v_med3_f32 v1, v1, s69, v150
	v_cvt_pk_fp8_f32 v4, v0, v1 op_sel:[0,0,1]
	s_mov_b64 s[2:3], -1
	global_store_dword v[48:49], v16, off offset:24
	global_store_dword v[50:51], v12, off offset:24
	global_store_dword v[52:53], v8, off offset:24
	global_store_dword v[54:55], v4, off offset:24
	s_cbranch_vccnz .LBB0_4154
	s_andn2_b64 vcc, exec, s[10:11]
	s_cbranch_vccnz .LBB0_4153
	s_barrier
	s_branch .LBB0_4153

; template <int MODE>
; __device__ __forceinline__ void partialSM(f32x16& p0, f32x16& p1, float& m_reg, float& mn, float& alpha, const bool first) {
;     ...
;     if constexpr (Cfg<MODE>::F8QK) {
;         float pmax = p0[0]; for (int r = 1; r < 16; ++r) pmax = fmaxf(pmax, p0[r]); for (int r = 0; r < 16; ++r) pmax = fmaxf(pmax, p1[r]);
;         { auto rr = __builtin_amdgcn_permlane32_swap(__float_as_uint(pmax), __float_as_uint(pmax), false, false);
;           pmax = fmaxf(__uint_as_float(rr[0]), __uint_as_float(rr[1])); }
;         constexpr float THR2 = Cfg<MODE>::THR * 1.4426950408889634f;
;         if (__builtin_expect(!first && __all(pmax <= THR2), 1)) { mn = m_reg; alpha = 1.f; }
;         else { const float moff = first ? 0.f : m_reg; mn = fmaxf(m_reg, moff + pmax); alpha = __builtin_amdgcn_exp2f(m_reg - mn); m_reg = mn; const float d = mn - moff;
;             for (int r = 0; r < 16; ++r) p0[r] -= d; for (int r = 0; r < 16; ++r) p1[r] -= d; }
;         for (int r = 0; r < 16; ++r) p0[r] = __builtin_amdgcn_exp2f(p0[r]);
; template <int MODE>
; __device__ __forceinline__ void attn_block(const AttnArgs& a, const BlockRef& cur, const BlockRef& nxt, char* lds, Seam<MODE>& S, const int tid) {
;     ...
;     float m_reg = cur.m0, l_reg = cur.l0; f32x16 o[4] = {};
.LBB0_4250:
	v_max_f32_e32 v36, v36, v36
	v_max_f32_e32 v0, v0, v0
	v_max_f32_e32 v0, v0, v36
	v_add_f32_e32 v0, 0, v0
	v_max_f32_e32 v181, 0xf149f2ca, v0
	v_xor_b32_e32 v232, 0x80000000, v181
	v_mov_b32_e32 v233, v232
	v_mov_b32_e32 v234, v232
	v_mov_b32_e32 v235, v232
	v_mov_b32_e32 v236, v232
	v_mov_b32_e32 v237, v232
	v_mov_b32_e32 v238, v232
	v_mov_b32_e32 v239, v232
	v_mov_b32_e32 v240, v232
	v_mov_b32_e32 v241, v232
	v_mov_b32_e32 v242, v232
	v_mov_b32_e32 v243, v232
	v_mov_b32_e32 v244, v232
	v_mov_b32_e32 v245, v232
	v_mov_b32_e32 v246, v232
	v_mov_b32_e32 v247, v232
	v_sub_f32_e32 v0, v18, v181
	s_and_b32 s60, s94, 0xffffffc0
	v_sub_f32_e32 v18, v19, v181
	v_sub_f32_e32 v19, v20, v181
	v_sub_f32_e32 v20, v21, v181
	v_sub_f32_e32 v21, v22, v181
	v_sub_f32_e32 v22, v23, v181
	v_sub_f32_e32 v23, v24, v181
	v_sub_f32_e32 v24, v25, v181
	v_sub_f32_e32 v25, v26, v181
	v_sub_f32_e32 v26, v27, v181
	v_sub_f32_e32 v27, v28, v181
	v_sub_f32_e32 v28, v29, v181
	v_sub_f32_e32 v29, v30, v181
	v_sub_f32_e32 v30, v31, v181
	v_sub_f32_e32 v31, v32, v181
	v_sub_f32_e32 v32, v33, v181
	v_exp_f32_e32 v219, v0
	v_sub_f32_e32 v0, 0xf149f2ca, v181
	s_lshl_b32 s30, s60, 2
	v_exp_f32_e32 v220, v18
	v_exp_f32_e32 v211, v19
	v_exp_f32_e32 v213, v20
	v_exp_f32_e32 v217, v21
	v_exp_f32_e32 v218, v22
	v_exp_f32_e32 v215, v23
	v_exp_f32_e32 v216, v24
	v_exp_f32_e32 v212, v25
	v_exp_f32_e32 v214, v26
	v_exp_f32_e32 v205, v27
	v_exp_f32_e32 v206, v28
	v_exp_f32_e32 v209, v29
	v_exp_f32_e32 v210, v30
	v_exp_f32_e32 v207, v31
	v_exp_f32_e32 v208, v32
	v_exp_f32_e32 v199, v0
	s_add_i32 s62, s30, 0
	s_add_i32 s62, s62, 0x10000
	s_cmp_lg_u32 s92, 2
	v_sub_f32_e32 v127, v17, v181
	v_sub_f32_e32 v126, v16, v181
	v_sub_f32_e32 v125, v15, v181
	v_sub_f32_e32 v124, v14, v181
	v_sub_f32_e32 v123, v13, v181
	v_sub_f32_e32 v122, v12, v181
	v_sub_f32_e32 v121, v11, v181
	v_sub_f32_e32 v120, v10, v181
	v_sub_f32_e32 v119, v9, v181
	v_sub_f32_e32 v118, v8, v181
	v_sub_f32_e32 v117, v7, v181
	v_sub_f32_e32 v116, v6, v181
	v_sub_f32_e32 v115, v5, v181
	v_sub_f32_e32 v114, v4, v181
	v_sub_f32_e32 v113, v3, v181
	v_sub_f32_e32 v112, v2, v181
	s_cselect_b32 s92, s54, 0
	s_cmp_lt_i32 s91, 2
	s_waitcnt lgkmcnt(0)
	s_barrier
	s_cbranch_scc1 .LBB0_4283
	v_lshl_add_u64 v[14:15], s[6:7], 0, v[178:179]
	s_lshl_b32 s6, s93, 6
	v_add_u32_e32 v2, s65, v193
	v_mov_b32_e32 v200, 0
	v_lshl_add_u64 v[10:11], s[28:29], 0, v[172:173]
	v_lshl_add_u64 v[12:13], v[34:35], 0, v[172:173]
	s_mov_b32 s58, 2
	v_lshl_add_u32 v0, v183, 2, s62
	v_lshl_add_u32 v180, v186, 2, s62
	s_add_i32 s59, s6, 0x7f
	v_subrev_u32_e32 v201, s6, v2
	v_mov_b32_e32 v64, 0
	v_mov_b32_e32 v65, v200
	v_mov_b32_e32 v66, v200
	v_mov_b32_e32 v67, v200
	v_mov_b32_e32 v68, v200
	v_mov_b32_e32 v69, v200
	v_mov_b32_e32 v70, v200
	v_mov_b32_e32 v71, v200
	v_mov_b32_e32 v72, v200
	v_mov_b32_e32 v73, v200
	v_mov_b32_e32 v74, v200
	v_mov_b32_e32 v75, v200
	v_mov_b32_e32 v76, v200
	v_mov_b32_e32 v77, v200
	v_mov_b32_e32 v78, v200
	v_mov_b32_e32 v79, v200
	v_mov_b32_e32 v48, 0
	v_mov_b32_e32 v49, v200
	v_mov_b32_e32 v50, v200
	v_mov_b32_e32 v51, v200
	v_mov_b32_e32 v52, v200
	v_mov_b32_e32 v53, v200
	v_mov_b32_e32 v54, v200
	v_mov_b32_e32 v55, v200
	v_mov_b32_e32 v56, v200
	v_mov_b32_e32 v57, v200
	v_mov_b32_e32 v58, v200
	v_mov_b32_e32 v59, v200
	v_mov_b32_e32 v60, v200
	v_mov_b32_e32 v61, v200
	v_mov_b32_e32 v62, v200
	v_mov_b32_e32 v63, v200
	v_mov_b32_e32 v32, 0
	v_mov_b32_e32 v33, v200
	v_mov_b32_e32 v34, v200
	v_mov_b32_e32 v35, v200
	v_mov_b32_e32 v36, v200
	v_mov_b32_e32 v37, v200
	v_mov_b32_e32 v38, v200
	v_mov_b32_e32 v39, v200
	v_mov_b32_e32 v40, v200
	v_mov_b32_e32 v41, v200
	v_mov_b32_e32 v42, v200
	v_mov_b32_e32 v43, v200
	v_mov_b32_e32 v44, v200
	v_mov_b32_e32 v45, v200
	v_mov_b32_e32 v46, v200
	v_mov_b32_e32 v47, v200
	v_mov_b32_e32 v16, 0
	v_mov_b32_e32 v17, v200
	v_mov_b32_e32 v18, v200
	v_mov_b32_e32 v19, v200
	v_mov_b32_e32 v20, v200
	v_mov_b32_e32 v21, v200
	v_mov_b32_e32 v22, v200
	v_mov_b32_e32 v23, v200
	v_mov_b32_e32 v24, v200
	v_mov_b32_e32 v25, v200
	v_mov_b32_e32 v26, v200
	v_mov_b32_e32 v27, v200
	v_mov_b32_e32 v28, v200
	v_mov_b32_e32 v29, v200
	v_mov_b32_e32 v30, v200
	v_mov_b32_e32 v31, v200
	s_branch .LBB0_4254

; __device__ __forceinline__ void finishSM8(f32x16& p0, f32x16& p1, float alpha, float& l_reg, v8i_t& pf) {
;     for (int r = 0; r < 16; ++r) p1[r] = __builtin_amdgcn_exp2f(p1[r]);
;     float ps = 0; for (int r = 0; r < 16; ++r) ps += p0[r]; for (int r = 0; r < 16; ++r) ps += p1[r];
;     { auto rr = __builtin_amdgcn_permlane32_swap(__float_as_uint(ps), __float_as_uint(ps), false, false);
;       ps = __uint_as_float(rr[0]) + __uint_as_float(rr[1]); }
;     l_reg = l_reg * alpha + ps;
; template <int MODE, int KB, bool PAD = false>
; __device__ __forceinline__ void qkt(f32x16& p0, f32x16& p1, const char* K_lds, const char* KP_lds, int r32, int hi, const bf16x8* qr, const v8i_t* q8, bool act, const float* ck, float cq, const char* qpe, const float minit, const char* krt = nullptr) {
;     ...
;         const float ni_ = -minit; const int sc1 = 0x7F7F7F7F, scq = 0x7C7C7C7C;
; #pragma unroll
;         for (int r = 0; r < 16; ++r) { p0[r] = ni_; p1[r] = ni_; }
;         const char* k0 = krt + r32 * K8P + hi * 32;
; #pragma unroll
;         for (int s = 0; s < 3; ++s) {
;             const u32x4 a0 = *reinterpret_cast<const u32x4*>(k0 + 64 * s), a1 = *reinterpret_cast<const u32x4*>(k0 + 64 * s + 16);
;             const u32x4 b0 = *reinterpret_cast<const u32x4*>(k0 + 32 * K8P + 64 * s), b1 = *reinterpret_cast<const u32x4*>(k0 + 32 * K8P + 64 * s + 16);
;             const v8i_t ka = (v8i_t){(int)a0[0], (int)a0[1], (int)a0[2], (int)a0[3], (int)a1[0], (int)a1[1], (int)a1[2], (int)a1[3]}, kb2 = (v8i_t){(int)b0[0], (int)b0[1], (int)b0[2], (int)b0[3], (int)b1[0], (int)b1[1], (int)b1[2], (int)b1[3]};
;             asm volatile("v_mfma_scale_f32_32x32x64_f8f6f4 %0, %1, %2, %0, %3, %4 op_sel_hi:[0,0,0]" : "+v"(p0) : "v"(ka), "v"(q8[s]), "v"(sc1), "v"(scq));
;             asm volatile("v_mfma_scale_f32_32x32x64_f8f6f4 %0, %1, %2, %0, %3, %4 op_sel_hi:[0,0,0]" : "+v"(p1) : "v"(kb2), "v"(q8[s]), "v"(sc1), "v"(scq)); }
.LBB0_4254:
	s_cmp_eq_u32 s92, 1
	s_cselect_b32 s30, s77, 0x15000
	s_cmp_eq_u32 s92, 0
	s_cselect_b64 s[28:29], -1, 0
	s_and_b64 s[6:7], s[28:29], exec
	s_cselect_b32 s6, 0x8000, s30
	v_add_u32_e32 v136, s6, v191
	ds_read_b128 v[2:5], v136
	s_waitcnt vmcnt(0)
	ds_read_b128 v[6:9], v136 offset:16
	s_waitcnt vmcnt(1)
	ds_read_b128 v[128:131], v136 offset:6656
	s_waitcnt vmcnt(0)
	ds_read_b128 v[132:135], v136 offset:6672
	s_waitcnt lgkmcnt(2)
	v_mfma_scale_f32_32x32x64_f8f6f4 v[80:95], v[2:9], v[144:151], v[232:247], v194, v195 op_sel_hi:[0,0,0]
	s_waitcnt lgkmcnt(0)
	v_mfma_scale_f32_32x32x64_f8f6f4 v[96:111], v[128:135], v[144:151], v[232:247], v194, v195 op_sel_hi:[0,0,0]
	ds_read_b128 v[2:5], v136 offset:64
	ds_read_b128 v[6:9], v136 offset:80
	ds_read_b128 v[128:131], v136 offset:6720
	ds_read_b128 v[132:135], v136 offset:6736
	s_waitcnt lgkmcnt(2)
	v_mfma_scale_f32_32x32x64_f8f6f4 v[80:95], v[2:9], v[152:159], v[80:95], v194, v195 op_sel_hi:[0,0,0]
	s_waitcnt lgkmcnt(0)
	v_mfma_scale_f32_32x32x64_f8f6f4 v[96:111], v[128:135], v[152:159], v[96:111], v194, v195 op_sel_hi:[0,0,0]
	ds_read_b128 v[2:5], v136 offset:128
	ds_read_b128 v[6:9], v136 offset:144
	ds_read_b128 v[128:131], v136 offset:6784
	ds_read_b128 v[132:135], v136 offset:6800
	s_waitcnt lgkmcnt(2)
	v_mfma_scale_f32_32x32x64_f8f6f4 v[80:95], v[2:9], v[160:167], v[80:95], v194, v195 op_sel_hi:[0,0,0]
	v_add_f32_e32 v2, 0, v219
	v_add_f32_e32 v2, v220, v2
	v_add_f32_e32 v2, v211, v2
	v_add_f32_e32 v2, v213, v2
	v_add_f32_e32 v2, v217, v2
	v_add_f32_e32 v2, v218, v2
	v_add_f32_e32 v2, v215, v2
	v_add_f32_e32 v2, v216, v2
	v_add_f32_e32 v2, v212, v2
	v_add_f32_e32 v2, v214, v2
	v_add_f32_e32 v2, v205, v2
	v_add_f32_e32 v2, v206, v2
	s_waitcnt lgkmcnt(0)
	v_mfma_scale_f32_32x32x64_f8f6f4 v[96:111], v[128:135], v[160:167], v[96:111], v194, v195 op_sel_hi:[0,0,0]
	v_exp_f32_e32 v134, v112
	v_add_f32_e32 v2, v209, v2
	v_exp_f32_e32 v135, v113
	v_add_f32_e32 v2, v210, v2
	v_exp_f32_e32 v128, v114
	v_add_f32_e32 v2, v207, v2
	v_exp_f32_e32 v129, v115
	v_add_f32_e32 v2, v208, v2
	v_exp_f32_e32 v132, v116
	v_add_f32_e32 v2, v134, v2
	v_exp_f32_e32 v133, v117
	v_add_f32_e32 v2, v135, v2
	v_exp_f32_e32 v130, v118
	v_add_f32_e32 v2, v128, v2
	v_exp_f32_e32 v131, v119
	v_add_f32_e32 v2, v129, v2
	v_exp_f32_e32 v118, v120
	v_add_f32_e32 v2, v132, v2
	v_exp_f32_e32 v119, v121
	v_add_f32_e32 v2, v133, v2
	v_exp_f32_e32 v112, v122
	v_add_f32_e32 v2, v130, v2
	v_exp_f32_e32 v113, v123
	v_add_f32_e32 v2, v131, v2
	v_exp_f32_e32 v116, v124
	v_add_f32_e32 v2, v118, v2
	v_exp_f32_e32 v117, v125
	v_add_f32_e32 v2, v119, v2
	v_exp_f32_e32 v114, v126
	v_add_f32_e32 v2, v112, v2
	v_exp_f32_e32 v115, v127
	v_add_f32_e32 v2, v113, v2
	v_add_f32_e32 v2, v116, v2
	v_add_f32_e32 v2, v117, v2
	v_add_f32_e32 v2, v114, v2
	v_add_f32_e32 v202, v115, v2
	v_mov_b32_e32 v203, v202
	s_nop 1
	v_permlane32_swap_b32_e32 v202, v203
	v_add_u32_e32 v223, s59, v184
	v_add_u32_e32 v4, 1, v223
	s_add_i32 s6, s59, 1
	v_ashrrev_i32_e32 v5, 31, v4
	s_ashr_i32 s7, s6, 31
	v_lshlrev_b64 v[4:5], 7, v[4:5]
	v_lshl_add_u64 v[2:3], v[12:13], 0, s[6:7]
	v_lshl_add_u64 v[6:7], v[14:15], 0, v[4:5]
	global_load_dwordx4 v[2:5], v[2:3], off
	s_nop 0
	global_load_dwordx4 v[6:9], v[6:7], off
	s_and_saveexec_b64 s[30:31], s[2:3]
	s_cbranch_execz .LBB0_4256
	v_add3_u32 v120, v174, s59, 1
	v_ashrrev_i32_e32 v121, 31, v120
	v_lshlrev_b64 v[120:121], 6, v[120:121]
	v_lshl_add_u64 v[120:121], v[10:11], 0, v[120:121]
	global_load_dwordx4 v[168:171], v[120:121], off
; __device__ __forceinline__ void mask_tile(f32x16& p0, f32x16& p1, int dq, unsigned W) {
;     const float NEG = -__builtin_inff();
; #pragma unroll
;     for (int r = 0; r < 16; ++r) {
;         const int c = (r & 3) + 8 * (r >> 2);
;         if ((unsigned)(dq - c) >= W) p0[r] = NEG;
;         if ((unsigned)(dq - c - 32) >= W) p1[r] = NEG;
;     }
; __device__ __forceinline__ void finishSM8(f32x16& p0, f32x16& p1, float alpha, float& l_reg, v8i_t& pf) {
;     ...
;     for (int j = 0; j < 4; ++j) { int w = __builtin_amdgcn_cvt_pk_fp8_f32(p0[4 * j], p0[4 * j + 1], 0, false); w = __builtin_amdgcn_cvt_pk_fp8_f32(p0[4 * j + 2], p0[4 * j + 3], w, true); pf[j] = w;
;         int x = __builtin_amdgcn_cvt_pk_fp8_f32(p1[4 * j], p1[4 * j + 1], 0, false); x = __builtin_amdgcn_cvt_pk_fp8_f32(p1[4 * j + 2], p1[4 * j + 3], x, true); pf[4 + j] = x; }
; }
; __device__ __forceinline__ void pv_tile8(f32x16* o, const char* vrt, int r32, int hi, const v8i_t pf) {
;     const char* vb = vrt + r32 * VP8 + hi * 32; const int sc1 = 0x7F7F7F7F;
; #pragma unroll
;     for (int d0 = 0; d0 < 4; ++d0) { const u32x4 a0 = *reinterpret_cast<const u32x4*>(vb + d0 * 32 * VP8), a1 = *reinterpret_cast<const u32x4*>(vb + d0 * 32 * VP8 + 16);
;         const v8i_t vf = (v8i_t){(int)a0[0], (int)a0[1], (int)a0[2], (int)a0[3], (int)a1[0], (int)a1[1], (int)a1[2], (int)a1[3]};
;         asm volatile("v_mfma_scale_f32_32x32x64_f8f6f4 %0, %1, %2, %0, %3, %3 op_sel_hi:[0,0,0]" : "+v"(o[d0]) : "v"(pf), "v"(vf), "v"(sc1)); }
.LBB0_4256:
	s_or_b64 exec, exec, s[30:31]
	v_cvt_pk_fp8_f32 v120, v219, v220
	v_cvt_pk_fp8_f32 v124, v134, v135
	v_cvt_pk_fp8_f32 v121, v217, v218
	v_cvt_pk_fp8_f32 v125, v132, v133
	v_cvt_pk_fp8_f32 v122, v212, v214
	v_cvt_pk_fp8_f32 v126, v118, v119
	v_cvt_pk_fp8_f32 v123, v209, v210
	v_cvt_pk_fp8_f32 v127, v116, v117
	v_cvt_pk_fp8_f32 v120, v211, v213 op_sel:[0,0,1]
	v_cvt_pk_fp8_f32 v124, v128, v129 op_sel:[0,0,1]
	v_cvt_pk_fp8_f32 v121, v215, v216 op_sel:[0,0,1]
	v_cvt_pk_fp8_f32 v125, v130, v131 op_sel:[0,0,1]
	v_cvt_pk_fp8_f32 v122, v205, v206 op_sel:[0,0,1]
	v_cvt_pk_fp8_f32 v126, v112, v113 op_sel:[0,0,1]
	v_cvt_pk_fp8_f32 v123, v207, v208 op_sel:[0,0,1]
	v_cvt_pk_fp8_f32 v127, v114, v115 op_sel:[0,0,1]
	s_sub_i32 s7, s59, 63
	s_add_i32 s30, s92, -1
	s_and_b64 s[28:29], s[28:29], exec
	s_cselect_b32 s28, 2, s30
	s_cmp_eq_u32 s28, 1
	s_cselect_b32 s29, s76, 0x19000
	s_cmp_lg_u32 s28, 0
	s_cselect_b32 s28, s29, 0
	v_add_u32_e32 v128, s28, v192
	ds_read_b128 v[112:115], v128
	ds_read_b128 v[116:119], v128 offset:16
	s_cmp_le_i32 s59, s65
	s_cselect_b64 s[28:29], -1, 0
	s_cmp_gt_i32 s7, s63
	s_waitcnt lgkmcnt(0)
	v_mfma_scale_f32_32x32x64_f8f6f4 v[64:79], v[120:127], v[112:119], v[64:79], v194, v194 op_sel_hi:[0,0,0]
	ds_read_b128 v[112:115], v128 offset:2560
	ds_read_b128 v[116:119], v128 offset:2576
	s_cselect_b64 s[30:31], -1, 0
	s_and_b64 s[28:29], s[30:31], s[28:29]
	s_waitcnt lgkmcnt(0)
	v_mfma_scale_f32_32x32x64_f8f6f4 v[48:63], v[120:127], v[112:119], v[48:63], v194, v194 op_sel_hi:[0,0,0]
	ds_read_b128 v[112:115], v128 offset:5120
	ds_read_b128 v[116:119], v128 offset:5136
	s_and_b64 vcc, exec, s[28:29]
	s_waitcnt lgkmcnt(0)
	v_mfma_scale_f32_32x32x64_f8f6f4 v[32:47], v[120:127], v[112:119], v[32:47], v194, v194 op_sel_hi:[0,0,0]
	ds_read_b128 v[112:115], v128 offset:7680
	ds_read_b128 v[116:119], v128 offset:7696
	s_waitcnt lgkmcnt(0)
	v_mfma_scale_f32_32x32x64_f8f6f4 v[16:31], v[120:127], v[112:119], v[16:31], v194, v194 op_sel_hi:[0,0,0]
	s_cbranch_vccnz .LBB0_4258
	v_add_u32_e32 v112, 0x7b, v201
	v_cmp_gt_u32_e32 vcc, 2.0, v112
	v_add_u32_e32 v112, 0x5b, v201
	s_nop 0
	v_cndmask_b32_e32 v80, v196, v80, vcc
	v_cmp_gt_u32_e32 vcc, 2.0, v112
	v_add_u32_e32 v112, 0x7a, v201
	s_nop 0
	v_cndmask_b32_e32 v96, v196, v96, vcc
	v_cmp_gt_u32_e32 vcc, 2.0, v112
	v_add_u32_e32 v112, 0x5a, v201
	s_nop 0
	v_cndmask_b32_e32 v81, v196, v81, vcc
	v_cmp_gt_u32_e32 vcc, 2.0, v112
	v_add_u32_e32 v112, 0x79, v201
	s_nop 0
	v_cndmask_b32_e32 v97, v196, v97, vcc
	v_cmp_gt_u32_e32 vcc, 2.0, v112
	v_add_u32_e32 v112, 0x59, v201
	s_nop 0
	v_cndmask_b32_e32 v82, v196, v82, vcc
	v_cmp_gt_u32_e32 vcc, 2.0, v112
	v_add_u32_e32 v112, 0x78, v201
	s_nop 0
	v_cndmask_b32_e32 v98, v196, v98, vcc
	v_cmp_gt_u32_e32 vcc, 2.0, v112
	v_add_u32_e32 v112, 0x58, v201
	s_nop 0
	v_cndmask_b32_e32 v83, v196, v83, vcc
	v_cmp_gt_u32_e32 vcc, 2.0, v112
	v_add_u32_e32 v112, 0x73, v201
	s_nop 0
	v_cndmask_b32_e32 v99, v196, v99, vcc
	v_cmp_gt_u32_e32 vcc, 2.0, v112
	v_add_u32_e32 v112, 0x53, v201
	s_nop 0
	v_cndmask_b32_e32 v84, v196, v84, vcc
	v_cmp_gt_u32_e32 vcc, 2.0, v112
	v_add_u32_e32 v112, 0x72, v201
	s_nop 0
	v_cndmask_b32_e32 v100, v196, v100, vcc
	v_cmp_gt_u32_e32 vcc, 2.0, v112
	v_add_u32_e32 v112, 0x52, v201
	s_nop 0
	v_cndmask_b32_e32 v85, v196, v85, vcc
	v_cmp_gt_u32_e32 vcc, 2.0, v112
	v_add_u32_e32 v112, 0x71, v201
	s_nop 0
	v_cndmask_b32_e32 v101, v196, v101, vcc
	v_cmp_gt_u32_e32 vcc, 2.0, v112
	v_add_u32_e32 v112, 0x51, v201
	s_nop 0
	v_cndmask_b32_e32 v86, v196, v86, vcc
	v_cmp_gt_u32_e32 vcc, 2.0, v112
	v_add_u32_e32 v112, 0x70, v201
	s_nop 0
	v_cndmask_b32_e32 v102, v196, v102, vcc
	v_cmp_gt_u32_e32 vcc, 2.0, v112
	v_add_u32_e32 v112, 0x50, v201
	s_nop 0
	v_cndmask_b32_e32 v87, v196, v87, vcc
	v_cmp_gt_u32_e32 vcc, 2.0, v112
	v_add_u32_e32 v112, 0x6b, v201
	s_nop 0
	v_cndmask_b32_e32 v103, v196, v103, vcc
	v_cmp_gt_u32_e32 vcc, 2.0, v112
	v_add_u32_e32 v112, 0x4b, v201
	s_nop 0
	v_cndmask_b32_e32 v88, v196, v88, vcc
	v_cmp_gt_u32_e32 vcc, 2.0, v112
	v_add_u32_e32 v112, 0x6a, v201
	s_nop 0
	v_cndmask_b32_e32 v104, v196, v104, vcc
	v_cmp_gt_u32_e32 vcc, 2.0, v112
	v_add_u32_e32 v112, 0x4a, v201
	s_nop 0
	v_cndmask_b32_e32 v89, v196, v89, vcc
	v_cmp_gt_u32_e32 vcc, 2.0, v112
	v_add_u32_e32 v112, 0x69, v201
	s_nop 0
	v_cndmask_b32_e32 v105, v196, v105, vcc
	v_cmp_gt_u32_e32 vcc, 2.0, v112
	v_add_u32_e32 v112, 0x49, v201
	s_nop 0
	v_cndmask_b32_e32 v90, v196, v90, vcc
	v_cmp_gt_u32_e32 vcc, 2.0, v112
	v_add_u32_e32 v112, 0x68, v201
	s_nop 0
	v_cndmask_b32_e32 v106, v196, v106, vcc
	v_cmp_gt_u32_e32 vcc, 2.0, v112
	v_add_u32_e32 v112, 0x48, v201
	s_nop 0
	v_cndmask_b32_e32 v91, v196, v91, vcc
	v_cmp_gt_u32_e32 vcc, 2.0, v112
	v_add_u32_e32 v112, 0x63, v201
	s_nop 0
	v_cndmask_b32_e32 v107, v196, v107, vcc
	v_cmp_gt_u32_e32 vcc, 2.0, v112
	v_add_u32_e32 v112, 0x43, v201
	s_nop 0
	v_cndmask_b32_e32 v92, v196, v92, vcc
	v_cmp_gt_u32_e32 vcc, 2.0, v112
	v_add_u32_e32 v112, 0x62, v201
	s_nop 0
	v_cndmask_b32_e32 v108, v196, v108, vcc
	v_cmp_gt_u32_e32 vcc, 2.0, v112
	v_add_u32_e32 v112, 0x42, v201
	s_nop 0
	v_cndmask_b32_e32 v93, v196, v93, vcc
	v_cmp_gt_u32_e32 vcc, 2.0, v112
	v_add_u32_e32 v112, 0x61, v201
	s_nop 0
	v_cndmask_b32_e32 v109, v196, v109, vcc
	v_cmp_gt_u32_e32 vcc, 2.0, v112
	v_add_u32_e32 v112, 0x41, v201
	s_nop 0
	v_cndmask_b32_e32 v94, v196, v94, vcc
	v_cmp_gt_u32_e32 vcc, 2.0, v112
	v_add_u32_e32 v112, 0x60, v201
	s_nop 0
	v_cndmask_b32_e32 v110, v196, v110, vcc
	v_cmp_gt_u32_e32 vcc, 2.0, v112
	v_add_u32_e32 v112, 64, v201
	s_nop 0
	v_cndmask_b32_e32 v95, v196, v95, vcc
	v_cmp_gt_u32_e32 vcc, 2.0, v112
	s_nop 1
	v_cndmask_b32_e32 v111, v196, v111, vcc

; template <int MODE>
; __device__ __forceinline__ void partialSM(f32x16& p0, f32x16& p1, float& m_reg, float& mn, float& alpha, const bool first) {
;     ...
;     for (int r = 0; r < 16; ++r) p0[r] = __builtin_amdgcn_exp2f(p0[r]);
; __device__ __forceinline__ void finishSM8(f32x16& p0, f32x16& p1, float alpha, float& l_reg, v8i_t& pf) {
;     for (int r = 0; r < 16; ++r) p1[r] = __builtin_amdgcn_exp2f(p1[r]);
;     float ps = 0; for (int r = 0; r < 16; ++r) ps += p0[r]; for (int r = 0; r < 16; ++r) ps += p1[r];
;     { auto rr = __builtin_amdgcn_permlane32_swap(__float_as_uint(ps), __float_as_uint(ps), false, false);
;       ps = __uint_as_float(rr[0]) + __uint_as_float(rr[1]); }
;     l_reg = l_reg * alpha + ps;
; template <int MODE, int KB, bool PAD = false>
; __device__ __forceinline__ void qkt(f32x16& p0, f32x16& p1, const char* K_lds, const char* KP_lds, int r32, int hi, const bf16x8* qr, const v8i_t* q8, bool act, const float* ck, float cq, const char* qpe, const float minit, const char* krt = nullptr) {
;     ...
;         const float ni_ = -minit; const int sc1 = 0x7F7F7F7F, scq = 0x7C7C7C7C;
; #pragma unroll
;         for (int r = 0; r < 16; ++r) { p0[r] = ni_; p1[r] = ni_; }
;         const char* k0 = krt + r32 * K8P + hi * 32;
; #pragma unroll
;         for (int s = 0; s < 3; ++s) {
;             const u32x4 a0 = *reinterpret_cast<const u32x4*>(k0 + 64 * s), a1 = *reinterpret_cast<const u32x4*>(k0 + 64 * s + 16);
;             const u32x4 b0 = *reinterpret_cast<const u32x4*>(k0 + 32 * K8P + 64 * s), b1 = *reinterpret_cast<const u32x4*>(k0 + 32 * K8P + 64 * s + 16);
;             const v8i_t ka = (v8i_t){(int)a0[0], (int)a0[1], (int)a0[2], (int)a0[3], (int)a1[0], (int)a1[1], (int)a1[2], (int)a1[3]}, kb2 = (v8i_t){(int)b0[0], (int)b0[1], (int)b0[2], (int)b0[3], (int)b1[0], (int)b1[1], (int)b1[2], (int)b1[3]};
;             asm volatile("v_mfma_scale_f32_32x32x64_f8f6f4 %0, %1, %2, %0, %3, %4 op_sel_hi:[0,0,0]" : "+v"(p0) : "v"(ka), "v"(q8[s]), "v"(sc1), "v"(scq));
;             asm volatile("v_mfma_scale_f32_32x32x64_f8f6f4 %0, %1, %2, %0, %3, %4 op_sel_hi:[0,0,0]" : "+v"(p1) : "v"(kb2), "v"(q8[s]), "v"(sc1), "v"(scq)); }
.LBB0_4265:
	v_exp_f32_e32 v80, v80
	v_exp_f32_e32 v81, v81
	v_exp_f32_e32 v82, v82
	v_exp_f32_e32 v83, v83
	v_exp_f32_e32 v84, v84
	v_exp_f32_e32 v85, v85
	v_exp_f32_e32 v86, v86
	v_exp_f32_e32 v87, v87
	v_exp_f32_e32 v88, v88
	v_exp_f32_e32 v89, v89
	v_exp_f32_e32 v90, v90
	v_exp_f32_e32 v91, v91
	v_exp_f32_e32 v92, v92
	v_exp_f32_e32 v93, v93
	v_exp_f32_e32 v94, v94
	v_exp_f32_e32 v95, v95
	s_waitcnt lgkmcnt(0)
	s_barrier
	v_add3_u32 v205, s7, v190, v188
	ds_read_b128 v[206:209], v205
	ds_read_b128 v[210:213], v205 offset:16
	ds_read_b128 v[214:217], v205 offset:6656
	ds_read_b128 v[218:221], v205 offset:6672
	s_waitcnt lgkmcnt(2)
	v_mfma_scale_f32_32x32x64_f8f6f4 v[128:143], v[206:213], v[144:151], v[232:247], v194, v195 op_sel_hi:[0,0,0]
	s_waitcnt lgkmcnt(0)
	v_mfma_scale_f32_32x32x64_f8f6f4 v[112:127], v[214:221], v[144:151], v[232:247], v194, v195 op_sel_hi:[0,0,0]
	ds_read_b128 v[206:209], v205 offset:64
	ds_read_b128 v[210:213], v205 offset:80
	ds_read_b128 v[214:217], v205 offset:6720
	ds_read_b128 v[218:221], v205 offset:6736
	s_waitcnt lgkmcnt(2)
	v_mfma_scale_f32_32x32x64_f8f6f4 v[128:143], v[206:213], v[152:159], v[128:143], v194, v195 op_sel_hi:[0,0,0]
	s_waitcnt lgkmcnt(0)
	v_mfma_scale_f32_32x32x64_f8f6f4 v[112:127], v[214:221], v[152:159], v[112:127], v194, v195 op_sel_hi:[0,0,0]
	ds_read_b128 v[206:209], v205 offset:128
	ds_read_b128 v[210:213], v205 offset:144
	ds_read_b128 v[214:217], v205 offset:6784
	ds_read_b128 v[218:221], v205 offset:6800
	v_add_f32_e32 v205, 0, v80
	v_add_f32_e32 v205, v81, v205
	v_add_f32_e32 v205, v82, v205
	v_add_f32_e32 v205, v83, v205
	v_add_f32_e32 v205, v84, v205
	v_add_f32_e32 v205, v85, v205
	v_add_f32_e32 v205, v86, v205
	v_add_f32_e32 v205, v87, v205
	v_add_f32_e32 v205, v88, v205
	v_add_f32_e32 v205, v89, v205
	v_add_f32_e32 v205, v90, v205
	v_add_f32_e32 v205, v91, v205
	v_exp_f32_e32 v96, v96
	v_add_f32_e32 v205, v92, v205
	v_exp_f32_e32 v97, v97
	v_add_f32_e32 v205, v93, v205
	v_exp_f32_e32 v98, v98
	v_add_f32_e32 v205, v94, v205
	v_exp_f32_e32 v99, v99
	v_add_f32_e32 v205, v95, v205
	v_exp_f32_e32 v100, v100
	v_add_f32_e32 v205, v96, v205
	v_exp_f32_e32 v101, v101
	v_add_f32_e32 v205, v97, v205
	v_exp_f32_e32 v102, v102
	v_add_f32_e32 v205, v98, v205
	v_exp_f32_e32 v103, v103
	v_add_f32_e32 v205, v99, v205
	v_exp_f32_e32 v104, v104
	v_add_f32_e32 v205, v100, v205
	v_exp_f32_e32 v105, v105
	v_add_f32_e32 v205, v101, v205
	v_exp_f32_e32 v106, v106
	v_add_f32_e32 v205, v102, v205
	v_exp_f32_e32 v107, v107
	v_add_f32_e32 v205, v103, v205
	v_exp_f32_e32 v108, v108
	v_add_f32_e32 v205, v104, v205
	v_exp_f32_e32 v109, v109
	v_add_f32_e32 v205, v105, v205
	v_exp_f32_e32 v110, v110
	v_add_f32_e32 v205, v106, v205
	v_exp_f32_e32 v111, v111
	v_add_f32_e32 v205, v107, v205
	v_add_f32_e32 v205, v108, v205
	v_add_f32_e32 v205, v109, v205
	v_add_f32_e32 v205, v110, v205
	s_waitcnt lgkmcnt(2)
	v_mfma_scale_f32_32x32x64_f8f6f4 v[128:143], v[206:213], v[160:167], v[128:143], v194, v195 op_sel_hi:[0,0,0]
	s_waitcnt lgkmcnt(0)
	v_mfma_scale_f32_32x32x64_f8f6f4 v[112:127], v[214:221], v[160:167], v[112:127], v194, v195 op_sel_hi:[0,0,0]
	v_add_f32_e32 v221, v111, v205
	v_mov_b32_e32 v222, v221
	s_nop 1
	v_permlane32_swap_b32_e32 v221, v222
	s_add_i32 s7, s58, 1
	s_cmp_le_i32 s7, s91
	s_cselect_b64 s[30:31], -1, 0
	s_cmp_gt_i32 s7, s91
	s_cbranch_scc1 .LBB0_4269
	v_add_u32_e32 v4, 0x41, v223
	s_add_i32 s54, s59, 0x41
	v_ashrrev_i32_e32 v5, 31, v4
	s_ashr_i32 s55, s54, 31
	v_lshlrev_b64 v[4:5], 7, v[4:5]
	v_lshl_add_u64 v[2:3], v[12:13], 0, s[54:55]
	v_lshl_add_u64 v[6:7], v[14:15], 0, v[4:5]
	global_load_dwordx4 v[2:5], v[2:3], off
	s_nop 0
	global_load_dwordx4 v[6:9], v[6:7], off
	s_and_saveexec_b64 s[54:55], s[2:3]
	s_cbranch_execz .LBB0_4268
	v_add_u32_e32 v168, s59, v174
	v_add_u32_e32 v168, 0x41, v168
	v_ashrrev_i32_e32 v169, 31, v168
	v_lshlrev_b64 v[168:169], 6, v[168:169]
	v_lshl_add_u64 v[168:169], v[10:11], 0, v[168:169]
	global_load_dwordx4 v[168:171], v[168:169], off

; __device__ __forceinline__ void mask_tile(f32x16& p0, f32x16& p1, int dq, unsigned W) {
;     const float NEG = -__builtin_inff();
; #pragma unroll
;     for (int r = 0; r < 16; ++r) {
;         const int c = (r & 3) + 8 * (r >> 2);
;         if ((unsigned)(dq - c) >= W) p0[r] = NEG;
;         if ((unsigned)(dq - c - 32) >= W) p1[r] = NEG;
;     }
; __device__ __forceinline__ void finishSM8(f32x16& p0, f32x16& p1, float alpha, float& l_reg, v8i_t& pf) {
;     ...
;     for (int j = 0; j < 4; ++j) { int w = __builtin_amdgcn_cvt_pk_fp8_f32(p0[4 * j], p0[4 * j + 1], 0, false); w = __builtin_amdgcn_cvt_pk_fp8_f32(p0[4 * j + 2], p0[4 * j + 3], w, true); pf[j] = w;
;         int x = __builtin_amdgcn_cvt_pk_fp8_f32(p1[4 * j], p1[4 * j + 1], 0, false); x = __builtin_amdgcn_cvt_pk_fp8_f32(p1[4 * j + 2], p1[4 * j + 3], x, true); pf[4 + j] = x; }
; }
; __device__ __forceinline__ void pv_tile8(f32x16* o, const char* vrt, int r32, int hi, const v8i_t pf) {
;     const char* vb = vrt + r32 * VP8 + hi * 32; const int sc1 = 0x7F7F7F7F;
; #pragma unroll
;     for (int d0 = 0; d0 < 4; ++d0) { const u32x4 a0 = *reinterpret_cast<const u32x4*>(vb + d0 * 32 * VP8), a1 = *reinterpret_cast<const u32x4*>(vb + d0 * 32 * VP8 + 16);
;         const v8i_t vf = (v8i_t){(int)a0[0], (int)a0[1], (int)a0[2], (int)a0[3], (int)a1[0], (int)a1[1], (int)a1[2], (int)a1[3]};
;         asm volatile("v_mfma_scale_f32_32x32x64_f8f6f4 %0, %1, %2, %0, %3, %3 op_sel_hi:[0,0,0]" : "+v"(o[d0]) : "v"(pf), "v"(vf), "v"(sc1)); }
.LBB0_4269:
	s_add_i32 s7, s59, 64
	s_add_i32 s54, s61, -1
	s_and_b64 s[28:29], s[28:29], exec
	s_cselect_b32 s28, 2, s54
	s_cmp_eq_u32 s28, 1
	s_cselect_b32 s29, s76, 0x19000
	s_cmp_lg_u32 s28, 0
	s_cselect_b32 s28, s29, 0
	v_add_u32_e32 v205, s28, v192
	ds_read_b128 v[224:227], v205
	ds_read_b128 v[228:231], v205 offset:16
	v_cvt_pk_fp8_f32 v206, v80, v81
	v_cvt_pk_fp8_f32 v210, v96, v97
	v_cvt_pk_fp8_f32 v207, v84, v85
	v_cvt_pk_fp8_f32 v211, v100, v101
	v_cvt_pk_fp8_f32 v208, v88, v89
	v_cvt_pk_fp8_f32 v212, v104, v105
	v_cvt_pk_fp8_f32 v209, v92, v93
	v_cvt_pk_fp8_f32 v213, v108, v109
	v_cvt_pk_fp8_f32 v206, v82, v83 op_sel:[0,0,1]
	v_cvt_pk_fp8_f32 v210, v98, v99 op_sel:[0,0,1]
	v_cvt_pk_fp8_f32 v207, v86, v87 op_sel:[0,0,1]
	v_cvt_pk_fp8_f32 v211, v102, v103 op_sel:[0,0,1]
	v_cvt_pk_fp8_f32 v208, v90, v91 op_sel:[0,0,1]
	v_cvt_pk_fp8_f32 v212, v106, v107 op_sel:[0,0,1]
	v_cvt_pk_fp8_f32 v209, v94, v95 op_sel:[0,0,1]
	v_cvt_pk_fp8_f32 v213, v110, v111 op_sel:[0,0,1]
	s_cmp_le_i32 s7, s65
	s_waitcnt lgkmcnt(0)
	v_mfma_scale_f32_32x32x64_f8f6f4 v[64:79], v[206:213], v[224:231], v[64:79], v194, v194 op_sel_hi:[0,0,0]
	ds_read_b128 v[224:227], v205 offset:2560
	ds_read_b128 v[228:231], v205 offset:2576
	s_waitcnt lgkmcnt(0)
	v_mfma_scale_f32_32x32x64_f8f6f4 v[48:63], v[206:213], v[224:231], v[48:63], v194, v194 op_sel_hi:[0,0,0]
	ds_read_b128 v[224:227], v205 offset:5120
	ds_read_b128 v[228:231], v205 offset:5136
	s_waitcnt lgkmcnt(0)
	v_mfma_scale_f32_32x32x64_f8f6f4 v[32:47], v[206:213], v[224:231], v[32:47], v194, v194 op_sel_hi:[0,0,0]
	ds_read_b128 v[224:227], v205 offset:7680
	ds_read_b128 v[228:231], v205 offset:7696
	s_cselect_b64 s[28:29], -1, 0
	s_cmp_gt_i32 s6, s63
	s_cselect_b64 s[6:7], -1, 0
	s_and_b64 s[6:7], s[6:7], s[28:29]
	s_and_b64 vcc, exec, s[6:7]
	s_waitcnt lgkmcnt(0)
	v_mfma_scale_f32_32x32x64_f8f6f4 v[16:31], v[206:213], v[224:231], v[16:31], v194, v194 op_sel_hi:[0,0,0]
	s_cbranch_vccnz .LBB0_4271
	v_add_u32_e32 v205, 59, v201
	v_cmp_gt_u32_e32 vcc, 2.0, v205
	v_add_u32_e32 v205, 27, v201
	s_nop 0
	v_cndmask_b32_e32 v128, v196, v128, vcc
	v_cmp_gt_u32_e32 vcc, 2.0, v205
	v_add_u32_e32 v205, 58, v201
	s_nop 0
	v_cndmask_b32_e32 v112, v196, v112, vcc
	v_cmp_gt_u32_e32 vcc, 2.0, v205
	v_add_u32_e32 v205, 26, v201
	s_nop 0
	v_cndmask_b32_e32 v129, v196, v129, vcc
	v_cmp_gt_u32_e32 vcc, 2.0, v205
	v_add_u32_e32 v205, 57, v201
	s_nop 0
	v_cndmask_b32_e32 v113, v196, v113, vcc
	v_cmp_gt_u32_e32 vcc, 2.0, v205
	v_add_u32_e32 v205, 25, v201
	s_nop 0
	v_cndmask_b32_e32 v130, v196, v130, vcc
	v_cmp_gt_u32_e32 vcc, 2.0, v205
	v_add_u32_e32 v205, 56, v201
	s_nop 0
	v_cndmask_b32_e32 v114, v196, v114, vcc
	v_cmp_gt_u32_e32 vcc, 2.0, v205
	v_add_u32_e32 v205, 24, v201
	s_nop 0
	v_cndmask_b32_e32 v131, v196, v131, vcc
	v_cmp_gt_u32_e32 vcc, 2.0, v205
	v_add_u32_e32 v205, 51, v201
	s_nop 0
	v_cndmask_b32_e32 v115, v196, v115, vcc
	v_cmp_gt_u32_e32 vcc, 2.0, v205
	v_add_u32_e32 v205, 19, v201
	s_nop 0
	v_cndmask_b32_e32 v132, v196, v132, vcc
	v_cmp_gt_u32_e32 vcc, 2.0, v205
	v_add_u32_e32 v205, 50, v201
	s_nop 0
	v_cndmask_b32_e32 v116, v196, v116, vcc
	v_cmp_gt_u32_e32 vcc, 2.0, v205
	v_add_u32_e32 v205, 18, v201
	s_nop 0
	v_cndmask_b32_e32 v133, v196, v133, vcc
	v_cmp_gt_u32_e32 vcc, 2.0, v205
	v_add_u32_e32 v205, 49, v201
	s_nop 0
	v_cndmask_b32_e32 v117, v196, v117, vcc
	v_cmp_gt_u32_e32 vcc, 2.0, v205
	v_add_u32_e32 v205, 17, v201
	s_nop 0
	v_cndmask_b32_e32 v134, v196, v134, vcc
	v_cmp_gt_u32_e32 vcc, 2.0, v205
	v_add_u32_e32 v205, 48, v201
	s_nop 0
	v_cndmask_b32_e32 v118, v196, v118, vcc
	v_cmp_gt_u32_e32 vcc, 2.0, v205
	v_add_u32_e32 v205, 16, v201
	s_nop 0
	v_cndmask_b32_e32 v135, v196, v135, vcc
	v_cmp_gt_u32_e32 vcc, 2.0, v205
	v_add_u32_e32 v205, 43, v201
	s_nop 0
	v_cndmask_b32_e32 v119, v196, v119, vcc
	v_cmp_gt_u32_e32 vcc, 2.0, v205
	v_add_u32_e32 v205, 11, v201
	s_nop 0
	v_cndmask_b32_e32 v136, v196, v136, vcc
	v_cmp_gt_u32_e32 vcc, 2.0, v205
	v_add_u32_e32 v205, 42, v201
	s_nop 0
	v_cndmask_b32_e32 v120, v196, v120, vcc
	v_cmp_gt_u32_e32 vcc, 2.0, v205
	v_add_u32_e32 v205, 10, v201
	s_nop 0
	v_cndmask_b32_e32 v137, v196, v137, vcc
	v_cmp_gt_u32_e32 vcc, 2.0, v205
	v_add_u32_e32 v205, 41, v201
	s_nop 0
	v_cndmask_b32_e32 v121, v196, v121, vcc
	v_cmp_gt_u32_e32 vcc, 2.0, v205
	v_add_u32_e32 v205, 9, v201
	s_nop 0
	v_cndmask_b32_e32 v138, v196, v138, vcc
	v_cmp_gt_u32_e32 vcc, 2.0, v205
	v_add_u32_e32 v205, 40, v201
	s_nop 0
	v_cndmask_b32_e32 v122, v196, v122, vcc
	v_cmp_gt_u32_e32 vcc, 2.0, v205
	v_add_u32_e32 v205, 8, v201
	s_nop 0
	v_cndmask_b32_e32 v139, v196, v139, vcc
	v_cmp_gt_u32_e32 vcc, 2.0, v205
	v_add_u32_e32 v205, 35, v201
	s_nop 0
	v_cndmask_b32_e32 v123, v196, v123, vcc
	v_cmp_gt_u32_e32 vcc, 2.0, v205
	v_add_u32_e32 v205, 3, v201
	s_nop 0
	v_cndmask_b32_e32 v140, v196, v140, vcc
	v_cmp_gt_u32_e32 vcc, 2.0, v205
	v_add_u32_e32 v205, 34, v201
	s_nop 0
	v_cndmask_b32_e32 v124, v196, v124, vcc
	v_cmp_gt_u32_e32 vcc, 2.0, v205
	v_add_u32_e32 v205, 2, v201
	s_nop 0
	v_cndmask_b32_e32 v141, v196, v141, vcc
	v_cmp_gt_u32_e32 vcc, 2.0, v205
	v_add_u32_e32 v205, 33, v201
	s_nop 0
	v_cndmask_b32_e32 v125, v196, v125, vcc
	v_cmp_gt_u32_e32 vcc, 2.0, v205
	v_add_u32_e32 v205, 1, v201
	s_nop 0
	v_cndmask_b32_e32 v142, v196, v142, vcc
	v_cmp_gt_u32_e32 vcc, 2.0, v205
	v_add_u32_e32 v205, 32, v201
	s_nop 0
	v_cndmask_b32_e32 v126, v196, v126, vcc
	v_cmp_gt_u32_e32 vcc, 2.0, v205
	s_nop 1
	v_cndmask_b32_e32 v143, v196, v143, vcc
	v_cmp_gt_u32_e32 vcc, 2.0, v201
	s_nop 1
	v_cndmask_b32_e32 v127, v196, v127, vcc

; template <int MODE>
; __device__ __forceinline__ void partialSM(f32x16& p0, f32x16& p1, float& m_reg, float& mn, float& alpha, const bool first) {
;     ...
;         if (__builtin_expect(!first && __all(pmax <= THR2), 1)) { mn = m_reg; alpha = 1.f; }
;         else { const float moff = first ? 0.f : m_reg; mn = fmaxf(m_reg, moff + pmax); alpha = __builtin_amdgcn_exp2f(m_reg - mn); m_reg = mn; const float d = mn - moff;
;             for (int r = 0; r < 16; ++r) p0[r] -= d; for (int r = 0; r < 16; ++r) p1[r] -= d; }
.LBB0_4277:
	v_add_f32_e32 v112, v181, v112
	v_max_f32_e32 v113, v181, v181
	v_max_f32_e32 v113, v113, v112
	v_sub_f32_e32 v112, v181, v113
	v_exp_f32_e32 v204, v112
	v_sub_f32_e32 v112, v113, v181
	v_pk_add_f32 v[80:81], v[80:81], v[112:113] op_sel_hi:[1,0] neg_lo:[0,1] neg_hi:[0,1]
	v_pk_add_f32 v[82:83], v[82:83], v[112:113] op_sel_hi:[1,0] neg_lo:[0,1] neg_hi:[0,1]
	v_pk_add_f32 v[84:85], v[84:85], v[112:113] op_sel_hi:[1,0] neg_lo:[0,1] neg_hi:[0,1]
	v_pk_add_f32 v[86:87], v[86:87], v[112:113] op_sel_hi:[1,0] neg_lo:[0,1] neg_hi:[0,1]
	v_pk_add_f32 v[88:89], v[88:89], v[112:113] op_sel_hi:[1,0] neg_lo:[0,1] neg_hi:[0,1]
	v_pk_add_f32 v[90:91], v[90:91], v[112:113] op_sel_hi:[1,0] neg_lo:[0,1] neg_hi:[0,1]
	v_pk_add_f32 v[92:93], v[92:93], v[112:113] op_sel_hi:[1,0] neg_lo:[0,1] neg_hi:[0,1]
	v_pk_add_f32 v[94:95], v[94:95], v[112:113] op_sel_hi:[1,0] neg_lo:[0,1] neg_hi:[0,1]
	v_sub_f32_e32 v111, v111, v112
	v_sub_f32_e32 v110, v110, v112
	v_sub_f32_e32 v109, v109, v112
	v_sub_f32_e32 v108, v108, v112
	v_sub_f32_e32 v107, v107, v112
	v_sub_f32_e32 v106, v106, v112
	v_sub_f32_e32 v105, v105, v112
	v_sub_f32_e32 v104, v104, v112
	v_sub_f32_e32 v103, v103, v112
	v_sub_f32_e32 v102, v102, v112
	v_sub_f32_e32 v101, v101, v112
	v_sub_f32_e32 v100, v100, v112
	v_sub_f32_e32 v99, v99, v112
	v_sub_f32_e32 v98, v98, v112
	v_sub_f32_e32 v97, v97, v112
	v_sub_f32_e32 v96, v96, v112
	v_mov_b32_e32 v181, v113
	v_xor_b32_e32 v232, 0x80000000, v181
	v_mov_b32_e32 v233, v232
	v_mov_b32_e32 v234, v232
	v_mov_b32_e32 v235, v232
	v_mov_b32_e32 v236, v232
	v_mov_b32_e32 v237, v232
	v_mov_b32_e32 v238, v232
	v_mov_b32_e32 v239, v232
	v_mov_b32_e32 v240, v232
	v_mov_b32_e32 v241, v232
	v_mov_b32_e32 v242, v232
	v_mov_b32_e32 v243, v232
	v_mov_b32_e32 v244, v232
	v_mov_b32_e32 v245, v232
	v_mov_b32_e32 v246, v232
	v_mov_b32_e32 v247, v232
	s_branch .LBB0_4259
.LBB0_4278:
	v_add_f32_e32 v205, v181, v205
	v_max_f32_e32 v206, v181, v181
	v_max_f32_e32 v205, v206, v205
	v_sub_f32_e32 v206, v181, v205
	v_exp_f32_e32 v223, v206
	v_sub_f32_e32 v206, v205, v181
	v_pk_add_f32 v[128:129], v[128:129], v[206:207] op_sel_hi:[1,0] neg_lo:[0,1] neg_hi:[0,1]
	v_pk_add_f32 v[130:131], v[130:131], v[206:207] op_sel_hi:[1,0] neg_lo:[0,1] neg_hi:[0,1]
	v_pk_add_f32 v[132:133], v[132:133], v[206:207] op_sel_hi:[1,0] neg_lo:[0,1] neg_hi:[0,1]
	v_pk_add_f32 v[134:135], v[134:135], v[206:207] op_sel_hi:[1,0] neg_lo:[0,1] neg_hi:[0,1]
	v_pk_add_f32 v[136:137], v[136:137], v[206:207] op_sel_hi:[1,0] neg_lo:[0,1] neg_hi:[0,1]
	v_pk_add_f32 v[138:139], v[138:139], v[206:207] op_sel_hi:[1,0] neg_lo:[0,1] neg_hi:[0,1]
	v_pk_add_f32 v[140:141], v[140:141], v[206:207] op_sel_hi:[1,0] neg_lo:[0,1] neg_hi:[0,1]
	v_pk_add_f32 v[142:143], v[142:143], v[206:207] op_sel_hi:[1,0] neg_lo:[0,1] neg_hi:[0,1]
	v_sub_f32_e32 v127, v127, v206
	v_sub_f32_e32 v126, v126, v206
	v_sub_f32_e32 v125, v125, v206
	v_sub_f32_e32 v124, v124, v206
	v_sub_f32_e32 v123, v123, v206
	v_sub_f32_e32 v122, v122, v206
	v_sub_f32_e32 v121, v121, v206
	v_sub_f32_e32 v120, v120, v206
	v_sub_f32_e32 v119, v119, v206
	v_sub_f32_e32 v118, v118, v206
	v_sub_f32_e32 v117, v117, v206
	v_sub_f32_e32 v116, v116, v206
	v_sub_f32_e32 v115, v115, v206
	v_sub_f32_e32 v114, v114, v206
	v_sub_f32_e32 v113, v113, v206
	v_sub_f32_e32 v112, v112, v206
	v_mov_b32_e32 v181, v205
	v_xor_b32_e32 v232, 0x80000000, v181
	v_mov_b32_e32 v233, v232
	v_mov_b32_e32 v234, v232
	v_mov_b32_e32 v235, v232
	v_mov_b32_e32 v236, v232
	v_mov_b32_e32 v237, v232
	v_mov_b32_e32 v238, v232
	v_mov_b32_e32 v239, v232
	v_mov_b32_e32 v240, v232
	v_mov_b32_e32 v241, v232
	v_mov_b32_e32 v242, v232
	v_mov_b32_e32 v243, v232
	v_mov_b32_e32 v244, v232
	v_mov_b32_e32 v245, v232
	v_mov_b32_e32 v246, v232
	v_mov_b32_e32 v247, v232
	s_mov_b64 s[6:7], -1
	s_and_b64 vcc, exec, s[30:31]
	s_cbranch_vccnz .LBB0_4273

; #define SBAR() __builtin_amdgcn_sched_barrier(0)
; #define QKT(KB_, PX0, PX1, t) qkt<MODE, KB_>(PX0, PX1, K_lds, KP_lds, r32, hi, S.qr, q8, ACT(t), cum_l + KBASE(t), cq, qpe, m_reg, KB3(bq))
; template <int MODE, int KB, bool PAD = false>
; __device__ __forceinline__ void qkt(f32x16& p0, f32x16& p1, const char* K_lds, const char* KP_lds, int r32, int hi, const bf16x8* qr, const v8i_t* q8, bool act, const float* ck, float cq, const char* qpe, const float minit, const char* krt = nullptr) {
;     ...
;         const float ni_ = -minit; const int sc1 = 0x7F7F7F7F, scq = 0x7C7C7C7C;
; #pragma unroll
;         for (int r = 0; r < 16; ++r) { p0[r] = ni_; p1[r] = ni_; }
;         const char* k0 = krt + r32 * K8P + hi * 32;
; #pragma unroll
;         for (int s = 0; s < 3; ++s) {
;             const u32x4 a0 = *reinterpret_cast<const u32x4*>(k0 + 64 * s), a1 = *reinterpret_cast<const u32x4*>(k0 + 64 * s + 16);
;             const u32x4 b0 = *reinterpret_cast<const u32x4*>(k0 + 32 * K8P + 64 * s), b1 = *reinterpret_cast<const u32x4*>(k0 + 32 * K8P + 64 * s + 16);
;             const v8i_t ka = (v8i_t){(int)a0[0], (int)a0[1], (int)a0[2], (int)a0[3], (int)a1[0], (int)a1[1], (int)a1[2], (int)a1[3]}, kb2 = (v8i_t){(int)b0[0], (int)b0[1], (int)b0[2], (int)b0[3], (int)b1[0], (int)b1[1], (int)b1[2], (int)b1[3]};
;             asm volatile("v_mfma_scale_f32_32x32x64_f8f6f4 %0, %1, %2, %0, %3, %4 op_sel_hi:[0,0,0]" : "+v"(p0) : "v"(ka), "v"(q8[s]), "v"(sc1), "v"(scq));
;             asm volatile("v_mfma_scale_f32_32x32x64_f8f6f4 %0, %1, %2, %0, %3, %4 op_sel_hi:[0,0,0]" : "+v"(p1) : "v"(kb2), "v"(q8[s]), "v"(sc1), "v"(scq)); }
; template <int MODE>
; __device__ __forceinline__ void attn_block(const AttnArgs& a, const BlockRef& cur, const BlockRef& nxt, char* lds, Seam<MODE>& S, const int tid) {
;     ...
;     const bool even = (NT & 1) == 0;
;     if (even) { SBAR(); QKT(1, pB0, pB1, NT - 1); SBAR(); }
.LBB0_4284:
	s_and_b32 s6, s91, 1
	s_cmp_eq_u32 s6, 0
	s_cselect_b64 s[28:29], -1, 0
	s_cmp_eq_u32 s6, 1
	s_cselect_b64 s[58:59], -1, 0
	v_mbcnt_lo_u32_b32 v15, -1, 0
	v_mbcnt_hi_u32_b32 v15, -1, v15
	s_and_b64 vcc, exec, s[58:59]
	v_and_b32_e32 v180, 31, v15
	v_and_b32_e32 v201, 0xffffffe0, v15
	s_cbranch_vccz .LBB0_4286
	s_cmp_eq_u32 s92, 1
	s_cselect_b32 s6, s77, 0x15000
	s_cmp_lg_u32 s92, 0
	s_cselect_b32 s6, s6, 0x8000
	s_add_i32 s6, s6, 0
	v_mul_u32_u24_e32 v0, 0xd0, v180
	v_add3_u32 v0, s6, v0, v201
	ds_read_b128 v[2:5], v0
	s_waitcnt vmcnt(0)
	ds_read_b128 v[6:9], v0 offset:16
	ds_read_b128 v[128:131], v0 offset:6656
	ds_read_b128 v[132:135], v0 offset:6672
	s_waitcnt lgkmcnt(2)
	v_mfma_scale_f32_32x32x64_f8f6f4 v[80:95], v[2:9], v[144:151], v[232:247], v194, v195 op_sel_hi:[0,0,0]
	s_waitcnt lgkmcnt(0)
	v_mfma_scale_f32_32x32x64_f8f6f4 v[96:111], v[128:135], v[144:151], v[232:247], v194, v195 op_sel_hi:[0,0,0]
	ds_read_b128 v[2:5], v0 offset:64
	ds_read_b128 v[6:9], v0 offset:80
	ds_read_b128 v[128:131], v0 offset:6720
	ds_read_b128 v[132:135], v0 offset:6736
	s_waitcnt lgkmcnt(2)
	v_mfma_scale_f32_32x32x64_f8f6f4 v[80:95], v[2:9], v[152:159], v[80:95], v194, v195 op_sel_hi:[0,0,0]
	s_waitcnt lgkmcnt(0)
	v_mfma_scale_f32_32x32x64_f8f6f4 v[96:111], v[128:135], v[152:159], v[96:111], v194, v195 op_sel_hi:[0,0,0]
	ds_read_b128 v[2:5], v0 offset:128
	ds_read_b128 v[6:9], v0 offset:144
	ds_read_b128 v[128:131], v0 offset:6784
	ds_read_b128 v[132:135], v0 offset:6800
	s_waitcnt lgkmcnt(2)
	v_mfma_scale_f32_32x32x64_f8f6f4 v[80:95], v[2:9], v[160:167], v[80:95], v194, v195 op_sel_hi:[0,0,0]
	s_waitcnt lgkmcnt(0)
	v_mfma_scale_f32_32x32x64_f8f6f4 v[96:111], v[128:135], v[160:167], v[96:111], v194, v195 op_sel_hi:[0,0,0]

; __device__ __forceinline__ int crow(int r, int hi) { return (r & 3) + 8 * (r >> 2) + 4 * hi; }
; template <int MODE>
; __device__ __forceinline__ void attn_block(const AttnArgs& a, const BlockRef& cur, const BlockRef& nxt, char* lds, Seam<MODE>& S, const int tid) {
;     ...
;     if (a.o8 != 0.f) {
;         unsigned char* Ob = (unsigned char*)a.O + (size_t)(orow_ + wid * QBLK) * ldo + hcol_; const float os = a.o8;
; #pragma unroll
;         for (int r = 0; r < 16; ++r) { const int orow = crow(r, hi);
; #pragma unroll
;             for (int d0 = 0; d0 < 4; ++d0) { const float v = __builtin_amdgcn_fmed3f(o[d0][r] * rli[r] * os, -448.f, 448.f);
;                 const float vn = __shfl_xor(v, 1);
;                 const int pk = __builtin_amdgcn_cvt_pk_fp8_f32(v, vn, 0, false) & 0xffff; const int pk2 = __shfl_xor(pk, 2);
;                 if ((r32 & 3) == 0) *(unsigned*)(Ob + (size_t)orow * ldo + d0 * 32 + r32) = (unsigned)pk | ((unsigned)pk2 << 16); } }
.LBB0_4303:
	s_or_b64 exec, exec, s[6:7]
	v_mul_f32_e32 v48, v48, v124
	v_mul_f32_e32 v48, 0x41800000, v48
	v_med3_f32 v48, v48, s79, v198
	s_nop 1
	v_mov_b32_dpp v64, v48 quad_perm:[1,0,3,2] row_mask:0xf bank_mask:0xf
	s_waitcnt lgkmcnt(0)
	v_mov_b32_e32 v125, v1
	s_waitcnt lgkmcnt(0)
	v_cvt_pk_fp8_f32 v125, v48, v64
	v_and_b32_e32 v48, 0xffff, v125
	s_nop 1
	v_mov_b32_dpp v64, v48 quad_perm:[2,3,0,1] row_mask:0xf bank_mask:0xf
	s_and_saveexec_b64 s[6:7], vcc
	s_cbranch_execz .LBB0_4305
	s_waitcnt lgkmcnt(0)
	v_lshl_or_b32 v48, v64, 16, v48
	global_store_dword v[122:123], v48, off offset:32
.LBB0_4305:
	s_or_b64 exec, exec, s[6:7]
	v_mul_f32_e32 v32, v32, v124
	v_mul_f32_e32 v32, 0x41800000, v32
	v_med3_f32 v32, v32, s79, v198
	s_nop 1
	v_mov_b32_dpp v48, v32 quad_perm:[1,0,3,2] row_mask:0xf bank_mask:0xf
	s_waitcnt lgkmcnt(0)
	v_mov_b32_e32 v64, v1
	s_waitcnt lgkmcnt(0)
	v_cvt_pk_fp8_f32 v64, v32, v48
	v_and_b32_e32 v32, 0xffff, v64
	s_nop 1
	v_mov_b32_dpp v48, v32 quad_perm:[2,3,0,1] row_mask:0xf bank_mask:0xf
	s_and_saveexec_b64 s[6:7], vcc
	s_cbranch_execz .LBB0_4307
	s_waitcnt lgkmcnt(0)
	v_lshl_or_b32 v32, v48, 16, v32
	global_store_dword v[122:123], v32, off offset:64
.LBB0_4307:
	s_or_b64 exec, exec, s[6:7]
	v_mul_f32_e32 v16, v16, v124
	v_mul_f32_e32 v16, 0x41800000, v16
	v_med3_f32 v16, v16, s79, v198
	s_nop 1
	v_mov_b32_dpp v32, v16 quad_perm:[1,0,3,2] row_mask:0xf bank_mask:0xf
	s_waitcnt lgkmcnt(0)
	v_mov_b32_e32 v48, v1
	s_waitcnt lgkmcnt(0)
	v_cvt_pk_fp8_f32 v48, v16, v32
	v_and_b32_e32 v16, 0xffff, v48
	s_nop 1
	v_mov_b32_dpp v32, v16 quad_perm:[2,3,0,1] row_mask:0xf bank_mask:0xf
	s_and_saveexec_b64 s[6:7], vcc
	s_cbranch_execz .LBB0_4309
	s_waitcnt lgkmcnt(0)
	v_lshl_or_b32 v16, v32, 16, v16
	global_store_dword v[122:123], v16, off offset:96

; __device__ __forceinline__ int crow(int r, int hi) { return (r & 3) + 8 * (r >> 2) + 4 * hi; }
; template <int MODE>
; __device__ __forceinline__ void attn_block(const AttnArgs& a, const BlockRef& cur, const BlockRef& nxt, char* lds, Seam<MODE>& S, const int tid) {
;     ...
;     if (a.o8 != 0.f) {
;         unsigned char* Ob = (unsigned char*)a.O + (size_t)(orow_ + wid * QBLK) * ldo + hcol_; const float os = a.o8;
; #pragma unroll
;         for (int r = 0; r < 16; ++r) { const int orow = crow(r, hi);
; #pragma unroll
;             for (int d0 = 0; d0 < 4; ++d0) { const float v = __builtin_amdgcn_fmed3f(o[d0][r] * rli[r] * os, -448.f, 448.f);
;                 const float vn = __shfl_xor(v, 1);
;                 const int pk = __builtin_amdgcn_cvt_pk_fp8_f32(v, vn, 0, false) & 0xffff; const int pk2 = __shfl_xor(pk, 2);
;                 if ((r32 & 3) == 0) *(unsigned*)(Ob + (size_t)orow * ldo + d0 * 32 + r32) = (unsigned)pk | ((unsigned)pk2 << 16); } }
.LBB0_4313:
	s_or_b64 exec, exec, s[6:7]
	v_mul_f32_e32 v32, v33, v16
	v_mul_f32_e32 v32, 0x41800000, v32
	v_med3_f32 v32, v32, s79, v198
	s_nop 1
	v_mov_b32_dpp v33, v32 quad_perm:[1,0,3,2] row_mask:0xf bank_mask:0xf
	s_waitcnt lgkmcnt(0)
	v_mov_b32_e32 v48, v1
	s_waitcnt lgkmcnt(0)
	v_cvt_pk_fp8_f32 v48, v32, v33
	v_and_b32_e32 v32, 0xffff, v48
	s_nop 1
	v_mov_b32_dpp v33, v32 quad_perm:[2,3,0,1] row_mask:0xf bank_mask:0xf
	s_and_saveexec_b64 s[6:7], vcc
	s_cbranch_execz .LBB0_4315
	s_waitcnt lgkmcnt(0)
	v_lshl_or_b32 v32, v33, 16, v32
	global_store_dword v[64:65], v32, off offset:64

; __device__ __forceinline__ int crow(int r, int hi) { return (r & 3) + 8 * (r >> 2) + 4 * hi; }
; template <int MODE>
; __device__ __forceinline__ void attn_block(const AttnArgs& a, const BlockRef& cur, const BlockRef& nxt, char* lds, Seam<MODE>& S, const int tid) {
;     ...
;     if (a.o8 != 0.f) {
;         unsigned char* Ob = (unsigned char*)a.O + (size_t)(orow_ + wid * QBLK) * ldo + hcol_; const float os = a.o8;
; #pragma unroll
;         for (int r = 0; r < 16; ++r) { const int orow = crow(r, hi);
; #pragma unroll
;             for (int d0 = 0; d0 < 4; ++d0) { const float v = __builtin_amdgcn_fmed3f(o[d0][r] * rli[r] * os, -448.f, 448.f);
;                 const float vn = __shfl_xor(v, 1);
;                 const int pk = __builtin_amdgcn_cvt_pk_fp8_f32(v, vn, 0, false) & 0xffff; const int pk2 = __shfl_xor(pk, 2);
;                 if ((r32 & 3) == 0) *(unsigned*)(Ob + (size_t)orow * ldo + d0 * 32 + r32) = (unsigned)pk | ((unsigned)pk2 << 16); } }
.LBB0_4321:
	s_or_b64 exec, exec, s[6:7]
	v_mul_f32_e32 v33, v34, v32
	v_mul_f32_e32 v33, 0x41800000, v33
	v_med3_f32 v33, v33, s79, v198
	s_nop 1
	v_mov_b32_dpp v34, v33 quad_perm:[1,0,3,2] row_mask:0xf bank_mask:0xf
	s_waitcnt lgkmcnt(0)
	v_mov_b32_e32 v48, v1
	s_waitcnt lgkmcnt(0)
	v_cvt_pk_fp8_f32 v48, v33, v34
	v_and_b32_e32 v33, 0xffff, v48
	s_nop 1
	v_mov_b32_dpp v34, v33 quad_perm:[2,3,0,1] row_mask:0xf bank_mask:0xf
	s_and_saveexec_b64 s[6:7], vcc
	s_cbranch_execz .LBB0_4323
	s_waitcnt lgkmcnt(0)
	v_lshl_or_b32 v33, v34, 16, v33
	global_store_dword v[16:17], v33, off offset:64

; __device__ __forceinline__ int crow(int r, int hi) { return (r & 3) + 8 * (r >> 2) + 4 * hi; }
; template <int MODE>
; __device__ __forceinline__ void attn_block(const AttnArgs& a, const BlockRef& cur, const BlockRef& nxt, char* lds, Seam<MODE>& S, const int tid) {
;     ...
;     if (a.o8 != 0.f) {
;         unsigned char* Ob = (unsigned char*)a.O + (size_t)(orow_ + wid * QBLK) * ldo + hcol_; const float os = a.o8;
; #pragma unroll
;         for (int r = 0; r < 16; ++r) { const int orow = crow(r, hi);
; #pragma unroll
;             for (int d0 = 0; d0 < 4; ++d0) { const float v = __builtin_amdgcn_fmed3f(o[d0][r] * rli[r] * os, -448.f, 448.f);
;                 const float vn = __shfl_xor(v, 1);
;                 const int pk = __builtin_amdgcn_cvt_pk_fp8_f32(v, vn, 0, false) & 0xffff; const int pk2 = __shfl_xor(pk, 2);
;                 if ((r32 & 3) == 0) *(unsigned*)(Ob + (size_t)orow * ldo + d0 * 32 + r32) = (unsigned)pk | ((unsigned)pk2 << 16); } }
.LBB0_4347:
	s_or_b64 exec, exec, s[6:7]
	v_mul_f32_e32 v18, v21, v18
	v_mul_f32_e32 v18, 0x41800000, v18
	v_med3_f32 v18, v18, s79, v198
	s_nop 1
	v_mov_b32_dpp v19, v18 quad_perm:[1,0,3,2] row_mask:0xf bank_mask:0xf
	s_waitcnt lgkmcnt(0)
	v_mov_b32_e32 v20, v1
	s_waitcnt lgkmcnt(0)
	v_cvt_pk_fp8_f32 v20, v18, v19
	v_and_b32_e32 v18, 0xffff, v20
	s_nop 1
	v_mov_b32_dpp v19, v18 quad_perm:[2,3,0,1] row_mask:0xf bank_mask:0xf
	s_and_saveexec_b64 s[6:7], vcc
	s_cbranch_execz .LBB0_4349
	s_waitcnt lgkmcnt(0)
	v_lshl_or_b32 v18, v19, 16, v18
	global_store_dword v[16:17], v18, off offset:96

; __device__ __forceinline__ int crow(int r, int hi) { return (r & 3) + 8 * (r >> 2) + 4 * hi; }
; template <int MODE>
; __device__ __forceinline__ void attn_block(const AttnArgs& a, const BlockRef& cur, const BlockRef& nxt, char* lds, Seam<MODE>& S, const int tid) {
;     ...
;     if (a.o8 != 0.f) {
;         unsigned char* Ob = (unsigned char*)a.O + (size_t)(orow_ + wid * QBLK) * ldo + hcol_; const float os = a.o8;
; #pragma unroll
;         for (int r = 0; r < 16; ++r) { const int orow = crow(r, hi);
; #pragma unroll
;             for (int d0 = 0; d0 < 4; ++d0) { const float v = __builtin_amdgcn_fmed3f(o[d0][r] * rli[r] * os, -448.f, 448.f);
;                 const float vn = __shfl_xor(v, 1);
;                 const int pk = __builtin_amdgcn_cvt_pk_fp8_f32(v, vn, 0, false) & 0xffff; const int pk2 = __shfl_xor(pk, 2);
;                 if ((r32 & 3) == 0) *(unsigned*)(Ob + (size_t)orow * ldo + d0 * 32 + r32) = (unsigned)pk | ((unsigned)pk2 << 16); } }
.LBB0_4355:
	s_or_b64 exec, exec, s[6:7]
	v_mul_f32_e32 v18, v22, v18
	v_mul_f32_e32 v18, 0x41800000, v18
	v_med3_f32 v18, v18, s79, v198
	s_nop 1
	v_mov_b32_dpp v19, v18 quad_perm:[1,0,3,2] row_mask:0xf bank_mask:0xf
	s_waitcnt lgkmcnt(0)
	v_mov_b32_e32 v20, v1
	s_waitcnt lgkmcnt(0)
	v_cvt_pk_fp8_f32 v20, v18, v19
	v_and_b32_e32 v18, 0xffff, v20
	s_nop 1
	v_mov_b32_dpp v19, v18 quad_perm:[2,3,0,1] row_mask:0xf bank_mask:0xf
	s_and_saveexec_b64 s[6:7], vcc
	s_cbranch_execz .LBB0_4357
	s_waitcnt lgkmcnt(0)
	v_lshl_or_b32 v18, v19, 16, v18
	global_store_dword v[16:17], v18, off offset:96

; __device__ __forceinline__ int crow(int r, int hi) { return (r & 3) + 8 * (r >> 2) + 4 * hi; }
; template <int MODE>
; __device__ __forceinline__ void attn_block(const AttnArgs& a, const BlockRef& cur, const BlockRef& nxt, char* lds, Seam<MODE>& S, const int tid) {
;     ...
;     if (a.o8 != 0.f) {
;         unsigned char* Ob = (unsigned char*)a.O + (size_t)(orow_ + wid * QBLK) * ldo + hcol_; const float os = a.o8;
; #pragma unroll
;         for (int r = 0; r < 16; ++r) { const int orow = crow(r, hi);
; #pragma unroll
;             for (int d0 = 0; d0 < 4; ++d0) { const float v = __builtin_amdgcn_fmed3f(o[d0][r] * rli[r] * os, -448.f, 448.f);
;                 const float vn = __shfl_xor(v, 1);
;                 const int pk = __builtin_amdgcn_cvt_pk_fp8_f32(v, vn, 0, false) & 0xffff; const int pk2 = __shfl_xor(pk, 2);
;                 if ((r32 & 3) == 0) *(unsigned*)(Ob + (size_t)orow * ldo + d0 * 32 + r32) = (unsigned)pk | ((unsigned)pk2 << 16); } }
.LBB0_4363:
	s_or_b64 exec, exec, s[6:7]
	v_mul_f32_e32 v18, v23, v18
	v_mul_f32_e32 v18, 0x41800000, v18
	v_med3_f32 v18, v18, s79, v198
	s_nop 1
	v_mov_b32_dpp v19, v18 quad_perm:[1,0,3,2] row_mask:0xf bank_mask:0xf
	s_waitcnt lgkmcnt(0)
	v_mov_b32_e32 v20, v1
	s_waitcnt lgkmcnt(0)
	v_cvt_pk_fp8_f32 v20, v18, v19
	v_and_b32_e32 v18, 0xffff, v20
	s_nop 1
	v_mov_b32_dpp v19, v18 quad_perm:[2,3,0,1] row_mask:0xf bank_mask:0xf
	s_and_saveexec_b64 s[6:7], vcc
	s_cbranch_execz .LBB0_4365
	s_waitcnt lgkmcnt(0)
	v_lshl_or_b32 v18, v19, 16, v18
	global_store_dword v[16:17], v18, off offset:96

; __device__ __forceinline__ int crow(int r, int hi) { return (r & 3) + 8 * (r >> 2) + 4 * hi; }
; template <int MODE>
; __device__ __forceinline__ void attn_block(const AttnArgs& a, const BlockRef& cur, const BlockRef& nxt, char* lds, Seam<MODE>& S, const int tid) {
;     ...
;     if (a.o8 != 0.f) {
;         unsigned char* Ob = (unsigned char*)a.O + (size_t)(orow_ + wid * QBLK) * ldo + hcol_; const float os = a.o8;
; #pragma unroll
;         for (int r = 0; r < 16; ++r) { const int orow = crow(r, hi);
; #pragma unroll
;             for (int d0 = 0; d0 < 4; ++d0) { const float v = __builtin_amdgcn_fmed3f(o[d0][r] * rli[r] * os, -448.f, 448.f);
;                 const float vn = __shfl_xor(v, 1);
;                 const int pk = __builtin_amdgcn_cvt_pk_fp8_f32(v, vn, 0, false) & 0xffff; const int pk2 = __shfl_xor(pk, 2);
;                 if ((r32 & 3) == 0) *(unsigned*)(Ob + (size_t)orow * ldo + d0 * 32 + r32) = (unsigned)pk | ((unsigned)pk2 << 16); } }
.LBB0_4371:
	s_or_b64 exec, exec, s[6:7]
	v_mul_f32_e32 v18, v24, v18
	v_mul_f32_e32 v18, 0x41800000, v18
	v_med3_f32 v18, v18, s79, v198
	s_nop 1
	v_mov_b32_dpp v19, v18 quad_perm:[1,0,3,2] row_mask:0xf bank_mask:0xf
	s_waitcnt lgkmcnt(0)
	v_mov_b32_e32 v20, v1
	s_waitcnt lgkmcnt(0)
	v_cvt_pk_fp8_f32 v20, v18, v19
	v_and_b32_e32 v18, 0xffff, v20
	s_nop 1
	v_mov_b32_dpp v19, v18 quad_perm:[2,3,0,1] row_mask:0xf bank_mask:0xf
	s_and_saveexec_b64 s[6:7], vcc
	s_cbranch_execz .LBB0_4373
	s_waitcnt lgkmcnt(0)
	v_lshl_or_b32 v18, v19, 16, v18
	global_store_dword v[16:17], v18, off offset:96

; __device__ __forceinline__ int crow(int r, int hi) { return (r & 3) + 8 * (r >> 2) + 4 * hi; }
; template <int MODE>
; __device__ __forceinline__ void attn_block(const AttnArgs& a, const BlockRef& cur, const BlockRef& nxt, char* lds, Seam<MODE>& S, const int tid) {
;     ...
;     if (a.o8 != 0.f) {
;         unsigned char* Ob = (unsigned char*)a.O + (size_t)(orow_ + wid * QBLK) * ldo + hcol_; const float os = a.o8;
; #pragma unroll
;         for (int r = 0; r < 16; ++r) { const int orow = crow(r, hi);
; #pragma unroll
;             for (int d0 = 0; d0 < 4; ++d0) { const float v = __builtin_amdgcn_fmed3f(o[d0][r] * rli[r] * os, -448.f, 448.f);
;                 const float vn = __shfl_xor(v, 1);
;                 const int pk = __builtin_amdgcn_cvt_pk_fp8_f32(v, vn, 0, false) & 0xffff; const int pk2 = __shfl_xor(pk, 2);
;                 if ((r32 & 3) == 0) *(unsigned*)(Ob + (size_t)orow * ldo + d0 * 32 + r32) = (unsigned)pk | ((unsigned)pk2 << 16); } }
.LBB0_4379:
	s_or_b64 exec, exec, s[6:7]
	v_mul_f32_e32 v18, v25, v18
	v_mul_f32_e32 v18, 0x41800000, v18
	v_med3_f32 v18, v18, s79, v198
	s_nop 1
	v_mov_b32_dpp v19, v18 quad_perm:[1,0,3,2] row_mask:0xf bank_mask:0xf
	s_waitcnt lgkmcnt(0)
	v_mov_b32_e32 v20, v1
	s_waitcnt lgkmcnt(0)
	v_cvt_pk_fp8_f32 v20, v18, v19
	v_and_b32_e32 v18, 0xffff, v20
	s_nop 1
	v_mov_b32_dpp v19, v18 quad_perm:[2,3,0,1] row_mask:0xf bank_mask:0xf
	s_and_saveexec_b64 s[6:7], vcc
	s_cbranch_execz .LBB0_4381
	s_waitcnt lgkmcnt(0)
	v_lshl_or_b32 v18, v19, 16, v18
	global_store_dword v[16:17], v18, off offset:96

; __device__ __forceinline__ int crow(int r, int hi) { return (r & 3) + 8 * (r >> 2) + 4 * hi; }
; template <int MODE>
; __device__ __forceinline__ void attn_block(const AttnArgs& a, const BlockRef& cur, const BlockRef& nxt, char* lds, Seam<MODE>& S, const int tid) {
;     ...
;     if (a.o8 != 0.f) {
;         unsigned char* Ob = (unsigned char*)a.O + (size_t)(orow_ + wid * QBLK) * ldo + hcol_; const float os = a.o8;
; #pragma unroll
;         for (int r = 0; r < 16; ++r) { const int orow = crow(r, hi);
; #pragma unroll
;             for (int d0 = 0; d0 < 4; ++d0) { const float v = __builtin_amdgcn_fmed3f(o[d0][r] * rli[r] * os, -448.f, 448.f);
;                 const float vn = __shfl_xor(v, 1);
;                 const int pk = __builtin_amdgcn_cvt_pk_fp8_f32(v, vn, 0, false) & 0xffff; const int pk2 = __shfl_xor(pk, 2);
;                 if ((r32 & 3) == 0) *(unsigned*)(Ob + (size_t)orow * ldo + d0 * 32 + r32) = (unsigned)pk | ((unsigned)pk2 << 16); } }
.LBB0_4387:
	s_or_b64 exec, exec, s[6:7]
	v_mul_f32_e32 v18, v26, v18
	v_mul_f32_e32 v18, 0x41800000, v18
	v_med3_f32 v18, v18, s79, v198
	s_nop 1
	v_mov_b32_dpp v19, v18 quad_perm:[1,0,3,2] row_mask:0xf bank_mask:0xf
	s_waitcnt lgkmcnt(0)
	v_mov_b32_e32 v20, v1
	s_waitcnt lgkmcnt(0)
	v_cvt_pk_fp8_f32 v20, v18, v19
	v_and_b32_e32 v18, 0xffff, v20
	s_nop 1
	v_mov_b32_dpp v19, v18 quad_perm:[2,3,0,1] row_mask:0xf bank_mask:0xf
	s_and_saveexec_b64 s[6:7], vcc
	s_cbranch_execz .LBB0_4389
	s_waitcnt lgkmcnt(0)
	v_lshl_or_b32 v18, v19, 16, v18
	global_store_dword v[16:17], v18, off offset:96

; __device__ __forceinline__ int crow(int r, int hi) { return (r & 3) + 8 * (r >> 2) + 4 * hi; }
; template <int MODE>
; __device__ __forceinline__ void attn_block(const AttnArgs& a, const BlockRef& cur, const BlockRef& nxt, char* lds, Seam<MODE>& S, const int tid) {
;     ...
;     if (a.o8 != 0.f) {
;         unsigned char* Ob = (unsigned char*)a.O + (size_t)(orow_ + wid * QBLK) * ldo + hcol_; const float os = a.o8;
; #pragma unroll
;         for (int r = 0; r < 16; ++r) { const int orow = crow(r, hi);
; #pragma unroll
;             for (int d0 = 0; d0 < 4; ++d0) { const float v = __builtin_amdgcn_fmed3f(o[d0][r] * rli[r] * os, -448.f, 448.f);
;                 const float vn = __shfl_xor(v, 1);
;                 const int pk = __builtin_amdgcn_cvt_pk_fp8_f32(v, vn, 0, false) & 0xffff; const int pk2 = __shfl_xor(pk, 2);
;                 if ((r32 & 3) == 0) *(unsigned*)(Ob + (size_t)orow * ldo + d0 * 32 + r32) = (unsigned)pk | ((unsigned)pk2 << 16); } }
.LBB0_4395:
	s_or_b64 exec, exec, s[6:7]
	v_mul_f32_e32 v18, v27, v18
	v_mul_f32_e32 v18, 0x41800000, v18
	v_med3_f32 v18, v18, s79, v198
	s_nop 1
	v_mov_b32_dpp v19, v18 quad_perm:[1,0,3,2] row_mask:0xf bank_mask:0xf
	s_waitcnt lgkmcnt(0)
	v_mov_b32_e32 v20, v1
	s_waitcnt lgkmcnt(0)
	v_cvt_pk_fp8_f32 v20, v18, v19
	v_and_b32_e32 v18, 0xffff, v20
	s_nop 1
	v_mov_b32_dpp v19, v18 quad_perm:[2,3,0,1] row_mask:0xf bank_mask:0xf
	s_and_saveexec_b64 s[6:7], vcc
	s_cbranch_execz .LBB0_4397
	s_waitcnt lgkmcnt(0)
	v_lshl_or_b32 v18, v19, 16, v18
	global_store_dword v[16:17], v18, off offset:96

; __device__ __forceinline__ int crow(int r, int hi) { return (r & 3) + 8 * (r >> 2) + 4 * hi; }
; template <int MODE>
; __device__ __forceinline__ void attn_block(const AttnArgs& a, const BlockRef& cur, const BlockRef& nxt, char* lds, Seam<MODE>& S, const int tid) {
;     ...
;     if (a.o8 != 0.f) {
;         unsigned char* Ob = (unsigned char*)a.O + (size_t)(orow_ + wid * QBLK) * ldo + hcol_; const float os = a.o8;
; #pragma unroll
;         for (int r = 0; r < 16; ++r) { const int orow = crow(r, hi);
; #pragma unroll
;             for (int d0 = 0; d0 < 4; ++d0) { const float v = __builtin_amdgcn_fmed3f(o[d0][r] * rli[r] * os, -448.f, 448.f);
;                 const float vn = __shfl_xor(v, 1);
;                 const int pk = __builtin_amdgcn_cvt_pk_fp8_f32(v, vn, 0, false) & 0xffff; const int pk2 = __shfl_xor(pk, 2);
;                 if ((r32 & 3) == 0) *(unsigned*)(Ob + (size_t)orow * ldo + d0 * 32 + r32) = (unsigned)pk | ((unsigned)pk2 << 16); } }
.LBB0_4403:
	s_or_b64 exec, exec, s[6:7]
	v_mul_f32_e32 v18, v28, v18
	v_mul_f32_e32 v18, 0x41800000, v18
	v_med3_f32 v18, v18, s79, v198
	s_nop 1
	v_mov_b32_dpp v19, v18 quad_perm:[1,0,3,2] row_mask:0xf bank_mask:0xf
	s_waitcnt lgkmcnt(0)
	v_mov_b32_e32 v20, v1
	s_waitcnt lgkmcnt(0)
	v_cvt_pk_fp8_f32 v20, v18, v19
	v_and_b32_e32 v18, 0xffff, v20
	s_nop 1
	v_mov_b32_dpp v19, v18 quad_perm:[2,3,0,1] row_mask:0xf bank_mask:0xf
	s_and_saveexec_b64 s[6:7], vcc
	s_cbranch_execz .LBB0_4405
	s_waitcnt lgkmcnt(0)
	v_lshl_or_b32 v18, v19, 16, v18
	global_store_dword v[16:17], v18, off offset:96

; __device__ __forceinline__ int crow(int r, int hi) { return (r & 3) + 8 * (r >> 2) + 4 * hi; }
; template <int MODE>
; __device__ __forceinline__ void attn_block(const AttnArgs& a, const BlockRef& cur, const BlockRef& nxt, char* lds, Seam<MODE>& S, const int tid) {
;     ...
;     if (a.o8 != 0.f) {
;         unsigned char* Ob = (unsigned char*)a.O + (size_t)(orow_ + wid * QBLK) * ldo + hcol_; const float os = a.o8;
; #pragma unroll
;         for (int r = 0; r < 16; ++r) { const int orow = crow(r, hi);
; #pragma unroll
;             for (int d0 = 0; d0 < 4; ++d0) { const float v = __builtin_amdgcn_fmed3f(o[d0][r] * rli[r] * os, -448.f, 448.f);
;                 const float vn = __shfl_xor(v, 1);
;                 const int pk = __builtin_amdgcn_cvt_pk_fp8_f32(v, vn, 0, false) & 0xffff; const int pk2 = __shfl_xor(pk, 2);
;                 if ((r32 & 3) == 0) *(unsigned*)(Ob + (size_t)orow * ldo + d0 * 32 + r32) = (unsigned)pk | ((unsigned)pk2 << 16); } }
.LBB0_4411:
	s_or_b64 exec, exec, s[6:7]
	v_mul_f32_e32 v18, v29, v18
	v_mul_f32_e32 v18, 0x41800000, v18
	v_med3_f32 v18, v18, s79, v198
	s_nop 1
	v_mov_b32_dpp v19, v18 quad_perm:[1,0,3,2] row_mask:0xf bank_mask:0xf
	s_waitcnt lgkmcnt(0)
	v_mov_b32_e32 v20, v1
	s_waitcnt lgkmcnt(0)
	v_cvt_pk_fp8_f32 v20, v18, v19
	v_and_b32_e32 v18, 0xffff, v20
	s_nop 1
	v_mov_b32_dpp v19, v18 quad_perm:[2,3,0,1] row_mask:0xf bank_mask:0xf
	s_and_saveexec_b64 s[6:7], vcc
	s_cbranch_execz .LBB0_4413
	s_waitcnt lgkmcnt(0)
	v_lshl_or_b32 v18, v19, 16, v18
	global_store_dword v[16:17], v18, off offset:96

; __device__ __forceinline__ int crow(int r, int hi) { return (r & 3) + 8 * (r >> 2) + 4 * hi; }
; template <int MODE>
; __device__ __forceinline__ void attn_block(const AttnArgs& a, const BlockRef& cur, const BlockRef& nxt, char* lds, Seam<MODE>& S, const int tid) {
;     ...
;     if (a.o8 != 0.f) {
;         unsigned char* Ob = (unsigned char*)a.O + (size_t)(orow_ + wid * QBLK) * ldo + hcol_; const float os = a.o8;
; #pragma unroll
;         for (int r = 0; r < 16; ++r) { const int orow = crow(r, hi);
; #pragma unroll
;             for (int d0 = 0; d0 < 4; ++d0) { const float v = __builtin_amdgcn_fmed3f(o[d0][r] * rli[r] * os, -448.f, 448.f);
;                 const float vn = __shfl_xor(v, 1);
;                 const int pk = __builtin_amdgcn_cvt_pk_fp8_f32(v, vn, 0, false) & 0xffff; const int pk2 = __shfl_xor(pk, 2);
;                 if ((r32 & 3) == 0) *(unsigned*)(Ob + (size_t)orow * ldo + d0 * 32 + r32) = (unsigned)pk | ((unsigned)pk2 << 16); } }
.LBB0_4419:
	s_or_b64 exec, exec, s[6:7]
	v_mul_f32_e32 v18, v30, v18
	v_mul_f32_e32 v18, 0x41800000, v18
	v_med3_f32 v18, v18, s79, v198
	s_nop 1
	v_mov_b32_dpp v19, v18 quad_perm:[1,0,3,2] row_mask:0xf bank_mask:0xf
	s_waitcnt lgkmcnt(0)
	v_mov_b32_e32 v20, v1
	s_waitcnt lgkmcnt(0)
	v_cvt_pk_fp8_f32 v20, v18, v19
	v_and_b32_e32 v18, 0xffff, v20
	s_nop 1
	v_mov_b32_dpp v19, v18 quad_perm:[2,3,0,1] row_mask:0xf bank_mask:0xf
	s_and_saveexec_b64 s[6:7], vcc
	s_cbranch_execz .LBB0_4421
	s_waitcnt lgkmcnt(0)
	v_lshl_or_b32 v18, v19, 16, v18
	global_store_dword v[16:17], v18, off offset:96

; __device__ __forceinline__ f32x4 bf4x(const u32x2 a) { return (f32x4){__uint_as_float(a.x << 16), __uint_as_float(a.x & 0xffff0000u), __uint_as_float(a.y << 16), __uint_as_float(a.y & 0xffff0000u)}; }
; __device__ __forceinline__ void ln_norm2(f32x4 (&v)[8], const float* g, const float* b, int lane, float& mean_o, float& rstd_o) {
;     float s = 0.f;
; #pragma unroll
;     for (int j = 0; j < 8; ++j) s += (v[j][0] + v[j][1]) + (v[j][2] + v[j][3]);
;     const float mean = wave_sum(s) * (1.f / DM); float s2 = 0.f;
; #pragma unroll
;     for (int j = 0; j < 8; ++j) { v[j] = v[j] - mean; s2 += (v[j][0] * v[j][0] + v[j][1] * v[j][1]) + (v[j][2] * v[j][2] + v[j][3] * v[j][3]); }
;     const float rstd = 1.f / sqrtf(wave_sum(s2) * (1.f / DM) + LN_EPS);
; __device__ __forceinline__ void ln3_router_phase(const Params& P, LAS unsigned char* lds, const int tid) {
;     ...
;         for (int i = 0; i < 8; ++i) { const int m = c * 64 + wave * 8 + i; asm volatile("" ::: "memory");
;             const u32x2* yr = (const u32x2*)(Y + (size_t)m * DM) + lane; f32x4 v[8];
; #pragma unroll
;             for (int j = 0; j < 8; ++j) v[j] = bf4x(yr[64 * j]);
;             float mu3, rs3; ln_norm2(v, P.in[19], P.in[20], lane, mu3, rs3); ln_store(v, nullptr, H3B, (size_t)m, lane, -ASC_XI8);
.LBB0_4582:
	v_add_u32_e32 v68, s49, v85
	v_ashrrev_i32_e32 v69, 31, v68
	v_lshlrev_b64 v[36:37], 12, v[68:69]
	v_lshl_add_u64 v[36:37], v[10:11], 0, v[36:37]
	global_load_dwordx2 v[38:39], v[36:37], off offset:1536
	global_load_dwordx2 v[40:41], v[36:37], off offset:2048
	global_load_dwordx2 v[44:45], v[36:37], off offset:3072
	global_load_dwordx2 v[52:53], v[36:37], off offset:3584
	global_load_dwordx2 v[56:57], v[36:37], off
	global_load_dwordx2 v[62:63], v[36:37], off offset:512
	global_load_dwordx2 v[64:65], v[36:37], off offset:1024
	global_load_dwordx2 v[66:67], v[36:37], off offset:2560
	v_cmp_lt_i32_e32 vcc, v88, v87
	v_lshlrev_b64 v[68:69], 11, v[68:69]
	v_lshl_add_u64 v[68:69], v[12:13], 0, v[68:69]
	v_cndmask_b32_e32 v35, v86, v88, vcc
	v_lshlrev_b32_e32 v100, 2, v35
	v_cmp_lt_i32_e32 vcc, v89, v87
	s_waitcnt vmcnt(7)
	v_lshlrev_b32_e32 v48, 16, v38
	s_waitcnt vmcnt(6)
	v_lshlrev_b32_e32 v46, 16, v40
	v_and_b32_e32 v76, 0xffff0000, v40
	s_waitcnt vmcnt(5)
	v_lshlrev_b32_e32 v36, 16, v44
	s_waitcnt vmcnt(3)
	v_lshlrev_b32_e32 v59, 16, v56
	s_waitcnt vmcnt(2)
	v_lshlrev_b32_e32 v58, 16, v62
	v_and_b32_e32 v61, 0xffff0000, v56
	v_and_b32_e32 v60, 0xffff0000, v62
	v_lshlrev_b32_e32 v55, 16, v57
	v_lshlrev_b32_e32 v54, 16, v63
	v_and_b32_e32 v57, 0xffff0000, v57
	v_and_b32_e32 v56, 0xffff0000, v63
	v_and_b32_e32 v37, 0xffff0000, v44
	v_lshlrev_b32_e32 v44, 16, v52
	v_and_b32_e32 v72, 0xffff0000, v52
	v_lshlrev_b32_e32 v40, 16, v53
	v_and_b32_e32 v70, 0xffff0000, v53
	s_waitcnt vmcnt(1)
	v_lshlrev_b32_e32 v53, 16, v65
	v_lshlrev_b32_e32 v52, 16, v64
	v_and_b32_e32 v63, 0xffff0000, v65
	v_and_b32_e32 v62, 0xffff0000, v64
	s_waitcnt vmcnt(0)
	v_lshlrev_b32_e32 v79, 16, v67
	v_lshlrev_b32_e32 v78, 16, v66
	v_and_b32_e32 v65, 0xffff0000, v67
	v_and_b32_e32 v64, 0xffff0000, v66
	v_pk_add_f32 v[66:67], v[58:59], v[60:61]
	v_pk_add_f32 v[80:81], v[54:55], v[56:57]
	v_pk_add_f32 v[102:103], v[52:53], v[62:63]
	v_pk_add_f32 v[66:67], v[66:67], v[80:81]
	v_and_b32_e32 v49, 0xffff0000, v38
	v_lshlrev_b32_e32 v50, 16, v39
	v_and_b32_e32 v51, 0xffff0000, v39
	v_pk_add_f32 v[80:81], v[102:103], v[102:103] op_sel_hi:[0,1]
	v_add_f32_e32 v35, 0, v67
	v_lshlrev_b32_e32 v42, 16, v41
	v_and_b32_e32 v74, 0xffff0000, v41
	v_add_f32_e32 v47, v48, v49
	v_add_f32_e32 v77, v50, v51
	v_mov_b32_e32 v43, v81
	v_add_f32_e32 v75, v66, v35
	v_pk_add_f32 v[102:103], v[46:47], v[76:77]
	v_pk_add_f32 v[66:67], v[42:43], v[74:75]
	v_pk_add_f32 v[104:105], v[78:79], v[64:65]
	v_pk_add_f32 v[66:67], v[102:103], v[66:67]
	v_lshlrev_b32_e32 v38, 16, v45
	v_and_b32_e32 v39, 0xffff0000, v45
	v_pk_add_f32 v[104:105], v[104:105], v[104:105] op_sel_hi:[0,1]
	v_pk_add_f32 v[66:67], v[66:67], v[66:67] op_sel_hi:[0,1]
	v_add_f32_e32 v45, v36, v37
	v_add_f32_e32 v73, v38, v39
	v_mov_b32_e32 v41, v105
	v_mov_b32_e32 v71, v67
	v_pk_add_f32 v[106:107], v[44:45], v[72:73]
	v_pk_add_f32 v[66:67], v[40:41], v[70:71]
	v_cndmask_b32_e32 v43, v86, v89, vcc
	v_pk_add_f32 v[66:67], v[106:107], v[66:67]
	v_lshlrev_b32_e32 v71, 2, v43
	v_add_f32_e32 v35, v66, v67
	s_nop 1
	v_mov_b32_dpp v41, v35 quad_perm:[1,0,3,2] row_mask:0xf bank_mask:0xf
	v_cmp_lt_i32_e32 vcc, v90, v87
	s_waitcnt lgkmcnt(0)
	v_add_f32_e32 v35, v35, v41
	s_nop 1
	v_mov_b32_dpp v41, v35 quad_perm:[2,3,0,1] row_mask:0xf bank_mask:0xf
	v_cndmask_b32_e32 v43, v86, v90, vcc
	v_lshlrev_b32_e32 v73, 2, v43
	v_cmp_lt_i32_e32 vcc, v91, v87
	s_waitcnt lgkmcnt(0)
	v_add_f32_e32 v35, v35, v41
	s_nop 1
	v_mov_b32_dpp v41, v35 row_half_mirror row_mask:0xf bank_mask:0xf
	v_cndmask_b32_e32 v43, v86, v91, vcc
	v_lshlrev_b32_e32 v75, 2, v43
	v_cmp_lt_i32_e32 vcc, v92, v87
	s_waitcnt lgkmcnt(0)
	v_add_f32_e32 v35, v35, v41
	s_nop 1
	v_mov_b32_dpp v41, v35 row_mirror row_mask:0xf bank_mask:0xf
	v_cndmask_b32_e32 v43, v86, v92, vcc
	v_lshlrev_b32_e32 v77, 2, v43
	v_cmp_lt_i32_e32 vcc, v93, v87
	s_waitcnt lgkmcnt(0)
	v_add_f32_e32 v35, v35, v41
	ds_bpermute_b32 v41, v77, v35
	v_cndmask_b32_e32 v43, v86, v93, vcc
	v_lshlrev_b32_e32 v101, 2, v43
	s_waitcnt lgkmcnt(0)
	v_add_f32_e32 v35, v35, v41
	ds_bpermute_b32 v41, v101, v35
	s_waitcnt lgkmcnt(0)
	v_add_f32_e32 v102, v35, v41
	v_fmac_f32_e32 v57, 0xba000000, v102
	v_fmac_f32_e32 v61, 0xba000000, v102
	v_fmac_f32_e32 v56, 0xba000000, v102
	v_fmac_f32_e32 v60, 0xba000000, v102
	v_fmac_f32_e32 v55, 0xba000000, v102
	v_fmac_f32_e32 v59, 0xba000000, v102
	v_fmac_f32_e32 v54, 0xba000000, v102
	v_fmac_f32_e32 v58, 0xba000000, v102
	v_fmac_f32_e32 v62, 0xba000000, v102
	v_fmac_f32_e32 v63, 0xba000000, v102
	v_fmac_f32_e32 v53, 0xba000000, v102
	v_mov_b32_e32 v104, v61
	v_mov_b32_e32 v105, v60
	v_mov_b32_e32 v108, v57
	v_mov_b32_e32 v109, v56
	v_mov_b32_e32 v66, v59
	v_mov_b32_e32 v67, v58
	v_mov_b32_e32 v106, v55
	v_mov_b32_e32 v107, v54
	v_mov_b32_e32 v80, v53
	v_mov_b32_e32 v81, v63
	v_mov_b32_e32 v53, v62
	v_pk_mul_f32 v[62:63], v[104:105], v[104:105]
	v_pk_mul_f32 v[104:105], v[108:109], v[108:109]
	v_pk_fma_f32 v[62:63], v[66:67], v[66:67], v[62:63]
	v_pk_fma_f32 v[66:67], v[106:107], v[106:107], v[104:105]
	v_fmac_f32_e32 v52, 0xba000000, v102
	v_pk_add_f32 v[62:63], v[62:63], v[66:67]
	v_fmac_f32_e32 v48, 0xba000000, v102
	v_pk_mul_f32 v[108:109], v[80:81], v[80:81]
	v_pk_mul_f32 v[110:111], v[52:53], v[52:53]
	v_pk_add_f32 v[62:63], v[62:63], v[62:63] op_sel_hi:[0,1]
	v_fmac_f32_e32 v49, 0xba000000, v102
	v_fmac_f32_e32 v50, 0xba000000, v102
	v_pk_mov_b32 v[104:105], v[110:111], v[108:109] op_sel:[1,0]
	v_mov_b32_e32 v111, v109
	v_mul_f32_e32 v62, v48, v48
	v_fmac_f32_e32 v51, 0xba000000, v102
	v_pk_add_f32 v[66:67], v[104:105], v[110:111]
	v_pk_fma_f32 v[104:105], v[48:49], v[48:49], v[62:63] op_sel_hi:[1,1,0]
; __device__ __forceinline__ float wave_sum(float v) {
; #pragma unroll
;     for (int o = 1; o < 64; o <<= 1) v += __shfl_xor(v, o);
;     return v;
; __device__ __forceinline__ void ln_norm2(f32x4 (&v)[8], const float* g, const float* b, int lane, float& mean_o, float& rstd_o) {
;     ...
;     const float mean = wave_sum(s) * (1.f / DM); float s2 = 0.f;
; #pragma unroll
;     for (int j = 0; j < 8; ++j) { v[j] = v[j] - mean; s2 += (v[j][0] * v[j][0] + v[j][1] * v[j][1]) + (v[j][2] * v[j][2] + v[j][3] * v[j][3]); }
;     const float rstd = 1.f / sqrtf(wave_sum(s2) * (1.f / DM) + LN_EPS);
; #pragma unroll
;     for (int j = 0; j < 8; ++j) { const f32x4 gv = *((const f32x4*)g + lane + 64 * j), bv = *((const f32x4*)b + lane + 64 * j); v[j] = v[j] * rstd * gv + bv; }
	v_mul_f32_e32 v62, v50, v50
	v_pk_add_f32 v[66:67], v[66:67], v[66:67] op_sel_hi:[0,1]
	v_pk_fma_f32 v[106:107], v[50:51], v[50:51], v[62:63] op_sel_hi:[1,1,0]
	v_fmac_f32_e32 v74, 0xba000000, v102
	v_fmac_f32_e32 v42, 0xba000000, v102
	v_fmac_f32_e32 v76, 0xba000000, v102
	v_fmac_f32_e32 v46, 0xba000000, v102
	v_mul_f32_e32 v104, v46, v46
	v_mul_f32_e32 v106, v76, v76
	v_mul_f32_e32 v66, v42, v42
	v_mul_f32_e32 v62, v74, v74
	v_pk_add_f32 v[104:105], v[104:105], v[106:107]
	v_pk_add_f32 v[62:63], v[66:67], v[62:63]
	v_fmac_f32_e32 v64, 0xba000000, v102
	v_fmac_f32_e32 v65, 0xba000000, v102
	v_fmac_f32_e32 v79, 0xba000000, v102
	v_pk_add_f32 v[62:63], v[104:105], v[62:63]
	v_fmac_f32_e32 v78, 0xba000000, v102
	v_mov_b32_e32 v164, v79
	v_mov_b32_e32 v165, v65
	v_mov_b32_e32 v79, v64
	v_pk_add_f32 v[62:63], v[62:63], v[62:63] op_sel_hi:[0,1]
	v_pk_mul_f32 v[66:67], v[164:165], v[164:165]
	v_pk_mul_f32 v[64:65], v[78:79], v[78:79]
	v_fmac_f32_e32 v36, 0xba000000, v102
	v_pk_mov_b32 v[104:105], v[64:65], v[66:67] op_sel:[1,0]
	v_mov_b32_e32 v65, v67
	v_fmac_f32_e32 v37, 0xba000000, v102
	v_fmac_f32_e32 v38, 0xba000000, v102
	v_mul_f32_e32 v62, v36, v36
	v_pk_add_f32 v[64:65], v[104:105], v[64:65]
	v_fmac_f32_e32 v39, 0xba000000, v102
	v_pk_fma_f32 v[66:67], v[36:37], v[36:37], v[62:63] op_sel_hi:[1,1,0]
	v_mul_f32_e32 v62, v38, v38
	v_pk_add_f32 v[64:65], v[64:65], v[64:65] op_sel_hi:[0,1]
	v_pk_fma_f32 v[104:105], v[38:39], v[38:39], v[62:63] op_sel_hi:[1,1,0]
	v_fmac_f32_e32 v70, 0xba000000, v102
	v_fmac_f32_e32 v40, 0xba000000, v102
	v_fmac_f32_e32 v72, 0xba000000, v102
	v_fmac_f32_e32 v44, 0xba000000, v102
	v_mul_f32_e32 v66, v44, v44
	v_mul_f32_e32 v104, v72, v72
	v_mul_f32_e32 v64, v40, v40
	v_mul_f32_e32 v62, v70, v70
	v_pk_add_f32 v[66:67], v[66:67], v[104:105]
	v_pk_add_f32 v[62:63], v[64:65], v[62:63]
	v_mov_b32_e32 v166, v58
	v_pk_add_f32 v[62:63], v[66:67], v[62:63]
	v_mov_b32_e32 v58, v54
	v_add_f32_e32 v35, v62, v63
	global_load_dwordx4 v[62:65], v[14:15], off
	global_load_dwordx4 v[104:107], v[16:17], off
	global_load_dwordx4 v[108:111], v[14:15], off offset:1024
	global_load_dwordx4 v[112:115], v[16:17], off offset:1024
	global_load_dwordx4 v[116:119], v[14:15], off offset:2048
	global_load_dwordx4 v[120:123], v[16:17], off offset:2048
	global_load_dwordx4 v[124:127], v[14:15], off offset:3072
	global_load_dwordx4 v[128:131], v[16:17], off offset:3072
	global_load_dwordx4 v[132:135], v[18:19], off
	global_load_dwordx4 v[136:139], v[20:21], off
	global_load_dwordx4 v[140:143], v[22:23], off
	global_load_dwordx4 v[144:147], v[24:25], off
	global_load_dwordx4 v[148:151], v[26:27], off
	global_load_dwordx4 v[152:155], v[28:29], off
	s_nop 1
	v_mov_b32_dpp v41, v35 quad_perm:[1,0,3,2] row_mask:0xf bank_mask:0xf
	global_load_dwordx4 v[156:159], v[30:31], off
	global_load_dwordx4 v[160:163], v[32:33], off
	v_mov_b32_e32 v167, v60
	v_mov_b32_e32 v60, v59
	v_mov_b32_e32 v59, v56
	s_waitcnt lgkmcnt(0)
	v_add_f32_e32 v35, v35, v41
	s_nop 1
	v_mov_b32_dpp v41, v35 quad_perm:[2,3,0,1] row_mask:0xf bank_mask:0xf
	v_mov_b32_e32 v56, v55
	s_waitcnt lgkmcnt(0)
	v_add_f32_e32 v35, v35, v41
	s_nop 1
	v_mov_b32_dpp v41, v35 row_half_mirror row_mask:0xf bank_mask:0xf
	s_waitcnt lgkmcnt(0)
	v_add_f32_e32 v35, v35, v41
	s_nop 1
	v_mov_b32_dpp v41, v35 row_mirror row_mask:0xf bank_mask:0xf
	s_waitcnt lgkmcnt(0)
	v_add_f32_e32 v35, v35, v41
	ds_bpermute_b32 v41, v77, v35
	s_waitcnt lgkmcnt(0)
	v_add_f32_e32 v35, v35, v41
	ds_bpermute_b32 v41, v101, v35
	s_waitcnt lgkmcnt(0)
	v_add_f32_e32 v35, v35, v41
	v_fmamk_f32 v35, v35, 0x3a000000, v94
	v_mul_f32_e32 v41, 0x4f800000, v35
	v_cmp_gt_f32_e32 vcc, s35, v35
	s_nop 1
	v_cndmask_b32_e32 v35, v35, v41, vcc
	v_sqrt_f32_e32 v41, v35
	s_nop 0
	v_add_u32_e32 v43, -1, v41
	v_fma_f32 v45, -v43, v41, v35
	v_cmp_ge_f32_e64 s[6:7], 0, v45
	v_add_u32_e32 v45, 1, v41
	s_nop 0
	v_cndmask_b32_e64 v43, v41, v43, s[6:7]
	v_fma_f32 v41, -v45, v41, v35
	v_cmp_lt_f32_e64 s[6:7], 0, v41
	s_nop 1
	v_cndmask_b32_e64 v41, v43, v45, s[6:7]
	v_mul_f32_e32 v43, 0x37800000, v41
	v_cndmask_b32_e32 v41, v41, v43, vcc
	v_cmp_class_f32_e32 vcc, v35, v95
	s_nop 1
	v_cndmask_b32_e32 v35, v41, v35, vcc
	v_div_scale_f32 v41, s[6:7], v35, v35, 1.0
	v_rcp_f32_e32 v43, v41
	s_nop 0
	v_fma_f32 v45, -v41, v43, 1.0
	v_fmac_f32_e32 v43, v45, v43
	v_div_scale_f32 v45, vcc, 1.0, v35, 1.0
	v_mul_f32_e32 v47, v45, v43
	v_fma_f32 v54, -v41, v47, v45
	v_fmac_f32_e32 v47, v54, v43
	v_fma_f32 v41, -v41, v47, v45
	v_div_fmas_f32 v41, v41, v43, v47
	v_div_fixup_f32 v82, v41, v35, 1.0
	v_mov_b32_e32 v47, v76
	v_pk_mul_f32 v[54:55], v[60:61], v[82:83] op_sel_hi:[1,0]
	v_pk_mul_f32 v[56:57], v[56:57], v[82:83] op_sel_hi:[1,0]
	v_pk_mul_f32 v[52:53], v[52:53], v[82:83] op_sel_hi:[1,0]
	v_pk_mul_f32 v[50:51], v[50:51], v[82:83] op_sel_hi:[1,0]
	v_pk_mul_f32 v[46:47], v[46:47], v[82:83] op_sel_hi:[1,0]
	s_waitcnt vmcnt(14)
	v_pk_fma_f32 v[64:65], v[64:65], v[56:57], v[106:107]
	v_pk_fma_f32 v[66:67], v[62:63], v[54:55], v[104:105]
	v_pk_mul_f32 v[54:55], v[166:167], v[82:83] op_sel_hi:[1,0]
	v_pk_mul_f32 v[56:57], v[58:59], v[82:83] op_sel_hi:[1,0]
	s_waitcnt vmcnt(10)
	v_pk_fma_f32 v[58:59], v[116:117], v[52:53], v[120:121]
	s_waitcnt vmcnt(8)
	v_pk_fma_f32 v[52:53], v[126:127], v[50:51], v[130:131]
	s_waitcnt vmcnt(6)
	v_pk_fma_f32 v[50:51], v[132:133], v[46:47], v[136:137]
	v_pk_mul_f32 v[46:47], v[78:79], v[82:83] op_sel_hi:[1,0]
	v_pk_mul_f32 v[78:79], v[36:37], v[82:83] op_sel_hi:[1,0]
	v_pk_fma_f32 v[62:63], v[108:109], v[54:55], v[112:113]
	v_pk_mul_f32 v[54:55], v[80:81], v[82:83] op_sel_hi:[1,0]
	v_pk_mul_f32 v[36:37], v[38:39], v[82:83] op_sel_hi:[1,0]
	s_waitcnt vmcnt(2)
; __device__ __forceinline__ float clamp448(float x) { return __builtin_amdgcn_fmed3f(x, -448.0f, 448.0f); }
; __device__ __forceinline__ void ln_norm2(f32x4 (&v)[8], const float* g, const float* b, int lane, float& mean_o, float& rstd_o) {
;     ...
;     for (int j = 0; j < 8; ++j) { const f32x4 gv = *((const f32x4*)g + lane + 64 * j), bv = *((const f32x4*)b + lane + 64 * j); v[j] = v[j] * rstd * gv + bv; }
;     mean_o = mean; rstd_o = rstd;
; }
; __device__ __forceinline__ void ln_norm(f32x4 (&v)[8], const float* g, const float* b, int lane) { float m_, r_; ln_norm2(v, g, b, lane, m_, r_); }
;     if (hf) { f32x4* o = (f32x4*)(hf + m * DM) + lane;
; #pragma unroll
;         for (int j = 0; j < 8; ++j) __builtin_nontemporal_store(v[j], o + 64 * j); }
;     if (hb && f8s != 0.f) { unsigned* o4 = (unsigned*)((unsigned char*)hb + m * DM) + lane;
; #pragma unroll
;         for (int j = 0; j < 8; ++j) { if (f8s < 0.f) { o4[64 * j] = pg8::pack4i8(v[j] * -f8s); continue; }
;             const f32x4 t = v[j] * f8s; int w = __builtin_amdgcn_cvt_pk_fp8_f32(pg8::clamp448(t[0]), pg8::clamp448(t[1]), 0, false); w = __builtin_amdgcn_cvt_pk_fp8_f32(pg8::clamp448(t[2]), pg8::clamp448(t[3]), w, true); o4[64 * j] = (unsigned)w; } }
; __device__ __forceinline__ void ln3_router_phase(const Params& P, LAS unsigned char* lds, const int tid) {
;     ...
;             float mu3, rs3; ln_norm2(v, P.in[19], P.in[20], lane, mu3, rs3); ln_store(v, nullptr, H3B, (size_t)m, lane, -ASC_XI8);
;             if (lane == 0) { st3[2 * m] = mu3; st3[2 * m + 1] = rs3; }
	v_pk_fma_f32 v[38:39], v[148:149], v[78:79], v[152:153]
	v_pk_mul_f32 v[78:79], v[64:65], s[38:39] op_sel_hi:[1,0]
	v_pk_mul_f32 v[80:81], v[66:67], s[38:39] op_sel_hi:[1,0]
	v_mov_b32_e32 v43, v74
	v_mov_b32_e32 v45, v72
	v_mov_b32_e32 v41, v70
	v_med3_f32 v35, v80, s39, v96
	v_med3_f32 v70, v81, s39, v96
	v_med3_f32 v72, v78, s39, v96
	v_med3_f32 v74, v79, s39, v96
	v_add_f32_e32 v35, 0x4b400000, v35
	v_add_f32_e32 v70, 0x4b400000, v70
	v_add_f32_e32 v72, 0x4b400000, v72
	v_add_f32_e32 v74, 0x4b400000, v74
	v_pk_fma_f32 v[60:61], v[110:111], v[56:57], v[114:115]
	v_perm_b32 v35, v70, v35, s42
	v_perm_b32 v70, v74, v72, s43
	v_or_b32_e32 v35, v35, v70
	v_pk_mul_f32 v[78:79], v[60:61], s[38:39] op_sel_hi:[1,0]
	v_pk_mul_f32 v[80:81], v[62:63], s[38:39] op_sel_hi:[1,0]
	global_store_dword v[68:69], v35, off
	v_med3_f32 v35, v80, s39, v96
	v_med3_f32 v70, v81, s39, v96
	v_med3_f32 v72, v78, s39, v96
	v_med3_f32 v74, v79, s39, v96
	v_add_f32_e32 v35, 0x4b400000, v35
	v_add_f32_e32 v70, 0x4b400000, v70
	v_add_f32_e32 v72, 0x4b400000, v72
	v_add_f32_e32 v74, 0x4b400000, v74
	v_pk_fma_f32 v[56:57], v[118:119], v[54:55], v[122:123]
	v_perm_b32 v35, v70, v35, s42
	v_perm_b32 v70, v74, v72, s43
	v_or_b32_e32 v35, v35, v70
	v_pk_mul_f32 v[78:79], v[56:57], s[38:39] op_sel_hi:[1,0]
	v_pk_mul_f32 v[80:81], v[58:59], s[38:39] op_sel_hi:[1,0]
	global_store_dword v[68:69], v35, off offset:256
	v_med3_f32 v35, v80, s39, v96
	v_med3_f32 v70, v81, s39, v96
	v_med3_f32 v72, v78, s39, v96
	v_med3_f32 v74, v79, s39, v96
	v_pk_mul_f32 v[48:49], v[48:49], v[82:83] op_sel_hi:[1,0]
	v_add_f32_e32 v35, 0x4b400000, v35
	v_add_f32_e32 v70, 0x4b400000, v70
	v_add_f32_e32 v72, 0x4b400000, v72
	v_add_f32_e32 v74, 0x4b400000, v74
	v_pk_fma_f32 v[54:55], v[124:125], v[48:49], v[128:129]
	v_perm_b32 v35, v70, v35, s42
	v_perm_b32 v70, v74, v72, s43
	v_or_b32_e32 v35, v35, v70
	v_pk_mul_f32 v[78:79], v[52:53], s[38:39] op_sel_hi:[1,0]
	v_pk_mul_f32 v[80:81], v[54:55], s[38:39] op_sel_hi:[1,0]
	global_store_dword v[68:69], v35, off offset:512
	v_med3_f32 v35, v80, s39, v96
	v_med3_f32 v70, v81, s39, v96
	v_med3_f32 v72, v78, s39, v96
	v_med3_f32 v74, v79, s39, v96
	v_pk_mul_f32 v[42:43], v[42:43], v[82:83] op_sel_hi:[1,0]
	v_add_f32_e32 v35, 0x4b400000, v35
	v_add_f32_e32 v70, 0x4b400000, v70
	v_add_f32_e32 v72, 0x4b400000, v72
	v_add_f32_e32 v74, 0x4b400000, v74
	v_pk_fma_f32 v[48:49], v[134:135], v[42:43], v[138:139]
	v_perm_b32 v35, v70, v35, s42
	v_perm_b32 v70, v74, v72, s43
	v_or_b32_e32 v35, v35, v70
	v_pk_mul_f32 v[78:79], v[48:49], s[38:39] op_sel_hi:[1,0]
	v_pk_mul_f32 v[80:81], v[50:51], s[38:39] op_sel_hi:[1,0]
	global_store_dword v[68:69], v35, off offset:768
	v_med3_f32 v35, v80, s39, v96
	v_med3_f32 v70, v81, s39, v96
	v_med3_f32 v72, v78, s39, v96
	v_med3_f32 v74, v79, s39, v96
	v_pk_mul_f32 v[42:43], v[164:165], v[82:83] op_sel_hi:[1,0]
	v_add_f32_e32 v35, 0x4b400000, v35
	v_add_f32_e32 v70, 0x4b400000, v70
	v_add_f32_e32 v72, 0x4b400000, v72
	v_add_f32_e32 v74, 0x4b400000, v74
	v_pk_fma_f32 v[42:43], v[142:143], v[42:43], v[146:147]
	v_pk_fma_f32 v[46:47], v[140:141], v[46:47], v[144:145]
	v_perm_b32 v35, v70, v35, s42
	v_perm_b32 v70, v74, v72, s43
	v_or_b32_e32 v35, v35, v70
	v_pk_mul_f32 v[78:79], v[42:43], s[38:39] op_sel_hi:[1,0]
	v_pk_mul_f32 v[80:81], v[46:47], s[38:39] op_sel_hi:[1,0]
	global_store_dword v[68:69], v35, off offset:1024
	v_med3_f32 v35, v80, s39, v96
	v_med3_f32 v70, v81, s39, v96
	v_med3_f32 v72, v78, s39, v96
	v_med3_f32 v74, v79, s39, v96
	v_add_f32_e32 v35, 0x4b400000, v35
	v_add_f32_e32 v70, 0x4b400000, v70
	v_add_f32_e32 v72, 0x4b400000, v72
	v_add_f32_e32 v74, 0x4b400000, v74
	v_pk_fma_f32 v[36:37], v[150:151], v[36:37], v[154:155]
	v_perm_b32 v35, v70, v35, s42
	v_perm_b32 v70, v74, v72, s43
	v_or_b32_e32 v35, v35, v70
	v_pk_mul_f32 v[78:79], v[36:37], s[38:39] op_sel_hi:[1,0]
	v_pk_mul_f32 v[80:81], v[38:39], s[38:39] op_sel_hi:[1,0]
	global_store_dword v[68:69], v35, off offset:1280
	v_med3_f32 v35, v80, s39, v96
	v_med3_f32 v70, v81, s39, v96
	v_med3_f32 v72, v78, s39, v96
	v_med3_f32 v74, v79, s39, v96
	v_pk_mul_f32 v[44:45], v[44:45], v[82:83] op_sel_hi:[1,0]
	v_pk_mul_f32 v[40:41], v[40:41], v[82:83] op_sel_hi:[1,0]
	v_add_f32_e32 v35, 0x4b400000, v35
	v_add_f32_e32 v70, 0x4b400000, v70
	v_add_f32_e32 v72, 0x4b400000, v72
	v_add_f32_e32 v74, 0x4b400000, v74
	s_waitcnt vmcnt(6)
	v_pk_fma_f32 v[40:41], v[158:159], v[40:41], v[162:163]
	v_pk_fma_f32 v[44:45], v[156:157], v[44:45], v[160:161]
	v_perm_b32 v35, v70, v35, s42
	v_perm_b32 v70, v74, v72, s43
	v_or_b32_e32 v35, v35, v70
	v_pk_mul_f32 v[78:79], v[40:41], s[38:39] op_sel_hi:[1,0]
	v_pk_mul_f32 v[80:81], v[44:45], s[38:39] op_sel_hi:[1,0]
	global_store_dword v[68:69], v35, off offset:1536
	v_med3_f32 v35, v80, s39, v96
	v_med3_f32 v70, v81, s39, v96
	v_med3_f32 v72, v78, s39, v96
	v_med3_f32 v74, v79, s39, v96
	v_add_f32_e32 v35, 0x4b400000, v35
	v_add_f32_e32 v70, 0x4b400000, v70
	v_add_f32_e32 v72, 0x4b400000, v72
	v_add_f32_e32 v74, 0x4b400000, v74
	v_perm_b32 v35, v70, v35, s42
	v_perm_b32 v70, v74, v72, s43
	v_or_b32_e32 v35, v35, v70
	global_store_dword v[68:69], v35, off offset:1792
	v_ashrrev_i32_e32 v35, 31, v34
	s_and_saveexec_b64 s[6:7], s[2:3]
	s_cbranch_execz .LBB0_4584
	v_mul_f32_e32 v68, 0x3a000000, v102
	v_lshl_add_u64 v[78:79], v[34:35], 2, s[28:29]
	v_mov_b32_e32 v69, v82
	global_store_dwordx2 v[78:79], v[68:69], off
; #define LAS __attribute__((address_space(3)))
; __device__ __forceinline__ void ln3_router_phase(const Params& P, LAS unsigned char* lds, const int tid) {
;     ...
;             float l[8];
; #pragma unroll
;             for (int e = 0; e < 8; ++e) { float s = 0.f;
; #pragma unroll
;                 for (int j = 0; j < 8; ++j) { const f32x4 w = *(const LAS f32x4*)(wr + e * 2048 + 256 * j + 4 * lane); s = fmaf(v[j][0], w[0], s); s = fmaf(v[j][1], w[1], s); s = fmaf(v[j][2], w[2], s); s = fmaf(v[j][3], w[3], s); }
;                 l[e] = wave_sum(s); }
.LBB0_4584:
	s_or_b64 exec, exec, s[6:7]
	ds_read_b128 v[78:81], v9
	ds_read_b128 v[102:105], v9 offset:1024
	ds_read_b128 v[106:109], v9 offset:2048
	ds_read_b128 v[110:113], v9 offset:3072
	ds_read_b128 v[114:117], v9 offset:8192
	ds_read_b128 v[118:121], v9 offset:4096
	ds_read_b128 v[122:125], v9 offset:5120
	ds_read_b128 v[126:129], v9 offset:6144
	ds_read_b128 v[130:133], v9 offset:7168
	ds_read_b128 v[134:137], v9 offset:9216
	s_waitcnt lgkmcnt(5)
	v_mov_b32_e32 v68, v114
	v_mov_b32_e32 v69, v78
	v_pk_fma_f32 v[68:69], v[66:67], v[68:69], 0 op_sel_hi:[0,1,0]
	v_mov_b32_e32 v78, v115
	v_pk_fma_f32 v[68:69], v[66:67], v[78:79], v[68:69] op_sel:[1,0,0]
	v_mov_b32_e32 v78, v116
	v_mov_b32_e32 v79, v80
	v_pk_fma_f32 v[68:69], v[64:65], v[78:79], v[68:69] op_sel_hi:[0,1,1]
	v_mov_b32_e32 v70, v65
	v_mov_b32_e32 v80, v117
	v_pk_fma_f32 v[68:69], v[70:71], v[80:81], v[68:69] op_sel_hi:[0,1,1]
	ds_read_b128 v[78:81], v9 offset:10240
	ds_read_b128 v[114:117], v9 offset:11264
	s_waitcnt lgkmcnt(2)
	v_mov_b32_e32 v138, v134
	v_mov_b32_e32 v139, v102
	v_pk_fma_f32 v[68:69], v[62:63], v[138:139], v[68:69] op_sel_hi:[0,1,1]
	v_mov_b32_e32 v102, v135
	v_pk_fma_f32 v[68:69], v[62:63], v[102:103], v[68:69] op_sel:[1,0,0]
	v_mov_b32_e32 v102, v136
	v_mov_b32_e32 v103, v104
	v_pk_fma_f32 v[68:69], v[60:61], v[102:103], v[68:69] op_sel_hi:[0,1,1]
	v_mov_b32_e32 v70, v61
	v_mov_b32_e32 v104, v137
	v_pk_fma_f32 v[68:69], v[70:71], v[104:105], v[68:69] op_sel_hi:[0,1,1]
	s_waitcnt lgkmcnt(1)
	v_mov_b32_e32 v102, v78
	v_mov_b32_e32 v103, v106
	v_pk_fma_f32 v[68:69], v[58:59], v[102:103], v[68:69] op_sel_hi:[0,1,1]
	v_mov_b32_e32 v106, v79
	v_pk_fma_f32 v[68:69], v[58:59], v[106:107], v[68:69] op_sel:[1,0,0]
	v_mov_b32_e32 v78, v80
	v_mov_b32_e32 v79, v108
	v_pk_fma_f32 v[68:69], v[56:57], v[78:79], v[68:69] op_sel_hi:[0,1,1]
	v_mov_b32_e32 v70, v57
	v_mov_b32_e32 v108, v81
	v_pk_fma_f32 v[68:69], v[70:71], v[108:109], v[68:69] op_sel_hi:[0,1,1]
	s_waitcnt lgkmcnt(0)
	v_mov_b32_e32 v78, v114
	v_mov_b32_e32 v79, v110
	v_pk_fma_f32 v[68:69], v[54:55], v[78:79], v[68:69] op_sel_hi:[0,1,1]
	v_mov_b32_e32 v110, v115
	v_pk_fma_f32 v[68:69], v[54:55], v[110:111], v[68:69] op_sel:[1,0,0]
	v_mov_b32_e32 v78, v116
	v_mov_b32_e32 v79, v112
	v_pk_fma_f32 v[68:69], v[52:53], v[78:79], v[68:69] op_sel_hi:[0,1,1]
	ds_read_b128 v[78:81], v9 offset:12288
	ds_read_b128 v[102:105], v9 offset:13312
	ds_read_b128 v[106:109], v9 offset:14336
	v_mov_b32_e32 v70, v53
	v_mov_b32_e32 v112, v117
	v_pk_fma_f32 v[68:69], v[70:71], v[112:113], v[68:69] op_sel_hi:[0,1,1]
	s_waitcnt lgkmcnt(2)
	v_mov_b32_e32 v110, v78
	v_mov_b32_e32 v111, v118
	v_pk_fma_f32 v[68:69], v[50:51], v[110:111], v[68:69] op_sel_hi:[0,1,1]
	v_mov_b32_e32 v118, v79
	v_pk_fma_f32 v[68:69], v[50:51], v[118:119], v[68:69] op_sel:[1,0,0]
	v_mov_b32_e32 v78, v80
	v_mov_b32_e32 v79, v120
	v_pk_fma_f32 v[68:69], v[48:49], v[78:79], v[68:69] op_sel_hi:[0,1,1]
	v_mov_b32_e32 v70, v49
	v_mov_b32_e32 v120, v81
	v_pk_fma_f32 v[68:69], v[70:71], v[120:121], v[68:69] op_sel_hi:[0,1,1]
	s_waitcnt lgkmcnt(1)
	v_mov_b32_e32 v78, v102
	v_mov_b32_e32 v79, v122
	v_pk_fma_f32 v[68:69], v[46:47], v[78:79], v[68:69] op_sel_hi:[0,1,1]
	v_mov_b32_e32 v122, v103
	v_pk_fma_f32 v[68:69], v[46:47], v[122:123], v[68:69] op_sel:[1,0,0]
	v_mov_b32_e32 v78, v104
	v_mov_b32_e32 v79, v124
	v_pk_fma_f32 v[68:69], v[42:43], v[78:79], v[68:69] op_sel_hi:[0,1,1]
	v_mov_b32_e32 v70, v43
	v_mov_b32_e32 v124, v105
	ds_read_b128 v[78:81], v9 offset:15360
	v_pk_fma_f32 v[68:69], v[70:71], v[124:125], v[68:69] op_sel_hi:[0,1,1]
	s_waitcnt lgkmcnt(1)
	v_mov_b32_e32 v102, v106
	v_mov_b32_e32 v103, v126
	v_pk_fma_f32 v[68:69], v[38:39], v[102:103], v[68:69] op_sel_hi:[0,1,1]
	v_mov_b32_e32 v126, v107
	v_pk_fma_f32 v[68:69], v[38:39], v[126:127], v[68:69] op_sel:[1,0,0]
	v_mov_b32_e32 v102, v108
	v_mov_b32_e32 v103, v128
	v_pk_fma_f32 v[68:69], v[36:37], v[102:103], v[68:69] op_sel_hi:[0,1,1]
	v_mov_b32_e32 v70, v37
	v_mov_b32_e32 v128, v109
	v_pk_fma_f32 v[68:69], v[70:71], v[128:129], v[68:69] op_sel_hi:[0,1,1]
	s_waitcnt lgkmcnt(0)
	v_mov_b32_e32 v102, v78
	v_mov_b32_e32 v103, v130
	v_pk_fma_f32 v[68:69], v[44:45], v[102:103], v[68:69] op_sel_hi:[0,1,1]
	v_mov_b32_e32 v130, v79
	v_pk_fma_f32 v[68:69], v[44:45], v[130:131], v[68:69] op_sel:[1,0,0]
	v_mov_b32_e32 v78, v80
	v_mov_b32_e32 v79, v132
	v_pk_fma_f32 v[68:69], v[40:41], v[78:79], v[68:69] op_sel_hi:[0,1,1]
	v_mov_b32_e32 v70, v41
	v_mov_b32_e32 v132, v81
	v_pk_fma_f32 v[68:69], v[70:71], v[132:133], v[68:69] op_sel_hi:[0,1,1]
	s_nop 1
	v_mov_b32_dpp v79, v69 quad_perm:[1,0,3,2] row_mask:0xf bank_mask:0xf
	s_nop 1
	v_mov_b32_dpp v78, v68 quad_perm:[1,0,3,2] row_mask:0xf bank_mask:0xf
	s_waitcnt lgkmcnt(0)
	v_pk_add_f32 v[68:69], v[68:69], v[78:79]
	s_nop 1
	v_mov_b32_dpp v103, v69 quad_perm:[2,3,0,1] row_mask:0xf bank_mask:0xf
	s_nop 1
	v_mov_b32_dpp v102, v68 quad_perm:[2,3,0,1] row_mask:0xf bank_mask:0xf
	ds_read_b128 v[78:81], v9 offset:16384
	s_waitcnt lgkmcnt(0)
	v_pk_add_f32 v[68:69], v[68:69], v[102:103]
	ds_read_b128 v[102:105], v9 offset:17408
	s_waitcnt lgkmcnt(1)
	v_fma_f32 v70, v66, v78, 0
	v_fmac_f32_e32 v70, v67, v79
	v_fmac_f32_e32 v70, v64, v80
	v_fmac_f32_e32 v70, v65, v81
	ds_read_b128 v[78:81], v9 offset:18432
	s_waitcnt lgkmcnt(1)
	v_fmac_f32_e32 v70, v62, v102
	v_fmac_f32_e32 v70, v63, v103
	v_fmac_f32_e32 v70, v60, v104
	v_fmac_f32_e32 v70, v61, v105
	ds_read_b128 v[102:105], v9 offset:19456
	s_waitcnt lgkmcnt(1)
	v_fmac_f32_e32 v70, v58, v78
	v_fmac_f32_e32 v70, v59, v79
	v_fmac_f32_e32 v70, v56, v80
	v_fmac_f32_e32 v70, v57, v81
	ds_read_b128 v[78:81], v9 offset:20480
	s_waitcnt lgkmcnt(1)
; #define LAS __attribute__((address_space(3)))
; __device__ __forceinline__ float wave_sum(float v) {
; #pragma unroll
;     for (int o = 1; o < 64; o <<= 1) v += __shfl_xor(v, o);
;     return v;
; __device__ __forceinline__ void ln3_router_phase(const Params& P, LAS unsigned char* lds, const int tid) {
;     ...
;             float l[8];
; #pragma unroll
;             for (int e = 0; e < 8; ++e) { float s = 0.f;
; #pragma unroll
;                 for (int j = 0; j < 8; ++j) { const f32x4 w = *(const LAS f32x4*)(wr + e * 2048 + 256 * j + 4 * lane); s = fmaf(v[j][0], w[0], s); s = fmaf(v[j][1], w[1], s); s = fmaf(v[j][2], w[2], s); s = fmaf(v[j][3], w[3], s); }
;                 l[e] = wave_sum(s); }
	v_fmac_f32_e32 v70, v54, v102
	v_fmac_f32_e32 v70, v55, v103
	v_fmac_f32_e32 v70, v52, v104
	v_fmac_f32_e32 v70, v53, v105
	ds_read_b128 v[102:105], v9 offset:21504
	s_waitcnt lgkmcnt(1)
	v_fmac_f32_e32 v70, v50, v78
	v_fmac_f32_e32 v70, v51, v79
	v_fmac_f32_e32 v70, v48, v80
	v_fmac_f32_e32 v70, v49, v81
	ds_read_b128 v[78:81], v9 offset:22528
	s_waitcnt lgkmcnt(1)
	v_fmac_f32_e32 v70, v46, v102
	v_fmac_f32_e32 v70, v47, v103
	v_fmac_f32_e32 v70, v42, v104
	v_fmac_f32_e32 v70, v43, v105
	ds_read_b128 v[102:105], v9 offset:23552
	s_waitcnt lgkmcnt(1)
	v_fmac_f32_e32 v70, v38, v78
	v_fmac_f32_e32 v70, v39, v79
	v_fmac_f32_e32 v70, v36, v80
	v_fmac_f32_e32 v70, v37, v81
	s_waitcnt lgkmcnt(0)
	v_fmac_f32_e32 v70, v44, v102
	v_fmac_f32_e32 v70, v45, v103
	v_fmac_f32_e32 v70, v40, v104
	s_nop 1
	v_mov_b32_dpp v107, v69 row_half_mirror row_mask:0xf bank_mask:0xf
	s_nop 1
	v_mov_b32_dpp v106, v68 row_half_mirror row_mask:0xf bank_mask:0xf
	v_fmac_f32_e32 v70, v41, v105
	s_nop 1
	v_mov_b32_dpp v72, v70 quad_perm:[1,0,3,2] row_mask:0xf bank_mask:0xf
	s_waitcnt lgkmcnt(0)
	v_pk_add_f32 v[68:69], v[68:69], v[106:107]
	s_nop 1
	v_mov_b32_dpp v79, v69 row_mirror row_mask:0xf bank_mask:0xf
	s_nop 1
	v_mov_b32_dpp v78, v68 row_mirror row_mask:0xf bank_mask:0xf
	s_waitcnt lgkmcnt(0)
	v_add_f32_e32 v70, v70, v72
	s_nop 1
	v_mov_b32_dpp v72, v70 quad_perm:[2,3,0,1] row_mask:0xf bank_mask:0xf
	s_waitcnt lgkmcnt(0)
	v_pk_add_f32 v[68:69], v[68:69], v[78:79]
	ds_bpermute_b32 v103, v77, v69
	ds_bpermute_b32 v102, v77, v68
	s_waitcnt lgkmcnt(2)
	v_add_f32_e32 v70, v70, v72
	s_nop 1
	v_mov_b32_dpp v72, v70 row_half_mirror row_mask:0xf bank_mask:0xf
	ds_read_b128 v[78:81], v9 offset:24576
	s_waitcnt lgkmcnt(1)
	v_pk_add_f32 v[68:69], v[68:69], v[102:103]
	ds_read_b128 v[102:105], v9 offset:25600
	s_waitcnt lgkmcnt(1)
	v_add_f32_e32 v70, v70, v72
	s_waitcnt lgkmcnt(0)
	v_fma_f32 v72, v66, v78, 0
	v_fmac_f32_e32 v72, v67, v79
	v_fmac_f32_e32 v72, v64, v80
	v_fmac_f32_e32 v72, v65, v81
	ds_read_b128 v[78:81], v9 offset:26624
	s_waitcnt lgkmcnt(1)
	v_fmac_f32_e32 v72, v62, v102
	v_fmac_f32_e32 v72, v63, v103
	v_fmac_f32_e32 v72, v60, v104
	v_fmac_f32_e32 v72, v61, v105
	ds_read_b128 v[102:105], v9 offset:27648
	s_waitcnt lgkmcnt(1)
	v_fmac_f32_e32 v72, v58, v78
	v_fmac_f32_e32 v72, v59, v79
	v_fmac_f32_e32 v72, v56, v80
	v_fmac_f32_e32 v72, v57, v81
	ds_read_b128 v[78:81], v9 offset:28672
	s_waitcnt lgkmcnt(1)
	v_fmac_f32_e32 v72, v54, v102
	v_fmac_f32_e32 v72, v55, v103
	v_fmac_f32_e32 v72, v52, v104
	v_fmac_f32_e32 v72, v53, v105
	ds_read_b128 v[102:105], v9 offset:29696
	s_waitcnt lgkmcnt(1)
	v_fmac_f32_e32 v72, v50, v78
	v_fmac_f32_e32 v72, v51, v79
	v_fmac_f32_e32 v72, v48, v80
	v_fmac_f32_e32 v72, v49, v81
	ds_read_b128 v[78:81], v9 offset:30720
	s_waitcnt lgkmcnt(1)
	v_fmac_f32_e32 v72, v46, v102
	v_fmac_f32_e32 v72, v47, v103
	v_fmac_f32_e32 v72, v42, v104
	v_fmac_f32_e32 v72, v43, v105
	ds_read_b128 v[102:105], v9 offset:31744
	s_waitcnt lgkmcnt(1)
	v_fmac_f32_e32 v72, v38, v78
	v_fmac_f32_e32 v72, v39, v79
	v_fmac_f32_e32 v72, v36, v80
	v_fmac_f32_e32 v72, v37, v81
	ds_read_b128 v[78:81], v9 offset:32768
	s_waitcnt lgkmcnt(1)
	v_fmac_f32_e32 v72, v44, v102
	v_fmac_f32_e32 v72, v45, v103
	v_fmac_f32_e32 v72, v40, v104
	v_fmac_f32_e32 v72, v41, v105
	ds_read_b128 v[102:105], v9 offset:33792
	s_waitcnt lgkmcnt(1)
	v_fma_f32 v76, v66, v78, 0
	v_fmac_f32_e32 v76, v67, v79
	v_fmac_f32_e32 v76, v64, v80
	v_fmac_f32_e32 v76, v65, v81
	ds_read_b128 v[78:81], v9 offset:34816
	s_waitcnt lgkmcnt(1)
	v_fmac_f32_e32 v76, v62, v102
	v_fmac_f32_e32 v76, v63, v103
	v_fmac_f32_e32 v76, v60, v104
	v_fmac_f32_e32 v76, v61, v105
	ds_read_b128 v[102:105], v9 offset:35840
	s_waitcnt lgkmcnt(1)
	v_fmac_f32_e32 v76, v58, v78
	v_fmac_f32_e32 v76, v59, v79
	v_fmac_f32_e32 v76, v56, v80
	v_fmac_f32_e32 v76, v57, v81
	ds_read_b128 v[78:81], v9 offset:36864
	s_waitcnt lgkmcnt(1)
	v_fmac_f32_e32 v76, v54, v102
	v_fmac_f32_e32 v76, v55, v103
	v_fmac_f32_e32 v76, v52, v104
	v_fmac_f32_e32 v76, v53, v105
	ds_read_b128 v[102:105], v9 offset:37888
	s_waitcnt lgkmcnt(1)
	v_fmac_f32_e32 v76, v50, v78
	v_fmac_f32_e32 v76, v51, v79
	v_fmac_f32_e32 v76, v48, v80
	v_fmac_f32_e32 v76, v49, v81
	ds_read_b128 v[78:81], v9 offset:38912
	s_waitcnt lgkmcnt(1)
	v_fmac_f32_e32 v76, v46, v102
	v_fmac_f32_e32 v76, v47, v103
	v_fmac_f32_e32 v76, v42, v104
	v_fmac_f32_e32 v76, v43, v105
	ds_read_b128 v[102:105], v9 offset:39936
	s_waitcnt lgkmcnt(1)
	v_fmac_f32_e32 v76, v38, v78
	v_fmac_f32_e32 v76, v39, v79
	v_fmac_f32_e32 v76, v36, v80
	v_fmac_f32_e32 v76, v37, v81
	s_waitcnt lgkmcnt(0)
	v_fmac_f32_e32 v76, v44, v102
	v_fmac_f32_e32 v76, v45, v103
	v_fmac_f32_e32 v76, v40, v104
	v_fmac_f32_e32 v76, v41, v105
	s_nop 1
	v_mov_b32_dpp v78, v76 quad_perm:[1,0,3,2] row_mask:0xf bank_mask:0xf
	s_nop 1
	v_mov_b32_dpp v80, v70 row_mirror row_mask:0xf bank_mask:0xf
	ds_bpermute_b32 v79, v101, v69
	ds_read_b128 v[102:105], v9 offset:41984
	s_nop 1
	v_mov_b32_dpp v74, v72 quad_perm:[1,0,3,2] row_mask:0xf bank_mask:0xf
	s_waitcnt lgkmcnt(1)
	v_add_f32_e32 v76, v76, v78
	s_nop 1
	v_mov_b32_dpp v78, v76 quad_perm:[2,3,0,1] row_mask:0xf bank_mask:0xf
	s_waitcnt lgkmcnt(0)
	v_add_f32_e32 v70, v70, v80
	ds_bpermute_b32 v80, v77, v70
	s_waitcnt lgkmcnt(2)
	v_add_f32_e32 v72, v72, v74
	s_nop 1
	v_mov_b32_dpp v74, v72 quad_perm:[2,3,0,1] row_mask:0xf bank_mask:0xf
	s_waitcnt lgkmcnt(1)
	v_add_f32_e32 v76, v76, v78
	s_nop 1
	v_mov_b32_dpp v81, v76 row_half_mirror row_mask:0xf bank_mask:0xf
	s_waitcnt lgkmcnt(0)
	v_add_f32_e32 v70, v70, v80
	ds_bpermute_b32 v78, v101, v68
	s_waitcnt lgkmcnt(2)
; #define LAS __attribute__((address_space(3)))
; __device__ __forceinline__ void ln3_router_phase(const Params& P, LAS unsigned char* lds, const int tid) {
;     ...
;             float l[8];
; #pragma unroll
;             for (int e = 0; e < 8; ++e) { float s = 0.f;
; #pragma unroll
;                 for (int j = 0; j < 8; ++j) { const f32x4 w = *(const LAS f32x4*)(wr + e * 2048 + 256 * j + 4 * lane); s = fmaf(v[j][0], w[0], s); s = fmaf(v[j][1], w[1], s); s = fmaf(v[j][2], w[2], s); s = fmaf(v[j][3], w[3], s); }
;                 l[e] = wave_sum(s); }
	v_add_f32_e32 v72, v72, v74
	s_nop 1
	v_mov_b32_dpp v74, v72 row_half_mirror row_mask:0xf bank_mask:0xf
	s_waitcnt lgkmcnt(1)
	v_add_f32_e32 v76, v76, v81
	s_nop 1
	v_mov_b32_dpp v80, v76 row_mirror row_mask:0xf bank_mask:0xf
	ds_bpermute_b32 v81, v101, v70
	s_waitcnt lgkmcnt(1)
	v_pk_add_f32 v[68:69], v[68:69], v[78:79]
	s_waitcnt lgkmcnt(0)
	v_add_f32_e32 v72, v72, v74
	s_nop 1
	v_mov_b32_dpp v74, v72 row_mirror row_mask:0xf bank_mask:0xf
	s_waitcnt lgkmcnt(1)
	v_add_f32_e32 v76, v76, v80
	s_waitcnt lgkmcnt(0)
	v_add_f32_e32 v70, v70, v81
	ds_read_b128 v[78:81], v9 offset:40960
	ds_bpermute_b32 v82, v77, v76
	s_waitcnt lgkmcnt(2)
	v_add_f32_e32 v72, v72, v74
	ds_bpermute_b32 v74, v77, v72
	v_cmp_gt_f32_e32 vcc, v68, v69
	s_waitcnt lgkmcnt(2)
	v_fma_f32 v106, v66, v78, 0
	v_fmac_f32_e32 v106, v67, v79
	v_fmac_f32_e32 v106, v64, v80
	v_fmac_f32_e32 v106, v65, v81
	ds_read_b128 v[78:81], v9 offset:43008
	v_fmac_f32_e32 v106, v62, v102
	v_fmac_f32_e32 v106, v63, v103
	v_fmac_f32_e32 v106, v60, v104
	v_fmac_f32_e32 v106, v61, v105
	ds_read_b128 v[102:105], v9 offset:44032
	s_waitcnt lgkmcnt(1)
	v_fmac_f32_e32 v106, v58, v78
	v_fmac_f32_e32 v106, v59, v79
	v_fmac_f32_e32 v106, v56, v80
	v_fmac_f32_e32 v106, v57, v81
	ds_read_b128 v[78:81], v9 offset:45056
	s_waitcnt lgkmcnt(1)
	v_fmac_f32_e32 v106, v54, v102
	v_fmac_f32_e32 v106, v55, v103
	v_fmac_f32_e32 v106, v52, v104
	v_fmac_f32_e32 v106, v53, v105
	ds_read_b128 v[102:105], v9 offset:46080
	s_waitcnt lgkmcnt(1)
	v_fmac_f32_e32 v106, v50, v78
	v_fmac_f32_e32 v106, v51, v79
	v_fmac_f32_e32 v106, v48, v80
	v_fmac_f32_e32 v106, v49, v81
	ds_read_b128 v[78:81], v9 offset:47104
	s_waitcnt lgkmcnt(1)
	v_fmac_f32_e32 v106, v46, v102
	v_fmac_f32_e32 v106, v47, v103
	v_fmac_f32_e32 v106, v42, v104
	v_fmac_f32_e32 v106, v43, v105
	ds_read_b128 v[102:105], v9 offset:48128
	s_waitcnt lgkmcnt(1)
	v_fmac_f32_e32 v106, v38, v78
	v_fmac_f32_e32 v106, v39, v79
	v_fmac_f32_e32 v106, v36, v80
	v_fmac_f32_e32 v106, v37, v81
	ds_read_b128 v[78:81], v9 offset:49152
	s_waitcnt lgkmcnt(1)
	v_fmac_f32_e32 v106, v44, v102
	v_fmac_f32_e32 v106, v45, v103
	v_fmac_f32_e32 v106, v40, v104
	v_fmac_f32_e32 v106, v41, v105
	ds_read_b128 v[102:105], v9 offset:50176
	s_waitcnt lgkmcnt(1)
	v_fma_f32 v108, v66, v78, 0
	v_fmac_f32_e32 v108, v67, v79
	v_fmac_f32_e32 v108, v64, v80
	v_fmac_f32_e32 v108, v65, v81
	ds_read_b128 v[78:81], v9 offset:51200
	s_waitcnt lgkmcnt(1)
	v_fmac_f32_e32 v108, v62, v102
	v_fmac_f32_e32 v108, v63, v103
	v_fmac_f32_e32 v108, v60, v104
	v_fmac_f32_e32 v108, v61, v105
	ds_read_b128 v[102:105], v9 offset:52224
	s_waitcnt lgkmcnt(1)
	v_fmac_f32_e32 v108, v58, v78
	v_fmac_f32_e32 v108, v59, v79
	v_fmac_f32_e32 v108, v56, v80
	v_fmac_f32_e32 v108, v57, v81
	ds_read_b128 v[78:81], v9 offset:53248
	s_waitcnt lgkmcnt(1)
	v_fmac_f32_e32 v108, v54, v102
	v_fmac_f32_e32 v108, v55, v103
	v_fmac_f32_e32 v108, v52, v104
	v_fmac_f32_e32 v108, v53, v105
	ds_read_b128 v[102:105], v9 offset:54272
	s_waitcnt lgkmcnt(1)
	v_fmac_f32_e32 v108, v50, v78
	v_fmac_f32_e32 v108, v51, v79
	v_fmac_f32_e32 v108, v48, v80
	v_fmac_f32_e32 v108, v49, v81
	ds_read_b128 v[78:81], v9 offset:55296
	s_waitcnt lgkmcnt(1)
	v_fmac_f32_e32 v108, v46, v102
	v_fmac_f32_e32 v108, v47, v103
	v_fmac_f32_e32 v108, v42, v104
	v_fmac_f32_e32 v108, v43, v105
	ds_read_b128 v[102:105], v9 offset:56320
	s_waitcnt lgkmcnt(1)
	v_fmac_f32_e32 v108, v38, v78
	v_fmac_f32_e32 v108, v39, v79
	v_fmac_f32_e32 v108, v36, v80
	v_fmac_f32_e32 v108, v37, v81
	ds_read_b128 v[78:81], v9 offset:57344
	s_waitcnt lgkmcnt(1)
	v_fmac_f32_e32 v108, v44, v102
	v_fmac_f32_e32 v108, v45, v103
	v_fmac_f32_e32 v108, v40, v104
	v_fmac_f32_e32 v108, v41, v105
	ds_read_b128 v[102:105], v9 offset:58368
	s_waitcnt lgkmcnt(1)
	v_fma_f32 v78, v66, v78, 0
	v_fmac_f32_e32 v78, v67, v79
	v_fmac_f32_e32 v78, v64, v80
	v_fmac_f32_e32 v78, v65, v81
	ds_read_b128 v[64:67], v9 offset:59392
	s_waitcnt lgkmcnt(1)
	v_fmac_f32_e32 v78, v62, v102
	v_fmac_f32_e32 v78, v63, v103
	v_fmac_f32_e32 v78, v60, v104
	v_fmac_f32_e32 v78, v61, v105
	ds_read_b128 v[60:63], v9 offset:60416
	s_waitcnt lgkmcnt(1)
	v_fmac_f32_e32 v78, v58, v64
	v_fmac_f32_e32 v78, v59, v65
	v_fmac_f32_e32 v78, v56, v66
	v_fmac_f32_e32 v78, v57, v67
	ds_read_b128 v[56:59], v9 offset:61440
	s_waitcnt lgkmcnt(1)
	v_fmac_f32_e32 v78, v54, v60
	v_fmac_f32_e32 v78, v55, v61
	v_fmac_f32_e32 v78, v52, v62
	v_fmac_f32_e32 v78, v53, v63
	ds_read_b128 v[52:55], v9 offset:62464
	s_waitcnt lgkmcnt(1)
	v_fmac_f32_e32 v78, v50, v56
	v_fmac_f32_e32 v78, v51, v57
	v_fmac_f32_e32 v78, v48, v58
	v_fmac_f32_e32 v78, v49, v59
	ds_read_b128 v[48:51], v9 offset:63488
	s_waitcnt lgkmcnt(1)
	v_fmac_f32_e32 v78, v46, v52
	v_fmac_f32_e32 v78, v47, v53
	v_fmac_f32_e32 v78, v42, v54
	v_fmac_f32_e32 v78, v43, v55
	ds_read_b128 v[52:55], v9 offset:64512
	s_waitcnt lgkmcnt(1)
	v_fmac_f32_e32 v78, v38, v48
	v_fmac_f32_e32 v78, v39, v49
	v_fmac_f32_e32 v78, v36, v50
	v_fmac_f32_e32 v78, v37, v51
	s_waitcnt lgkmcnt(0)
	v_fmac_f32_e32 v78, v44, v52
	v_fmac_f32_e32 v78, v45, v53
	v_fmac_f32_e32 v78, v40, v54
	v_fmac_f32_e32 v78, v41, v55
	s_nop 1
	v_mov_b32_dpp v107, v106 quad_perm:[1,0,3,2] row_mask:0xf bank_mask:0xf
	s_nop 1
	v_mov_b32_dpp v36, v78 quad_perm:[1,0,3,2] row_mask:0xf bank_mask:0xf
	s_nop 1
	v_mov_b32_dpp v109, v108 quad_perm:[1,0,3,2] row_mask:0xf bank_mask:0xf
	v_add_f32_e32 v72, v72, v74
	ds_bpermute_b32 v74, v101, v72
	s_waitcnt lgkmcnt(0)
	v_add_f32_e32 v37, v106, v107
	s_waitcnt lgkmcnt(2)
	v_add_f32_e32 v36, v78, v36
	s_nop 1
	v_mov_b32_dpp v38, v37 quad_perm:[2,3,0,1] row_mask:0xf bank_mask:0xf
	s_waitcnt lgkmcnt(1)
; #define LAS __attribute__((address_space(3)))
; __device__ __forceinline__ void ln3_router_phase(const Params& P, LAS unsigned char* lds, const int tid) {
;     ...
;             for (int e = 0; e < 8; ++e) { float s = 0.f;
; #pragma unroll
;                 for (int j = 0; j < 8; ++j) { const f32x4 w = *(const LAS f32x4*)(wr + e * 2048 + 256 * j + 4 * lane); s = fmaf(v[j][0], w[0], s); s = fmaf(v[j][1], w[1], s); s = fmaf(v[j][2], w[2], s); s = fmaf(v[j][3], w[3], s); }
;                 l[e] = wave_sum(s); }
;             float v1 = l[0]; int e1 = 0;
; #pragma unroll
;             for (int e = 1; e < 8; ++e) if (l[e] > v1) { v1 = l[e]; e1 = e; }
;             float v2 = -__builtin_inff(); int e2 = 0;
; #pragma unroll
;             for (int e = 0; e < 8; ++e) if (e != e1 && l[e] > v2) { v2 = l[e]; e2 = e; }
;             const float ex = expf(v2 - v1), g1 = 1.0f / (1.0f + ex), g2 = ex / (1.0f + ex);
;             if (lane == 0) { rte[2 * m] = e1; rte[2 * m + 1] = e2; rtg[2 * m] = g1; rtg[2 * m + 1] = g2; }
	v_add_f32_e32 v39, v108, v109
	s_nop 1
	v_mov_b32_dpp v41, v36 quad_perm:[2,3,0,1] row_mask:0xf bank_mask:0xf
	s_nop 1
	v_mov_b32_dpp v40, v39 quad_perm:[2,3,0,1] row_mask:0xf bank_mask:0xf
	v_add_f32_e32 v76, v76, v82
	s_waitcnt lgkmcnt(0)
	v_add_f32_e32 v37, v37, v38
	s_nop 1
	v_mov_b32_dpp v38, v37 row_half_mirror row_mask:0xf bank_mask:0xf
	s_waitcnt lgkmcnt(1)
	v_add_f32_e32 v36, v36, v41
	s_waitcnt lgkmcnt(0)
	v_add_f32_e32 v39, v39, v40
	s_nop 1
	v_mov_b32_dpp v41, v36 row_half_mirror row_mask:0xf bank_mask:0xf
	s_nop 1
	v_mov_b32_dpp v40, v39 row_half_mirror row_mask:0xf bank_mask:0xf
	s_waitcnt lgkmcnt(0)
	v_add_f32_e32 v37, v37, v38
	s_nop 1
	v_mov_b32_dpp v38, v37 row_mirror row_mask:0xf bank_mask:0xf
	ds_bpermute_b32 v82, v101, v76
	s_waitcnt lgkmcnt(2)
	v_add_f32_e32 v36, v36, v41
	s_waitcnt lgkmcnt(1)
	v_add_f32_e32 v39, v39, v40
	s_nop 1
	v_mov_b32_dpp v41, v36 row_mirror row_mask:0xf bank_mask:0xf
	s_nop 1
	v_mov_b32_dpp v40, v39 row_mirror row_mask:0xf bank_mask:0xf
	s_waitcnt lgkmcnt(0)
	v_add_f32_e32 v37, v37, v38
	ds_bpermute_b32 v38, v77, v37
	v_add_f32_e32 v42, v72, v74
	s_waitcnt lgkmcnt(2)
	v_add_f32_e32 v36, v36, v41
	s_waitcnt lgkmcnt(1)
	v_add_f32_e32 v39, v39, v40
	ds_bpermute_b32 v41, v77, v36
	ds_bpermute_b32 v40, v77, v39
	s_waitcnt lgkmcnt(2)
	v_add_f32_e32 v37, v37, v38
	ds_bpermute_b32 v38, v101, v37
	v_add_f32_e32 v43, v76, v82
	s_waitcnt lgkmcnt(2)
	v_add_f32_e32 v36, v36, v41
	s_waitcnt lgkmcnt(1)
	v_add_f32_e32 v39, v39, v40
	ds_bpermute_b32 v41, v101, v36
	ds_bpermute_b32 v40, v101, v39
	s_waitcnt lgkmcnt(2)
	v_add_f32_e32 v37, v37, v38
	v_cmp_nlg_f32_e64 s[10:11], s44, v69
	s_waitcnt lgkmcnt(1)
	v_add_f32_e32 v38, v36, v41
	v_cndmask_b32_e32 v36, v69, v68, vcc
	s_waitcnt lgkmcnt(0)
	v_add_f32_e32 v40, v39, v40
	v_cndmask_b32_e64 v39, 0, 1, vcc
	v_cmp_gt_f32_e32 vcc, v70, v36
	s_nop 1
	v_cndmask_b32_e32 v36, v36, v70, vcc
	v_cndmask_b32_e64 v39, v39, 2, vcc
	v_cmp_gt_f32_e32 vcc, v42, v36
	s_nop 1
	v_cndmask_b32_e32 v36, v36, v42, vcc
	v_cndmask_b32_e64 v39, v39, 3, vcc
	v_cmp_gt_f32_e32 vcc, v43, v36
	s_nop 1
	v_cndmask_b32_e32 v36, v36, v43, vcc
	v_cndmask_b32_e64 v39, v39, 4, vcc
	v_cmp_gt_f32_e32 vcc, v37, v36
	s_nop 1
	v_cndmask_b32_e32 v36, v36, v37, vcc
	v_cndmask_b32_e64 v41, v39, 5, vcc
	v_cmp_gt_f32_e32 vcc, v40, v36
	s_nop 1
	v_cndmask_b32_e32 v39, v36, v40, vcc
	v_cndmask_b32_e64 v36, v41, 6, vcc
	v_cmp_gt_f32_e64 s[6:7], v38, v39
	v_cmp_ngt_f32_e64 s[20:21], v38, v39
	s_nop 0
	v_cndmask_b32_e64 v36, v36, 7, s[6:7]
	v_cmp_eq_u32_e64 s[8:9], 0, v36
	s_or_b64 s[10:11], s[8:9], s[10:11]
	v_cndmask_b32_e64 v41, v69, v98, s[10:11]
	v_cmp_eq_u32_e64 s[10:11], 1, v36
	v_cmp_ngt_f32_e64 s[12:13], v68, v41
	s_or_b64 s[12:13], s[10:11], s[12:13]
	s_nop 0
	v_cndmask_b32_e64 v41, v68, v41, s[12:13]
	s_xor_b64 s[12:13], s[12:13], -1
	v_cndmask_b32_e64 v44, 0, 1, s[12:13]
	v_cmp_eq_u32_e64 s[12:13], 2, v36
	v_cmp_ngt_f32_e64 s[14:15], v70, v41
	s_or_b64 s[14:15], s[12:13], s[14:15]
	s_nop 0
	v_cndmask_b32_e64 v41, v70, v41, s[14:15]
	v_cndmask_b32_e64 v44, 2, v44, s[14:15]
	v_cmp_eq_u32_e64 s[14:15], 3, v36
	v_cmp_ngt_f32_e64 s[16:17], v42, v41
	s_or_b64 s[16:17], s[14:15], s[16:17]
	s_nop 0
	v_cndmask_b32_e64 v41, v42, v41, s[16:17]
	v_cndmask_b32_e64 v42, 3, v44, s[16:17]
	v_cmp_eq_u32_e64 s[16:17], 4, v36
	v_cmp_ngt_f32_e64 s[18:19], v43, v41
	s_or_b64 s[18:19], s[16:17], s[18:19]
	s_nop 0
	v_cndmask_b32_e64 v41, v43, v41, s[18:19]
	v_cndmask_b32_e64 v42, 4, v42, s[18:19]
	v_cmp_eq_u32_e64 s[18:19], 5, v36
	v_cmp_ngt_f32_e64 s[24:25], v37, v41
	s_or_b64 s[24:25], s[18:19], s[24:25]
	s_nop 0
	v_cndmask_b32_e64 v37, v37, v41, s[24:25]
	v_cndmask_b32_e64 v41, 5, v42, s[24:25]
	s_and_b64 s[24:25], vcc, s[20:21]
	v_cmp_ngt_f32_e32 vcc, v40, v37
	s_or_b64 vcc, s[24:25], vcc
	s_nop 0
	v_cndmask_b32_e32 v40, v40, v37, vcc
	v_cndmask_b32_e32 v37, 6, v41, vcc
	v_cmp_ngt_f32_e32 vcc, v38, v40
	s_or_b64 s[20:21], s[6:7], vcc
	v_cndmask_b32_e64 v37, 7, v37, s[20:21]
	s_and_saveexec_b64 s[40:41], s[2:3]
	s_cbranch_execz .LBB0_4581
	v_cndmask_b32_e64 v40, v38, v40, s[20:21]
	v_cndmask_b32_e64 v38, v39, v38, s[6:7]
	v_sub_f32_e32 v38, v40, v38
	v_mul_f32_e32 v39, 0x3fb8aa3b, v38
	v_fma_f32 v40, v38, s45, -v39
	v_rndne_f32_e32 v41, v39
	v_fmac_f32_e32 v40, 0x32a5705f, v38
	v_sub_f32_e32 v39, v39, v41
	v_add_f32_e32 v39, v39, v40
	v_exp_f32_e32 v39, v39
	v_cvt_i32_f32_e32 v40, v41
	v_cmp_ngt_f32_e32 vcc, s46, v38
	v_ldexp_f32 v39, v39, v40
	s_nop 0
	v_cndmask_b32_e32 v39, 0, v39, vcc
	v_cmp_nlt_f32_e32 vcc, s47, v38
	s_nop 1
	v_cndmask_b32_e32 v38, v99, v39, vcc
	v_add_f32_e32 v39, 1.0, v38
	v_div_scale_f32 v40, s[50:51], v39, v39, v38
	v_rcp_f32_e32 v41, v40
	s_nop 0
	v_fma_f32 v42, -v40, v41, 1.0
	v_fmac_f32_e32 v41, v42, v41
	v_div_scale_f32 v42, vcc, v38, v39, v38
	v_mul_f32_e32 v43, v42, v41
	v_fma_f32 v44, -v40, v43, v42
	v_fmac_f32_e32 v43, v44, v41
	v_fma_f32 v40, -v40, v43, v42
	v_div_scale_f32 v42, s[50:51], v39, v39, 1.0
	v_rcp_f32_e32 v44, v42
	v_div_fmas_f32 v40, v40, v41, v43
	v_div_fixup_f32 v45, v40, v39, v38
	v_fma_f32 v38, -v42, v44, 1.0
	v_fmac_f32_e32 v44, v38, v44
	v_div_scale_f32 v38, vcc, 1.0, v39, 1.0
	v_mul_f32_e32 v40, v38, v44
	v_fma_f32 v41, -v42, v40, v38
	v_fmac_f32_e32 v40, v41, v44
	v_fma_f32 v38, -v42, v40, v38
	v_div_fmas_f32 v38, v38, v44, v40
	v_div_fixup_f32 v44, v38, v39, 1.0
	v_lshlrev_b64 v[38:39], 2, v[34:35]
	v_add_u32_e32 v42, 1, v34
	v_lshl_add_u64 v[40:41], s[26:27], 0, v[38:39]
	v_ashrrev_i32_e32 v43, 31, v42
	v_lshl_add_u64 v[38:39], s[30:31], 0, v[38:39]
	global_store_dword v[38:39], v44, off
	v_lshl_add_u64 v[38:39], v[42:43], 2, s[30:31]
	global_store_dwordx2 v[40:41], v[36:37], off
	global_store_dword v[38:39], v45, off
	s_branch .LBB0_4581

;     __device__ __forceinline__ float qscale(const Unit& u) const { return ((u.pn >= 8 && u.pn <= 11) || u.pn == 17) ? 0.5f : 1.0f; }
;     ...
;         if constexpr (QM == 2) { const float qs0_ = g.qs * E.qscale(cur), qs1_ = qs0_ * g.qs_b1; _Pragma("unroll") for (int a = 0; a < 2; ++a) _Pragma("unroll") for (int b = 0; b < 2; ++b) _Pragma("unroll") for (int m = 0; m < 4; ++m) _Pragma("unroll") for (int n = 0; n < 2; ++n) { const v4i t_ = __builtin_bit_cast(v4i, acc[a][b][m][n]); acc[a][b][m][n] = (f32x4){(float)t_[0], (float)t_[1], (float)t_[2], (float)t_[3]} * (b == 0 ? qs0_ : qs1_); } }
.LBB0_4741:
	v_cvt_f32_i32_e32 v147, v121
	v_cvt_f32_i32_e32 v123, v123
	v_cvt_f32_i32_e32 v122, v122
	v_cvt_f32_i32_e32 v146, v120
	v_cvt_f32_i32_e32 v145, v125
	v_cvt_f32_i32_e32 v144, v124
	v_pk_mul_f32 v[120:121], v[122:123], s[28:29] op_sel_hi:[1,0]
	v_pk_mul_f32 v[122:123], v[146:147], s[28:29] op_sel_hi:[1,0]
	v_cvt_f32_i32_e32 v147, v113
	v_cvt_f32_i32_e32 v115, v115
	v_cvt_f32_i32_e32 v114, v114
	v_cvt_f32_i32_e32 v146, v112
	v_cvt_f32_i32_e32 v125, v127
	v_cvt_f32_i32_e32 v124, v126
	v_pk_mul_f32 v[126:127], v[144:145], s[28:29] op_sel_hi:[1,0]
	v_cvt_f32_i32_e32 v145, v117
	v_cvt_f32_i32_e32 v144, v116
	v_pk_mul_f32 v[112:113], v[114:115], s[28:29] op_sel_hi:[1,0]
	v_pk_mul_f32 v[114:115], v[146:147], s[28:29] op_sel_hi:[1,0]
	v_cvt_f32_i32_e32 v147, v105
	v_cvt_f32_i32_e32 v107, v107
	v_cvt_f32_i32_e32 v106, v106
	v_cvt_f32_i32_e32 v146, v104
	v_cvt_f32_i32_e32 v117, v119
	v_cvt_f32_i32_e32 v116, v118
	v_pk_mul_f32 v[118:119], v[144:145], s[28:29] op_sel_hi:[1,0]
	v_cvt_f32_i32_e32 v145, v109
	v_cvt_f32_i32_e32 v144, v108
	v_pk_mul_f32 v[104:105], v[106:107], s[28:29] op_sel_hi:[1,0]
	v_pk_mul_f32 v[106:107], v[146:147], s[28:29] op_sel_hi:[1,0]
	v_cvt_f32_i32_e32 v147, v97
	v_cvt_f32_i32_e32 v99, v99
	v_cvt_f32_i32_e32 v98, v98
	v_cvt_f32_i32_e32 v146, v96
	v_cvt_f32_i32_e32 v93, v93
	v_cvt_f32_i32_e32 v92, v92
	v_cvt_f32_i32_e32 v91, v91
	v_cvt_f32_i32_e32 v90, v90
	v_cvt_f32_i32_e32 v85, v85
	v_cvt_f32_i32_e32 v84, v84
	v_cvt_f32_i32_e32 v83, v83
	v_cvt_f32_i32_e32 v82, v82
	v_cvt_f32_i32_e32 v77, v77
	v_cvt_f32_i32_e32 v76, v76
	v_cvt_f32_i32_e32 v75, v75
	v_cvt_f32_i32_e32 v74, v74
	v_cvt_f32_i32_e32 v109, v111
	v_cvt_f32_i32_e32 v108, v110
	v_pk_mul_f32 v[110:111], v[144:145], s[28:29] op_sel_hi:[1,0]
	v_cvt_f32_i32_e32 v145, v101
	v_cvt_f32_i32_e32 v144, v100
	v_cvt_f32_i32_e32 v95, v95
	v_cvt_f32_i32_e32 v94, v94
	v_cvt_f32_i32_e32 v89, v89
	v_cvt_f32_i32_e32 v88, v88
	v_cvt_f32_i32_e32 v87, v87
	v_cvt_f32_i32_e32 v86, v86
	v_cvt_f32_i32_e32 v81, v81
	v_cvt_f32_i32_e32 v80, v80
	v_cvt_f32_i32_e32 v79, v79
	v_cvt_f32_i32_e32 v78, v78
	v_cvt_f32_i32_e32 v73, v73
	v_cvt_f32_i32_e32 v72, v72
	v_pk_mul_f32 v[96:97], v[98:99], s[28:29] op_sel_hi:[1,0]
	v_pk_mul_f32 v[98:99], v[146:147], s[28:29] op_sel_hi:[1,0]
	v_pk_mul_f32 v[146:147], v[92:93], s[30:31] op_sel_hi:[1,0]
	v_pk_mul_f32 v[92:93], v[90:91], s[30:31] op_sel_hi:[1,0]
	v_pk_mul_f32 v[90:91], v[84:85], s[30:31] op_sel_hi:[1,0]
	v_pk_mul_f32 v[84:85], v[82:83], s[30:31] op_sel_hi:[1,0]
	v_pk_mul_f32 v[82:83], v[76:77], s[30:31] op_sel_hi:[1,0]
	v_pk_mul_f32 v[76:77], v[74:75], s[30:31] op_sel_hi:[1,0]
	v_cvt_f32_i32_e32 v75, v65
	v_cvt_f32_i32_e32 v67, v67
	v_cvt_f32_i32_e32 v66, v66
	v_cvt_f32_i32_e32 v74, v64
	v_cvt_f32_i32_e32 v101, v103
	v_cvt_f32_i32_e32 v100, v102
	v_pk_mul_f32 v[102:103], v[144:145], s[28:29] op_sel_hi:[1,0]
	v_pk_mul_f32 v[144:145], v[94:95], s[30:31] op_sel_hi:[1,0]
	v_pk_mul_f32 v[94:95], v[88:89], s[30:31] op_sel_hi:[1,0]
	v_pk_mul_f32 v[88:89], v[86:87], s[30:31] op_sel_hi:[1,0]
	v_pk_mul_f32 v[86:87], v[80:81], s[30:31] op_sel_hi:[1,0]
	v_pk_mul_f32 v[80:81], v[78:79], s[30:31] op_sel_hi:[1,0]
	v_pk_mul_f32 v[78:79], v[72:73], s[30:31] op_sel_hi:[1,0]
	v_cvt_f32_i32_e32 v73, v69
	v_cvt_f32_i32_e32 v72, v68
	v_pk_mul_f32 v[64:65], v[66:67], s[30:31] op_sel_hi:[1,0]
	v_pk_mul_f32 v[66:67], v[74:75], s[30:31] op_sel_hi:[1,0]
	v_cvt_f32_i32_e32 v75, v57
	v_cvt_f32_i32_e32 v59, v59
	v_cvt_f32_i32_e32 v58, v58
	v_cvt_f32_i32_e32 v74, v56
	v_cvt_f32_i32_e32 v69, v71
	v_cvt_f32_i32_e32 v68, v70
	v_pk_mul_f32 v[70:71], v[72:73], s[30:31] op_sel_hi:[1,0]
	v_cvt_f32_i32_e32 v73, v61
	v_cvt_f32_i32_e32 v72, v60
	v_pk_mul_f32 v[56:57], v[58:59], s[28:29] op_sel_hi:[1,0]
	v_pk_mul_f32 v[58:59], v[74:75], s[28:29] op_sel_hi:[1,0]
	v_cvt_f32_i32_e32 v75, v49
	v_cvt_f32_i32_e32 v51, v51
	v_cvt_f32_i32_e32 v50, v50
	v_cvt_f32_i32_e32 v74, v48
	v_cvt_f32_i32_e32 v61, v63
	v_cvt_f32_i32_e32 v60, v62
	v_pk_mul_f32 v[62:63], v[72:73], s[28:29] op_sel_hi:[1,0]
	v_cvt_f32_i32_e32 v73, v53
	v_cvt_f32_i32_e32 v72, v52
	v_pk_mul_f32 v[48:49], v[50:51], s[28:29] op_sel_hi:[1,0]
	v_pk_mul_f32 v[50:51], v[74:75], s[28:29] op_sel_hi:[1,0]
	v_cvt_f32_i32_e32 v75, v41
	v_cvt_f32_i32_e32 v43, v43
	v_cvt_f32_i32_e32 v42, v42
	v_cvt_f32_i32_e32 v74, v40
	v_cvt_f32_i32_e32 v53, v55
	v_cvt_f32_i32_e32 v52, v54
	v_pk_mul_f32 v[54:55], v[72:73], s[28:29] op_sel_hi:[1,0]
	v_cvt_f32_i32_e32 v73, v45
	v_cvt_f32_i32_e32 v72, v44
	v_pk_mul_f32 v[40:41], v[42:43], s[28:29] op_sel_hi:[1,0]
	v_pk_mul_f32 v[42:43], v[74:75], s[28:29] op_sel_hi:[1,0]
	v_cvt_f32_i32_e32 v75, v33
	v_cvt_f32_i32_e32 v35, v35
	v_cvt_f32_i32_e32 v34, v34
	v_cvt_f32_i32_e32 v74, v32
	v_cvt_f32_i32_e32 v29, v29
	v_cvt_f32_i32_e32 v28, v28
	v_cvt_f32_i32_e32 v27, v27
	v_cvt_f32_i32_e32 v26, v26
	v_cvt_f32_i32_e32 v21, v21
	v_cvt_f32_i32_e32 v20, v20
	v_cvt_f32_i32_e32 v19, v19
	v_cvt_f32_i32_e32 v18, v18
	v_cvt_f32_i32_e32 v13, v13
	v_cvt_f32_i32_e32 v12, v12
	v_cvt_f32_i32_e32 v9, v9
	v_cvt_f32_i32_e32 v8, v8
	v_cvt_f32_i32_e32 v5, v5
	v_cvt_f32_i32_e32 v4, v4
	v_cvt_f32_i32_e32 v1, v1
	v_cvt_f32_i32_e32 v0, v0
	v_cvt_f32_i32_e32 v45, v47
	v_cvt_f32_i32_e32 v44, v46
	v_pk_mul_f32 v[46:47], v[72:73], s[28:29] op_sel_hi:[1,0]
	v_cvt_f32_i32_e32 v73, v37
	v_cvt_f32_i32_e32 v72, v36
	v_cvt_f32_i32_e32 v31, v31
	v_cvt_f32_i32_e32 v30, v30
	v_cvt_f32_i32_e32 v25, v25
	v_cvt_f32_i32_e32 v24, v24
	v_cvt_f32_i32_e32 v23, v23
	v_cvt_f32_i32_e32 v22, v22
	v_cvt_f32_i32_e32 v17, v17
	v_cvt_f32_i32_e32 v16, v16
	v_cvt_f32_i32_e32 v15, v15
	v_cvt_f32_i32_e32 v14, v14
	v_pk_mul_f32 v[32:33], v[34:35], s[28:29] op_sel_hi:[1,0]
; __device__ __forceinline__ float clamp448(float x) { return __builtin_amdgcn_fmed3f(x, -448.0f, 448.0f); }
; __device__ __forceinline__ u32x4 pack8bf(const f32x4 a, const f32x4 b) { u32x4 w; w.x = cvt_pk_bf16(a[0], a[1]); w.y = cvt_pk_bf16(a[2], a[3]); w.z = cvt_pk_bf16(b[0], b[1]); w.w = cvt_pk_bf16(b[2], b[3]); return w; }
; __device__ __forceinline__ void ln_stats(const float* st, int row, float& mu, float& rs) { const f32x2 s = *(const f32x2*)(st + 2 * (size_t)row); mu = s[0] * (1.0f / DM); rs = 1.0f / sqrtf(s[1] * (1.0f / DM) - mu * mu + LN_EPS); }
; __device__ __forceinline__ u32x2 pack8fp8(const f32x4 a, const f32x4 b) {
;     int lo = __builtin_amdgcn_cvt_pk_fp8_f32(clamp448(a[0]), clamp448(a[1]), 0, false); lo = __builtin_amdgcn_cvt_pk_fp8_f32(clamp448(a[2]), clamp448(a[3]), lo, true);
;     int hi = __builtin_amdgcn_cvt_pk_fp8_f32(clamp448(b[0]), clamp448(b[1]), 0, false); hi = __builtin_amdgcn_cvt_pk_fp8_f32(clamp448(b[2]), clamp448(b[3]), hi, true);
;     return (u32x2){(unsigned)lo, (unsigned)hi}; }
;     __device__ __forceinline__ void operator()(EPI_ARGS) const {
;     ...
; #pragma unroll
;         for (int ai = 0; ai < 2; ++ai)
; #pragma unroll
;             for (int m = 0; m < 4; ++m) { const int row = row0 + ai * HALF + m * 16; f32x4 r[2];
;                 float mu = 0.f, rs = 1.f; if constexpr (FOLD) ln_stats(st, row, mu, rs);
; #pragma unroll
;                 for (int n = 0; n < 2; ++n) { f32x4 g = acc[ai][0][m][n], up = acc[ai][1][m][n];
;                     if constexpr (!PRE) { g = g * ascale; up = up * ascale; }
;                     if constexpr (FOLD) { g = (g - cg[n] * mu) * rs + dg[n]; up = (up - cu[n] * mu) * rs + du[n]; }
;                     if constexpr (!PRE) up = up * oscale;
; #pragma unroll
;                     for (int j = 0; j < 4; ++j) { const float e = __builtin_amdgcn_exp2f(g[j] * -1.4426950408889634f); r[n][j] = g[j] * __builtin_amdgcn_rcpf(1.0f + e) * up[j]; } }
;                 if constexpr (F8OUT) *(u32x2*)((unsigned char*)O + (size_t)row * ldc + col0) = pack8fp8(r[0], r[1]);
;                 else *(u32x4*)((bf16_t*)O + (size_t)row * ldc + col0) = pack8bf(r[0], r[1]); }
	v_pk_mul_f32 v[34:35], v[74:75], s[28:29] op_sel_hi:[1,0]
	v_pk_mul_f32 v[74:75], v[28:29], s[30:31] op_sel_hi:[1,0]
	v_pk_mul_f32 v[28:29], v[26:27], s[30:31] op_sel_hi:[1,0]
	v_pk_mul_f32 v[26:27], v[20:21], s[30:31] op_sel_hi:[1,0]
	v_pk_mul_f32 v[20:21], v[18:19], s[30:31] op_sel_hi:[1,0]
	v_pk_mul_f32 v[18:19], v[12:13], s[30:31] op_sel_hi:[1,0]
	v_pk_mul_f32 v[12:13], v[8:9], s[30:31] op_sel_hi:[1,0]
	v_pk_mul_f32 v[8:9], v[4:5], s[30:31] op_sel_hi:[1,0]
	v_pk_mul_f32 v[4:5], v[0:1], s[30:31] op_sel_hi:[1,0]
	v_mul_f32_e32 v0, 0xbfb8aa3b, v126
	v_exp_f32_e32 v1, v0
	v_mul_f32_e32 v0, 0xbfb8aa3b, v127
	v_cvt_f32_i32_e32 v37, v39
	v_cvt_f32_i32_e32 v36, v38
	v_pk_mul_f32 v[38:39], v[72:73], s[28:29] op_sel_hi:[1,0]
	v_pk_mul_f32 v[72:73], v[30:31], s[30:31] op_sel_hi:[1,0]
	v_pk_mul_f32 v[30:31], v[24:25], s[30:31] op_sel_hi:[1,0]
	v_pk_mul_f32 v[24:25], v[22:23], s[30:31] op_sel_hi:[1,0]
	v_pk_mul_f32 v[22:23], v[16:17], s[30:31] op_sel_hi:[1,0]
	v_pk_mul_f32 v[16:17], v[14:15], s[30:31] op_sel_hi:[1,0]
	v_exp_f32_e32 v14, v0
	v_add_f32_e32 v1, 1.0, v1
	v_rcp_f32_e32 v15, v1
	v_pk_mul_f32 v[124:125], v[124:125], s[28:29] op_sel_hi:[1,0]
	v_add_f32_e32 v1, 1.0, v14
	v_rcp_f32_e32 v14, v1
	v_mul_f32_e32 v15, v126, v15
	v_mul_f32_e32 v126, 0xbfb8aa3b, v124
	v_exp_f32_e32 v126, v126
	v_mul_f32_e32 v14, v127, v14
	v_mul_f32_e32 v127, 0xbfb8aa3b, v125
	v_exp_f32_e32 v127, v127
	v_mul_f32_e32 v15, v146, v15
	v_add_f32_e32 v126, 1.0, v126
	v_mul_f32_e32 v146, 0xbfb8aa3b, v122
	v_rcp_f32_e32 v126, v126
	v_add_f32_e32 v127, 1.0, v127
	v_exp_f32_e32 v146, v146
	v_rcp_f32_e32 v127, v127
	v_mul_f32_e32 v124, v124, v126
	v_mul_f32_e32 v14, v147, v14
	v_add_f32_e32 v126, 1.0, v146
	v_mul_f32_e32 v125, v125, v127
	v_rcp_f32_e32 v126, v126
	v_mul_f32_e32 v127, 0xbfb8aa3b, v123
	v_exp_f32_e32 v127, v127
	v_med3_f32 v15, v15, s63, v154
	v_mul_f32_e32 v122, v122, v126
	v_mul_f32_e32 v94, v94, v122
	v_add_f32_e32 v122, 1.0, v127
	v_mul_f32_e32 v126, 0xbfb8aa3b, v120
	v_rcp_f32_e32 v122, v122
	v_exp_f32_e32 v126, v126
	v_mul_f32_e32 v127, 0xbfb8aa3b, v121
	v_exp_f32_e32 v127, v127
	v_mul_f32_e32 v122, v123, v122
	v_add_f32_e32 v123, 1.0, v126
	v_rcp_f32_e32 v123, v123
	v_add_f32_e32 v126, 1.0, v127
	v_rcp_f32_e32 v126, v126
	v_med3_f32 v14, v14, s63, v154
	v_mul_f32_e32 v120, v120, v123
	v_mul_f32_e32 v120, v92, v120
	v_mul_f32_e32 v92, v121, v126
	v_mul_f32_e32 v121, v93, v92
	v_cvt_pk_fp8_f32 v92, v15, v14
	v_mul_f32_e32 v95, v95, v122
	v_mul_f32_e32 v124, v144, v124
	v_mul_f32_e32 v125, v145, v125
	v_med3_f32 v94, v94, s63, v154
	v_med3_f32 v95, v95, s63, v154
	v_med3_f32 v14, v124, s63, v154
	v_med3_f32 v15, v125, s63, v154
	v_cvt_pk_fp8_f32 v93, v94, v95
	v_cvt_pk_fp8_f32 v92, v14, v15 op_sel:[0,0,1]
	v_med3_f32 v14, v120, s63, v154
	v_mul_f32_e32 v120, 0xbfb8aa3b, v118
	v_med3_f32 v15, v121, s63, v154
	v_exp_f32_e32 v120, v120
	v_mul_f32_e32 v121, 0xbfb8aa3b, v119
	v_exp_f32_e32 v121, v121
	v_cvt_pk_fp8_f32 v93, v14, v15 op_sel:[0,0,1]
	v_lshl_add_u32 v156, s44, 8, v148
	v_lshl_or_b32 v0, s42, 7, v150
	v_mov_b64_e32 v[14:15], s[16:17]
	v_ashrrev_i32_e32 v1, 31, v0
	v_mad_i64_i32 v[94:95], s[4:5], v156, s64, v[14:15]
	v_add_f32_e32 v120, 1.0, v120
	v_pk_mul_f32 v[116:117], v[116:117], s[28:29] op_sel_hi:[1,0]
	v_lshl_add_u64 v[94:95], v[94:95], 0, v[0:1]
	v_rcp_f32_e32 v120, v120
	v_add_f32_e32 v121, 1.0, v121
	v_rcp_f32_e32 v121, v121
	global_store_dwordx2 v[94:95], v[92:93], off
	v_mul_f32_e32 v93, 0xbfb8aa3b, v116
	v_exp_f32_e32 v93, v93
	v_mul_f32_e32 v94, 0xbfb8aa3b, v117
	v_exp_f32_e32 v94, v94
	v_mul_f32_e32 v92, v118, v120
	v_mul_f32_e32 v90, v90, v92
	v_mul_f32_e32 v92, v119, v121
	v_mul_f32_e32 v91, v91, v92
	v_add_f32_e32 v92, 1.0, v93
	v_rcp_f32_e32 v92, v92
	v_add_f32_e32 v93, 1.0, v94
	v_mul_f32_e32 v94, 0xbfb8aa3b, v114
	v_rcp_f32_e32 v93, v93
	v_exp_f32_e32 v94, v94
	v_mul_f32_e32 v92, v116, v92
	v_mul_f32_e32 v88, v88, v92
	v_mul_f32_e32 v92, v117, v93
	v_add_f32_e32 v93, 1.0, v94
	v_rcp_f32_e32 v93, v93
	v_mul_f32_e32 v94, 0xbfb8aa3b, v115
	v_exp_f32_e32 v94, v94
	v_mul_f32_e32 v89, v89, v92
	v_mul_f32_e32 v92, v114, v93
	v_mul_f32_e32 v93, 0xbfb8aa3b, v112
	v_mul_f32_e32 v86, v86, v92
	v_add_f32_e32 v92, 1.0, v94
	v_exp_f32_e32 v93, v93
	v_mul_f32_e32 v94, 0xbfb8aa3b, v113
	v_exp_f32_e32 v94, v94
	v_rcp_f32_e32 v92, v92
	v_add_f32_e32 v93, 1.0, v93
	v_rcp_f32_e32 v93, v93
	v_add_f32_e32 v94, 1.0, v94
	v_rcp_f32_e32 v94, v94
	v_mul_f32_e32 v92, v115, v92
	v_mul_f32_e32 v87, v87, v92
	v_mul_f32_e32 v92, v112, v93
	v_mul_f32_e32 v92, v84, v92
	v_mul_f32_e32 v84, v113, v94
	v_mul_f32_e32 v93, v85, v84
	v_med3_f32 v85, v90, s63, v154
	v_med3_f32 v90, v91, s63, v154
	v_cvt_pk_fp8_f32 v84, v85, v90
	v_med3_f32 v86, v86, s63, v154
	v_med3_f32 v87, v87, s63, v154
	v_med3_f32 v88, v88, s63, v154
	v_med3_f32 v89, v89, s63, v154
	v_cvt_pk_fp8_f32 v85, v86, v87
	v_cvt_pk_fp8_f32 v84, v88, v89 op_sel:[0,0,1]
	v_mul_f32_e32 v88, 0xbfb8aa3b, v110
	v_exp_f32_e32 v88, v88
	v_mul_f32_e32 v89, 0xbfb8aa3b, v111
	v_med3_f32 v86, v92, s63, v154
	v_med3_f32 v87, v93, s63, v154
	v_exp_f32_e32 v89, v89
	v_cvt_pk_fp8_f32 v85, v86, v87 op_sel:[0,0,1]
	v_or_b32_e32 v94, 16, v156
	v_mad_i64_i32 v[86:87], s[4:5], v94, s64, v[14:15]
	v_add_f32_e32 v88, 1.0, v88
	v_pk_mul_f32 v[108:109], v[108:109], s[28:29] op_sel_hi:[1,0]
	v_lshl_add_u64 v[86:87], v[86:87], 0, v[0:1]
	v_rcp_f32_e32 v88, v88
	v_add_f32_e32 v89, 1.0, v89
	v_rcp_f32_e32 v89, v89
	global_store_dwordx2 v[86:87], v[84:85], off
	v_mul_f32_e32 v85, 0xbfb8aa3b, v108
	v_exp_f32_e32 v85, v85
	v_mul_f32_e32 v86, 0xbfb8aa3b, v109
	v_exp_f32_e32 v86, v86
	v_mul_f32_e32 v84, v110, v88
	v_mul_f32_e32 v82, v82, v84
; __device__ __forceinline__ float clamp448(float x) { return __builtin_amdgcn_fmed3f(x, -448.0f, 448.0f); }
; __device__ __forceinline__ u32x4 pack8bf(const f32x4 a, const f32x4 b) { u32x4 w; w.x = cvt_pk_bf16(a[0], a[1]); w.y = cvt_pk_bf16(a[2], a[3]); w.z = cvt_pk_bf16(b[0], b[1]); w.w = cvt_pk_bf16(b[2], b[3]); return w; }
; __device__ __forceinline__ void ln_stats(const float* st, int row, float& mu, float& rs) { const f32x2 s = *(const f32x2*)(st + 2 * (size_t)row); mu = s[0] * (1.0f / DM); rs = 1.0f / sqrtf(s[1] * (1.0f / DM) - mu * mu + LN_EPS); }
; __device__ __forceinline__ u32x2 pack8fp8(const f32x4 a, const f32x4 b) {
;     int lo = __builtin_amdgcn_cvt_pk_fp8_f32(clamp448(a[0]), clamp448(a[1]), 0, false); lo = __builtin_amdgcn_cvt_pk_fp8_f32(clamp448(a[2]), clamp448(a[3]), lo, true);
;     int hi = __builtin_amdgcn_cvt_pk_fp8_f32(clamp448(b[0]), clamp448(b[1]), 0, false); hi = __builtin_amdgcn_cvt_pk_fp8_f32(clamp448(b[2]), clamp448(b[3]), hi, true);
;     return (u32x2){(unsigned)lo, (unsigned)hi}; }
;     __device__ __forceinline__ void operator()(EPI_ARGS) const {
;     ...
; #pragma unroll
;         for (int ai = 0; ai < 2; ++ai)
; #pragma unroll
;             for (int m = 0; m < 4; ++m) { const int row = row0 + ai * HALF + m * 16; f32x4 r[2];
;                 float mu = 0.f, rs = 1.f; if constexpr (FOLD) ln_stats(st, row, mu, rs);
; #pragma unroll
;                 for (int n = 0; n < 2; ++n) { f32x4 g = acc[ai][0][m][n], up = acc[ai][1][m][n];
;                     if constexpr (!PRE) { g = g * ascale; up = up * ascale; }
;                     if constexpr (FOLD) { g = (g - cg[n] * mu) * rs + dg[n]; up = (up - cu[n] * mu) * rs + du[n]; }
;                     if constexpr (!PRE) up = up * oscale;
; #pragma unroll
;                     for (int j = 0; j < 4; ++j) { const float e = __builtin_amdgcn_exp2f(g[j] * -1.4426950408889634f); r[n][j] = g[j] * __builtin_amdgcn_rcpf(1.0f + e) * up[j]; } }
;                 if constexpr (F8OUT) *(u32x2*)((unsigned char*)O + (size_t)row * ldc + col0) = pack8fp8(r[0], r[1]);
;                 else *(u32x4*)((bf16_t*)O + (size_t)row * ldc + col0) = pack8bf(r[0], r[1]); }
	v_mul_f32_e32 v84, v111, v89
	v_mul_f32_e32 v83, v83, v84
	v_add_f32_e32 v84, 1.0, v85
	v_rcp_f32_e32 v84, v84
	v_add_f32_e32 v85, 1.0, v86
	v_mul_f32_e32 v86, 0xbfb8aa3b, v106
	v_rcp_f32_e32 v85, v85
	v_exp_f32_e32 v86, v86
	v_mul_f32_e32 v84, v108, v84
	v_mul_f32_e32 v80, v80, v84
	v_mul_f32_e32 v84, v109, v85
	v_add_f32_e32 v85, 1.0, v86
	v_rcp_f32_e32 v85, v85
	v_mul_f32_e32 v86, 0xbfb8aa3b, v107
	v_exp_f32_e32 v86, v86
	v_mul_f32_e32 v81, v81, v84
	v_mul_f32_e32 v84, v106, v85
	v_mul_f32_e32 v85, 0xbfb8aa3b, v104
	v_mul_f32_e32 v78, v78, v84
	v_add_f32_e32 v84, 1.0, v86
	v_exp_f32_e32 v85, v85
	v_mul_f32_e32 v86, 0xbfb8aa3b, v105
	v_exp_f32_e32 v86, v86
	v_rcp_f32_e32 v84, v84
	v_add_f32_e32 v85, 1.0, v85
	v_rcp_f32_e32 v85, v85
	v_add_f32_e32 v86, 1.0, v86
	v_rcp_f32_e32 v86, v86
	v_mul_f32_e32 v84, v107, v84
	v_mul_f32_e32 v79, v79, v84
	v_mul_f32_e32 v84, v104, v85
	v_mul_f32_e32 v84, v76, v84
	v_mul_f32_e32 v76, v105, v86
	v_mul_f32_e32 v85, v77, v76
	v_med3_f32 v77, v82, s63, v154
	v_med3_f32 v82, v83, s63, v154
	v_cvt_pk_fp8_f32 v76, v77, v82
	v_med3_f32 v78, v78, s63, v154
	v_med3_f32 v79, v79, s63, v154
	v_med3_f32 v80, v80, s63, v154
	v_med3_f32 v81, v81, s63, v154
	v_cvt_pk_fp8_f32 v77, v78, v79
	v_cvt_pk_fp8_f32 v76, v80, v81 op_sel:[0,0,1]
	v_mul_f32_e32 v80, 0xbfb8aa3b, v102
	v_exp_f32_e32 v80, v80
	v_mul_f32_e32 v81, 0xbfb8aa3b, v103
	v_med3_f32 v78, v84, s63, v154
	v_med3_f32 v79, v85, s63, v154
	v_exp_f32_e32 v81, v81
	v_cvt_pk_fp8_f32 v77, v78, v79 op_sel:[0,0,1]
	v_or_b32_e32 v86, 32, v156
	v_mad_i64_i32 v[78:79], s[4:5], v86, s64, v[14:15]
	v_add_f32_e32 v80, 1.0, v80
	v_pk_mul_f32 v[100:101], v[100:101], s[28:29] op_sel_hi:[1,0]
	v_lshl_add_u64 v[78:79], v[78:79], 0, v[0:1]
	v_rcp_f32_e32 v80, v80
	v_add_f32_e32 v81, 1.0, v81
	v_rcp_f32_e32 v81, v81
	global_store_dwordx2 v[78:79], v[76:77], off
	v_mul_f32_e32 v77, 0xbfb8aa3b, v100
	v_exp_f32_e32 v77, v77
	v_mul_f32_e32 v78, 0xbfb8aa3b, v101
	v_exp_f32_e32 v78, v78
	v_mul_f32_e32 v76, v102, v80
	v_mul_f32_e32 v70, v70, v76
	v_mul_f32_e32 v76, v103, v81
	v_mul_f32_e32 v71, v71, v76
	v_add_f32_e32 v76, 1.0, v77
	v_rcp_f32_e32 v76, v76
	v_add_f32_e32 v77, 1.0, v78
	v_mul_f32_e32 v78, 0xbfb8aa3b, v98
	v_rcp_f32_e32 v77, v77
	v_exp_f32_e32 v78, v78
	v_pk_mul_f32 v[68:69], v[68:69], s[30:31] op_sel_hi:[1,0]
	v_mul_f32_e32 v76, v100, v76
	v_mul_f32_e32 v68, v68, v76
	v_mul_f32_e32 v76, v101, v77
	v_add_f32_e32 v77, 1.0, v78
	v_rcp_f32_e32 v77, v77
	v_mul_f32_e32 v78, 0xbfb8aa3b, v99
	v_exp_f32_e32 v78, v78
	v_mul_f32_e32 v69, v69, v76
	v_mul_f32_e32 v76, v98, v77
	v_mul_f32_e32 v77, 0xbfb8aa3b, v96
	v_mul_f32_e32 v66, v66, v76
	v_add_f32_e32 v76, 1.0, v78
	v_exp_f32_e32 v77, v77
	v_mul_f32_e32 v78, 0xbfb8aa3b, v97
	v_exp_f32_e32 v78, v78
	v_rcp_f32_e32 v76, v76
	v_add_f32_e32 v77, 1.0, v77
	v_rcp_f32_e32 v77, v77
	v_add_f32_e32 v78, 1.0, v78
	v_rcp_f32_e32 v78, v78
	v_mul_f32_e32 v76, v99, v76
	v_mul_f32_e32 v67, v67, v76
	v_mul_f32_e32 v76, v96, v77
	v_mul_f32_e32 v76, v64, v76
	v_mul_f32_e32 v64, v97, v78
	v_mul_f32_e32 v77, v65, v64
	v_med3_f32 v65, v70, s63, v154
	v_med3_f32 v70, v71, s63, v154
	v_cvt_pk_fp8_f32 v64, v65, v70
	v_med3_f32 v66, v66, s63, v154
	v_med3_f32 v67, v67, s63, v154
	v_cvt_pk_fp8_f32 v65, v66, v67
	v_med3_f32 v68, v68, s63, v154
	v_med3_f32 v69, v69, s63, v154
	v_cvt_pk_fp8_f32 v64, v68, v69 op_sel:[0,0,1]
	v_med3_f32 v66, v76, s63, v154
	v_med3_f32 v67, v77, s63, v154
	v_mul_f32_e32 v68, 0xbfb8aa3b, v62
	v_cvt_pk_fp8_f32 v65, v66, v67 op_sel:[0,0,1]
	v_exp_f32_e32 v68, v68
	v_mul_f32_e32 v69, 0xbfb8aa3b, v63
	v_or_b32_e32 v78, 48, v156
	v_exp_f32_e32 v69, v69
	v_mad_i64_i32 v[66:67], s[4:5], v78, s64, v[14:15]
	v_lshl_add_u64 v[66:67], v[66:67], 0, v[0:1]
	global_store_dwordx2 v[66:67], v[64:65], off
	v_add_f32_e32 v64, 1.0, v68
	v_rcp_f32_e32 v64, v64
	v_add_f32_e32 v65, 1.0, v69
	v_rcp_f32_e32 v65, v65
	v_pk_mul_f32 v[60:61], v[60:61], s[28:29] op_sel_hi:[1,0]
	v_mul_f32_e32 v62, v62, v64
	v_mul_f32_e32 v64, 0xbfb8aa3b, v60
	v_mul_f32_e32 v63, v63, v65
	v_exp_f32_e32 v64, v64
	v_mul_f32_e32 v65, 0xbfb8aa3b, v61
	v_exp_f32_e32 v65, v65
	v_mul_f32_e32 v67, 0xbfb8aa3b, v58
	v_add_f32_e32 v64, 1.0, v64
	v_rcp_f32_e32 v64, v64
	v_add_f32_e32 v65, 1.0, v65
	v_exp_f32_e32 v67, v67
	v_rcp_f32_e32 v65, v65
	v_mul_f32_e32 v60, v60, v64
	v_mul_f32_e32 v62, v74, v62
	v_add_f32_e32 v64, 1.0, v67
	v_mul_f32_e32 v61, v61, v65
	v_rcp_f32_e32 v64, v64
	v_mul_f32_e32 v65, 0xbfb8aa3b, v59
	v_exp_f32_e32 v65, v65
	v_mul_f32_e32 v63, v75, v63
	v_mul_f32_e32 v58, v58, v64
	v_mul_f32_e32 v30, v30, v58
	v_add_f32_e32 v58, 1.0, v65
	v_mul_f32_e32 v64, 0xbfb8aa3b, v56
	v_rcp_f32_e32 v58, v58
	v_exp_f32_e32 v64, v64
	v_mul_f32_e32 v65, 0xbfb8aa3b, v57
	v_exp_f32_e32 v65, v65
	v_mul_f32_e32 v58, v59, v58
	v_add_f32_e32 v59, 1.0, v64
	v_rcp_f32_e32 v59, v59
	v_add_f32_e32 v64, 1.0, v65
	v_rcp_f32_e32 v64, v64
	v_mul_f32_e32 v31, v31, v58
	v_mul_f32_e32 v56, v56, v59
	v_mul_f32_e32 v56, v28, v56
	v_mul_f32_e32 v28, v57, v64
	v_mul_f32_e32 v57, v29, v28
	v_med3_f32 v29, v62, s63, v154
	v_med3_f32 v58, v63, s63, v154
	v_cvt_pk_fp8_f32 v28, v29, v58
	v_med3_f32 v30, v30, s63, v154
	v_med3_f32 v31, v31, s63, v154
	v_cvt_pk_fp8_f32 v29, v30, v31
	v_med3_f32 v30, v56, s63, v154
	v_mul_f32_e32 v56, 0xbfb8aa3b, v54
	v_mul_f32_e32 v60, v72, v60
	v_mul_f32_e32 v61, v73, v61
	v_med3_f32 v31, v57, s63, v154
	v_exp_f32_e32 v56, v56
	v_mul_f32_e32 v57, 0xbfb8aa3b, v55
	v_med3_f32 v58, v60, s63, v154
	v_med3_f32 v59, v61, s63, v154
	v_exp_f32_e32 v57, v57
	v_cvt_pk_fp8_f32 v28, v58, v59 op_sel:[0,0,1]
	v_cvt_pk_fp8_f32 v29, v30, v31 op_sel:[0,0,1]
	v_add_u32_e32 v66, 0x80, v156
; #define PG8_BAR __builtin_amdgcn_s_barrier()
; __device__ __forceinline__ u32x4 pack8bf(const f32x4 a, const f32x4 b) { u32x4 w; w.x = cvt_pk_bf16(a[0], a[1]); w.y = cvt_pk_bf16(a[2], a[3]); w.z = cvt_pk_bf16(b[0], b[1]); w.w = cvt_pk_bf16(b[2], b[3]); return w; }
; __device__ __forceinline__ void ln_stats(const float* st, int row, float& mu, float& rs) { const f32x2 s = *(const f32x2*)(st + 2 * (size_t)row); mu = s[0] * (1.0f / DM); rs = 1.0f / sqrtf(s[1] * (1.0f / DM) - mu * mu + LN_EPS); }
;     ...
;         if (!has_next) break;
; #pragma unroll
;         for (int a = 0; a < 2; ++a)
; #pragma unroll
;             for (int b = 0; b < 2; ++b)
; #pragma unroll
;                 for (int m = 0; m < 4; ++m)
; #pragma unroll
;                     for (int n = 0; n < 2; ++n) acc[a][b][m][n] = (f32x4){0.f, 0.f, 0.f, 0.f};
;         cur = nxt; cA = nA; cB = nB; ++ui;
;         if (wr == 1) PG8_BAR;
;     __device__ __forceinline__ void operator()(EPI_ARGS) const {
;     ...
; #pragma unroll
;         for (int ai = 0; ai < 2; ++ai)
; #pragma unroll
;             for (int m = 0; m < 4; ++m) { const int row = row0 + ai * HALF + m * 16; f32x4 r[2];
;                 float mu = 0.f, rs = 1.f; if constexpr (FOLD) ln_stats(st, row, mu, rs);
; #pragma unroll
;                 for (int n = 0; n < 2; ++n) { f32x4 g = acc[ai][0][m][n], up = acc[ai][1][m][n];
;                     if constexpr (!PRE) { g = g * ascale; up = up * ascale; }
;                     if constexpr (FOLD) { g = (g - cg[n] * mu) * rs + dg[n]; up = (up - cu[n] * mu) * rs + du[n]; }
;                     if constexpr (!PRE) up = up * oscale;
; #pragma unroll
;                     for (int j = 0; j < 4; ++j) { const float e = __builtin_amdgcn_exp2f(g[j] * -1.4426950408889634f); r[n][j] = g[j] * __builtin_amdgcn_rcpf(1.0f + e) * up[j]; } }
;                 if constexpr (F8OUT) *(u32x2*)((unsigned char*)O + (size_t)row * ldc + col0) = pack8fp8(r[0], r[1]);
;                 else *(u32x4*)((bf16_t*)O + (size_t)row * ldc + col0) = pack8bf(r[0], r[1]); }
	v_mad_i64_i32 v[30:31], s[4:5], v66, s64, v[14:15]
	v_add_f32_e32 v56, 1.0, v56
	v_pk_mul_f32 v[52:53], v[52:53], s[28:29] op_sel_hi:[1,0]
	v_lshl_add_u64 v[30:31], v[30:31], 0, v[0:1]
	v_rcp_f32_e32 v56, v56
	v_add_f32_e32 v57, 1.0, v57
	v_rcp_f32_e32 v57, v57
	global_store_dwordx2 v[30:31], v[28:29], off
	v_mul_f32_e32 v29, 0xbfb8aa3b, v52
	v_exp_f32_e32 v29, v29
	v_mul_f32_e32 v30, 0xbfb8aa3b, v53
	v_exp_f32_e32 v30, v30
	v_mul_f32_e32 v28, v54, v56
	v_mul_f32_e32 v26, v26, v28
	v_mul_f32_e32 v28, v55, v57
	v_mul_f32_e32 v27, v27, v28
	v_add_f32_e32 v28, 1.0, v29
	v_rcp_f32_e32 v28, v28
	v_add_f32_e32 v29, 1.0, v30
	v_mul_f32_e32 v30, 0xbfb8aa3b, v50
	v_rcp_f32_e32 v29, v29
	v_exp_f32_e32 v30, v30
	v_mul_f32_e32 v28, v52, v28
	v_mul_f32_e32 v24, v24, v28
	v_mul_f32_e32 v28, v53, v29
	v_add_f32_e32 v29, 1.0, v30
	v_rcp_f32_e32 v29, v29
	v_mul_f32_e32 v30, 0xbfb8aa3b, v51
	v_exp_f32_e32 v30, v30
	v_mul_f32_e32 v25, v25, v28
	v_mul_f32_e32 v28, v50, v29
	v_mul_f32_e32 v29, 0xbfb8aa3b, v48
	v_mul_f32_e32 v22, v22, v28
	v_add_f32_e32 v28, 1.0, v30
	v_exp_f32_e32 v29, v29
	v_mul_f32_e32 v30, 0xbfb8aa3b, v49
	v_exp_f32_e32 v30, v30
	v_rcp_f32_e32 v28, v28
	v_add_f32_e32 v29, 1.0, v29
	v_rcp_f32_e32 v29, v29
	v_add_f32_e32 v30, 1.0, v30
	v_rcp_f32_e32 v30, v30
	v_mul_f32_e32 v28, v51, v28
	v_mul_f32_e32 v23, v23, v28
	v_mul_f32_e32 v28, v48, v29
	v_mul_f32_e32 v28, v20, v28
	v_mul_f32_e32 v20, v49, v30
	v_mul_f32_e32 v29, v21, v20
	v_med3_f32 v21, v26, s63, v154
	v_med3_f32 v26, v27, s63, v154
	v_cvt_pk_fp8_f32 v20, v21, v26
	v_med3_f32 v22, v22, s63, v154
	v_med3_f32 v23, v23, s63, v154
	v_med3_f32 v24, v24, s63, v154
	v_med3_f32 v25, v25, s63, v154
	v_cvt_pk_fp8_f32 v21, v22, v23
	v_cvt_pk_fp8_f32 v20, v24, v25 op_sel:[0,0,1]
	v_mul_f32_e32 v24, 0xbfb8aa3b, v46
	v_exp_f32_e32 v24, v24
	v_mul_f32_e32 v25, 0xbfb8aa3b, v47
	v_med3_f32 v22, v28, s63, v154
	v_med3_f32 v23, v29, s63, v154
	v_exp_f32_e32 v25, v25
	v_cvt_pk_fp8_f32 v21, v22, v23 op_sel:[0,0,1]
	v_add_u32_e32 v30, 0x90, v156
	v_mad_i64_i32 v[22:23], s[4:5], v30, s64, v[14:15]
	v_add_f32_e32 v24, 1.0, v24
	v_pk_mul_f32 v[44:45], v[44:45], s[28:29] op_sel_hi:[1,0]
	v_lshl_add_u64 v[22:23], v[22:23], 0, v[0:1]
	v_rcp_f32_e32 v24, v24
	v_add_f32_e32 v25, 1.0, v25
	v_rcp_f32_e32 v25, v25
	global_store_dwordx2 v[22:23], v[20:21], off
	v_mul_f32_e32 v21, 0xbfb8aa3b, v44
	v_exp_f32_e32 v21, v21
	v_mul_f32_e32 v22, 0xbfb8aa3b, v45
	v_exp_f32_e32 v22, v22
	v_mul_f32_e32 v20, v46, v24
	v_mul_f32_e32 v18, v18, v20
	v_mul_f32_e32 v20, v47, v25
	v_mul_f32_e32 v19, v19, v20
	v_add_f32_e32 v20, 1.0, v21
	v_rcp_f32_e32 v20, v20
	v_add_f32_e32 v21, 1.0, v22
	v_mul_f32_e32 v22, 0xbfb8aa3b, v42
	v_rcp_f32_e32 v21, v21
	v_exp_f32_e32 v22, v22
	v_mul_f32_e32 v20, v44, v20
	v_mul_f32_e32 v16, v16, v20
	v_mul_f32_e32 v20, v45, v21
	v_add_f32_e32 v21, 1.0, v22
	v_rcp_f32_e32 v21, v21
	v_mul_f32_e32 v22, 0xbfb8aa3b, v43
	v_exp_f32_e32 v22, v22
	v_mul_f32_e32 v17, v17, v20
	v_mul_f32_e32 v20, v42, v21
	v_mul_f32_e32 v21, 0xbfb8aa3b, v40
	v_mul_f32_e32 v12, v12, v20
	v_add_f32_e32 v20, 1.0, v22
	v_exp_f32_e32 v21, v21
	v_mul_f32_e32 v22, 0xbfb8aa3b, v41
	v_exp_f32_e32 v22, v22
	v_rcp_f32_e32 v20, v20
	v_add_f32_e32 v21, 1.0, v21
	v_cvt_f32_i32_e32 v11, v11
	v_cvt_f32_i32_e32 v10, v10
	v_rcp_f32_e32 v21, v21
	v_add_f32_e32 v22, 1.0, v22
	v_rcp_f32_e32 v22, v22
	v_mul_f32_e32 v20, v43, v20
	v_pk_mul_f32 v[10:11], v[10:11], s[30:31] op_sel_hi:[1,0]
	v_mul_f32_e32 v13, v13, v20
	v_mul_f32_e32 v20, v40, v21
	v_mul_f32_e32 v20, v10, v20
	v_mul_f32_e32 v10, v41, v22
	v_mul_f32_e32 v21, v11, v10
	v_med3_f32 v11, v18, s63, v154
	v_med3_f32 v18, v19, s63, v154
	v_cvt_pk_fp8_f32 v10, v11, v18
	v_med3_f32 v12, v12, s63, v154
	v_med3_f32 v13, v13, s63, v154
	v_med3_f32 v16, v16, s63, v154
	v_med3_f32 v17, v17, s63, v154
	v_cvt_pk_fp8_f32 v11, v12, v13
	v_cvt_pk_fp8_f32 v10, v16, v17 op_sel:[0,0,1]
	v_mul_f32_e32 v16, 0xbfb8aa3b, v38
	v_exp_f32_e32 v16, v16
	v_mul_f32_e32 v17, 0xbfb8aa3b, v39
	v_med3_f32 v12, v20, s63, v154
	v_med3_f32 v13, v21, s63, v154
	v_exp_f32_e32 v17, v17
	v_cvt_pk_fp8_f32 v11, v12, v13 op_sel:[0,0,1]
	v_add_u32_e32 v22, 0xa0, v156
	v_mad_i64_i32 v[12:13], s[4:5], v22, s64, v[14:15]
	v_add_f32_e32 v16, 1.0, v16
	v_pk_mul_f32 v[36:37], v[36:37], s[28:29] op_sel_hi:[1,0]
	v_lshl_add_u64 v[12:13], v[12:13], 0, v[0:1]
	v_rcp_f32_e32 v16, v16
	v_add_f32_e32 v17, 1.0, v17
	v_rcp_f32_e32 v17, v17
	global_store_dwordx2 v[12:13], v[10:11], off
	v_mul_f32_e32 v11, 0xbfb8aa3b, v36
	v_exp_f32_e32 v11, v11
	v_mul_f32_e32 v12, 0xbfb8aa3b, v37
	v_exp_f32_e32 v12, v12
	v_mul_f32_e32 v10, v38, v16
	v_mul_f32_e32 v8, v8, v10
	v_mul_f32_e32 v10, v39, v17
	v_mul_f32_e32 v9, v9, v10
	v_add_f32_e32 v10, 1.0, v11
	v_cvt_f32_i32_e32 v7, v7
	v_cvt_f32_i32_e32 v6, v6
	v_rcp_f32_e32 v10, v10
	v_add_f32_e32 v11, 1.0, v12
	v_mul_f32_e32 v12, 0xbfb8aa3b, v34
	v_rcp_f32_e32 v11, v11
	v_exp_f32_e32 v12, v12
	v_pk_mul_f32 v[6:7], v[6:7], s[30:31] op_sel_hi:[1,0]
	v_mul_f32_e32 v10, v36, v10
	v_mul_f32_e32 v6, v6, v10
	v_mul_f32_e32 v10, v37, v11
	v_add_f32_e32 v11, 1.0, v12
	v_rcp_f32_e32 v11, v11
	v_mul_f32_e32 v12, 0xbfb8aa3b, v35
	v_exp_f32_e32 v12, v12
	v_mul_f32_e32 v7, v7, v10
	v_mul_f32_e32 v10, v34, v11
	v_mul_f32_e32 v11, 0xbfb8aa3b, v32
	v_mul_f32_e32 v4, v4, v10
	v_add_f32_e32 v10, 1.0, v12
	v_exp_f32_e32 v11, v11
	v_mul_f32_e32 v12, 0xbfb8aa3b, v33
	v_exp_f32_e32 v12, v12
	v_rcp_f32_e32 v10, v10
	v_add_f32_e32 v11, 1.0, v11
	v_cvt_f32_i32_e32 v3, v3
	v_cvt_f32_i32_e32 v2, v2
	v_rcp_f32_e32 v11, v11
	v_add_f32_e32 v12, 1.0, v12
	v_rcp_f32_e32 v12, v12
	v_mul_f32_e32 v10, v35, v10
	v_pk_mul_f32 v[2:3], v[2:3], s[30:31] op_sel_hi:[1,0]
	v_mul_f32_e32 v5, v5, v10
	v_mul_f32_e32 v10, v32, v11
	v_mul_f32_e32 v10, v2, v10
	v_mul_f32_e32 v2, v33, v12
	v_mul_f32_e32 v11, v3, v2
	v_med3_f32 v3, v8, s63, v154
	v_med3_f32 v8, v9, s63, v154
	v_cvt_pk_fp8_f32 v2, v3, v8
	v_med3_f32 v4, v4, s63, v154
	v_med3_f32 v5, v5, s63, v154
	v_cvt_pk_fp8_f32 v3, v4, v5
	v_med3_f32 v6, v6, s63, v154
	v_med3_f32 v7, v7, s63, v154
	v_med3_f32 v4, v10, s63, v154
	v_med3_f32 v5, v11, s63, v154
	v_cvt_pk_fp8_f32 v2, v6, v7 op_sel:[0,0,1]
	v_cvt_pk_fp8_f32 v3, v4, v5 op_sel:[0,0,1]
	v_add_u32_e32 v12, 0xb0, v156
	v_mad_i64_i32 v[4:5], s[4:5], v12, s64, v[14:15]
	v_lshl_add_u64 v[0:1], v[4:5], 0, v[0:1]
	s_and_b64 vcc, exec, s[2:3]
	s_mov_b64 s[2:3], -1
	global_store_dwordx2 v[0:1], v[2:3], off
	s_cbranch_vccnz .LBB0_4732
	s_andn2_b64 vcc, exec, s[14:15]
	s_cbranch_vccnz .LBB0_4731
	s_barrier
	s_branch .LBB0_4731

.LBB0_4900:
	global_load_dwordx4 v[0:3], v[14:15], off
	global_load_dwordx4 v[4:7], v[12:13], off
	global_load_dwordx4 v[184:187], v[12:13], off offset:1024
	global_load_dwordx4 v[188:191], v[14:15], off offset:1024
	global_load_dwordx4 v[192:195], v[14:15], off offset:2048
	global_load_dwordx4 v[196:199], v[12:13], off offset:2048
	global_load_dwordx4 v[200:203], v[12:13], off offset:3072
	global_load_dwordx4 v[204:207], v[14:15], off offset:3072
	global_load_dwordx4 v[208:211], v[16:17], off
	global_load_dwordx4 v[212:215], v[18:19], off
	global_load_dwordx4 v[216:219], v[20:21], off
	global_load_dwordx4 v[220:223], v[22:23], off
	global_load_dwordx4 v[224:227], v[24:25], off
	global_load_dwordx4 v[228:231], v[26:27], off
	global_load_dwordx4 v[232:235], v[28:29], off
	global_load_dwordx4 v[236:239], v[30:31], off
	v_mul_f32_e32 v162, 0x3b23d70a, v112
	v_mul_f32_e32 v112, 0x3b23d70a, v113
	v_lshlrev_b32_e32 v113, 16, v100
	v_and_b32_e32 v100, 0xffff0000, v100
	v_lshlrev_b32_e32 v183, 16, v101
	v_and_b32_e32 v101, 0xffff0000, v101
	v_lshlrev_b32_e32 v240, 16, v96
	v_and_b32_e32 v96, 0xffff0000, v96
	v_lshlrev_b32_e32 v241, 16, v97
	v_and_b32_e32 v242, 0xffff0000, v97
	v_lshlrev_b32_e32 v243, 16, v90
	v_and_b32_e32 v244, 0xffff0000, v90
	v_lshlrev_b32_e32 v245, 16, v91
	v_and_b32_e32 v246, 0xffff0000, v91
	v_lshlrev_b32_e32 v247, 16, v88
	v_and_b32_e32 v248, 0xffff0000, v88
	v_lshlrev_b32_e32 v249, 16, v89
	v_and_b32_e32 v250, 0xffff0000, v89
	v_sub_f32_e32 v89, v100, v81
	v_sub_f32_e32 v88, v113, v81
	v_sub_f32_e32 v91, v101, v81
	v_sub_f32_e32 v90, v183, v81
	v_sub_f32_e32 v97, v96, v81
	v_sub_f32_e32 v96, v240, v81
	v_sub_f32_e32 v101, v242, v81
	v_sub_f32_e32 v100, v241, v81
	v_sub_f32_e32 v241, v244, v81
	v_sub_f32_e32 v240, v243, v81
	v_sub_f32_e32 v243, v246, v81
	v_sub_f32_e32 v242, v245, v81
	v_sub_f32_e32 v245, v248, v81
	v_sub_f32_e32 v244, v247, v81
	v_sub_f32_e32 v247, v250, v81
	v_sub_f32_e32 v246, v249, v81
	v_pk_mul_f32 v[90:91], v[80:81], v[90:91] op_sel_hi:[0,1]
	v_pk_mul_f32 v[88:89], v[80:81], v[88:89] op_sel_hi:[0,1]
	v_pk_mul_f32 v[100:101], v[80:81], v[100:101] op_sel_hi:[0,1]
	v_pk_mul_f32 v[96:97], v[80:81], v[96:97] op_sel_hi:[0,1]
	v_pk_mul_f32 v[242:243], v[80:81], v[242:243] op_sel_hi:[0,1]
	v_pk_mul_f32 v[240:241], v[80:81], v[240:241] op_sel_hi:[0,1]
	v_pk_mul_f32 v[246:247], v[80:81], v[246:247] op_sel_hi:[0,1]
	v_pk_mul_f32 v[244:245], v[80:81], v[244:245] op_sel_hi:[0,1]
	s_waitcnt vmcnt(14)
	v_pk_fma_f32 v[0:1], v[88:89], v[4:5], v[0:1]
	v_pk_fma_f32 v[2:3], v[90:91], v[6:7], v[2:3]
	s_waitcnt vmcnt(12)
	v_pk_fma_f32 v[4:5], v[96:97], v[184:185], v[188:189]
	v_pk_fma_f32 v[6:7], v[100:101], v[186:187], v[190:191]
	s_waitcnt vmcnt(10)
	v_pk_fma_f32 v[88:89], v[240:241], v[196:197], v[192:193]
	v_pk_fma_f32 v[90:91], v[242:243], v[198:199], v[194:195]
	s_waitcnt vmcnt(8)
	v_pk_fma_f32 v[96:97], v[244:245], v[200:201], v[204:205]
	v_pk_fma_f32 v[100:101], v[246:247], v[202:203], v[206:207]
	v_pk_mul_f32 v[2:3], v[2:3], s[22:23] op_sel_hi:[1,0]
	v_pk_mul_f32 v[0:1], v[0:1], s[22:23] op_sel_hi:[1,0]
	v_pk_mul_f32 v[6:7], v[6:7], s[22:23] op_sel_hi:[1,0]
	v_pk_mul_f32 v[4:5], v[4:5], s[22:23] op_sel_hi:[1,0]
	v_pk_mul_f32 v[90:91], v[90:91], s[22:23] op_sel_hi:[1,0]
	v_pk_mul_f32 v[88:89], v[88:89], s[22:23] op_sel_hi:[1,0]
	v_pk_mul_f32 v[100:101], v[100:101], s[22:23] op_sel_hi:[1,0]
	v_pk_mul_f32 v[96:97], v[96:97], s[22:23] op_sel_hi:[1,0]
	v_pk_fma_f32 v[118:119], v[162:163], v[118:119], v[0:1] op_sel_hi:[0,1,1]
	v_pk_fma_f32 v[0:1], v[162:163], v[120:121], v[2:3] op_sel_hi:[0,1,1]
	v_pk_fma_f32 v[120:121], v[162:163], v[122:123], v[4:5] op_sel_hi:[0,1,1]
	v_pk_fma_f32 v[4:5], v[162:163], v[124:125], v[6:7] op_sel_hi:[0,1,1]
	v_pk_fma_f32 v[122:123], v[162:163], v[126:127], v[88:89] op_sel_hi:[0,1,1]
	v_pk_fma_f32 v[88:89], v[162:163], v[128:129], v[90:91] op_sel_hi:[0,1,1]
	v_pk_fma_f32 v[114:115], v[162:163], v[114:115], v[96:97] op_sel_hi:[0,1,1]
	v_pk_fma_f32 v[96:97], v[162:163], v[116:117], v[100:101] op_sel_hi:[0,1,1]
	v_pk_fma_f32 v[0:1], v[112:113], v[134:135], v[0:1] op_sel_hi:[0,1,1]
	v_pk_fma_f32 v[2:3], v[112:113], v[130:131], v[118:119] op_sel_hi:[0,1,1]
	v_pk_fma_f32 v[4:5], v[112:113], v[142:143], v[4:5] op_sel_hi:[0,1,1]
	v_pk_fma_f32 v[6:7], v[112:113], v[138:139], v[120:121] op_sel_hi:[0,1,1]
	v_pk_fma_f32 v[88:89], v[112:113], v[154:155], v[88:89] op_sel_hi:[0,1,1]
	v_pk_fma_f32 v[90:91], v[112:113], v[148:149], v[122:123] op_sel_hi:[0,1,1]
	v_pk_fma_f32 v[96:97], v[112:113], v[160:161], v[96:97] op_sel_hi:[0,1,1]
	v_pk_fma_f32 v[100:101], v[112:113], v[158:159], v[114:115] op_sel_hi:[0,1,1]
	v_lshlrev_b32_e32 v113, 16, v86
	v_and_b32_e32 v86, 0xffff0000, v86
	v_lshlrev_b32_e32 v114, 16, v87
	v_and_b32_e32 v115, 0xffff0000, v87
	v_sub_f32_e32 v87, v86, v81
	v_sub_f32_e32 v86, v113, v81
	v_sub_f32_e32 v115, v115, v81
	v_sub_f32_e32 v114, v114, v81
	v_pk_mul_f32 v[114:115], v[80:81], v[114:115] op_sel_hi:[0,1]
	v_pk_mul_f32 v[86:87], v[80:81], v[86:87] op_sel_hi:[0,1]
	s_waitcnt vmcnt(6)
	v_pk_fma_f32 v[86:87], v[86:87], v[208:209], v[212:213]
	v_pk_fma_f32 v[114:115], v[114:115], v[210:211], v[214:215]
	v_pk_mul_f32 v[86:87], v[86:87], s[22:23] op_sel_hi:[1,0]
	v_pk_mul_f32 v[114:115], v[114:115], s[22:23] op_sel_hi:[1,0]
	v_pk_fma_f32 v[106:107], v[162:163], v[106:107], v[86:87] op_sel_hi:[0,1,1]
	v_pk_fma_f32 v[86:87], v[162:163], v[110:111], v[114:115] op_sel_hi:[0,1,1]
	v_pk_fma_f32 v[86:87], v[112:113], v[156:157], v[86:87] op_sel_hi:[0,1,1]
	v_pk_fma_f32 v[106:107], v[112:113], v[152:153], v[106:107] op_sel_hi:[0,1,1]
	v_lshlrev_b32_e32 v110, 16, v84
	v_and_b32_e32 v84, 0xffff0000, v84
	v_lshlrev_b32_e32 v113, 16, v85
	v_and_b32_e32 v111, 0xffff0000, v85
	v_sub_f32_e32 v85, v84, v81
	v_sub_f32_e32 v84, v110, v81
	v_sub_f32_e32 v111, v111, v81
	v_sub_f32_e32 v110, v113, v81
	v_pk_mul_f32 v[110:111], v[80:81], v[110:111] op_sel_hi:[0,1]
	v_pk_mul_f32 v[84:85], v[80:81], v[84:85] op_sel_hi:[0,1]
	s_waitcnt vmcnt(4)
; __device__ __forceinline__ float wave_sum(float v) {
; #pragma unroll
;     for (int o = 1; o < 64; o <<= 1) v += __shfl_xor(v, o);
;     return v;
; __device__ __forceinline__ void ln_norm2(f32x4 (&v)[8], const float* g, const float* b, int lane, float& mean_o, float& rstd_o) {
;     float s = 0.f;
; #pragma unroll
;     for (int j = 0; j < 8; ++j) s += (v[j][0] + v[j][1]) + (v[j][2] + v[j][3]);
;     const float mean = wave_sum(s) * (1.f / DM); float s2 = 0.f;
	v_pk_fma_f32 v[84:85], v[84:85], v[216:217], v[220:221]
	v_pk_fma_f32 v[110:111], v[110:111], v[218:219], v[222:223]
	v_pk_mul_f32 v[84:85], v[84:85], s[22:23] op_sel_hi:[1,0]
	v_pk_mul_f32 v[110:111], v[110:111], s[22:23] op_sel_hi:[1,0]
	v_pk_fma_f32 v[104:105], v[162:163], v[104:105], v[84:85] op_sel_hi:[0,1,1]
	v_pk_fma_f32 v[84:85], v[162:163], v[108:109], v[110:111] op_sel_hi:[0,1,1]
	v_lshlrev_b32_e32 v108, 16, v82
	v_and_b32_e32 v82, 0xffff0000, v82
	v_lshlrev_b32_e32 v110, 16, v83
	v_and_b32_e32 v109, 0xffff0000, v83
	v_sub_f32_e32 v83, v82, v81
	v_sub_f32_e32 v82, v108, v81
	v_sub_f32_e32 v109, v109, v81
	v_sub_f32_e32 v108, v110, v81
	v_pk_mul_f32 v[108:109], v[80:81], v[108:109] op_sel_hi:[0,1]
	v_pk_mul_f32 v[82:83], v[80:81], v[82:83] op_sel_hi:[0,1]
	s_waitcnt vmcnt(2)
	v_pk_fma_f32 v[82:83], v[82:83], v[224:225], v[228:229]
	v_pk_fma_f32 v[108:109], v[108:109], v[226:227], v[230:231]
	v_pk_mul_f32 v[82:83], v[82:83], s[22:23] op_sel_hi:[1,0]
	v_pk_mul_f32 v[108:109], v[108:109], s[22:23] op_sel_hi:[1,0]
	v_pk_fma_f32 v[98:99], v[162:163], v[98:99], v[82:83] op_sel_hi:[0,1,1]
	v_pk_fma_f32 v[82:83], v[162:163], v[102:103], v[108:109] op_sel_hi:[0,1,1]
	v_lshlrev_b32_e32 v102, 16, v78
	v_and_b32_e32 v78, 0xffff0000, v78
	v_lshlrev_b32_e32 v108, 16, v79
	v_and_b32_e32 v103, 0xffff0000, v79
	v_sub_f32_e32 v79, v78, v81
	v_sub_f32_e32 v78, v102, v81
	v_sub_f32_e32 v103, v103, v81
	v_sub_f32_e32 v102, v108, v81
	v_pk_mul_f32 v[78:79], v[80:81], v[78:79] op_sel_hi:[0,1]
	v_pk_mul_f32 v[102:103], v[80:81], v[102:103] op_sel_hi:[0,1]
	s_waitcnt vmcnt(0)
	v_pk_fma_f32 v[78:79], v[78:79], v[232:233], v[236:237]
	v_pk_fma_f32 v[80:81], v[102:103], v[234:235], v[238:239]
	v_pk_mul_f32 v[78:79], v[78:79], s[22:23] op_sel_hi:[1,0]
	v_pk_mul_f32 v[80:81], v[80:81], s[22:23] op_sel_hi:[1,0]
	v_pk_fma_f32 v[94:95], v[162:163], v[94:95], v[78:79] op_sel_hi:[0,1,1]
	v_pk_fma_f32 v[78:79], v[162:163], v[92:93], v[80:81] op_sel_hi:[0,1,1]
	v_pk_fma_f32 v[80:81], v[112:113], v[132:133], v[94:95] op_sel_hi:[0,1,1]
	v_mov_b32_e32 v92, v2
	v_mov_b32_e32 v93, v6
	v_mov_b32_e32 v94, v3
	v_mov_b32_e32 v95, v7
	v_pk_add_f32 v[92:93], v[92:93], v[94:95]
	v_mov_b32_e32 v94, v0
	v_mov_b32_e32 v95, v4
	v_mov_b32_e32 v102, v1
	v_mov_b32_e32 v103, v5
	v_pk_add_f32 v[94:95], v[94:95], v[102:103]
	v_mov_b32_e32 v102, v90
	v_pk_add_f32 v[92:93], v[92:93], v[94:95]
	v_pk_mov_b32 v[94:95], v[90:91], v[88:89] op_sel:[1,0]
	v_mov_b32_e32 v103, v89
	v_pk_add_f32 v[94:95], v[94:95], v[102:103]
	v_add_f32_e32 v92, 0, v92
	v_pk_add_f32 v[94:95], v[94:95], v[94:95] op_sel:[0,1] op_sel_hi:[1,0]
	v_add_f32_e32 v92, v92, v93
	v_add_f32_e32 v102, v100, v101
	v_add_f32_e32 v108, v96, v97
	v_mov_b32_e32 v93, v106
	v_mov_b32_e32 v95, v107
	v_mov_b32_e32 v103, v86
	v_mov_b32_e32 v109, v87
	v_pk_fma_f32 v[84:85], v[112:113], v[150:151], v[84:85] op_sel_hi:[0,1,1]
	v_pk_fma_f32 v[104:105], v[112:113], v[146:147], v[104:105] op_sel_hi:[0,1,1]
	v_pk_add_f32 v[92:93], v[92:93], v[94:95]
	v_pk_add_f32 v[94:95], v[102:103], v[108:109]
	v_mov_b32_e32 v102, v104
	v_pk_add_f32 v[92:93], v[92:93], v[94:95]
	v_pk_mov_b32 v[94:95], v[104:105], v[84:85] op_sel:[1,0]
	v_mov_b32_e32 v103, v85
	v_pk_add_f32 v[94:95], v[94:95], v[102:103]
	v_pk_fma_f32 v[82:83], v[112:113], v[144:145], v[82:83] op_sel_hi:[0,1,1]
	v_pk_fma_f32 v[98:99], v[112:113], v[140:141], v[98:99] op_sel_hi:[0,1,1]
	v_pk_fma_f32 v[78:79], v[112:113], v[136:137], v[78:79] op_sel_hi:[0,1,1]
	v_pk_add_f32 v[92:93], v[92:93], v[92:93] op_sel:[0,1] op_sel_hi:[1,0]
	v_pk_add_f32 v[94:95], v[94:95], v[94:95] op_sel:[0,1] op_sel_hi:[1,0]
	v_add_f32_e32 v102, v98, v99
	v_add_f32_e32 v108, v82, v83
	v_mov_b32_e32 v93, v80
	v_mov_b32_e32 v95, v81
	v_mov_b32_e32 v103, v78
	v_mov_b32_e32 v109, v79
	v_pk_add_f32 v[92:93], v[92:93], v[94:95]
	v_pk_add_f32 v[94:95], v[102:103], v[108:109]
	s_nop 0
	v_pk_add_f32 v[92:93], v[92:93], v[94:95]
	v_xor_b32_e32 v94, 1, v164
	v_add_f32_e32 v92, v92, v93
	v_and_b32_e32 v93, 64, v164
	v_add_u32_e32 v93, 64, v93
	v_cmp_lt_i32_e32 vcc, v94, v93
	s_nop 1
	v_cndmask_b32_e32 v94, v164, v94, vcc
	v_lshlrev_b32_e32 v143, 2, v94
	s_nop 1
	v_mov_b32_dpp v94, v92 quad_perm:[1,0,3,2] row_mask:0xf bank_mask:0xf
	s_waitcnt lgkmcnt(0)
	v_add_f32_e32 v92, v92, v94
	v_xor_b32_e32 v94, 2, v164
	v_cmp_lt_i32_e32 vcc, v94, v93
	s_nop 1
	v_cndmask_b32_e32 v94, v164, v94, vcc
	v_lshlrev_b32_e32 v145, 2, v94
	s_nop 1
	v_mov_b32_dpp v94, v92 quad_perm:[2,3,0,1] row_mask:0xf bank_mask:0xf
	s_waitcnt lgkmcnt(0)
	v_add_f32_e32 v92, v92, v94
	v_xor_b32_e32 v94, 4, v164
	v_cmp_lt_i32_e32 vcc, v94, v93
	s_nop 1
	v_cndmask_b32_e32 v94, v164, v94, vcc
	v_lshlrev_b32_e32 v146, 2, v94
	s_nop 1
	v_mov_b32_dpp v94, v92 row_half_mirror row_mask:0xf bank_mask:0xf
	s_waitcnt lgkmcnt(0)
	v_add_f32_e32 v92, v92, v94
	v_xor_b32_e32 v94, 8, v164
	v_cmp_lt_i32_e32 vcc, v94, v93
	s_nop 1
	v_cndmask_b32_e32 v94, v164, v94, vcc
	v_lshlrev_b32_e32 v147, 2, v94
	s_nop 1
	v_mov_b32_dpp v94, v92 row_mirror row_mask:0xf bank_mask:0xf
	s_waitcnt lgkmcnt(0)
	v_add_f32_e32 v92, v92, v94
	v_xor_b32_e32 v94, 16, v164
	v_cmp_lt_i32_e32 vcc, v94, v93
	s_nop 1
	v_cndmask_b32_e32 v94, v164, v94, vcc
	v_lshlrev_b32_e32 v148, 2, v94
	ds_bpermute_b32 v94, v148, v92
	s_waitcnt lgkmcnt(0)
	v_add_f32_e32 v92, v92, v94
	v_xor_b32_e32 v94, 32, v164
	v_cmp_lt_i32_e32 vcc, v94, v93
	s_nop 1
	v_cndmask_b32_e32 v93, v164, v94, vcc
	v_lshlrev_b32_e32 v149, 2, v93
	ds_bpermute_b32 v93, v149, v92
	s_andn2_b64 vcc, exec, s[16:17]
	s_waitcnt lgkmcnt(0)
; __device__ __forceinline__ void ln_norm2(f32x4 (&v)[8], const float* g, const float* b, int lane, float& mean_o, float& rstd_o) {
;     ...
;     const float mean = wave_sum(s) * (1.f / DM); float s2 = 0.f;
; #pragma unroll
;     for (int j = 0; j < 8; ++j) { v[j] = v[j] - mean; s2 += (v[j][0] * v[j][0] + v[j][1] * v[j][1]) + (v[j][2] * v[j][2] + v[j][3] * v[j][3]); }
;     const float rstd = 1.f / sqrtf(wave_sum(s2) * (1.f / DM) + LN_EPS);
	v_add_f32_e32 v92, v92, v93
	v_fmamk_f32 v1, v92, 0xba000000, v1
	v_fmamk_f32 v3, v92, 0xba000000, v3
	v_fmac_f32_e32 v0, 0xba000000, v92
	v_fmac_f32_e32 v2, 0xba000000, v92
	v_mul_f32_e32 v93, v3, v3
	v_mul_f32_e32 v94, v1, v1
	v_fmac_f32_e32 v93, v2, v2
	v_fmac_f32_e32 v94, v0, v0
	v_fmamk_f32 v5, v92, 0xba000000, v5
	v_fmamk_f32 v7, v92, 0xba000000, v7
	v_add_f32_e32 v93, v93, v94
	v_fmac_f32_e32 v4, 0xba000000, v92
	v_fmac_f32_e32 v6, 0xba000000, v92
	v_mul_f32_e32 v94, v7, v7
	v_mul_f32_e32 v95, v5, v5
	v_fmac_f32_e32 v94, v6, v6
	v_fmac_f32_e32 v95, v4, v4
	v_add_f32_e32 v94, v94, v95
	v_fmamk_f32 v89, v92, 0xba000000, v89
	v_fmamk_f32 v91, v92, 0xba000000, v91
	v_add_f32_e32 v93, v93, v94
	v_fmac_f32_e32 v88, 0xba000000, v92
	v_fmac_f32_e32 v90, 0xba000000, v92
	v_mul_f32_e32 v94, v91, v91
	v_mul_f32_e32 v95, v89, v89
	v_fmac_f32_e32 v94, v90, v90
	v_fmac_f32_e32 v95, v88, v88
	v_add_f32_e32 v94, v94, v95
	v_fmamk_f32 v97, v92, 0xba000000, v97
	v_fmamk_f32 v101, v92, 0xba000000, v101
	v_add_f32_e32 v93, v94, v93
	v_fmac_f32_e32 v96, 0xba000000, v92
	v_fmac_f32_e32 v100, 0xba000000, v92
	v_mul_f32_e32 v94, v101, v101
	v_mul_f32_e32 v95, v97, v97
	v_fmac_f32_e32 v94, v100, v100
	v_fmac_f32_e32 v95, v96, v96
	v_add_f32_e32 v94, v94, v95
	v_fmamk_f32 v87, v92, 0xba000000, v87
	v_fmamk_f32 v107, v92, 0xba000000, v107
	v_add_f32_e32 v93, v94, v93
	v_fmac_f32_e32 v86, 0xba000000, v92
	v_fmac_f32_e32 v106, 0xba000000, v92
	v_mul_f32_e32 v94, v107, v107
	v_mul_f32_e32 v95, v87, v87
	v_fmac_f32_e32 v94, v106, v106
	v_fmac_f32_e32 v95, v86, v86
	v_add_f32_e32 v94, v94, v95
	v_fmamk_f32 v85, v92, 0xba000000, v85
	v_fmamk_f32 v105, v92, 0xba000000, v105
	v_add_f32_e32 v93, v94, v93
	v_fmac_f32_e32 v84, 0xba000000, v92
	v_fmac_f32_e32 v104, 0xba000000, v92
	v_mul_f32_e32 v94, v105, v105
	v_mul_f32_e32 v95, v85, v85
	v_fmac_f32_e32 v94, v104, v104
	v_fmac_f32_e32 v95, v84, v84
	v_add_f32_e32 v94, v94, v95
	v_fmamk_f32 v83, v92, 0xba000000, v83
	v_fmamk_f32 v99, v92, 0xba000000, v99
	v_add_f32_e32 v93, v94, v93
	v_fmac_f32_e32 v82, 0xba000000, v92
	v_fmac_f32_e32 v98, 0xba000000, v92
	v_mul_f32_e32 v94, v99, v99
	v_mul_f32_e32 v95, v83, v83
	v_fmac_f32_e32 v94, v98, v98
	v_fmac_f32_e32 v95, v82, v82
	v_add_f32_e32 v94, v94, v95
	v_fmamk_f32 v79, v92, 0xba000000, v79
	v_fmamk_f32 v81, v92, 0xba000000, v81
	v_add_f32_e32 v93, v94, v93
	v_fmac_f32_e32 v78, 0xba000000, v92
	v_fmac_f32_e32 v80, 0xba000000, v92
	v_mul_f32_e32 v92, v81, v81
	v_mul_f32_e32 v94, v79, v79
	v_fmac_f32_e32 v92, v80, v80
	v_fmac_f32_e32 v94, v78, v78
	v_add_f32_e32 v92, v92, v94
	v_add_f32_e32 v92, v92, v93
	s_nop 1
	v_mov_b32_dpp v93, v92 quad_perm:[1,0,3,2] row_mask:0xf bank_mask:0xf
	s_waitcnt lgkmcnt(0)
	v_add_f32_e32 v92, v92, v93
	s_nop 1
	v_mov_b32_dpp v93, v92 quad_perm:[2,3,0,1] row_mask:0xf bank_mask:0xf
	s_waitcnt lgkmcnt(0)
	v_add_f32_e32 v92, v92, v93
	s_nop 1
	v_mov_b32_dpp v93, v92 row_half_mirror row_mask:0xf bank_mask:0xf
	s_waitcnt lgkmcnt(0)
	v_add_f32_e32 v92, v92, v93
	s_nop 1
	v_mov_b32_dpp v93, v92 row_mirror row_mask:0xf bank_mask:0xf
	s_waitcnt lgkmcnt(0)
	v_add_f32_e32 v92, v92, v93
	ds_bpermute_b32 v93, v148, v92
	s_waitcnt lgkmcnt(0)
	v_add_f32_e32 v92, v92, v93
	ds_bpermute_b32 v93, v149, v92
	s_cbranch_vccnz .LBB0_4902
; __device__ __forceinline__ void ln_norm2(f32x4 (&v)[8], const float* g, const float* b, int lane, float& mean_o, float& rstd_o) {
;     ...
;     const float rstd = 1.f / sqrtf(wave_sum(s2) * (1.f / DM) + LN_EPS);
; #pragma unroll
;     for (int j = 0; j < 8; ++j) { const f32x4 gv = *((const f32x4*)g + lane + 64 * j), bv = *((const f32x4*)b + lane + 64 * j); v[j] = v[j] * rstd * gv + bv; }
;     mean_o = mean; rstd_o = rstd;
; }
; __device__ __forceinline__ void ln_norm(f32x4 (&v)[8], const float* g, const float* b, int lane) { float m_, r_; ln_norm2(v, g, b, lane, m_, r_); }
;     if (hf) { f32x4* o = (f32x4*)(hf + m * DM) + lane;
; #pragma unroll
;         for (int j = 0; j < 8; ++j) __builtin_nontemporal_store(v[j], o + 64 * j); }
	global_load_dwordx4 v[108:111], v[34:35], off
	global_load_dwordx4 v[112:115], v[38:39], off
	global_load_dwordx4 v[116:119], v[40:41], off
	global_load_dwordx4 v[120:123], v[42:43], off
	global_load_dwordx4 v[124:127], v[44:45], off
	global_load_dwordx4 v[128:131], v[46:47], off
	global_load_dwordx4 v[132:135], v[48:49], off
	global_load_dwordx4 v[136:139], v[50:51], off
	global_load_dwordx4 v[150:153], v[36:37], off offset:3072
	global_load_dwordx4 v[154:157], v[32:33], off offset:3072
	global_load_dwordx4 v[158:161], v[32:33], off offset:2048
	global_load_dwordx4 v[184:187], v[36:37], off offset:2048
	global_load_dwordx4 v[188:191], v[36:37], off offset:1024
	global_load_dwordx4 v[192:195], v[32:33], off offset:1024
	global_load_dwordx4 v[196:199], v[32:33], off
	global_load_dwordx4 v[200:203], v[36:37], off
	s_waitcnt lgkmcnt(0)
	v_add_f32_e32 v92, v92, v93
	v_fmamk_f32 v92, v92, 0x3a000000, v165
	v_mul_f32_e32 v93, 0x4f800000, v92
	v_cmp_gt_f32_e32 vcc, s40, v92
	s_nop 1
	v_cndmask_b32_e32 v92, v92, v93, vcc
	v_sqrt_f32_e32 v93, v92
	s_nop 0
	v_add_u32_e32 v94, -1, v93
	v_add_u32_e32 v95, 1, v93
	v_fma_f32 v102, -v94, v93, v92
	v_fma_f32 v103, -v95, v93, v92
	v_cmp_ge_f32_e64 s[2:3], 0, v102
	s_nop 1
	v_cndmask_b32_e64 v93, v93, v94, s[2:3]
	v_cmp_lt_f32_e64 s[2:3], 0, v103
	v_lshlrev_b64 v[102:103], 13, v[8:9]
	v_lshl_add_u64 v[102:103], v[52:53], 0, v[102:103]
	v_cndmask_b32_e64 v93, v93, v95, s[2:3]
	v_mul_f32_e32 v94, 0x37800000, v93
	v_cndmask_b32_e32 v93, v93, v94, vcc
	v_cmp_class_f32_e32 vcc, v92, v166
	s_nop 1
	v_cndmask_b32_e32 v92, v93, v92, vcc
	v_div_scale_f32 v93, s[2:3], v92, v92, 1.0
	v_rcp_f32_e32 v94, v93
	v_div_scale_f32 v9, vcc, 1.0, v92, 1.0
	v_fma_f32 v95, -v93, v94, 1.0
	v_fmac_f32_e32 v94, v95, v94
	v_mul_f32_e32 v95, v9, v94
	v_fma_f32 v140, -v93, v95, v9
	v_fmac_f32_e32 v95, v140, v94
	v_fma_f32 v9, -v93, v95, v9
	v_div_fmas_f32 v9, v9, v94, v95
	v_div_fixup_f32 v92, v9, v92, 1.0
	v_pk_mul_f32 v[80:81], v[80:81], v[92:93] op_sel_hi:[1,0]
	v_pk_mul_f32 v[78:79], v[78:79], v[92:93] op_sel_hi:[1,0]
	v_pk_mul_f32 v[94:95], v[98:99], v[92:93] op_sel_hi:[1,0]
	v_pk_mul_f32 v[98:99], v[104:105], v[92:93] op_sel_hi:[1,0]
	v_pk_mul_f32 v[84:85], v[84:85], v[92:93] op_sel_hi:[1,0]
	v_pk_mul_f32 v[86:87], v[86:87], v[92:93] op_sel_hi:[1,0]
	v_pk_mul_f32 v[100:101], v[100:101], v[92:93] op_sel_hi:[1,0]
	v_pk_mul_f32 v[206:207], v[2:3], v[92:93] op_sel_hi:[1,0]
	v_pk_mul_f32 v[208:209], v[0:1], v[92:93] op_sel_hi:[1,0]
	v_pk_mul_f32 v[104:105], v[106:107], v[92:93] op_sel_hi:[1,0]
	v_pk_mul_f32 v[96:97], v[96:97], v[92:93] op_sel_hi:[1,0]
	v_pk_mul_f32 v[90:91], v[90:91], v[92:93] op_sel_hi:[1,0]
	v_pk_mul_f32 v[106:107], v[88:89], v[92:93] op_sel_hi:[1,0]
	v_pk_mul_f32 v[140:141], v[6:7], v[92:93] op_sel_hi:[1,0]
	v_pk_mul_f32 v[204:205], v[4:5], v[92:93] op_sel_hi:[1,0]
	v_pk_mul_f32 v[82:83], v[82:83], v[92:93] op_sel_hi:[1,0]
	s_waitcnt vmcnt(14)
	v_pk_fma_f32 v[2:3], v[78:79], v[114:115], v[110:111]
	v_pk_fma_f32 v[0:1], v[80:81], v[112:113], v[108:109]
	s_waitcnt vmcnt(12)
	v_pk_fma_f32 v[4:5], v[94:95], v[120:121], v[116:117]
	v_pk_fma_f32 v[6:7], v[82:83], v[122:123], v[118:119]
	s_waitcnt vmcnt(10)
	v_pk_fma_f32 v[80:81], v[84:85], v[130:131], v[126:127]
	v_pk_fma_f32 v[78:79], v[98:99], v[128:129], v[124:125]
	s_waitcnt vmcnt(8)
	v_pk_fma_f32 v[84:85], v[86:87], v[138:139], v[134:135]
	v_pk_fma_f32 v[82:83], v[104:105], v[136:137], v[132:133]
	s_waitcnt vmcnt(6)
	v_pk_fma_f32 v[86:87], v[100:101], v[150:151], v[154:155]
	v_pk_fma_f32 v[88:89], v[96:97], v[152:153], v[156:157]
	s_waitcnt vmcnt(4)
	v_pk_fma_f32 v[92:93], v[106:107], v[186:187], v[160:161]
	v_pk_fma_f32 v[90:91], v[90:91], v[184:185], v[158:159]
	s_waitcnt vmcnt(2)
	v_pk_fma_f32 v[96:97], v[204:205], v[190:191], v[194:195]
	v_pk_fma_f32 v[94:95], v[140:141], v[188:189], v[192:193]
	s_waitcnt vmcnt(0)
	v_pk_fma_f32 v[100:101], v[208:209], v[202:203], v[198:199]
	v_pk_fma_f32 v[98:99], v[206:207], v[200:201], v[196:197]
	global_store_dwordx4 v[102:103], v[98:101], off nt
	global_store_dwordx4 v[102:103], v[94:97], off offset:1024 nt
	global_store_dwordx4 v[102:103], v[90:93], off offset:2048 nt
	global_store_dwordx4 v[102:103], v[86:89], off offset:3072 nt
	s_nop 1
	v_add_co_u32_e32 v86, vcc, 0x1000, v102
	s_nop 1
	v_addc_co_u32_e32 v87, vcc, 0, v103, vcc
	global_store_dwordx4 v[86:87], v[82:85], off nt
	global_store_dwordx4 v[86:87], v[78:81], off offset:1024 nt
	global_store_dwordx4 v[86:87], v[4:7], off offset:2048 nt
	global_store_dwordx4 v[86:87], v[0:3], off offset:3072 nt

.LBB0_4908:
	global_load_dwordx4 v[0:3], v[14:15], off
	global_load_dwordx4 v[4:7], v[12:13], off
	global_load_dwordx4 v[150:153], v[12:13], off offset:1024
	global_load_dwordx4 v[154:157], v[14:15], off offset:1024
	global_load_dwordx4 v[158:161], v[14:15], off offset:2048
	global_load_dwordx4 v[168:171], v[12:13], off offset:2048
	global_load_dwordx4 v[172:175], v[12:13], off offset:3072
	global_load_dwordx4 v[176:179], v[14:15], off offset:3072
	global_load_dwordx4 v[180:183], v[16:17], off
	global_load_dwordx4 v[184:187], v[18:19], off
	global_load_dwordx4 v[188:191], v[20:21], off
	global_load_dwordx4 v[192:195], v[22:23], off
	global_load_dwordx4 v[196:199], v[24:25], off
	global_load_dwordx4 v[200:203], v[26:27], off
	global_load_dwordx4 v[204:207], v[28:29], off
	global_load_dwordx4 v[208:211], v[30:31], off
	v_lshlrev_b32_e32 v9, 16, v74
	v_and_b32_e32 v74, 0xffff0000, v74
	v_mul_f32_e32 v144, 0x3b23d70a, v76
	v_mul_f32_e32 v142, 0x3b23d70a, v77
	v_lshlrev_b32_e32 v76, 16, v75
	v_and_b32_e32 v75, 0xffff0000, v75
	v_lshlrev_b32_e32 v77, 16, v72
	v_and_b32_e32 v72, 0xffff0000, v72
	v_lshlrev_b32_e32 v212, 16, v70
	v_and_b32_e32 v213, 0xffff0000, v70
	v_lshlrev_b32_e32 v214, 16, v71
	v_and_b32_e32 v215, 0xffff0000, v71
	v_lshlrev_b32_e32 v216, 16, v68
	v_and_b32_e32 v217, 0xffff0000, v68
	v_lshlrev_b32_e32 v218, 16, v69
	v_and_b32_e32 v219, 0xffff0000, v69
	v_sub_f32_e32 v69, v74, v58
	v_sub_f32_e32 v68, v9, v58
	v_lshlrev_b32_e32 v162, 16, v73
	v_and_b32_e32 v167, 0xffff0000, v73
	v_sub_f32_e32 v71, v75, v58
	v_sub_f32_e32 v70, v76, v58
	v_sub_f32_e32 v73, v72, v58
	v_sub_f32_e32 v72, v77, v58
	v_sub_f32_e32 v77, v213, v58
	v_sub_f32_e32 v76, v212, v58
	v_sub_f32_e32 v213, v215, v58
	v_sub_f32_e32 v212, v214, v58
	v_sub_f32_e32 v215, v217, v58
	v_sub_f32_e32 v214, v216, v58
	v_pk_mul_f32 v[68:69], v[58:59], v[68:69] op_sel:[1,0]
	v_sub_f32_e32 v75, v167, v58
	v_sub_f32_e32 v74, v162, v58
	v_sub_f32_e32 v217, v219, v58
	v_sub_f32_e32 v216, v218, v58
	v_pk_mul_f32 v[70:71], v[58:59], v[70:71] op_sel:[1,0]
	v_pk_mul_f32 v[72:73], v[58:59], v[72:73] op_sel:[1,0]
	v_pk_mul_f32 v[214:215], v[58:59], v[214:215] op_sel:[1,0]
	v_pk_mul_f32 v[74:75], v[58:59], v[74:75] op_sel:[1,0]
	v_pk_mul_f32 v[76:77], v[58:59], v[76:77] op_sel:[1,0]
	v_pk_mul_f32 v[216:217], v[58:59], v[216:217] op_sel:[1,0]
	v_lshlrev_b32_e32 v9, 16, v66
	v_and_b32_e32 v66, 0xffff0000, v66
	v_pk_mul_f32 v[212:213], v[58:59], v[212:213] op_sel:[1,0]
	s_nor_b64 s[0:1], s[0:1], s[14:15]
	s_waitcnt vmcnt(14)
	v_pk_fma_f32 v[0:1], v[68:69], v[4:5], v[0:1]
	v_pk_fma_f32 v[2:3], v[70:71], v[6:7], v[2:3]
	s_waitcnt vmcnt(12)
	v_pk_fma_f32 v[4:5], v[72:73], v[150:151], v[154:155]
	v_pk_mul_f32 v[0:1], v[0:1], s[22:23] op_sel_hi:[1,0]
	v_pk_fma_f32 v[6:7], v[74:75], v[152:153], v[156:157]
	s_waitcnt vmcnt(10)
	v_pk_fma_f32 v[68:69], v[76:77], v[168:169], v[158:159]
	s_waitcnt vmcnt(8)
	v_pk_fma_f32 v[72:73], v[214:215], v[172:173], v[176:177]
	v_pk_fma_f32 v[74:75], v[216:217], v[174:175], v[178:179]
	v_pk_mul_f32 v[2:3], v[2:3], s[22:23] op_sel_hi:[1,0]
	v_pk_fma_f32 v[76:77], v[144:145], v[78:79], v[0:1] op_sel_hi:[0,1,1]
	v_pk_mul_f32 v[72:73], v[72:73], s[22:23] op_sel_hi:[1,0]
	v_pk_fma_f32 v[0:1], v[144:145], v[84:85], v[2:3] op_sel_hi:[0,1,1]
	v_pk_fma_f32 v[2:3], v[142:143], v[110:111], v[76:77] op_sel_hi:[0,1,1]
	v_pk_mul_f32 v[74:75], v[74:75], s[22:23] op_sel_hi:[1,0]
	v_pk_fma_f32 v[76:77], v[144:145], v[106:107], v[72:73] op_sel_hi:[0,1,1]
	v_pk_fma_f32 v[72:73], v[144:145], v[108:109], v[74:75] op_sel_hi:[0,1,1]
	v_pk_fma_f32 v[74:75], v[142:143], v[138:139], v[76:77] op_sel_hi:[0,1,1]
	v_lshlrev_b32_e32 v76, 16, v67
	v_and_b32_e32 v77, 0xffff0000, v67
	v_sub_f32_e32 v67, v66, v58
	v_sub_f32_e32 v66, v9, v58
	v_sub_f32_e32 v77, v77, v58
	v_sub_f32_e32 v76, v76, v58
	v_pk_mul_f32 v[66:67], v[58:59], v[66:67] op_sel:[1,0]
	v_pk_mul_f32 v[4:5], v[4:5], s[22:23] op_sel_hi:[1,0]
	v_pk_mul_f32 v[76:77], v[58:59], v[76:77] op_sel:[1,0]
	s_waitcnt vmcnt(6)
	v_pk_fma_f32 v[66:67], v[66:67], v[180:181], v[184:185]
	v_pk_mul_f32 v[6:7], v[6:7], s[22:23] op_sel_hi:[1,0]
	v_pk_fma_f32 v[78:79], v[144:145], v[88:89], v[4:5] op_sel_hi:[0,1,1]
	v_pk_fma_f32 v[76:77], v[76:77], v[182:183], v[186:187]
	v_pk_mul_f32 v[66:67], v[66:67], s[22:23] op_sel_hi:[1,0]
	v_pk_fma_f32 v[4:5], v[144:145], v[92:93], v[6:7] op_sel_hi:[0,1,1]
	v_pk_fma_f32 v[6:7], v[142:143], v[118:119], v[78:79] op_sel_hi:[0,1,1]
	v_pk_mul_f32 v[76:77], v[76:77], s[22:23] op_sel_hi:[1,0]
	v_pk_fma_f32 v[78:79], v[144:145], v[98:99], v[66:67] op_sel_hi:[0,1,1]
	v_lshlrev_b32_e32 v9, 16, v64
	v_and_b32_e32 v64, 0xffff0000, v64
	v_pk_fma_f32 v[66:67], v[144:145], v[100:101], v[76:77] op_sel_hi:[0,1,1]
	v_pk_fma_f32 v[76:77], v[142:143], v[132:133], v[78:79] op_sel_hi:[0,1,1]
	v_lshlrev_b32_e32 v78, 16, v65
	v_and_b32_e32 v79, 0xffff0000, v65
	v_sub_f32_e32 v65, v64, v58
	v_sub_f32_e32 v64, v9, v58
	v_sub_f32_e32 v79, v79, v58
	v_sub_f32_e32 v78, v78, v58
	v_pk_mul_f32 v[64:65], v[58:59], v[64:65] op_sel:[1,0]
	v_pk_fma_f32 v[70:71], v[212:213], v[170:171], v[160:161]
	v_pk_mul_f32 v[68:69], v[68:69], s[22:23] op_sel_hi:[1,0]
	v_pk_mul_f32 v[78:79], v[58:59], v[78:79] op_sel:[1,0]
	s_waitcnt vmcnt(4)
; __device__ __forceinline__ void ln_norm2(f32x4 (&v)[8], const float* g, const float* b, int lane, float& mean_o, float& rstd_o) {
;     float s = 0.f;
; #pragma unroll
;     for (int j = 0; j < 8; ++j) s += (v[j][0] + v[j][1]) + (v[j][2] + v[j][3]);
;     const float mean = wave_sum(s) * (1.f / DM); float s2 = 0.f;
	v_pk_fma_f32 v[64:65], v[64:65], v[188:189], v[192:193]
	v_pk_mul_f32 v[70:71], v[70:71], s[22:23] op_sel_hi:[1,0]
	v_pk_fma_f32 v[84:85], v[144:145], v[102:103], v[68:69] op_sel_hi:[0,1,1]
	v_pk_fma_f32 v[78:79], v[78:79], v[190:191], v[194:195]
	v_pk_mul_f32 v[64:65], v[64:65], s[22:23] op_sel_hi:[1,0]
	v_pk_fma_f32 v[68:69], v[144:145], v[104:105], v[70:71] op_sel_hi:[0,1,1]
	v_pk_fma_f32 v[70:71], v[142:143], v[128:129], v[84:85] op_sel_hi:[0,1,1]
	v_pk_mul_f32 v[78:79], v[78:79], s[22:23] op_sel_hi:[1,0]
	v_pk_fma_f32 v[84:85], v[144:145], v[94:95], v[64:65] op_sel_hi:[0,1,1]
	v_lshlrev_b32_e32 v9, 16, v62
	v_and_b32_e32 v62, 0xffff0000, v62
	v_pk_fma_f32 v[64:65], v[144:145], v[96:97], v[78:79] op_sel_hi:[0,1,1]
	v_pk_fma_f32 v[78:79], v[142:143], v[126:127], v[84:85] op_sel_hi:[0,1,1]
	v_lshlrev_b32_e32 v84, 16, v63
	v_and_b32_e32 v85, 0xffff0000, v63
	v_sub_f32_e32 v63, v62, v58
	v_sub_f32_e32 v62, v9, v58
	v_sub_f32_e32 v85, v85, v58
	v_sub_f32_e32 v84, v84, v58
	v_pk_mul_f32 v[62:63], v[58:59], v[62:63] op_sel:[1,0]
	v_pk_mul_f32 v[84:85], v[58:59], v[84:85] op_sel:[1,0]
	s_waitcnt vmcnt(2)
	v_pk_fma_f32 v[62:63], v[62:63], v[196:197], v[200:201]
	v_pk_fma_f32 v[84:85], v[84:85], v[198:199], v[202:203]
	v_pk_mul_f32 v[62:63], v[62:63], s[22:23] op_sel_hi:[1,0]
	v_pk_mul_f32 v[84:85], v[84:85], s[22:23] op_sel_hi:[1,0]
	v_pk_fma_f32 v[86:87], v[144:145], v[86:87], v[62:63] op_sel_hi:[0,1,1]
	v_pk_fma_f32 v[62:63], v[144:145], v[90:91], v[84:85] op_sel_hi:[0,1,1]
	v_pk_fma_f32 v[84:85], v[142:143], v[120:121], v[86:87] op_sel_hi:[0,1,1]
	v_lshlrev_b32_e32 v9, 16, v60
	v_and_b32_e32 v60, 0xffff0000, v60
	v_lshlrev_b32_e32 v86, 16, v61
	v_and_b32_e32 v87, 0xffff0000, v61
	v_sub_f32_e32 v61, v60, v58
	v_sub_f32_e32 v60, v9, v58
	v_sub_f32_e32 v87, v87, v58
	v_sub_f32_e32 v86, v86, v58
	v_pk_mul_f32 v[86:87], v[58:59], v[86:87] op_sel:[1,0]
	v_pk_mul_f32 v[58:59], v[58:59], v[60:61] op_sel:[1,0]
	s_waitcnt vmcnt(0)
	v_pk_fma_f32 v[60:61], v[86:87], v[206:207], v[210:211]
	v_pk_fma_f32 v[58:59], v[58:59], v[204:205], v[208:209]
	v_pk_mul_f32 v[60:61], v[60:61], s[22:23] op_sel_hi:[1,0]
	v_pk_mul_f32 v[58:59], v[58:59], s[22:23] op_sel_hi:[1,0]
	v_pk_fma_f32 v[0:1], v[142:143], v[114:115], v[0:1] op_sel_hi:[0,1,1]
	v_pk_fma_f32 v[82:83], v[144:145], v[82:83], v[58:59] op_sel_hi:[0,1,1]
	v_pk_fma_f32 v[4:5], v[142:143], v[122:123], v[4:5] op_sel_hi:[0,1,1]
	v_pk_fma_f32 v[58:59], v[144:145], v[80:81], v[60:61] op_sel_hi:[0,1,1]
	v_pk_fma_f32 v[60:61], v[142:143], v[112:113], v[82:83] op_sel_hi:[0,1,1]
	v_mov_b32_e32 v80, v2
	v_mov_b32_e32 v81, v6
	v_mov_b32_e32 v82, v3
	v_mov_b32_e32 v83, v7
	v_pk_add_f32 v[80:81], v[80:81], v[82:83]
	v_mov_b32_e32 v82, v0
	v_mov_b32_e32 v83, v4
	v_mov_b32_e32 v86, v1
	v_mov_b32_e32 v87, v5
	v_pk_fma_f32 v[68:69], v[142:143], v[134:135], v[68:69] op_sel_hi:[0,1,1]
	v_pk_add_f32 v[82:83], v[82:83], v[86:87]
	v_mov_b32_e32 v86, v70
	v_pk_add_f32 v[80:81], v[80:81], v[82:83]
	v_pk_mov_b32 v[82:83], v[70:71], v[68:69] op_sel:[1,0]
	v_mov_b32_e32 v87, v69
	v_pk_add_f32 v[82:83], v[82:83], v[86:87]
	v_pk_fma_f32 v[72:73], v[142:143], v[140:141], v[72:73] op_sel_hi:[0,1,1]
	v_pk_fma_f32 v[66:67], v[142:143], v[136:137], v[66:67] op_sel_hi:[0,1,1]
	v_add_f32_e32 v9, 0, v80
	v_pk_add_f32 v[82:83], v[82:83], v[82:83] op_sel:[0,1] op_sel_hi:[1,0]
	v_add_f32_e32 v80, v9, v81
	v_add_f32_e32 v86, v74, v75
	v_add_f32_e32 v88, v72, v73
	v_mov_b32_e32 v81, v76
	v_mov_b32_e32 v83, v77
	v_mov_b32_e32 v87, v66
	v_mov_b32_e32 v89, v67
	v_pk_fma_f32 v[64:65], v[142:143], v[130:131], v[64:65] op_sel_hi:[0,1,1]
	v_pk_add_f32 v[80:81], v[80:81], v[82:83]
	v_pk_add_f32 v[82:83], v[86:87], v[88:89]
	v_mov_b32_e32 v86, v78
	v_pk_add_f32 v[80:81], v[80:81], v[82:83]
	v_pk_mov_b32 v[82:83], v[78:79], v[64:65] op_sel:[1,0]
	v_mov_b32_e32 v87, v65
	v_pk_add_f32 v[82:83], v[82:83], v[86:87]
	v_pk_fma_f32 v[62:63], v[142:143], v[124:125], v[62:63] op_sel_hi:[0,1,1]
	v_pk_fma_f32 v[58:59], v[142:143], v[116:117], v[58:59] op_sel_hi:[0,1,1]
	v_pk_add_f32 v[80:81], v[80:81], v[80:81] op_sel:[0,1] op_sel_hi:[1,0]
	v_pk_add_f32 v[82:83], v[82:83], v[82:83] op_sel:[0,1] op_sel_hi:[1,0]
	v_add_f32_e32 v86, v84, v85
	v_add_f32_e32 v88, v62, v63
	v_mov_b32_e32 v81, v60
	v_mov_b32_e32 v83, v61
	v_mov_b32_e32 v87, v58
	v_mov_b32_e32 v89, v59
	v_pk_add_f32 v[80:81], v[80:81], v[82:83]
	v_pk_add_f32 v[82:83], v[86:87], v[88:89]
	s_nop 0
	v_pk_add_f32 v[80:81], v[80:81], v[82:83]
	s_nop 0
	v_add_f32_e32 v9, v80, v81
	s_nop 1
	v_mov_b32_dpp v80, v9 quad_perm:[1,0,3,2] row_mask:0xf bank_mask:0xf
	s_waitcnt lgkmcnt(0)
	v_add_f32_e32 v9, v9, v80
	s_nop 1
	v_mov_b32_dpp v80, v9 quad_perm:[2,3,0,1] row_mask:0xf bank_mask:0xf
	s_waitcnt lgkmcnt(0)
	v_add_f32_e32 v9, v9, v80
	s_nop 1
	v_mov_b32_dpp v80, v9 row_half_mirror row_mask:0xf bank_mask:0xf
	s_waitcnt lgkmcnt(0)
	v_add_f32_e32 v9, v9, v80
	s_nop 1
	v_mov_b32_dpp v80, v9 row_mirror row_mask:0xf bank_mask:0xf
	s_waitcnt lgkmcnt(0)
	v_add_f32_e32 v9, v9, v80
	ds_bpermute_b32 v80, v148, v9
	s_waitcnt lgkmcnt(0)
	v_add_f32_e32 v9, v9, v80
	ds_bpermute_b32 v80, v149, v9
	s_waitcnt lgkmcnt(0)
; __device__ __forceinline__ void ln_norm2(f32x4 (&v)[8], const float* g, const float* b, int lane, float& mean_o, float& rstd_o) {
;     ...
;     const float mean = wave_sum(s) * (1.f / DM); float s2 = 0.f;
; #pragma unroll
;     for (int j = 0; j < 8; ++j) { v[j] = v[j] - mean; s2 += (v[j][0] * v[j][0] + v[j][1] * v[j][1]) + (v[j][2] * v[j][2] + v[j][3] * v[j][3]); }
;     const float rstd = 1.f / sqrtf(wave_sum(s2) * (1.f / DM) + LN_EPS);
	v_add_f32_e32 v9, v9, v80
	v_fmamk_f32 v1, v9, 0xba000000, v1
	v_fmamk_f32 v3, v9, 0xba000000, v3
	v_fmac_f32_e32 v0, 0xba000000, v9
	v_fmac_f32_e32 v2, 0xba000000, v9
	v_mul_f32_e32 v80, v3, v3
	v_mul_f32_e32 v81, v1, v1
	v_fmac_f32_e32 v80, v2, v2
	v_fmac_f32_e32 v81, v0, v0
	v_fmamk_f32 v5, v9, 0xba000000, v5
	v_fmamk_f32 v7, v9, 0xba000000, v7
	v_add_f32_e32 v80, v80, v81
	v_fmac_f32_e32 v4, 0xba000000, v9
	v_fmac_f32_e32 v6, 0xba000000, v9
	v_mul_f32_e32 v81, v7, v7
	v_mul_f32_e32 v82, v5, v5
	v_fmac_f32_e32 v81, v6, v6
	v_fmac_f32_e32 v82, v4, v4
	v_add_f32_e32 v81, v81, v82
	v_fmamk_f32 v69, v9, 0xba000000, v69
	v_fmamk_f32 v71, v9, 0xba000000, v71
	v_add_f32_e32 v80, v80, v81
	v_fmac_f32_e32 v68, 0xba000000, v9
	v_fmac_f32_e32 v70, 0xba000000, v9
	v_mul_f32_e32 v81, v71, v71
	v_mul_f32_e32 v82, v69, v69
	v_fmac_f32_e32 v81, v70, v70
	v_fmac_f32_e32 v82, v68, v68
	v_add_f32_e32 v81, v81, v82
	v_fmamk_f32 v73, v9, 0xba000000, v73
	v_fmamk_f32 v75, v9, 0xba000000, v75
	v_add_f32_e32 v80, v81, v80
	v_fmac_f32_e32 v72, 0xba000000, v9
	v_fmac_f32_e32 v74, 0xba000000, v9
	v_mul_f32_e32 v81, v75, v75
	v_mul_f32_e32 v82, v73, v73
	v_fmac_f32_e32 v81, v74, v74
	v_fmac_f32_e32 v82, v72, v72
	v_add_f32_e32 v81, v81, v82
	v_fmamk_f32 v67, v9, 0xba000000, v67
	v_fmamk_f32 v77, v9, 0xba000000, v77
	v_add_f32_e32 v80, v81, v80
	v_fmac_f32_e32 v66, 0xba000000, v9
	v_fmac_f32_e32 v76, 0xba000000, v9
	v_mul_f32_e32 v81, v77, v77
	v_mul_f32_e32 v82, v67, v67
	v_fmac_f32_e32 v81, v76, v76
	v_fmac_f32_e32 v82, v66, v66
	v_add_f32_e32 v81, v81, v82
	v_fmamk_f32 v65, v9, 0xba000000, v65
	v_fmamk_f32 v79, v9, 0xba000000, v79
	v_add_f32_e32 v80, v81, v80
	v_fmac_f32_e32 v64, 0xba000000, v9
	v_fmac_f32_e32 v78, 0xba000000, v9
	v_mul_f32_e32 v81, v79, v79
	v_mul_f32_e32 v82, v65, v65
	v_fmac_f32_e32 v81, v78, v78
	v_fmac_f32_e32 v82, v64, v64
	v_add_f32_e32 v81, v81, v82
	v_fmamk_f32 v63, v9, 0xba000000, v63
	v_fmamk_f32 v85, v9, 0xba000000, v85
	v_add_f32_e32 v80, v81, v80
	v_fmac_f32_e32 v62, 0xba000000, v9
	v_fmac_f32_e32 v84, 0xba000000, v9
	v_mul_f32_e32 v81, v85, v85
	v_mul_f32_e32 v82, v63, v63
	v_fmac_f32_e32 v81, v84, v84
	v_fmac_f32_e32 v82, v62, v62
	v_add_f32_e32 v81, v81, v82
	v_fmamk_f32 v59, v9, 0xba000000, v59
	v_fmamk_f32 v61, v9, 0xba000000, v61
	v_add_f32_e32 v80, v81, v80
	v_fmac_f32_e32 v58, 0xba000000, v9
	v_fmac_f32_e32 v60, 0xba000000, v9
	v_mul_f32_e32 v9, v61, v61
	v_mul_f32_e32 v81, v59, v59
	v_fmac_f32_e32 v9, v60, v60
	v_fmac_f32_e32 v81, v58, v58
	v_add_f32_e32 v9, v9, v81
	v_add_f32_e32 v9, v9, v80
	s_nop 1
	v_mov_b32_dpp v80, v9 quad_perm:[1,0,3,2] row_mask:0xf bank_mask:0xf
	s_waitcnt lgkmcnt(0)
	v_add_f32_e32 v9, v9, v80
	s_nop 1
	v_mov_b32_dpp v80, v9 quad_perm:[2,3,0,1] row_mask:0xf bank_mask:0xf
	s_waitcnt lgkmcnt(0)
	v_add_f32_e32 v9, v9, v80
	s_nop 1
	v_mov_b32_dpp v80, v9 row_half_mirror row_mask:0xf bank_mask:0xf
	s_waitcnt lgkmcnt(0)
	v_add_f32_e32 v9, v9, v80
	s_nop 1
	v_mov_b32_dpp v80, v9 row_mirror row_mask:0xf bank_mask:0xf
	s_waitcnt lgkmcnt(0)
	v_add_f32_e32 v9, v9, v80
	ds_bpermute_b32 v80, v148, v9
	s_waitcnt lgkmcnt(0)
	v_add_f32_e32 v9, v9, v80
	ds_bpermute_b32 v80, v149, v9
	s_and_saveexec_b64 s[2:3], s[0:1]
	s_cbranch_execz .LBB0_4893
; __device__ __forceinline__ void ln_norm2(f32x4 (&v)[8], const float* g, const float* b, int lane, float& mean_o, float& rstd_o) {
;     ...
;     const float rstd = 1.f / sqrtf(wave_sum(s2) * (1.f / DM) + LN_EPS);
; #pragma unroll
;     for (int j = 0; j < 8; ++j) { const f32x4 gv = *((const f32x4*)g + lane + 64 * j), bv = *((const f32x4*)b + lane + 64 * j); v[j] = v[j] * rstd * gv + bv; }
;     mean_o = mean; rstd_o = rstd;
; }
; __device__ __forceinline__ void ln_norm(f32x4 (&v)[8], const float* g, const float* b, int lane) { float m_, r_; ln_norm2(v, g, b, lane, m_, r_); }
;     if (hf) { f32x4* o = (f32x4*)(hf + m * DM) + lane;
; #pragma unroll
;         for (int j = 0; j < 8; ++j) __builtin_nontemporal_store(v[j], o + 64 * j); }
	global_load_dwordx4 v[86:89], v[34:35], off
	global_load_dwordx4 v[90:93], v[38:39], off
	global_load_dwordx4 v[94:97], v[40:41], off
	global_load_dwordx4 v[98:101], v[42:43], off
	global_load_dwordx4 v[102:105], v[44:45], off
	global_load_dwordx4 v[106:109], v[46:47], off
	global_load_dwordx4 v[110:113], v[48:49], off
	global_load_dwordx4 v[114:117], v[50:51], off
	global_load_dwordx4 v[118:121], v[36:37], off offset:3072
	global_load_dwordx4 v[122:125], v[32:33], off offset:3072
	global_load_dwordx4 v[126:129], v[32:33], off offset:2048
	global_load_dwordx4 v[130:133], v[36:37], off offset:2048
	global_load_dwordx4 v[134:137], v[36:37], off offset:1024
	global_load_dwordx4 v[138:141], v[32:33], off offset:1024
	global_load_dwordx4 v[142:145], v[32:33], off
	global_load_dwordx4 v[146:149], v[36:37], off
	s_waitcnt lgkmcnt(0)
	v_add_f32_e32 v9, v9, v80
	v_fmamk_f32 v9, v9, 0x3a000000, v165
	v_mul_f32_e32 v80, 0x4f800000, v9
	v_cmp_gt_f32_e32 vcc, s40, v9
	s_nop 1
	v_cndmask_b32_e32 v9, v9, v80, vcc
	v_sqrt_f32_e32 v80, v9
	s_nop 0
	v_add_u32_e32 v81, -1, v80
	v_add_u32_e32 v82, 1, v80
	v_fma_f32 v83, -v81, v80, v9
	v_fma_f32 v150, -v82, v80, v9
	v_cmp_ge_f32_e64 s[0:1], 0, v83
	s_nop 1
	v_cndmask_b32_e64 v80, v80, v81, s[0:1]
	v_cmp_lt_f32_e64 s[0:1], 0, v150
	s_nop 1
	v_cndmask_b32_e64 v80, v80, v82, s[0:1]
	v_mul_f32_e32 v81, 0x37800000, v80
	v_cndmask_b32_e32 v80, v80, v81, vcc
	v_cmp_class_f32_e32 vcc, v9, v166
	s_nop 1
	v_cndmask_b32_e32 v9, v80, v9, vcc
	v_div_scale_f32 v82, s[0:1], v9, v9, 1.0
	v_rcp_f32_e32 v83, v82
	v_lshlrev_b64 v[80:81], 13, v[56:57]
	v_div_scale_f32 v56, vcc, 1.0, v9, 1.0
	v_fma_f32 v57, -v82, v83, 1.0
	v_fmac_f32_e32 v83, v57, v83
	v_mul_f32_e32 v57, v56, v83
	v_fma_f32 v150, -v82, v57, v56
	v_fmac_f32_e32 v57, v150, v83
	v_fma_f32 v56, -v82, v57, v56
	v_div_fmas_f32 v56, v56, v83, v57
	v_div_fixup_f32 v56, v56, v9, 1.0
	v_pk_mul_f32 v[60:61], v[60:61], v[56:57] op_sel_hi:[1,0]
	v_pk_mul_f32 v[58:59], v[58:59], v[56:57] op_sel_hi:[1,0]
	v_pk_mul_f32 v[78:79], v[78:79], v[56:57] op_sel_hi:[1,0]
	v_pk_mul_f32 v[64:65], v[64:65], v[56:57] op_sel_hi:[1,0]
	v_pk_mul_f32 v[76:77], v[76:77], v[56:57] op_sel_hi:[1,0]
	v_pk_mul_f32 v[74:75], v[74:75], v[56:57] op_sel_hi:[1,0]
	v_pk_mul_f32 v[154:155], v[2:3], v[56:57] op_sel_hi:[1,0]
	v_pk_mul_f32 v[156:157], v[0:1], v[56:57] op_sel_hi:[1,0]
	v_pk_mul_f32 v[82:83], v[84:85], v[56:57] op_sel_hi:[1,0]
	v_pk_mul_f32 v[62:63], v[62:63], v[56:57] op_sel_hi:[1,0]
	v_pk_mul_f32 v[66:67], v[66:67], v[56:57] op_sel_hi:[1,0]
	v_pk_mul_f32 v[72:73], v[72:73], v[56:57] op_sel_hi:[1,0]
	v_pk_mul_f32 v[84:85], v[70:71], v[56:57] op_sel_hi:[1,0]
	v_pk_mul_f32 v[68:69], v[68:69], v[56:57] op_sel_hi:[1,0]
	v_pk_mul_f32 v[150:151], v[6:7], v[56:57] op_sel_hi:[1,0]
	v_pk_mul_f32 v[152:153], v[4:5], v[56:57] op_sel_hi:[1,0]
	v_lshl_add_u64 v[80:81], v[52:53], 0, v[80:81]
	s_waitcnt vmcnt(14)
	v_pk_fma_f32 v[2:3], v[92:93], v[58:59], v[88:89]
	v_pk_fma_f32 v[0:1], v[90:91], v[60:61], v[86:87]
	s_waitcnt vmcnt(12)
	v_pk_fma_f32 v[6:7], v[100:101], v[62:63], v[96:97]
	v_pk_fma_f32 v[4:5], v[98:99], v[82:83], v[94:95]
	s_waitcnt vmcnt(10)
	v_pk_fma_f32 v[58:59], v[108:109], v[64:65], v[104:105]
	v_pk_fma_f32 v[56:57], v[106:107], v[78:79], v[102:103]
	s_waitcnt vmcnt(8)
	v_pk_fma_f32 v[60:61], v[114:115], v[76:77], v[110:111]
	v_pk_fma_f32 v[62:63], v[116:117], v[66:67], v[112:113]
	s_waitcnt vmcnt(6)
	v_pk_fma_f32 v[64:65], v[118:119], v[74:75], v[122:123]
	v_pk_fma_f32 v[66:67], v[120:121], v[72:73], v[124:125]
	s_waitcnt vmcnt(4)
	v_pk_fma_f32 v[70:71], v[132:133], v[68:69], v[128:129]
	v_pk_fma_f32 v[68:69], v[130:131], v[84:85], v[126:127]
	s_waitcnt vmcnt(2)
	v_pk_fma_f32 v[74:75], v[136:137], v[152:153], v[140:141]
	v_pk_fma_f32 v[72:73], v[134:135], v[150:151], v[138:139]
	s_waitcnt vmcnt(0)
	v_pk_fma_f32 v[78:79], v[148:149], v[156:157], v[144:145]
	v_pk_fma_f32 v[76:77], v[146:147], v[154:155], v[142:143]
	global_store_dwordx4 v[80:81], v[76:79], off nt
	global_store_dwordx4 v[80:81], v[72:75], off offset:1024 nt
	global_store_dwordx4 v[80:81], v[68:71], off offset:2048 nt
	global_store_dwordx4 v[80:81], v[64:67], off offset:3072 nt
	s_nop 1
	v_add_co_u32_e32 v64, vcc, 0x1000, v80
	s_nop 1
	v_addc_co_u32_e32 v65, vcc, 0, v81, vcc
	global_store_dwordx4 v[64:65], v[60:63], off nt
	global_store_dwordx4 v[64:65], v[56:59], off offset:1024 nt
	global_store_dwordx4 v[64:65], v[4:7], off offset:2048 nt
	global_store_dwordx4 v[64:65], v[0:3], off offset:3072 nt
	s_branch .LBB0_4893
